# v28 plus extra s_setprio 0/1 priority windows after every 8 MFMAs
# baseline (speedup 1.0000x reference)
.LBB0_379:
	v_add_u32_e32 v14, s56, v140
	v_add_u32_e32 v30, s57, v140
	ds_read_b128 v[2:5], v14
	ds_read_b128 v[6:9], v14 offset:1024
	ds_read_b128 v[10:13], v14 offset:2048
	ds_read_b128 v[14:17], v14 offset:3072
	ds_read_b128 v[18:21], v30
	ds_read_b128 v[22:25], v30 offset:1024
	ds_read_b128 v[26:29], v30 offset:2048
	ds_read_b128 v[30:33], v30 offset:3072
	v_add_u32_e32 v141, 0, v1
	ds_read_b128 v[34:37], v141
	ds_read_b128 v[38:41], v141 offset:1024
	ds_read_b128 v[42:45], v141 offset:2048
	ds_read_b128 v[46:49], v141 offset:3072
	ds_read_b128 v[50:53], v141 offset:4096
	ds_read_b128 v[54:57], v141 offset:5120
	ds_read_b128 v[58:61], v141 offset:6144
	ds_read_b128 v[62:65], v141 offset:7168
	s_waitcnt vmcnt(8)
	s_waitcnt lgkmcnt(0)
	s_barrier
	s_setprio 1
	s_waitcnt lgkmcnt(0)
	v_mfma_f32_16x16x32_bf16 v[66:69], v[2:5], v[34:37], 0
	v_mfma_f32_16x16x32_bf16 v[66:69], v[6:9], v[38:41], v[66:69]
	v_mfma_f32_16x16x32_bf16 v[70:73], v[10:13], v[34:37], 0
	v_mfma_f32_16x16x32_bf16 v[70:73], v[14:17], v[38:41], v[70:73]
	v_mfma_f32_16x16x32_bf16 v[78:81], v[10:13], v[42:45], 0
	v_mfma_f32_16x16x32_bf16 v[78:81], v[14:17], v[46:49], v[78:81]
	v_mfma_f32_16x16x32_bf16 v[74:77], v[2:5], v[42:45], 0
	v_mfma_f32_16x16x32_bf16 v[74:77], v[6:9], v[46:49], v[74:77]
	s_setprio 0
	s_setprio 1
	v_mfma_f32_16x16x32_bf16 v[82:85], v[2:5], v[50:53], 0
	v_mfma_f32_16x16x32_bf16 v[82:85], v[6:9], v[54:57], v[82:85]
	v_mfma_f32_16x16x32_bf16 v[86:89], v[10:13], v[50:53], 0
	v_mfma_f32_16x16x32_bf16 v[86:89], v[14:17], v[54:57], v[86:89]
	v_mfma_f32_16x16x32_bf16 v[94:97], v[10:13], v[58:61], 0
	v_mfma_f32_16x16x32_bf16 v[94:97], v[14:17], v[62:65], v[94:97]
	v_mfma_f32_16x16x32_bf16 v[90:93], v[2:5], v[58:61], 0
	v_mfma_f32_16x16x32_bf16 v[90:93], v[6:9], v[62:65], v[90:93]
	s_setprio 0
	s_setprio 1
	v_mfma_f32_16x16x32_bf16 v[98:101], v[18:21], v[34:37], 0
	v_mfma_f32_16x16x32_bf16 v[34:37], v[26:29], v[34:37], 0
	v_mfma_f32_16x16x32_bf16 v[102:105], v[18:21], v[42:45], 0
	v_mfma_f32_16x16x32_bf16 v[42:45], v[26:29], v[42:45], 0
	v_mfma_f32_16x16x32_bf16 v[106:109], v[18:21], v[50:53], 0
	v_mfma_f32_16x16x32_bf16 v[50:53], v[26:29], v[50:53], 0
	v_mfma_f32_16x16x32_bf16 v[110:113], v[18:21], v[58:61], 0
	v_mfma_f32_16x16x32_bf16 v[58:61], v[26:29], v[58:61], 0
	s_setprio 0
	s_setprio 1
	v_mfma_f32_16x16x32_bf16 v[98:101], v[22:25], v[38:41], v[98:101]
	v_mfma_f32_16x16x32_bf16 v[38:41], v[30:33], v[38:41], v[34:37]
	v_mfma_f32_16x16x32_bf16 v[102:105], v[22:25], v[46:49], v[102:105]
	v_mfma_f32_16x16x32_bf16 v[46:49], v[30:33], v[46:49], v[42:45]
	v_mfma_f32_16x16x32_bf16 v[106:109], v[22:25], v[54:57], v[106:109]
	v_mfma_f32_16x16x32_bf16 v[54:57], v[30:33], v[54:57], v[50:53]
	s_setprio 2
	s_barrier
	v_mfma_f32_16x16x32_bf16 v[110:113], v[22:25], v[62:65], v[110:113]
	v_mfma_f32_16x16x32_bf16 v[62:65], v[30:33], v[62:65], v[58:61]
	s_setprio 0
	v_lshl_add_u64 v[136:137], s[38:39], 0, v[130:131]
	s_add_i32 s60, s56, s21
	v_mov_b32_e32 v135, v131
	v_lshl_add_u64 v[142:143], v[136:137], 0, s[10:11]
	s_mov_b32 m0, s60
	v_lshl_add_u64 v[244:245], s[38:39], 0, v[134:135]
	ds_read_b128 v[34:37], v141 offset:16384
	ds_read_b128 v[42:45], v141 offset:17408
	ds_read_b128 v[50:53], v141 offset:18432
	ds_read_b128 v[58:61], v141 offset:19456
	ds_read_b128 v[114:117], v141 offset:20480
	ds_read_b128 v[118:121], v141 offset:21504
	ds_read_b128 v[122:125], v141 offset:22528
	ds_read_b128 v[126:129], v141 offset:23552
	global_load_lds_dwordx4 v[142:143], off
	v_lshl_add_u64 v[142:143], v[244:245], 0, s[10:11]
	s_add_i32 m0, s60, 0x2000
	s_add_i32 s60, s57, s21
	global_load_lds_dwordx4 v[142:143], off
	s_mov_b32 m0, s60
	v_mov_b32_e32 v139, v131
	global_load_lds_dwordx4 v130, s[40:41]
	s_add_i32 m0, s60, 0x2000
	v_lshl_add_u64 v[246:247], s[36:37], 0, v[138:139]
	v_mov_b32_e32 v133, v131
	global_load_lds_dwordx4 v134, s[40:41]
	v_lshl_add_u64 v[142:143], v[246:247], 0, s[10:11]
	s_mov_b32 m0, s33
	v_lshl_add_u64 v[248:249], s[36:37], 0, v[132:133]
	global_load_lds_dwordx4 v[142:143], off
	v_lshl_add_u64 v[142:143], v[248:249], 0, s[10:11]
	s_mov_b32 m0, s46
	s_nop 0
	global_load_lds_dwordx4 v[142:143], off
	s_waitcnt vmcnt(8)
	s_waitcnt lgkmcnt(0)
	s_barrier
	s_setprio 1
	s_waitcnt lgkmcnt(0)
	v_mfma_f32_16x16x32_bf16 v[142:145], v[2:5], v[34:37], 0
	v_mfma_f32_16x16x32_bf16 v[148:151], v[10:13], v[34:37], 0
	v_mfma_f32_16x16x32_bf16 v[152:155], v[2:5], v[50:53], 0
	v_mfma_f32_16x16x32_bf16 v[156:159], v[10:13], v[50:53], 0
	v_mfma_f32_16x16x32_bf16 v[160:163], v[2:5], v[114:117], 0
	v_mfma_f32_16x16x32_bf16 v[164:167], v[10:13], v[114:117], 0
	v_mfma_f32_16x16x32_bf16 v[2:5], v[2:5], v[122:125], 0
	v_mfma_f32_16x16x32_bf16 v[10:13], v[10:13], v[122:125], 0
	s_setprio 0
	s_setprio 1
	v_mfma_f32_16x16x32_bf16 v[142:145], v[6:9], v[42:45], v[142:145]
	v_mfma_f32_16x16x32_bf16 v[148:151], v[14:17], v[42:45], v[148:151]
	v_mfma_f32_16x16x32_bf16 v[152:155], v[6:9], v[58:61], v[152:155]
	v_mfma_f32_16x16x32_bf16 v[156:159], v[14:17], v[58:61], v[156:159]
	v_mfma_f32_16x16x32_bf16 v[160:163], v[6:9], v[118:121], v[160:163]
	v_mfma_f32_16x16x32_bf16 v[164:167], v[14:17], v[118:121], v[164:167]
	v_mfma_f32_16x16x32_bf16 v[168:171], v[6:9], v[126:129], v[2:5]
	v_mfma_f32_16x16x32_bf16 v[172:175], v[14:17], v[126:129], v[10:13]
	s_setprio 0
	s_setprio 1
	v_mfma_f32_16x16x32_bf16 v[2:5], v[18:21], v[34:37], 0
	v_mfma_f32_16x16x32_bf16 v[6:9], v[26:29], v[34:37], 0
	v_mfma_f32_16x16x32_bf16 v[10:13], v[18:21], v[50:53], 0
	v_mfma_f32_16x16x32_bf16 v[14:17], v[26:29], v[50:53], 0
	v_mfma_f32_16x16x32_bf16 v[34:37], v[18:21], v[114:117], 0
	v_mfma_f32_16x16x32_bf16 v[50:53], v[26:29], v[114:117], 0
	v_mfma_f32_16x16x32_bf16 v[18:21], v[18:21], v[122:125], 0
	v_mfma_f32_16x16x32_bf16 v[26:29], v[26:29], v[122:125], 0
	s_setprio 0
	s_setprio 1
	v_mfma_f32_16x16x32_bf16 v[114:117], v[22:25], v[42:45], v[2:5]
	v_mfma_f32_16x16x32_bf16 v[188:191], v[22:25], v[118:121], v[34:37]
	v_mfma_f32_16x16x32_bf16 v[118:121], v[30:33], v[118:121], v[50:53]
	v_mfma_f32_16x16x32_bf16 v[176:179], v[30:33], v[42:45], v[6:9]
	v_mfma_f32_16x16x32_bf16 v[180:183], v[22:25], v[58:61], v[10:13]
	v_mfma_f32_16x16x32_bf16 v[184:187], v[30:33], v[58:61], v[14:17]
	s_setprio 2
	s_barrier
	v_mfma_f32_16x16x32_bf16 v[192:195], v[22:25], v[126:129], v[18:21]
	v_mfma_f32_16x16x32_bf16 v[196:199], v[30:33], v[126:129], v[26:29]
	s_setprio 0
	s_add_i32 s60, 0, 0x18000
	v_add_u32_e32 v2, s60, v140
	s_add_i32 s61, 0, 0x1c000
	ds_read_b128 v[200:203], v2
	ds_read_b128 v[204:207], v2 offset:1024
	ds_read_b128 v[208:211], v2 offset:2048
	ds_read_b128 v[212:215], v2 offset:3072
	v_add_u32_e32 v2, s61, v140
	ds_read_b128 v[216:219], v2
	ds_read_b128 v[220:223], v2 offset:1024
	ds_read_b128 v[224:227], v2 offset:2048
	ds_read_b128 v[228:231], v2 offset:3072
	s_mov_b32 m0, s47
	ds_read_b128 v[42:45], v141 offset:32768
	ds_read_b128 v[50:53], v141 offset:33792
	ds_read_b128 v[58:61], v141 offset:34816
	ds_read_b128 v[122:125], v141 offset:35840
	ds_read_b128 v[126:129], v141 offset:36864
	ds_read_b128 v[232:235], v141 offset:37888
	ds_read_b128 v[236:239], v141 offset:38912
	ds_read_b128 v[240:243], v141 offset:39936
	global_load_lds_dwordx4 v138, s[42:43]
	s_mov_b32 m0, s48
	s_nop 0
	global_load_lds_dwordx4 v132, s[42:43]
	s_waitcnt vmcnt(8)
	s_waitcnt lgkmcnt(0)
	s_barrier
	s_setprio 1
	s_waitcnt lgkmcnt(0)
	v_mfma_f32_16x16x32_bf16 v[2:5], v[200:203], v[42:45], v[66:69]
	v_mfma_f32_16x16x32_bf16 v[6:9], v[208:211], v[42:45], v[70:73]
	v_mfma_f32_16x16x32_bf16 v[10:13], v[200:203], v[58:61], v[74:77]
	v_mfma_f32_16x16x32_bf16 v[14:17], v[208:211], v[58:61], v[78:81]
	v_mfma_f32_16x16x32_bf16 v[18:21], v[200:203], v[126:129], v[82:85]
	v_mfma_f32_16x16x32_bf16 v[22:25], v[208:211], v[126:129], v[86:89]
	v_mfma_f32_16x16x32_bf16 v[26:29], v[200:203], v[236:239], v[90:93]
	v_mfma_f32_16x16x32_bf16 v[30:33], v[208:211], v[236:239], v[94:97]
	s_setprio 0
	s_setprio 1
	v_mfma_f32_16x16x32_bf16 v[2:5], v[204:207], v[50:53], v[2:5]
	v_mfma_f32_16x16x32_bf16 v[6:9], v[212:215], v[50:53], v[6:9]
	v_mfma_f32_16x16x32_bf16 v[10:13], v[204:207], v[122:125], v[10:13]
	v_mfma_f32_16x16x32_bf16 v[14:17], v[212:215], v[122:125], v[14:17]
	v_mfma_f32_16x16x32_bf16 v[18:21], v[204:207], v[232:235], v[18:21]
	v_mfma_f32_16x16x32_bf16 v[22:25], v[212:215], v[232:235], v[22:25]
	v_mfma_f32_16x16x32_bf16 v[26:29], v[204:207], v[240:243], v[26:29]
	v_mfma_f32_16x16x32_bf16 v[30:33], v[212:215], v[240:243], v[30:33]
	s_setprio 0
	s_setprio 1
	v_mfma_f32_16x16x32_bf16 v[34:37], v[216:219], v[42:45], v[98:101]
	v_mfma_f32_16x16x32_bf16 v[38:41], v[224:227], v[42:45], v[38:41]
	v_mfma_f32_16x16x32_bf16 v[34:37], v[220:223], v[50:53], v[34:37]
	v_mfma_f32_16x16x32_bf16 v[38:41], v[228:231], v[50:53], v[38:41]
	v_mfma_f32_16x16x32_bf16 v[42:45], v[216:219], v[58:61], v[102:105]
	v_mfma_f32_16x16x32_bf16 v[46:49], v[224:227], v[58:61], v[46:49]
	v_mfma_f32_16x16x32_bf16 v[50:53], v[216:219], v[126:129], v[106:109]
	v_mfma_f32_16x16x32_bf16 v[54:57], v[224:227], v[126:129], v[54:57]
	s_setprio 0
	s_setprio 1
	v_mfma_f32_16x16x32_bf16 v[58:61], v[216:219], v[236:239], v[110:113]
	v_mfma_f32_16x16x32_bf16 v[62:65], v[224:227], v[236:239], v[62:65]
	v_mfma_f32_16x16x32_bf16 v[42:45], v[220:223], v[122:125], v[42:45]
	v_mfma_f32_16x16x32_bf16 v[46:49], v[228:231], v[122:125], v[46:49]
	v_mfma_f32_16x16x32_bf16 v[50:53], v[220:223], v[232:235], v[50:53]
	v_mfma_f32_16x16x32_bf16 v[54:57], v[228:231], v[232:235], v[54:57]
	s_setprio 2
	s_barrier
	v_mfma_f32_16x16x32_bf16 v[58:61], v[220:223], v[240:243], v[58:61]
	v_mfma_f32_16x16x32_bf16 v[62:65], v[228:231], v[240:243], v[62:65]
	s_setprio 0
	s_add_i32 s60, s60, s21
	v_lshl_add_u64 v[66:67], v[136:137], 0, s[12:13]
	s_mov_b32 m0, s60
	ds_read_b128 v[94:97], v141 offset:49152
	ds_read_b128 v[98:101], v141 offset:50176
	ds_read_b128 v[102:105], v141 offset:51200
	ds_read_b128 v[106:109], v141 offset:52224
	ds_read_b128 v[110:113], v141 offset:53248
	ds_read_b128 v[232:235], v141 offset:54272
	ds_read_b128 v[236:239], v141 offset:55296
	ds_read_b128 v[240:243], v141 offset:56320
	global_load_lds_dwordx4 v[66:67], off
	v_lshl_add_u64 v[66:67], v[244:245], 0, s[12:13]
	s_add_i32 m0, s60, 0x2000
	s_add_i32 s60, s61, s21
	global_load_lds_dwordx4 v[66:67], off
	s_mov_b32 m0, s60
	v_lshl_add_u64 v[66:67], v[246:247], 0, s[12:13]
	global_load_lds_dwordx4 v130, s[44:45]
	s_add_i32 m0, s60, 0x2000
	s_nop 0
	global_load_lds_dwordx4 v134, s[44:45]
	s_mov_b32 m0, s52
	s_nop 0
	global_load_lds_dwordx4 v[66:67], off
	v_lshl_add_u64 v[66:67], v[248:249], 0, s[12:13]
	s_mov_b32 m0, s53
	s_nop 0
	global_load_lds_dwordx4 v[66:67], off
	s_waitcnt vmcnt(8)
	s_waitcnt lgkmcnt(0)
	s_barrier
	s_setprio 1
	s_waitcnt lgkmcnt(0)
	v_mfma_f32_16x16x32_bf16 v[66:69], v[200:203], v[94:97], v[142:145]
	v_mfma_f32_16x16x32_bf16 v[122:125], v[204:207], v[98:101], v[66:69]
	v_mfma_f32_16x16x32_bf16 v[66:69], v[208:211], v[94:97], v[148:151]
	v_mfma_f32_16x16x32_bf16 v[126:129], v[212:215], v[98:101], v[66:69]
	v_mfma_f32_16x16x32_bf16 v[66:69], v[200:203], v[102:105], v[152:155]
	v_mfma_f32_16x16x32_bf16 v[70:73], v[208:211], v[102:105], v[156:159]
	v_mfma_f32_16x16x32_bf16 v[74:77], v[200:203], v[110:113], v[160:163]
	v_mfma_f32_16x16x32_bf16 v[78:81], v[208:211], v[110:113], v[164:167]
	s_setprio 0
	s_setprio 1
	v_mfma_f32_16x16x32_bf16 v[82:85], v[200:203], v[236:239], v[168:171]
	v_mfma_f32_16x16x32_bf16 v[86:89], v[208:211], v[236:239], v[172:175]
	v_mfma_f32_16x16x32_bf16 v[66:69], v[204:207], v[106:109], v[66:69]
	v_mfma_f32_16x16x32_bf16 v[70:73], v[212:215], v[106:109], v[70:73]
	v_mfma_f32_16x16x32_bf16 v[74:77], v[204:207], v[232:235], v[74:77]
	v_mfma_f32_16x16x32_bf16 v[78:81], v[212:215], v[232:235], v[78:81]
	v_mfma_f32_16x16x32_bf16 v[82:85], v[204:207], v[240:243], v[82:85]
	v_mfma_f32_16x16x32_bf16 v[86:89], v[212:215], v[240:243], v[86:89]
	s_setprio 0
	s_setprio 1
	v_mfma_f32_16x16x32_bf16 v[90:93], v[216:219], v[94:97], v[114:117]
	v_mfma_f32_16x16x32_bf16 v[94:97], v[224:227], v[94:97], v[176:179]
	v_mfma_f32_16x16x32_bf16 v[90:93], v[220:223], v[98:101], v[90:93]
	v_mfma_f32_16x16x32_bf16 v[94:97], v[228:231], v[98:101], v[94:97]
	v_mfma_f32_16x16x32_bf16 v[98:101], v[216:219], v[102:105], v[180:183]
	v_mfma_f32_16x16x32_bf16 v[102:105], v[224:227], v[102:105], v[184:187]
	v_mfma_f32_16x16x32_bf16 v[98:101], v[220:223], v[106:109], v[98:101]
	v_mfma_f32_16x16x32_bf16 v[102:105], v[228:231], v[106:109], v[102:105]
	s_setprio 0
	s_setprio 1
	v_mfma_f32_16x16x32_bf16 v[106:109], v[216:219], v[110:113], v[188:191]
	v_mfma_f32_16x16x32_bf16 v[110:113], v[224:227], v[110:113], v[118:121]
	v_mfma_f32_16x16x32_bf16 v[114:117], v[216:219], v[236:239], v[192:195]
	v_mfma_f32_16x16x32_bf16 v[118:121], v[224:227], v[236:239], v[196:199]
	v_mfma_f32_16x16x32_bf16 v[106:109], v[220:223], v[232:235], v[106:109]
	v_mfma_f32_16x16x32_bf16 v[110:113], v[228:231], v[232:235], v[110:113]
	s_setprio 2
	s_barrier
	v_mfma_f32_16x16x32_bf16 v[114:117], v[220:223], v[240:243], v[114:117]
	v_mfma_f32_16x16x32_bf16 v[118:121], v[228:231], v[240:243], v[118:121]
	s_setprio 0
	s_add_i32 s59, s59, 2
	s_cmp_ge_i32 s59, s15
	s_cbranch_scc0 .LBB0_379
	v_mov_b32_e32 v136, v130
	s_branch .LBB0_382

.LBB0_383:
	v_add_u32_e32 v133, s56, v140
	ds_read_b128 v[142:145], v133
	ds_read_b128 v[148:151], v133 offset:1024
	ds_read_b128 v[152:155], v133 offset:2048
	ds_read_b128 v[156:159], v133 offset:3072
	v_add_u32_e32 v133, s57, v140
	ds_read_b128 v[160:163], v133
	ds_read_b128 v[164:167], v133 offset:1024
	ds_read_b128 v[168:171], v133 offset:2048
	ds_read_b128 v[172:175], v133 offset:3072
	s_add_u32 s38, s36, 0xfff80080
	s_addc_u32 s39, s37, -1
	s_cmp_eq_u32 s43, 28
	s_cselect_b32 s41, s31, s39
	s_cselect_b32 s40, s30, s38
	s_cselect_b32 s39, s35, s42
	s_cselect_b32 s38, s34, s15
	s_mov_b32 m0, s54
	v_add_u32_e32 v141, 0, v1
	ds_read_b128 v[176:179], v141
	ds_read_b128 v[180:183], v141 offset:1024
	ds_read_b128 v[184:187], v141 offset:2048
	ds_read_b128 v[188:191], v141 offset:3072
	ds_read_b128 v[192:195], v141 offset:4096
	ds_read_b128 v[196:199], v141 offset:5120
	ds_read_b128 v[200:203], v141 offset:6144
	ds_read_b128 v[204:207], v141 offset:7168
	global_load_lds_dwordx4 v130, s[36:37]
	s_mov_b32 m0, s55
	v_mov_b32_e32 v133, v131
	global_load_lds_dwordx4 v132, s[36:37]
	s_waitcnt vmcnt(8)
	s_waitcnt lgkmcnt(0)
	s_barrier
	s_setprio 1
	s_waitcnt lgkmcnt(0)
	v_mfma_f32_16x16x32_bf16 v[2:5], v[142:145], v[176:179], v[2:5]
	v_mfma_f32_16x16x32_bf16 v[2:5], v[148:151], v[180:183], v[2:5]
	v_mfma_f32_16x16x32_bf16 v[6:9], v[156:159], v[180:183], v[6:9]
	v_mfma_f32_16x16x32_bf16 v[6:9], v[152:155], v[176:179], v[6:9]
	v_mfma_f32_16x16x32_bf16 v[14:17], v[152:155], v[184:187], v[14:17]
	v_mfma_f32_16x16x32_bf16 v[14:17], v[156:159], v[188:191], v[14:17]
	v_mfma_f32_16x16x32_bf16 v[10:13], v[148:151], v[188:191], v[10:13]
	v_mfma_f32_16x16x32_bf16 v[10:13], v[142:145], v[184:187], v[10:13]
	s_setprio 0
	s_setprio 1
	v_mfma_f32_16x16x32_bf16 v[18:21], v[142:145], v[192:195], v[18:21]
	v_mfma_f32_16x16x32_bf16 v[18:21], v[148:151], v[196:199], v[18:21]
	v_mfma_f32_16x16x32_bf16 v[22:25], v[156:159], v[196:199], v[22:25]
	v_mfma_f32_16x16x32_bf16 v[22:25], v[152:155], v[192:195], v[22:25]
	v_mfma_f32_16x16x32_bf16 v[30:33], v[152:155], v[200:203], v[30:33]
	v_mfma_f32_16x16x32_bf16 v[30:33], v[156:159], v[204:207], v[30:33]
	v_mfma_f32_16x16x32_bf16 v[26:29], v[148:151], v[204:207], v[26:29]
	v_mfma_f32_16x16x32_bf16 v[26:29], v[142:145], v[200:203], v[26:29]
	s_setprio 0
	s_setprio 1
	v_mfma_f32_16x16x32_bf16 v[34:37], v[160:163], v[176:179], v[34:37]
	v_mfma_f32_16x16x32_bf16 v[34:37], v[164:167], v[180:183], v[34:37]
	v_mfma_f32_16x16x32_bf16 v[38:41], v[172:175], v[180:183], v[38:41]
	v_mfma_f32_16x16x32_bf16 v[38:41], v[168:171], v[176:179], v[38:41]
	v_mfma_f32_16x16x32_bf16 v[46:49], v[168:171], v[184:187], v[46:49]
	v_mfma_f32_16x16x32_bf16 v[46:49], v[172:175], v[188:191], v[46:49]
	v_mfma_f32_16x16x32_bf16 v[42:45], v[164:167], v[188:191], v[42:45]
	v_mfma_f32_16x16x32_bf16 v[42:45], v[160:163], v[184:187], v[42:45]
	s_setprio 0
	s_setprio 1
	v_mfma_f32_16x16x32_bf16 v[50:53], v[160:163], v[192:195], v[50:53]
	v_mfma_f32_16x16x32_bf16 v[50:53], v[164:167], v[196:199], v[50:53]
	v_mfma_f32_16x16x32_bf16 v[54:57], v[172:175], v[196:199], v[54:57]
	v_mfma_f32_16x16x32_bf16 v[54:57], v[168:171], v[192:195], v[54:57]
	v_mfma_f32_16x16x32_bf16 v[62:65], v[168:171], v[200:203], v[62:65]
	v_mfma_f32_16x16x32_bf16 v[62:65], v[172:175], v[204:207], v[62:65]
	s_setprio 2
	s_barrier
	v_mfma_f32_16x16x32_bf16 v[58:61], v[164:167], v[204:207], v[58:61]
	v_mfma_f32_16x16x32_bf16 v[58:61], v[160:163], v[200:203], v[58:61]
	s_setprio 0
	s_add_i32 s44, s56, s21
	s_mov_b32 m0, s44
	ds_read_b128 v[176:179], v141 offset:16384
	ds_read_b128 v[180:183], v141 offset:17408
	ds_read_b128 v[184:187], v141 offset:18432
	ds_read_b128 v[188:191], v141 offset:19456
	ds_read_b128 v[192:195], v141 offset:20480
	ds_read_b128 v[196:199], v141 offset:21504
	ds_read_b128 v[200:203], v141 offset:22528
	ds_read_b128 v[204:207], v141 offset:23552
	global_load_lds_dwordx4 v136, s[38:39]
	s_add_i32 m0, s44, 0x2000
	s_add_u32 s44, s38, 0x80000
	s_addc_u32 s45, s39, 0
	s_add_i32 s59, s57, s21
	global_load_lds_dwordx4 v134, s[38:39]
	s_mov_b32 m0, s59
	v_mov_b32_e32 v137, v131
	global_load_lds_dwordx4 v136, s[44:45]
	s_add_i32 m0, s59, 0x2000
	v_mov_b32_e32 v135, v131
	global_load_lds_dwordx4 v134, s[44:45]
	s_mov_b32 m0, s33
	v_lshl_add_u64 v[138:139], s[38:39], 0, v[136:137]
	global_load_lds_dwordx4 v130, s[40:41]
	s_mov_b32 m0, s46
	v_lshl_add_u64 v[208:209], s[38:39], 0, v[134:135]
	global_load_lds_dwordx4 v132, s[40:41]
	s_waitcnt vmcnt(8)
	s_waitcnt lgkmcnt(0)
	v_lshl_add_u64 v[210:211], s[40:41], 0, v[130:131]
	v_lshl_add_u64 v[212:213], s[40:41], 0, v[132:133]
	s_barrier
	s_setprio 1
	s_waitcnt lgkmcnt(0)
	v_mfma_f32_16x16x32_bf16 v[122:125], v[142:145], v[176:179], v[122:125]
	v_mfma_f32_16x16x32_bf16 v[122:125], v[148:151], v[180:183], v[122:125]
	v_mfma_f32_16x16x32_bf16 v[126:129], v[156:159], v[180:183], v[126:129]
	v_mfma_f32_16x16x32_bf16 v[126:129], v[152:155], v[176:179], v[126:129]
	v_mfma_f32_16x16x32_bf16 v[70:73], v[152:155], v[184:187], v[70:73]
	v_mfma_f32_16x16x32_bf16 v[70:73], v[156:159], v[188:191], v[70:73]
	v_mfma_f32_16x16x32_bf16 v[66:69], v[148:151], v[188:191], v[66:69]
	v_mfma_f32_16x16x32_bf16 v[66:69], v[142:145], v[184:187], v[66:69]
	s_setprio 0
	s_setprio 1
	v_mfma_f32_16x16x32_bf16 v[74:77], v[142:145], v[192:195], v[74:77]
	v_mfma_f32_16x16x32_bf16 v[74:77], v[148:151], v[196:199], v[74:77]
	v_mfma_f32_16x16x32_bf16 v[78:81], v[156:159], v[196:199], v[78:81]
	v_mfma_f32_16x16x32_bf16 v[78:81], v[152:155], v[192:195], v[78:81]
	v_mfma_f32_16x16x32_bf16 v[86:89], v[152:155], v[200:203], v[86:89]
	v_mfma_f32_16x16x32_bf16 v[86:89], v[156:159], v[204:207], v[86:89]
	v_mfma_f32_16x16x32_bf16 v[82:85], v[148:151], v[204:207], v[82:85]
	v_mfma_f32_16x16x32_bf16 v[82:85], v[142:145], v[200:203], v[82:85]
	s_setprio 0
	s_setprio 1
	v_mfma_f32_16x16x32_bf16 v[90:93], v[160:163], v[176:179], v[90:93]
	v_mfma_f32_16x16x32_bf16 v[90:93], v[164:167], v[180:183], v[90:93]
	v_mfma_f32_16x16x32_bf16 v[94:97], v[172:175], v[180:183], v[94:97]
	v_mfma_f32_16x16x32_bf16 v[94:97], v[168:171], v[176:179], v[94:97]
	v_mfma_f32_16x16x32_bf16 v[102:105], v[168:171], v[184:187], v[102:105]
	v_mfma_f32_16x16x32_bf16 v[102:105], v[172:175], v[188:191], v[102:105]
	v_mfma_f32_16x16x32_bf16 v[98:101], v[164:167], v[188:191], v[98:101]
	v_mfma_f32_16x16x32_bf16 v[98:101], v[160:163], v[184:187], v[98:101]
	s_setprio 0
	s_setprio 1
	v_mfma_f32_16x16x32_bf16 v[106:109], v[160:163], v[192:195], v[106:109]
	v_mfma_f32_16x16x32_bf16 v[106:109], v[164:167], v[196:199], v[106:109]
	v_mfma_f32_16x16x32_bf16 v[110:113], v[172:175], v[196:199], v[110:113]
	v_mfma_f32_16x16x32_bf16 v[110:113], v[168:171], v[192:195], v[110:113]
	v_mfma_f32_16x16x32_bf16 v[118:121], v[168:171], v[200:203], v[118:121]
	v_mfma_f32_16x16x32_bf16 v[118:121], v[172:175], v[204:207], v[118:121]
	s_setprio 2
	s_barrier
	v_mfma_f32_16x16x32_bf16 v[114:117], v[164:167], v[204:207], v[114:117]
	v_mfma_f32_16x16x32_bf16 v[114:117], v[160:163], v[200:203], v[114:117]
	s_setprio 0
	s_add_i32 s44, 0, 0x18000
	v_add_u32_e32 v135, s44, v140
	s_add_i32 s45, 0, 0x1c000
	ds_read_b128 v[142:145], v135
	ds_read_b128 v[148:151], v135 offset:1024
	ds_read_b128 v[152:155], v135 offset:2048
	ds_read_b128 v[156:159], v135 offset:3072
	v_add_u32_e32 v135, s45, v140
	ds_read_b128 v[160:163], v135
	ds_read_b128 v[164:167], v135 offset:1024
	ds_read_b128 v[168:171], v135 offset:2048
	ds_read_b128 v[172:175], v135 offset:3072
	s_add_u32 s40, s40, 0x80000
	s_addc_u32 s41, s41, 0
	s_mov_b32 m0, s47
	ds_read_b128 v[176:179], v141 offset:32768
	ds_read_b128 v[180:183], v141 offset:33792
	ds_read_b128 v[184:187], v141 offset:34816
	ds_read_b128 v[188:191], v141 offset:35840
	ds_read_b128 v[192:195], v141 offset:36864
	ds_read_b128 v[196:199], v141 offset:37888
	ds_read_b128 v[200:203], v141 offset:38912
	ds_read_b128 v[204:207], v141 offset:39936
	global_load_lds_dwordx4 v130, s[40:41]
	s_mov_b32 m0, s48
	s_nop 0
	global_load_lds_dwordx4 v132, s[40:41]
	s_waitcnt vmcnt(8)
	s_waitcnt lgkmcnt(0)
	s_barrier
	s_setprio 1
	s_waitcnt lgkmcnt(0)
	v_mfma_f32_16x16x32_bf16 v[2:5], v[142:145], v[176:179], v[2:5]
	v_mfma_f32_16x16x32_bf16 v[2:5], v[148:151], v[180:183], v[2:5]
	v_mfma_f32_16x16x32_bf16 v[6:9], v[156:159], v[180:183], v[6:9]
	v_mfma_f32_16x16x32_bf16 v[6:9], v[152:155], v[176:179], v[6:9]
	v_mfma_f32_16x16x32_bf16 v[14:17], v[152:155], v[184:187], v[14:17]
	v_mfma_f32_16x16x32_bf16 v[14:17], v[156:159], v[188:191], v[14:17]
	v_mfma_f32_16x16x32_bf16 v[10:13], v[148:151], v[188:191], v[10:13]
	v_mfma_f32_16x16x32_bf16 v[10:13], v[142:145], v[184:187], v[10:13]
	s_setprio 0
	s_setprio 1
	v_mfma_f32_16x16x32_bf16 v[18:21], v[142:145], v[192:195], v[18:21]
	v_mfma_f32_16x16x32_bf16 v[18:21], v[148:151], v[196:199], v[18:21]
	v_mfma_f32_16x16x32_bf16 v[22:25], v[156:159], v[196:199], v[22:25]
	v_mfma_f32_16x16x32_bf16 v[22:25], v[152:155], v[192:195], v[22:25]
	v_mfma_f32_16x16x32_bf16 v[30:33], v[152:155], v[200:203], v[30:33]
	v_mfma_f32_16x16x32_bf16 v[30:33], v[156:159], v[204:207], v[30:33]
	v_mfma_f32_16x16x32_bf16 v[26:29], v[148:151], v[204:207], v[26:29]
	v_mfma_f32_16x16x32_bf16 v[26:29], v[142:145], v[200:203], v[26:29]
	s_setprio 0
	s_setprio 1
	v_mfma_f32_16x16x32_bf16 v[34:37], v[160:163], v[176:179], v[34:37]
	v_mfma_f32_16x16x32_bf16 v[34:37], v[164:167], v[180:183], v[34:37]
	v_mfma_f32_16x16x32_bf16 v[38:41], v[172:175], v[180:183], v[38:41]
	v_mfma_f32_16x16x32_bf16 v[38:41], v[168:171], v[176:179], v[38:41]
	v_mfma_f32_16x16x32_bf16 v[46:49], v[168:171], v[184:187], v[46:49]
	v_mfma_f32_16x16x32_bf16 v[46:49], v[172:175], v[188:191], v[46:49]
	v_mfma_f32_16x16x32_bf16 v[42:45], v[164:167], v[188:191], v[42:45]
	v_mfma_f32_16x16x32_bf16 v[42:45], v[160:163], v[184:187], v[42:45]
	s_setprio 0
	s_setprio 1
	v_mfma_f32_16x16x32_bf16 v[50:53], v[160:163], v[192:195], v[50:53]
	v_mfma_f32_16x16x32_bf16 v[50:53], v[164:167], v[196:199], v[50:53]
	v_mfma_f32_16x16x32_bf16 v[54:57], v[172:175], v[196:199], v[54:57]
	v_mfma_f32_16x16x32_bf16 v[54:57], v[168:171], v[192:195], v[54:57]
	v_mfma_f32_16x16x32_bf16 v[62:65], v[168:171], v[200:203], v[62:65]
	v_mfma_f32_16x16x32_bf16 v[62:65], v[172:175], v[204:207], v[62:65]
	s_setprio 2
	s_barrier
	v_mfma_f32_16x16x32_bf16 v[58:61], v[164:167], v[204:207], v[58:61]
	v_mfma_f32_16x16x32_bf16 v[58:61], v[160:163], v[200:203], v[58:61]
	s_setprio 0
	s_add_i32 s40, s44, s21
	v_lshl_add_u64 v[138:139], v[138:139], 0, s[6:7]
	s_mov_b32 m0, s40
	ds_read_b128 v[176:179], v141 offset:49152
	ds_read_b128 v[180:183], v141 offset:50176
	ds_read_b128 v[184:187], v141 offset:51200
	ds_read_b128 v[188:191], v141 offset:52224
	ds_read_b128 v[192:195], v141 offset:53248
	ds_read_b128 v[196:199], v141 offset:54272
	ds_read_b128 v[200:203], v141 offset:55296
	ds_read_b128 v[204:207], v141 offset:56320
	global_load_lds_dwordx4 v[138:139], off
	s_add_i32 m0, s40, 0x2000
	s_add_u32 s38, s38, 0x80080
	v_lshl_add_u64 v[138:139], v[208:209], 0, s[6:7]
	s_addc_u32 s39, s39, 0
	s_add_i32 s40, s45, s21
	global_load_lds_dwordx4 v[138:139], off
	s_mov_b32 m0, s40
	v_lshl_add_u64 v[138:139], v[210:211], 0, s[6:7]
	global_load_lds_dwordx4 v136, s[38:39]
	s_add_i32 m0, s40, 0x2000
	s_nop 0
	global_load_lds_dwordx4 v134, s[38:39]
	s_mov_b32 m0, s52
	s_nop 0
	global_load_lds_dwordx4 v[138:139], off
	v_lshl_add_u64 v[138:139], v[212:213], 0, s[6:7]
	s_mov_b32 m0, s53
	s_nop 0
	global_load_lds_dwordx4 v[138:139], off
	s_waitcnt vmcnt(8)
	s_waitcnt lgkmcnt(0)
	s_barrier
	s_setprio 1
	s_waitcnt lgkmcnt(0)
	v_mfma_f32_16x16x32_bf16 v[122:125], v[142:145], v[176:179], v[122:125]
	v_mfma_f32_16x16x32_bf16 v[122:125], v[148:151], v[180:183], v[122:125]
	v_mfma_f32_16x16x32_bf16 v[126:129], v[156:159], v[180:183], v[126:129]
	v_mfma_f32_16x16x32_bf16 v[126:129], v[152:155], v[176:179], v[126:129]
	v_mfma_f32_16x16x32_bf16 v[70:73], v[152:155], v[184:187], v[70:73]
	v_mfma_f32_16x16x32_bf16 v[70:73], v[156:159], v[188:191], v[70:73]
	v_mfma_f32_16x16x32_bf16 v[66:69], v[148:151], v[188:191], v[66:69]
	v_mfma_f32_16x16x32_bf16 v[66:69], v[142:145], v[184:187], v[66:69]
	s_setprio 0
	s_setprio 1
	v_mfma_f32_16x16x32_bf16 v[74:77], v[142:145], v[192:195], v[74:77]
	v_mfma_f32_16x16x32_bf16 v[74:77], v[148:151], v[196:199], v[74:77]
	v_mfma_f32_16x16x32_bf16 v[78:81], v[156:159], v[196:199], v[78:81]
	v_mfma_f32_16x16x32_bf16 v[78:81], v[152:155], v[192:195], v[78:81]
	v_mfma_f32_16x16x32_bf16 v[86:89], v[152:155], v[200:203], v[86:89]
	v_mfma_f32_16x16x32_bf16 v[86:89], v[156:159], v[204:207], v[86:89]
	v_mfma_f32_16x16x32_bf16 v[82:85], v[148:151], v[204:207], v[82:85]
	v_mfma_f32_16x16x32_bf16 v[82:85], v[142:145], v[200:203], v[82:85]
	s_setprio 0
	s_setprio 1
	v_mfma_f32_16x16x32_bf16 v[90:93], v[160:163], v[176:179], v[90:93]
	v_mfma_f32_16x16x32_bf16 v[90:93], v[164:167], v[180:183], v[90:93]
	v_mfma_f32_16x16x32_bf16 v[94:97], v[172:175], v[180:183], v[94:97]
	v_mfma_f32_16x16x32_bf16 v[94:97], v[168:171], v[176:179], v[94:97]
	v_mfma_f32_16x16x32_bf16 v[102:105], v[168:171], v[184:187], v[102:105]
	v_mfma_f32_16x16x32_bf16 v[102:105], v[172:175], v[188:191], v[102:105]
	v_mfma_f32_16x16x32_bf16 v[98:101], v[164:167], v[188:191], v[98:101]
	v_mfma_f32_16x16x32_bf16 v[98:101], v[160:163], v[184:187], v[98:101]
	s_setprio 0
	s_setprio 1
	v_mfma_f32_16x16x32_bf16 v[106:109], v[160:163], v[192:195], v[106:109]
	v_mfma_f32_16x16x32_bf16 v[106:109], v[164:167], v[196:199], v[106:109]
	v_mfma_f32_16x16x32_bf16 v[110:113], v[172:175], v[196:199], v[110:113]
	v_mfma_f32_16x16x32_bf16 v[110:113], v[168:171], v[192:195], v[110:113]
	v_mfma_f32_16x16x32_bf16 v[118:121], v[168:171], v[200:203], v[118:121]
	v_mfma_f32_16x16x32_bf16 v[118:121], v[172:175], v[204:207], v[118:121]
	s_setprio 2
	s_barrier
	v_mfma_f32_16x16x32_bf16 v[114:117], v[164:167], v[204:207], v[114:117]
	v_mfma_f32_16x16x32_bf16 v[114:117], v[160:163], v[200:203], v[114:117]
	s_setprio 0
	s_add_i32 s43, s43, 2
	s_add_u32 s36, s36, 0x100
	s_addc_u32 s37, s37, 0
	s_add_u32 s15, s15, 0x100
	s_addc_u32 s42, s42, 0
	s_cmp_gt_u32 s43, 29
	s_cbranch_scc0 .LBB0_383
	s_and_b64 vcc, exec, s[8:9]
	s_cbranch_vccz .LBB0_386
	s_barrier

.LBB0_462:
	v_add_u32_e32 v14, s54, v140
	v_add_u32_e32 v30, s55, v140
	ds_read_b128 v[2:5], v14
	ds_read_b128 v[6:9], v14 offset:1024
	ds_read_b128 v[10:13], v14 offset:2048
	ds_read_b128 v[14:17], v14 offset:3072
	ds_read_b128 v[18:21], v30
	ds_read_b128 v[22:25], v30 offset:1024
	ds_read_b128 v[26:29], v30 offset:2048
	ds_read_b128 v[30:33], v30 offset:3072
	v_add_u32_e32 v141, 0, v1
	ds_read_b128 v[34:37], v141
	ds_read_b128 v[38:41], v141 offset:1024
	ds_read_b128 v[42:45], v141 offset:2048
	ds_read_b128 v[46:49], v141 offset:3072
	ds_read_b128 v[50:53], v141 offset:4096
	ds_read_b128 v[54:57], v141 offset:5120
	ds_read_b128 v[58:61], v141 offset:6144
	ds_read_b128 v[62:65], v141 offset:7168
	s_waitcnt vmcnt(8)
	s_waitcnt lgkmcnt(0)
	s_barrier
	s_setprio 1
	s_waitcnt lgkmcnt(0)
	v_mfma_f32_16x16x32_bf16 v[66:69], v[2:5], v[34:37], 0
	v_mfma_f32_16x16x32_bf16 v[66:69], v[6:9], v[38:41], v[66:69]
	v_mfma_f32_16x16x32_bf16 v[70:73], v[10:13], v[34:37], 0
	v_mfma_f32_16x16x32_bf16 v[70:73], v[14:17], v[38:41], v[70:73]
	v_mfma_f32_16x16x32_bf16 v[78:81], v[10:13], v[42:45], 0
	v_mfma_f32_16x16x32_bf16 v[78:81], v[14:17], v[46:49], v[78:81]
	v_mfma_f32_16x16x32_bf16 v[74:77], v[2:5], v[42:45], 0
	v_mfma_f32_16x16x32_bf16 v[74:77], v[6:9], v[46:49], v[74:77]
	s_setprio 0
	s_setprio 1
	v_mfma_f32_16x16x32_bf16 v[82:85], v[2:5], v[50:53], 0
	v_mfma_f32_16x16x32_bf16 v[82:85], v[6:9], v[54:57], v[82:85]
	v_mfma_f32_16x16x32_bf16 v[86:89], v[10:13], v[50:53], 0
	v_mfma_f32_16x16x32_bf16 v[86:89], v[14:17], v[54:57], v[86:89]
	v_mfma_f32_16x16x32_bf16 v[94:97], v[10:13], v[58:61], 0
	v_mfma_f32_16x16x32_bf16 v[94:97], v[14:17], v[62:65], v[94:97]
	v_mfma_f32_16x16x32_bf16 v[90:93], v[2:5], v[58:61], 0
	v_mfma_f32_16x16x32_bf16 v[90:93], v[6:9], v[62:65], v[90:93]
	s_setprio 0
	s_setprio 1
	v_mfma_f32_16x16x32_bf16 v[98:101], v[18:21], v[34:37], 0
	v_mfma_f32_16x16x32_bf16 v[34:37], v[26:29], v[34:37], 0
	v_mfma_f32_16x16x32_bf16 v[102:105], v[18:21], v[42:45], 0
	v_mfma_f32_16x16x32_bf16 v[42:45], v[26:29], v[42:45], 0
	v_mfma_f32_16x16x32_bf16 v[106:109], v[18:21], v[50:53], 0
	v_mfma_f32_16x16x32_bf16 v[50:53], v[26:29], v[50:53], 0
	v_mfma_f32_16x16x32_bf16 v[110:113], v[18:21], v[58:61], 0
	v_mfma_f32_16x16x32_bf16 v[58:61], v[26:29], v[58:61], 0
	s_setprio 0
	s_setprio 1
	v_mfma_f32_16x16x32_bf16 v[98:101], v[22:25], v[38:41], v[98:101]
	v_mfma_f32_16x16x32_bf16 v[38:41], v[30:33], v[38:41], v[34:37]
	v_mfma_f32_16x16x32_bf16 v[102:105], v[22:25], v[46:49], v[102:105]
	v_mfma_f32_16x16x32_bf16 v[46:49], v[30:33], v[46:49], v[42:45]
	v_mfma_f32_16x16x32_bf16 v[106:109], v[22:25], v[54:57], v[106:109]
	v_mfma_f32_16x16x32_bf16 v[54:57], v[30:33], v[54:57], v[50:53]
	s_setprio 2
	s_barrier
	v_mfma_f32_16x16x32_bf16 v[110:113], v[22:25], v[62:65], v[110:113]
	v_mfma_f32_16x16x32_bf16 v[62:65], v[30:33], v[62:65], v[58:61]
	s_setprio 0
	v_lshl_add_u64 v[136:137], s[36:37], 0, v[130:131]
	s_add_i32 s62, s54, s21
	v_mov_b32_e32 v135, v131
	v_lshl_add_u64 v[142:143], v[136:137], 0, s[12:13]
	s_mov_b32 m0, s62
	v_lshl_add_u64 v[244:245], s[36:37], 0, v[134:135]
	ds_read_b128 v[34:37], v141 offset:16384
	ds_read_b128 v[42:45], v141 offset:17408
	ds_read_b128 v[50:53], v141 offset:18432
	ds_read_b128 v[58:61], v141 offset:19456
	ds_read_b128 v[114:117], v141 offset:20480
	ds_read_b128 v[118:121], v141 offset:21504
	ds_read_b128 v[122:125], v141 offset:22528
	ds_read_b128 v[126:129], v141 offset:23552
	global_load_lds_dwordx4 v[142:143], off
	v_lshl_add_u64 v[142:143], v[244:245], 0, s[12:13]
	s_add_i32 m0, s62, 0x2000
	s_add_i32 s62, s55, s21
	global_load_lds_dwordx4 v[142:143], off
	s_mov_b32 m0, s62
	v_mov_b32_e32 v139, v131
	global_load_lds_dwordx4 v130, s[38:39]
	s_add_i32 m0, s62, 0x2000
	v_lshl_add_u64 v[246:247], s[34:35], 0, v[138:139]
	v_mov_b32_e32 v133, v131
	global_load_lds_dwordx4 v134, s[38:39]
	v_lshl_add_u64 v[142:143], v[246:247], 0, s[12:13]
	s_mov_b32 m0, s33
	v_lshl_add_u64 v[248:249], s[34:35], 0, v[132:133]
	global_load_lds_dwordx4 v[142:143], off
	v_lshl_add_u64 v[142:143], v[248:249], 0, s[12:13]
	s_mov_b32 m0, s44
	s_nop 0
	global_load_lds_dwordx4 v[142:143], off
	s_waitcnt vmcnt(8)
	s_waitcnt lgkmcnt(0)
	s_barrier
	s_setprio 1
	s_waitcnt lgkmcnt(0)
	v_mfma_f32_16x16x32_bf16 v[142:145], v[2:5], v[34:37], 0
	v_mfma_f32_16x16x32_bf16 v[148:151], v[10:13], v[34:37], 0
	v_mfma_f32_16x16x32_bf16 v[152:155], v[2:5], v[50:53], 0
	v_mfma_f32_16x16x32_bf16 v[156:159], v[10:13], v[50:53], 0
	v_mfma_f32_16x16x32_bf16 v[160:163], v[2:5], v[114:117], 0
	v_mfma_f32_16x16x32_bf16 v[164:167], v[10:13], v[114:117], 0
	v_mfma_f32_16x16x32_bf16 v[2:5], v[2:5], v[122:125], 0
	v_mfma_f32_16x16x32_bf16 v[10:13], v[10:13], v[122:125], 0
	s_setprio 0
	s_setprio 1
	v_mfma_f32_16x16x32_bf16 v[142:145], v[6:9], v[42:45], v[142:145]
	v_mfma_f32_16x16x32_bf16 v[148:151], v[14:17], v[42:45], v[148:151]
	v_mfma_f32_16x16x32_bf16 v[152:155], v[6:9], v[58:61], v[152:155]
	v_mfma_f32_16x16x32_bf16 v[156:159], v[14:17], v[58:61], v[156:159]
	v_mfma_f32_16x16x32_bf16 v[160:163], v[6:9], v[118:121], v[160:163]
	v_mfma_f32_16x16x32_bf16 v[164:167], v[14:17], v[118:121], v[164:167]
	v_mfma_f32_16x16x32_bf16 v[168:171], v[6:9], v[126:129], v[2:5]
	v_mfma_f32_16x16x32_bf16 v[172:175], v[14:17], v[126:129], v[10:13]
	s_setprio 0
	s_setprio 1
	v_mfma_f32_16x16x32_bf16 v[2:5], v[18:21], v[34:37], 0
	v_mfma_f32_16x16x32_bf16 v[6:9], v[26:29], v[34:37], 0
	v_mfma_f32_16x16x32_bf16 v[10:13], v[18:21], v[50:53], 0
	v_mfma_f32_16x16x32_bf16 v[14:17], v[26:29], v[50:53], 0
	v_mfma_f32_16x16x32_bf16 v[34:37], v[18:21], v[114:117], 0
	v_mfma_f32_16x16x32_bf16 v[50:53], v[26:29], v[114:117], 0
	v_mfma_f32_16x16x32_bf16 v[18:21], v[18:21], v[122:125], 0
	v_mfma_f32_16x16x32_bf16 v[26:29], v[26:29], v[122:125], 0
	s_setprio 0
	s_setprio 1
	v_mfma_f32_16x16x32_bf16 v[114:117], v[22:25], v[42:45], v[2:5]
	v_mfma_f32_16x16x32_bf16 v[122:125], v[30:33], v[42:45], v[6:9]
	v_mfma_f32_16x16x32_bf16 v[184:187], v[22:25], v[118:121], v[34:37]
	v_mfma_f32_16x16x32_bf16 v[118:121], v[30:33], v[118:121], v[50:53]
	v_mfma_f32_16x16x32_bf16 v[188:191], v[22:25], v[126:129], v[18:21]
	v_mfma_f32_16x16x32_bf16 v[126:129], v[30:33], v[126:129], v[26:29]
	s_setprio 2
	s_barrier
	v_mfma_f32_16x16x32_bf16 v[176:179], v[22:25], v[58:61], v[10:13]
	v_mfma_f32_16x16x32_bf16 v[180:183], v[30:33], v[58:61], v[14:17]
	s_setprio 0
	s_add_i32 s62, 0, 0x18000
	v_add_u32_e32 v2, s62, v140
	s_add_i32 s63, 0, 0x1c000
	ds_read_b128 v[192:195], v2
	ds_read_b128 v[196:199], v2 offset:1024
	ds_read_b128 v[200:203], v2 offset:2048
	ds_read_b128 v[204:207], v2 offset:3072
	v_add_u32_e32 v2, s63, v140
	ds_read_b128 v[208:211], v2
	ds_read_b128 v[212:215], v2 offset:1024
	ds_read_b128 v[216:219], v2 offset:2048
	ds_read_b128 v[220:223], v2 offset:3072
	s_mov_b32 m0, s45
	ds_read_b128 v[42:45], v141 offset:32768
	ds_read_b128 v[50:53], v141 offset:33792
	ds_read_b128 v[58:61], v141 offset:34816
	ds_read_b128 v[224:227], v141 offset:35840
	ds_read_b128 v[228:231], v141 offset:36864
	ds_read_b128 v[232:235], v141 offset:37888
	ds_read_b128 v[236:239], v141 offset:38912
	ds_read_b128 v[240:243], v141 offset:39936
	global_load_lds_dwordx4 v138, s[40:41]
	s_mov_b32 m0, s46
	s_nop 0
	global_load_lds_dwordx4 v132, s[40:41]
	s_waitcnt vmcnt(8)
	s_waitcnt lgkmcnt(0)
	s_barrier
	s_setprio 1
	s_waitcnt lgkmcnt(0)
	v_mfma_f32_16x16x32_bf16 v[2:5], v[192:195], v[42:45], v[66:69]
	v_mfma_f32_16x16x32_bf16 v[6:9], v[200:203], v[42:45], v[70:73]
	v_mfma_f32_16x16x32_bf16 v[10:13], v[192:195], v[58:61], v[74:77]
	v_mfma_f32_16x16x32_bf16 v[14:17], v[200:203], v[58:61], v[78:81]
	v_mfma_f32_16x16x32_bf16 v[18:21], v[192:195], v[228:231], v[82:85]
	v_mfma_f32_16x16x32_bf16 v[22:25], v[200:203], v[228:231], v[86:89]
	v_mfma_f32_16x16x32_bf16 v[26:29], v[192:195], v[236:239], v[90:93]
	v_mfma_f32_16x16x32_bf16 v[30:33], v[200:203], v[236:239], v[94:97]
	s_setprio 0
	s_setprio 1
	v_mfma_f32_16x16x32_bf16 v[2:5], v[196:199], v[50:53], v[2:5]
	v_mfma_f32_16x16x32_bf16 v[6:9], v[204:207], v[50:53], v[6:9]
	v_mfma_f32_16x16x32_bf16 v[10:13], v[196:199], v[224:227], v[10:13]
	v_mfma_f32_16x16x32_bf16 v[14:17], v[204:207], v[224:227], v[14:17]
	v_mfma_f32_16x16x32_bf16 v[18:21], v[196:199], v[232:235], v[18:21]
	v_mfma_f32_16x16x32_bf16 v[22:25], v[204:207], v[232:235], v[22:25]
	v_mfma_f32_16x16x32_bf16 v[26:29], v[196:199], v[240:243], v[26:29]
	v_mfma_f32_16x16x32_bf16 v[30:33], v[204:207], v[240:243], v[30:33]
	s_setprio 0
	s_setprio 1
	v_mfma_f32_16x16x32_bf16 v[34:37], v[208:211], v[42:45], v[98:101]
	v_mfma_f32_16x16x32_bf16 v[38:41], v[216:219], v[42:45], v[38:41]
	v_mfma_f32_16x16x32_bf16 v[34:37], v[212:215], v[50:53], v[34:37]
	v_mfma_f32_16x16x32_bf16 v[38:41], v[220:223], v[50:53], v[38:41]
	v_mfma_f32_16x16x32_bf16 v[42:45], v[208:211], v[58:61], v[102:105]
	v_mfma_f32_16x16x32_bf16 v[46:49], v[216:219], v[58:61], v[46:49]
	v_mfma_f32_16x16x32_bf16 v[50:53], v[208:211], v[228:231], v[106:109]
	v_mfma_f32_16x16x32_bf16 v[54:57], v[216:219], v[228:231], v[54:57]
	s_setprio 0
	s_setprio 1
	v_mfma_f32_16x16x32_bf16 v[58:61], v[208:211], v[236:239], v[110:113]
	v_mfma_f32_16x16x32_bf16 v[62:65], v[216:219], v[236:239], v[62:65]
	v_mfma_f32_16x16x32_bf16 v[42:45], v[212:215], v[224:227], v[42:45]
	v_mfma_f32_16x16x32_bf16 v[46:49], v[220:223], v[224:227], v[46:49]
	v_mfma_f32_16x16x32_bf16 v[50:53], v[212:215], v[232:235], v[50:53]
	v_mfma_f32_16x16x32_bf16 v[54:57], v[220:223], v[232:235], v[54:57]
	s_setprio 2
	s_barrier
	v_mfma_f32_16x16x32_bf16 v[58:61], v[212:215], v[240:243], v[58:61]
	v_mfma_f32_16x16x32_bf16 v[62:65], v[220:223], v[240:243], v[62:65]
	s_setprio 0
	s_add_i32 s62, s62, s21
	v_lshl_add_u64 v[66:67], v[136:137], 0, s[14:15]
	s_mov_b32 m0, s62
	ds_read_b128 v[102:105], v141 offset:49152
	ds_read_b128 v[106:109], v141 offset:50176
	ds_read_b128 v[110:113], v141 offset:51200
	ds_read_b128 v[224:227], v141 offset:52224
	ds_read_b128 v[228:231], v141 offset:53248
	ds_read_b128 v[232:235], v141 offset:54272
	ds_read_b128 v[236:239], v141 offset:55296
	ds_read_b128 v[240:243], v141 offset:56320
	global_load_lds_dwordx4 v[66:67], off
	v_lshl_add_u64 v[66:67], v[244:245], 0, s[14:15]
	s_add_i32 m0, s62, 0x2000
	s_add_i32 s62, s63, s21
	global_load_lds_dwordx4 v[66:67], off
	s_mov_b32 m0, s62
	v_lshl_add_u64 v[66:67], v[246:247], 0, s[14:15]
	global_load_lds_dwordx4 v130, s[42:43]
	s_add_i32 m0, s62, 0x2000
	s_nop 0
	global_load_lds_dwordx4 v134, s[42:43]
	s_mov_b32 m0, s50
	s_nop 0
	global_load_lds_dwordx4 v[66:67], off
	v_lshl_add_u64 v[66:67], v[248:249], 0, s[14:15]
	s_mov_b32 m0, s51
	s_nop 0
	global_load_lds_dwordx4 v[66:67], off
	s_waitcnt vmcnt(8)
	s_waitcnt lgkmcnt(0)
	s_barrier
	s_setprio 1
	s_waitcnt lgkmcnt(0)
	v_mfma_f32_16x16x32_bf16 v[66:69], v[192:195], v[102:105], v[142:145]
	v_mfma_f32_16x16x32_bf16 v[70:73], v[200:203], v[102:105], v[148:151]
	v_mfma_f32_16x16x32_bf16 v[74:77], v[192:195], v[110:113], v[152:155]
	v_mfma_f32_16x16x32_bf16 v[78:81], v[200:203], v[110:113], v[156:159]
	v_mfma_f32_16x16x32_bf16 v[82:85], v[192:195], v[228:231], v[160:163]
	v_mfma_f32_16x16x32_bf16 v[86:89], v[200:203], v[228:231], v[164:167]
	v_mfma_f32_16x16x32_bf16 v[90:93], v[192:195], v[236:239], v[168:171]
	v_mfma_f32_16x16x32_bf16 v[94:97], v[200:203], v[236:239], v[172:175]
	s_setprio 0
	s_setprio 1
	v_mfma_f32_16x16x32_bf16 v[66:69], v[196:199], v[106:109], v[66:69]
	v_mfma_f32_16x16x32_bf16 v[70:73], v[204:207], v[106:109], v[70:73]
	v_mfma_f32_16x16x32_bf16 v[74:77], v[196:199], v[224:227], v[74:77]
	v_mfma_f32_16x16x32_bf16 v[78:81], v[204:207], v[224:227], v[78:81]
	v_mfma_f32_16x16x32_bf16 v[82:85], v[196:199], v[232:235], v[82:85]
	v_mfma_f32_16x16x32_bf16 v[86:89], v[204:207], v[232:235], v[86:89]
	v_mfma_f32_16x16x32_bf16 v[90:93], v[196:199], v[240:243], v[90:93]
	v_mfma_f32_16x16x32_bf16 v[94:97], v[204:207], v[240:243], v[94:97]
	s_setprio 0
	s_setprio 1
	v_mfma_f32_16x16x32_bf16 v[98:101], v[208:211], v[102:105], v[114:117]
	v_mfma_f32_16x16x32_bf16 v[102:105], v[216:219], v[102:105], v[122:125]
	v_mfma_f32_16x16x32_bf16 v[98:101], v[212:215], v[106:109], v[98:101]
	v_mfma_f32_16x16x32_bf16 v[102:105], v[220:223], v[106:109], v[102:105]
	v_mfma_f32_16x16x32_bf16 v[106:109], v[208:211], v[110:113], v[176:179]
	v_mfma_f32_16x16x32_bf16 v[110:113], v[216:219], v[110:113], v[180:183]
	v_mfma_f32_16x16x32_bf16 v[114:117], v[208:211], v[228:231], v[184:187]
	v_mfma_f32_16x16x32_bf16 v[118:121], v[216:219], v[228:231], v[118:121]
	s_setprio 0
	s_setprio 1
	v_mfma_f32_16x16x32_bf16 v[122:125], v[208:211], v[236:239], v[188:191]
	v_mfma_f32_16x16x32_bf16 v[126:129], v[216:219], v[236:239], v[126:129]
	v_mfma_f32_16x16x32_bf16 v[106:109], v[212:215], v[224:227], v[106:109]
	v_mfma_f32_16x16x32_bf16 v[110:113], v[220:223], v[224:227], v[110:113]
	v_mfma_f32_16x16x32_bf16 v[114:117], v[212:215], v[232:235], v[114:117]
	v_mfma_f32_16x16x32_bf16 v[118:121], v[220:223], v[232:235], v[118:121]
	s_setprio 2
	s_barrier
	v_mfma_f32_16x16x32_bf16 v[122:125], v[212:215], v[240:243], v[122:125]
	v_mfma_f32_16x16x32_bf16 v[126:129], v[220:223], v[240:243], v[126:129]
	s_setprio 0
	s_add_i32 s61, s61, 2
	s_cmp_ge_i32 s61, s60
	s_cbranch_scc0 .LBB0_462
	v_mov_b32_e32 v136, v130
	s_branch .LBB0_465

.LBB0_466:
	v_add_u32_e32 v133, s54, v140
	ds_read_b128 v[142:145], v133
	ds_read_b128 v[148:151], v133 offset:1024
	ds_read_b128 v[152:155], v133 offset:2048
	ds_read_b128 v[156:159], v133 offset:3072
	v_add_u32_e32 v133, s55, v140
	ds_read_b128 v[160:163], v133
	ds_read_b128 v[164:167], v133 offset:1024
	ds_read_b128 v[168:171], v133 offset:2048
	ds_read_b128 v[172:175], v133 offset:3072
	s_add_u32 s36, s34, 0xffc00080
	s_addc_u32 s37, s35, -1
	s_cmp_eq_u32 s42, 4
	s_cselect_b32 s39, s29, s37
	s_cselect_b32 s38, s28, s36
	s_cselect_b32 s37, s31, s41
	s_cselect_b32 s36, s30, s40
	s_mov_b32 m0, s52
	v_add_u32_e32 v141, 0, v1
	ds_read_b128 v[176:179], v141
	ds_read_b128 v[180:183], v141 offset:1024
	ds_read_b128 v[184:187], v141 offset:2048
	ds_read_b128 v[188:191], v141 offset:3072
	ds_read_b128 v[192:195], v141 offset:4096
	ds_read_b128 v[196:199], v141 offset:5120
	ds_read_b128 v[200:203], v141 offset:6144
	ds_read_b128 v[204:207], v141 offset:7168
	global_load_lds_dwordx4 v130, s[34:35]
	s_mov_b32 m0, s53
	v_mov_b32_e32 v133, v131
	global_load_lds_dwordx4 v132, s[34:35]
	s_waitcnt vmcnt(8)
	s_waitcnt lgkmcnt(0)
	s_barrier
	s_setprio 1
	s_waitcnt lgkmcnt(0)
	v_mfma_f32_16x16x32_bf16 v[2:5], v[142:145], v[176:179], v[2:5]
	v_mfma_f32_16x16x32_bf16 v[2:5], v[148:151], v[180:183], v[2:5]
	v_mfma_f32_16x16x32_bf16 v[6:9], v[156:159], v[180:183], v[6:9]
	v_mfma_f32_16x16x32_bf16 v[6:9], v[152:155], v[176:179], v[6:9]
	v_mfma_f32_16x16x32_bf16 v[14:17], v[152:155], v[184:187], v[14:17]
	v_mfma_f32_16x16x32_bf16 v[14:17], v[156:159], v[188:191], v[14:17]
	v_mfma_f32_16x16x32_bf16 v[10:13], v[148:151], v[188:191], v[10:13]
	v_mfma_f32_16x16x32_bf16 v[10:13], v[142:145], v[184:187], v[10:13]
	s_setprio 0
	s_setprio 1
	v_mfma_f32_16x16x32_bf16 v[18:21], v[142:145], v[192:195], v[18:21]
	v_mfma_f32_16x16x32_bf16 v[18:21], v[148:151], v[196:199], v[18:21]
	v_mfma_f32_16x16x32_bf16 v[22:25], v[156:159], v[196:199], v[22:25]
	v_mfma_f32_16x16x32_bf16 v[22:25], v[152:155], v[192:195], v[22:25]
	v_mfma_f32_16x16x32_bf16 v[30:33], v[152:155], v[200:203], v[30:33]
	v_mfma_f32_16x16x32_bf16 v[30:33], v[156:159], v[204:207], v[30:33]
	v_mfma_f32_16x16x32_bf16 v[26:29], v[148:151], v[204:207], v[26:29]
	v_mfma_f32_16x16x32_bf16 v[26:29], v[142:145], v[200:203], v[26:29]
	s_setprio 0
	s_setprio 1
	v_mfma_f32_16x16x32_bf16 v[34:37], v[160:163], v[176:179], v[34:37]
	v_mfma_f32_16x16x32_bf16 v[34:37], v[164:167], v[180:183], v[34:37]
	v_mfma_f32_16x16x32_bf16 v[38:41], v[172:175], v[180:183], v[38:41]
	v_mfma_f32_16x16x32_bf16 v[38:41], v[168:171], v[176:179], v[38:41]
	v_mfma_f32_16x16x32_bf16 v[46:49], v[168:171], v[184:187], v[46:49]
	v_mfma_f32_16x16x32_bf16 v[46:49], v[172:175], v[188:191], v[46:49]
	v_mfma_f32_16x16x32_bf16 v[42:45], v[164:167], v[188:191], v[42:45]
	v_mfma_f32_16x16x32_bf16 v[42:45], v[160:163], v[184:187], v[42:45]
	s_setprio 0
	s_setprio 1
	v_mfma_f32_16x16x32_bf16 v[50:53], v[160:163], v[192:195], v[50:53]
	v_mfma_f32_16x16x32_bf16 v[50:53], v[164:167], v[196:199], v[50:53]
	v_mfma_f32_16x16x32_bf16 v[54:57], v[172:175], v[196:199], v[54:57]
	v_mfma_f32_16x16x32_bf16 v[54:57], v[168:171], v[192:195], v[54:57]
	v_mfma_f32_16x16x32_bf16 v[62:65], v[168:171], v[200:203], v[62:65]
	v_mfma_f32_16x16x32_bf16 v[62:65], v[172:175], v[204:207], v[62:65]
	s_setprio 2
	s_barrier
	v_mfma_f32_16x16x32_bf16 v[58:61], v[164:167], v[204:207], v[58:61]
	v_mfma_f32_16x16x32_bf16 v[58:61], v[160:163], v[200:203], v[58:61]
	s_setprio 0
	s_add_i32 s43, s54, s21
	s_mov_b32 m0, s43
	ds_read_b128 v[176:179], v141 offset:16384
	ds_read_b128 v[180:183], v141 offset:17408
	ds_read_b128 v[184:187], v141 offset:18432
	ds_read_b128 v[188:191], v141 offset:19456
	ds_read_b128 v[192:195], v141 offset:20480
	ds_read_b128 v[196:199], v141 offset:21504
	ds_read_b128 v[200:203], v141 offset:22528
	ds_read_b128 v[204:207], v141 offset:23552
	global_load_lds_dwordx4 v136, s[36:37]
	s_add_i32 m0, s43, 0x2000
	s_add_u32 s60, s36, 0x80000
	s_addc_u32 s61, s37, 0
	s_add_i32 s43, s55, s21
	global_load_lds_dwordx4 v134, s[36:37]
	s_mov_b32 m0, s43
	v_mov_b32_e32 v137, v131
	global_load_lds_dwordx4 v136, s[60:61]
	s_add_i32 m0, s43, 0x2000
	v_mov_b32_e32 v135, v131
	global_load_lds_dwordx4 v134, s[60:61]
	s_mov_b32 m0, s33
	v_lshl_add_u64 v[138:139], s[36:37], 0, v[136:137]
	global_load_lds_dwordx4 v130, s[38:39]
	s_mov_b32 m0, s44
	v_lshl_add_u64 v[208:209], s[36:37], 0, v[134:135]
	global_load_lds_dwordx4 v132, s[38:39]
	s_waitcnt vmcnt(8)
	s_waitcnt lgkmcnt(0)
	v_lshl_add_u64 v[210:211], s[38:39], 0, v[130:131]
	v_lshl_add_u64 v[212:213], s[38:39], 0, v[132:133]
	s_barrier
	s_setprio 1
	s_waitcnt lgkmcnt(0)
	v_mfma_f32_16x16x32_bf16 v[66:69], v[142:145], v[176:179], v[66:69]
	v_mfma_f32_16x16x32_bf16 v[66:69], v[148:151], v[180:183], v[66:69]
	v_mfma_f32_16x16x32_bf16 v[70:73], v[156:159], v[180:183], v[70:73]
	v_mfma_f32_16x16x32_bf16 v[70:73], v[152:155], v[176:179], v[70:73]
	v_mfma_f32_16x16x32_bf16 v[78:81], v[152:155], v[184:187], v[78:81]
	v_mfma_f32_16x16x32_bf16 v[78:81], v[156:159], v[188:191], v[78:81]
	v_mfma_f32_16x16x32_bf16 v[74:77], v[148:151], v[188:191], v[74:77]
	v_mfma_f32_16x16x32_bf16 v[74:77], v[142:145], v[184:187], v[74:77]
	s_setprio 0
	s_setprio 1
	v_mfma_f32_16x16x32_bf16 v[82:85], v[142:145], v[192:195], v[82:85]
	v_mfma_f32_16x16x32_bf16 v[82:85], v[148:151], v[196:199], v[82:85]
	v_mfma_f32_16x16x32_bf16 v[86:89], v[156:159], v[196:199], v[86:89]
	v_mfma_f32_16x16x32_bf16 v[86:89], v[152:155], v[192:195], v[86:89]
	v_mfma_f32_16x16x32_bf16 v[94:97], v[152:155], v[200:203], v[94:97]
	v_mfma_f32_16x16x32_bf16 v[94:97], v[156:159], v[204:207], v[94:97]
	v_mfma_f32_16x16x32_bf16 v[90:93], v[148:151], v[204:207], v[90:93]
	v_mfma_f32_16x16x32_bf16 v[90:93], v[142:145], v[200:203], v[90:93]
	s_setprio 0
	s_setprio 1
	v_mfma_f32_16x16x32_bf16 v[98:101], v[160:163], v[176:179], v[98:101]
	v_mfma_f32_16x16x32_bf16 v[98:101], v[164:167], v[180:183], v[98:101]
	v_mfma_f32_16x16x32_bf16 v[102:105], v[172:175], v[180:183], v[102:105]
	v_mfma_f32_16x16x32_bf16 v[102:105], v[168:171], v[176:179], v[102:105]
	v_mfma_f32_16x16x32_bf16 v[110:113], v[168:171], v[184:187], v[110:113]
	v_mfma_f32_16x16x32_bf16 v[110:113], v[172:175], v[188:191], v[110:113]
	v_mfma_f32_16x16x32_bf16 v[106:109], v[164:167], v[188:191], v[106:109]
	v_mfma_f32_16x16x32_bf16 v[106:109], v[160:163], v[184:187], v[106:109]
	s_setprio 0
	s_setprio 1
	v_mfma_f32_16x16x32_bf16 v[114:117], v[160:163], v[192:195], v[114:117]
	v_mfma_f32_16x16x32_bf16 v[114:117], v[164:167], v[196:199], v[114:117]
	v_mfma_f32_16x16x32_bf16 v[118:121], v[172:175], v[196:199], v[118:121]
	v_mfma_f32_16x16x32_bf16 v[118:121], v[168:171], v[192:195], v[118:121]
	v_mfma_f32_16x16x32_bf16 v[126:129], v[168:171], v[200:203], v[126:129]
	v_mfma_f32_16x16x32_bf16 v[126:129], v[172:175], v[204:207], v[126:129]
	s_setprio 2
	s_barrier
	v_mfma_f32_16x16x32_bf16 v[122:125], v[164:167], v[204:207], v[122:125]
	v_mfma_f32_16x16x32_bf16 v[122:125], v[160:163], v[200:203], v[122:125]
	s_setprio 0
	s_add_i32 s43, 0, 0x18000
	v_add_u32_e32 v135, s43, v140
	s_add_i32 s60, 0, 0x1c000
	ds_read_b128 v[142:145], v135
	ds_read_b128 v[148:151], v135 offset:1024
	ds_read_b128 v[152:155], v135 offset:2048
	ds_read_b128 v[156:159], v135 offset:3072
	v_add_u32_e32 v135, s60, v140
	ds_read_b128 v[160:163], v135
	ds_read_b128 v[164:167], v135 offset:1024
	ds_read_b128 v[168:171], v135 offset:2048
	ds_read_b128 v[172:175], v135 offset:3072
	s_add_u32 s38, s38, 0x400000
	s_addc_u32 s39, s39, 0
	s_mov_b32 m0, s45
	ds_read_b128 v[176:179], v141 offset:32768
	ds_read_b128 v[180:183], v141 offset:33792
	ds_read_b128 v[184:187], v141 offset:34816
	ds_read_b128 v[188:191], v141 offset:35840
	ds_read_b128 v[192:195], v141 offset:36864
	ds_read_b128 v[196:199], v141 offset:37888
	ds_read_b128 v[200:203], v141 offset:38912
	ds_read_b128 v[204:207], v141 offset:39936
	global_load_lds_dwordx4 v130, s[38:39]
	s_mov_b32 m0, s46
	s_nop 0
	global_load_lds_dwordx4 v132, s[38:39]
	s_waitcnt vmcnt(8)
	s_waitcnt lgkmcnt(0)
	s_barrier
	s_setprio 1
	s_waitcnt lgkmcnt(0)
	v_mfma_f32_16x16x32_bf16 v[2:5], v[142:145], v[176:179], v[2:5]
	v_mfma_f32_16x16x32_bf16 v[2:5], v[148:151], v[180:183], v[2:5]
	v_mfma_f32_16x16x32_bf16 v[6:9], v[156:159], v[180:183], v[6:9]
	v_mfma_f32_16x16x32_bf16 v[6:9], v[152:155], v[176:179], v[6:9]
	v_mfma_f32_16x16x32_bf16 v[14:17], v[152:155], v[184:187], v[14:17]
	v_mfma_f32_16x16x32_bf16 v[14:17], v[156:159], v[188:191], v[14:17]
	v_mfma_f32_16x16x32_bf16 v[10:13], v[148:151], v[188:191], v[10:13]
	v_mfma_f32_16x16x32_bf16 v[10:13], v[142:145], v[184:187], v[10:13]
	s_setprio 0
	s_setprio 1
	v_mfma_f32_16x16x32_bf16 v[18:21], v[142:145], v[192:195], v[18:21]
	v_mfma_f32_16x16x32_bf16 v[18:21], v[148:151], v[196:199], v[18:21]
	v_mfma_f32_16x16x32_bf16 v[22:25], v[156:159], v[196:199], v[22:25]
	v_mfma_f32_16x16x32_bf16 v[22:25], v[152:155], v[192:195], v[22:25]
	v_mfma_f32_16x16x32_bf16 v[30:33], v[152:155], v[200:203], v[30:33]
	v_mfma_f32_16x16x32_bf16 v[30:33], v[156:159], v[204:207], v[30:33]
	v_mfma_f32_16x16x32_bf16 v[26:29], v[148:151], v[204:207], v[26:29]
	v_mfma_f32_16x16x32_bf16 v[26:29], v[142:145], v[200:203], v[26:29]
	s_setprio 0
	s_setprio 1
	v_mfma_f32_16x16x32_bf16 v[34:37], v[160:163], v[176:179], v[34:37]
	v_mfma_f32_16x16x32_bf16 v[34:37], v[164:167], v[180:183], v[34:37]
	v_mfma_f32_16x16x32_bf16 v[38:41], v[172:175], v[180:183], v[38:41]
	v_mfma_f32_16x16x32_bf16 v[38:41], v[168:171], v[176:179], v[38:41]
	v_mfma_f32_16x16x32_bf16 v[46:49], v[168:171], v[184:187], v[46:49]
	v_mfma_f32_16x16x32_bf16 v[46:49], v[172:175], v[188:191], v[46:49]
	v_mfma_f32_16x16x32_bf16 v[42:45], v[164:167], v[188:191], v[42:45]
	v_mfma_f32_16x16x32_bf16 v[42:45], v[160:163], v[184:187], v[42:45]
	s_setprio 0
	s_setprio 1
	v_mfma_f32_16x16x32_bf16 v[50:53], v[160:163], v[192:195], v[50:53]
	v_mfma_f32_16x16x32_bf16 v[50:53], v[164:167], v[196:199], v[50:53]
	v_mfma_f32_16x16x32_bf16 v[54:57], v[172:175], v[196:199], v[54:57]
	v_mfma_f32_16x16x32_bf16 v[54:57], v[168:171], v[192:195], v[54:57]
	v_mfma_f32_16x16x32_bf16 v[62:65], v[168:171], v[200:203], v[62:65]
	v_mfma_f32_16x16x32_bf16 v[62:65], v[172:175], v[204:207], v[62:65]
	s_setprio 2
	s_barrier
	v_mfma_f32_16x16x32_bf16 v[58:61], v[164:167], v[204:207], v[58:61]
	v_mfma_f32_16x16x32_bf16 v[58:61], v[160:163], v[200:203], v[58:61]
	s_setprio 0
	s_add_i32 s38, s43, s21
	v_lshl_add_u64 v[138:139], v[138:139], 0, s[8:9]
	s_mov_b32 m0, s38
	ds_read_b128 v[176:179], v141 offset:49152
	ds_read_b128 v[180:183], v141 offset:50176
	ds_read_b128 v[184:187], v141 offset:51200
	ds_read_b128 v[188:191], v141 offset:52224
	ds_read_b128 v[192:195], v141 offset:53248
	ds_read_b128 v[196:199], v141 offset:54272
	ds_read_b128 v[200:203], v141 offset:55296
	ds_read_b128 v[204:207], v141 offset:56320
	global_load_lds_dwordx4 v[138:139], off
	s_add_i32 m0, s38, 0x2000
	s_add_u32 s36, s36, 0x80080
	v_lshl_add_u64 v[138:139], v[208:209], 0, s[8:9]
	s_addc_u32 s37, s37, 0
	s_add_i32 s38, s60, s21
	global_load_lds_dwordx4 v[138:139], off
	s_mov_b32 m0, s38
	v_lshl_add_u64 v[138:139], v[210:211], 0, s[8:9]
	global_load_lds_dwordx4 v136, s[36:37]
	s_add_i32 m0, s38, 0x2000
	s_nop 0
	global_load_lds_dwordx4 v134, s[36:37]
	s_mov_b32 m0, s50
	s_nop 0
	global_load_lds_dwordx4 v[138:139], off
	v_lshl_add_u64 v[138:139], v[212:213], 0, s[8:9]
	s_mov_b32 m0, s51
	s_nop 0
	global_load_lds_dwordx4 v[138:139], off
	s_waitcnt vmcnt(8)
	s_waitcnt lgkmcnt(0)
	s_barrier
	s_setprio 1
	s_waitcnt lgkmcnt(0)
	v_mfma_f32_16x16x32_bf16 v[66:69], v[142:145], v[176:179], v[66:69]
	v_mfma_f32_16x16x32_bf16 v[66:69], v[148:151], v[180:183], v[66:69]
	v_mfma_f32_16x16x32_bf16 v[70:73], v[156:159], v[180:183], v[70:73]
	v_mfma_f32_16x16x32_bf16 v[70:73], v[152:155], v[176:179], v[70:73]
	v_mfma_f32_16x16x32_bf16 v[78:81], v[152:155], v[184:187], v[78:81]
	v_mfma_f32_16x16x32_bf16 v[78:81], v[156:159], v[188:191], v[78:81]
	v_mfma_f32_16x16x32_bf16 v[74:77], v[148:151], v[188:191], v[74:77]
	v_mfma_f32_16x16x32_bf16 v[74:77], v[142:145], v[184:187], v[74:77]
	s_setprio 0
	s_setprio 1
	v_mfma_f32_16x16x32_bf16 v[82:85], v[142:145], v[192:195], v[82:85]
	v_mfma_f32_16x16x32_bf16 v[82:85], v[148:151], v[196:199], v[82:85]
	v_mfma_f32_16x16x32_bf16 v[86:89], v[156:159], v[196:199], v[86:89]
	v_mfma_f32_16x16x32_bf16 v[86:89], v[152:155], v[192:195], v[86:89]
	v_mfma_f32_16x16x32_bf16 v[94:97], v[152:155], v[200:203], v[94:97]
	v_mfma_f32_16x16x32_bf16 v[94:97], v[156:159], v[204:207], v[94:97]
	v_mfma_f32_16x16x32_bf16 v[90:93], v[148:151], v[204:207], v[90:93]
	v_mfma_f32_16x16x32_bf16 v[90:93], v[142:145], v[200:203], v[90:93]
	s_setprio 0
	s_setprio 1
	v_mfma_f32_16x16x32_bf16 v[98:101], v[160:163], v[176:179], v[98:101]
	v_mfma_f32_16x16x32_bf16 v[98:101], v[164:167], v[180:183], v[98:101]
	v_mfma_f32_16x16x32_bf16 v[102:105], v[172:175], v[180:183], v[102:105]
	v_mfma_f32_16x16x32_bf16 v[102:105], v[168:171], v[176:179], v[102:105]
	v_mfma_f32_16x16x32_bf16 v[110:113], v[168:171], v[184:187], v[110:113]
	v_mfma_f32_16x16x32_bf16 v[110:113], v[172:175], v[188:191], v[110:113]
	v_mfma_f32_16x16x32_bf16 v[106:109], v[164:167], v[188:191], v[106:109]
	v_mfma_f32_16x16x32_bf16 v[106:109], v[160:163], v[184:187], v[106:109]
	s_setprio 0
	s_setprio 1
	v_mfma_f32_16x16x32_bf16 v[114:117], v[160:163], v[192:195], v[114:117]
	v_mfma_f32_16x16x32_bf16 v[114:117], v[164:167], v[196:199], v[114:117]
	v_mfma_f32_16x16x32_bf16 v[118:121], v[172:175], v[196:199], v[118:121]
	v_mfma_f32_16x16x32_bf16 v[118:121], v[168:171], v[192:195], v[118:121]
	v_mfma_f32_16x16x32_bf16 v[126:129], v[168:171], v[200:203], v[126:129]
	v_mfma_f32_16x16x32_bf16 v[126:129], v[172:175], v[204:207], v[126:129]
	s_setprio 2
	s_barrier
	v_mfma_f32_16x16x32_bf16 v[122:125], v[164:167], v[204:207], v[122:125]
	v_mfma_f32_16x16x32_bf16 v[122:125], v[160:163], v[200:203], v[122:125]
	s_setprio 0
	s_add_i32 s42, s42, 2
	s_add_u32 s34, s34, 0x100
	s_addc_u32 s35, s35, 0
	s_add_u32 s40, s40, 0x100
	s_addc_u32 s41, s41, 0
	s_cmp_gt_u32 s42, 5
	s_cbranch_scc0 .LBB0_466
	s_and_b64 vcc, exec, s[10:11]
	s_cbranch_vccz .LBB0_469
	s_barrier

.LBB0_495:
	v_add_u32_e32 v14, s58, v140
	v_add_u32_e32 v30, s59, v140
	ds_read_b128 v[2:5], v14
	ds_read_b128 v[6:9], v14 offset:1024
	ds_read_b128 v[10:13], v14 offset:2048
	ds_read_b128 v[14:17], v14 offset:3072
	ds_read_b128 v[18:21], v30
	ds_read_b128 v[22:25], v30 offset:1024
	ds_read_b128 v[26:29], v30 offset:2048
	ds_read_b128 v[30:33], v30 offset:3072
	v_add_u32_e32 v141, 0, v1
	ds_read_b128 v[34:37], v141
	ds_read_b128 v[38:41], v141 offset:1024
	ds_read_b128 v[42:45], v141 offset:2048
	ds_read_b128 v[46:49], v141 offset:3072
	ds_read_b128 v[50:53], v141 offset:4096
	ds_read_b128 v[54:57], v141 offset:5120
	ds_read_b128 v[58:61], v141 offset:6144
	ds_read_b128 v[62:65], v141 offset:7168
	s_waitcnt vmcnt(8)
	s_waitcnt lgkmcnt(0)
	s_barrier
	s_setprio 1
	s_waitcnt lgkmcnt(0)
	v_mfma_f32_16x16x32_bf16 v[66:69], v[2:5], v[34:37], 0
	v_mfma_f32_16x16x32_bf16 v[66:69], v[6:9], v[38:41], v[66:69]
	v_mfma_f32_16x16x32_bf16 v[70:73], v[10:13], v[34:37], 0
	v_mfma_f32_16x16x32_bf16 v[70:73], v[14:17], v[38:41], v[70:73]
	v_mfma_f32_16x16x32_bf16 v[78:81], v[10:13], v[42:45], 0
	v_mfma_f32_16x16x32_bf16 v[78:81], v[14:17], v[46:49], v[78:81]
	v_mfma_f32_16x16x32_bf16 v[74:77], v[2:5], v[42:45], 0
	v_mfma_f32_16x16x32_bf16 v[74:77], v[6:9], v[46:49], v[74:77]
	s_setprio 0
	s_setprio 1
	v_mfma_f32_16x16x32_bf16 v[82:85], v[2:5], v[50:53], 0
	v_mfma_f32_16x16x32_bf16 v[82:85], v[6:9], v[54:57], v[82:85]
	v_mfma_f32_16x16x32_bf16 v[86:89], v[10:13], v[50:53], 0
	v_mfma_f32_16x16x32_bf16 v[86:89], v[14:17], v[54:57], v[86:89]
	v_mfma_f32_16x16x32_bf16 v[94:97], v[10:13], v[58:61], 0
	v_mfma_f32_16x16x32_bf16 v[94:97], v[14:17], v[62:65], v[94:97]
	v_mfma_f32_16x16x32_bf16 v[90:93], v[2:5], v[58:61], 0
	v_mfma_f32_16x16x32_bf16 v[90:93], v[6:9], v[62:65], v[90:93]
	s_setprio 0
	s_setprio 1
	v_mfma_f32_16x16x32_bf16 v[98:101], v[18:21], v[34:37], 0
	v_mfma_f32_16x16x32_bf16 v[34:37], v[26:29], v[34:37], 0
	v_mfma_f32_16x16x32_bf16 v[102:105], v[18:21], v[42:45], 0
	v_mfma_f32_16x16x32_bf16 v[42:45], v[26:29], v[42:45], 0
	v_mfma_f32_16x16x32_bf16 v[106:109], v[18:21], v[50:53], 0
	v_mfma_f32_16x16x32_bf16 v[50:53], v[26:29], v[50:53], 0
	v_mfma_f32_16x16x32_bf16 v[110:113], v[18:21], v[58:61], 0
	v_mfma_f32_16x16x32_bf16 v[58:61], v[26:29], v[58:61], 0
	s_setprio 0
	s_setprio 1
	v_mfma_f32_16x16x32_bf16 v[98:101], v[22:25], v[38:41], v[98:101]
	v_mfma_f32_16x16x32_bf16 v[38:41], v[30:33], v[38:41], v[34:37]
	v_mfma_f32_16x16x32_bf16 v[102:105], v[22:25], v[46:49], v[102:105]
	v_mfma_f32_16x16x32_bf16 v[46:49], v[30:33], v[46:49], v[42:45]
	v_mfma_f32_16x16x32_bf16 v[106:109], v[22:25], v[54:57], v[106:109]
	v_mfma_f32_16x16x32_bf16 v[54:57], v[30:33], v[54:57], v[50:53]
	s_setprio 2
	s_barrier
	v_mfma_f32_16x16x32_bf16 v[110:113], v[22:25], v[62:65], v[110:113]
	v_mfma_f32_16x16x32_bf16 v[62:65], v[30:33], v[62:65], v[58:61]
	s_setprio 0
	v_lshl_add_u64 v[136:137], s[38:39], 0, v[130:131]
	s_add_i32 s62, s58, s46
	v_mov_b32_e32 v135, v131
	v_lshl_add_u64 v[142:143], v[136:137], 0, s[10:11]
	s_mov_b32 m0, s62
	v_lshl_add_u64 v[244:245], s[38:39], 0, v[134:135]
	ds_read_b128 v[34:37], v141 offset:16384
	ds_read_b128 v[42:45], v141 offset:17408
	ds_read_b128 v[50:53], v141 offset:18432
	ds_read_b128 v[58:61], v141 offset:19456
	ds_read_b128 v[114:117], v141 offset:20480
	ds_read_b128 v[118:121], v141 offset:21504
	ds_read_b128 v[122:125], v141 offset:22528
	ds_read_b128 v[126:129], v141 offset:23552
	global_load_lds_dwordx4 v[142:143], off
	v_lshl_add_u64 v[142:143], v[244:245], 0, s[10:11]
	s_add_i32 m0, s62, 0x2000
	s_add_i32 s62, s59, s46
	global_load_lds_dwordx4 v[142:143], off
	s_mov_b32 m0, s62
	v_mov_b32_e32 v139, v131
	global_load_lds_dwordx4 v130, s[40:41]
	s_add_i32 m0, s62, 0x2000
	v_lshl_add_u64 v[246:247], s[36:37], 0, v[138:139]
	v_mov_b32_e32 v133, v131
	global_load_lds_dwordx4 v134, s[40:41]
	v_lshl_add_u64 v[142:143], v[246:247], 0, s[10:11]
	s_mov_b32 m0, s47
	v_lshl_add_u64 v[248:249], s[36:37], 0, v[132:133]
	global_load_lds_dwordx4 v[142:143], off
	v_lshl_add_u64 v[142:143], v[248:249], 0, s[10:11]
	s_mov_b32 m0, s48
	s_nop 0
	global_load_lds_dwordx4 v[142:143], off
	s_waitcnt vmcnt(8)
	s_waitcnt lgkmcnt(0)
	s_barrier
	s_setprio 1
	s_waitcnt lgkmcnt(0)
	v_mfma_f32_16x16x32_bf16 v[142:145], v[2:5], v[34:37], 0
	v_mfma_f32_16x16x32_bf16 v[148:151], v[10:13], v[34:37], 0
	v_mfma_f32_16x16x32_bf16 v[152:155], v[2:5], v[50:53], 0
	v_mfma_f32_16x16x32_bf16 v[156:159], v[10:13], v[50:53], 0
	v_mfma_f32_16x16x32_bf16 v[160:163], v[2:5], v[114:117], 0
	v_mfma_f32_16x16x32_bf16 v[164:167], v[10:13], v[114:117], 0
	v_mfma_f32_16x16x32_bf16 v[2:5], v[2:5], v[122:125], 0
	v_mfma_f32_16x16x32_bf16 v[10:13], v[10:13], v[122:125], 0
	s_setprio 0
	s_setprio 1
	v_mfma_f32_16x16x32_bf16 v[142:145], v[6:9], v[42:45], v[142:145]
	v_mfma_f32_16x16x32_bf16 v[148:151], v[14:17], v[42:45], v[148:151]
	v_mfma_f32_16x16x32_bf16 v[152:155], v[6:9], v[58:61], v[152:155]
	v_mfma_f32_16x16x32_bf16 v[156:159], v[14:17], v[58:61], v[156:159]
	v_mfma_f32_16x16x32_bf16 v[160:163], v[6:9], v[118:121], v[160:163]
	v_mfma_f32_16x16x32_bf16 v[164:167], v[14:17], v[118:121], v[164:167]
	v_mfma_f32_16x16x32_bf16 v[168:171], v[6:9], v[126:129], v[2:5]
	v_mfma_f32_16x16x32_bf16 v[172:175], v[14:17], v[126:129], v[10:13]
	s_setprio 0
	s_setprio 1
	v_mfma_f32_16x16x32_bf16 v[2:5], v[18:21], v[34:37], 0
	v_mfma_f32_16x16x32_bf16 v[6:9], v[26:29], v[34:37], 0
	v_mfma_f32_16x16x32_bf16 v[10:13], v[18:21], v[50:53], 0
	v_mfma_f32_16x16x32_bf16 v[14:17], v[26:29], v[50:53], 0
	v_mfma_f32_16x16x32_bf16 v[34:37], v[18:21], v[114:117], 0
	v_mfma_f32_16x16x32_bf16 v[50:53], v[26:29], v[114:117], 0
	v_mfma_f32_16x16x32_bf16 v[18:21], v[18:21], v[122:125], 0
	v_mfma_f32_16x16x32_bf16 v[26:29], v[26:29], v[122:125], 0
	s_setprio 0
	s_setprio 1
	v_mfma_f32_16x16x32_bf16 v[114:117], v[22:25], v[42:45], v[2:5]
	v_mfma_f32_16x16x32_bf16 v[122:125], v[30:33], v[42:45], v[6:9]
	v_mfma_f32_16x16x32_bf16 v[184:187], v[22:25], v[118:121], v[34:37]
	v_mfma_f32_16x16x32_bf16 v[118:121], v[30:33], v[118:121], v[50:53]
	v_mfma_f32_16x16x32_bf16 v[188:191], v[22:25], v[126:129], v[18:21]
	v_mfma_f32_16x16x32_bf16 v[126:129], v[30:33], v[126:129], v[26:29]
	s_setprio 2
	s_barrier
	v_mfma_f32_16x16x32_bf16 v[176:179], v[22:25], v[58:61], v[10:13]
	v_mfma_f32_16x16x32_bf16 v[180:183], v[30:33], v[58:61], v[14:17]
	s_setprio 0
	s_add_i32 s62, 0, 0x18000
	v_add_u32_e32 v2, s62, v140
	s_add_i32 s63, 0, 0x1c000
	ds_read_b128 v[192:195], v2
	ds_read_b128 v[196:199], v2 offset:1024
	ds_read_b128 v[200:203], v2 offset:2048
	ds_read_b128 v[204:207], v2 offset:3072
	v_add_u32_e32 v2, s63, v140
	ds_read_b128 v[208:211], v2
	ds_read_b128 v[212:215], v2 offset:1024
	ds_read_b128 v[216:219], v2 offset:2048
	ds_read_b128 v[220:223], v2 offset:3072
	s_mov_b32 m0, s49
	ds_read_b128 v[42:45], v141 offset:32768
	ds_read_b128 v[50:53], v141 offset:33792
	ds_read_b128 v[58:61], v141 offset:34816
	ds_read_b128 v[224:227], v141 offset:35840
	ds_read_b128 v[228:231], v141 offset:36864
	ds_read_b128 v[232:235], v141 offset:37888
	ds_read_b128 v[236:239], v141 offset:38912
	ds_read_b128 v[240:243], v141 offset:39936
	global_load_lds_dwordx4 v138, s[42:43]
	s_mov_b32 m0, s50
	s_nop 0
	global_load_lds_dwordx4 v132, s[42:43]
	s_waitcnt vmcnt(8)
	s_waitcnt lgkmcnt(0)
	s_barrier
	s_setprio 1
	s_waitcnt lgkmcnt(0)
	v_mfma_f32_16x16x32_bf16 v[2:5], v[192:195], v[42:45], v[66:69]
	v_mfma_f32_16x16x32_bf16 v[6:9], v[200:203], v[42:45], v[70:73]
	v_mfma_f32_16x16x32_bf16 v[10:13], v[192:195], v[58:61], v[74:77]
	v_mfma_f32_16x16x32_bf16 v[14:17], v[200:203], v[58:61], v[78:81]
	v_mfma_f32_16x16x32_bf16 v[18:21], v[192:195], v[228:231], v[82:85]
	v_mfma_f32_16x16x32_bf16 v[22:25], v[200:203], v[228:231], v[86:89]
	v_mfma_f32_16x16x32_bf16 v[26:29], v[192:195], v[236:239], v[90:93]
	v_mfma_f32_16x16x32_bf16 v[30:33], v[200:203], v[236:239], v[94:97]
	s_setprio 0
	s_setprio 1
	v_mfma_f32_16x16x32_bf16 v[2:5], v[196:199], v[50:53], v[2:5]
	v_mfma_f32_16x16x32_bf16 v[6:9], v[204:207], v[50:53], v[6:9]
	v_mfma_f32_16x16x32_bf16 v[10:13], v[196:199], v[224:227], v[10:13]
	v_mfma_f32_16x16x32_bf16 v[14:17], v[204:207], v[224:227], v[14:17]
	v_mfma_f32_16x16x32_bf16 v[18:21], v[196:199], v[232:235], v[18:21]
	v_mfma_f32_16x16x32_bf16 v[22:25], v[204:207], v[232:235], v[22:25]
	v_mfma_f32_16x16x32_bf16 v[26:29], v[196:199], v[240:243], v[26:29]
	v_mfma_f32_16x16x32_bf16 v[30:33], v[204:207], v[240:243], v[30:33]
	s_setprio 0
	s_setprio 1
	v_mfma_f32_16x16x32_bf16 v[34:37], v[208:211], v[42:45], v[98:101]
	v_mfma_f32_16x16x32_bf16 v[38:41], v[216:219], v[42:45], v[38:41]
	v_mfma_f32_16x16x32_bf16 v[34:37], v[212:215], v[50:53], v[34:37]
	v_mfma_f32_16x16x32_bf16 v[38:41], v[220:223], v[50:53], v[38:41]
	v_mfma_f32_16x16x32_bf16 v[42:45], v[208:211], v[58:61], v[102:105]
	v_mfma_f32_16x16x32_bf16 v[46:49], v[216:219], v[58:61], v[46:49]
	v_mfma_f32_16x16x32_bf16 v[50:53], v[208:211], v[228:231], v[106:109]
	v_mfma_f32_16x16x32_bf16 v[54:57], v[216:219], v[228:231], v[54:57]
	s_setprio 0
	s_setprio 1
	v_mfma_f32_16x16x32_bf16 v[58:61], v[208:211], v[236:239], v[110:113]
	v_mfma_f32_16x16x32_bf16 v[62:65], v[216:219], v[236:239], v[62:65]
	v_mfma_f32_16x16x32_bf16 v[42:45], v[212:215], v[224:227], v[42:45]
	v_mfma_f32_16x16x32_bf16 v[46:49], v[220:223], v[224:227], v[46:49]
	v_mfma_f32_16x16x32_bf16 v[50:53], v[212:215], v[232:235], v[50:53]
	v_mfma_f32_16x16x32_bf16 v[54:57], v[220:223], v[232:235], v[54:57]
	s_setprio 2
	s_barrier
	v_mfma_f32_16x16x32_bf16 v[58:61], v[212:215], v[240:243], v[58:61]
	v_mfma_f32_16x16x32_bf16 v[62:65], v[220:223], v[240:243], v[62:65]
	s_setprio 0
	s_add_i32 s62, s62, s46
	v_lshl_add_u64 v[66:67], v[136:137], 0, s[12:13]
	s_mov_b32 m0, s62
	ds_read_b128 v[102:105], v141 offset:49152
	ds_read_b128 v[106:109], v141 offset:50176
	ds_read_b128 v[110:113], v141 offset:51200
	ds_read_b128 v[224:227], v141 offset:52224
	ds_read_b128 v[228:231], v141 offset:53248
	ds_read_b128 v[232:235], v141 offset:54272
	ds_read_b128 v[236:239], v141 offset:55296
	ds_read_b128 v[240:243], v141 offset:56320
	global_load_lds_dwordx4 v[66:67], off
	v_lshl_add_u64 v[66:67], v[244:245], 0, s[12:13]
	s_add_i32 m0, s62, 0x2000
	s_add_i32 s62, s63, s46
	global_load_lds_dwordx4 v[66:67], off
	s_mov_b32 m0, s62
	v_lshl_add_u64 v[66:67], v[246:247], 0, s[12:13]
	global_load_lds_dwordx4 v130, s[44:45]
	s_add_i32 m0, s62, 0x2000
	s_nop 0
	global_load_lds_dwordx4 v134, s[44:45]
	s_mov_b32 m0, s54
	s_nop 0
	global_load_lds_dwordx4 v[66:67], off
	v_lshl_add_u64 v[66:67], v[248:249], 0, s[12:13]
	s_mov_b32 m0, s55
	s_nop 0
	global_load_lds_dwordx4 v[66:67], off
	s_waitcnt vmcnt(8)
	s_waitcnt lgkmcnt(0)
	s_barrier
	s_setprio 1
	s_waitcnt lgkmcnt(0)
	v_mfma_f32_16x16x32_bf16 v[66:69], v[192:195], v[102:105], v[142:145]
	v_mfma_f32_16x16x32_bf16 v[70:73], v[200:203], v[102:105], v[148:151]
	v_mfma_f32_16x16x32_bf16 v[74:77], v[192:195], v[110:113], v[152:155]
	v_mfma_f32_16x16x32_bf16 v[78:81], v[200:203], v[110:113], v[156:159]
	v_mfma_f32_16x16x32_bf16 v[82:85], v[192:195], v[228:231], v[160:163]
	v_mfma_f32_16x16x32_bf16 v[86:89], v[200:203], v[228:231], v[164:167]
	v_mfma_f32_16x16x32_bf16 v[90:93], v[192:195], v[236:239], v[168:171]
	v_mfma_f32_16x16x32_bf16 v[94:97], v[200:203], v[236:239], v[172:175]
	s_setprio 0
	s_setprio 1
	v_mfma_f32_16x16x32_bf16 v[66:69], v[196:199], v[106:109], v[66:69]
	v_mfma_f32_16x16x32_bf16 v[70:73], v[204:207], v[106:109], v[70:73]
	v_mfma_f32_16x16x32_bf16 v[74:77], v[196:199], v[224:227], v[74:77]
	v_mfma_f32_16x16x32_bf16 v[78:81], v[204:207], v[224:227], v[78:81]
	v_mfma_f32_16x16x32_bf16 v[82:85], v[196:199], v[232:235], v[82:85]
	v_mfma_f32_16x16x32_bf16 v[86:89], v[204:207], v[232:235], v[86:89]
	v_mfma_f32_16x16x32_bf16 v[90:93], v[196:199], v[240:243], v[90:93]
	v_mfma_f32_16x16x32_bf16 v[94:97], v[204:207], v[240:243], v[94:97]
	s_setprio 0
	s_setprio 1
	v_mfma_f32_16x16x32_bf16 v[98:101], v[208:211], v[102:105], v[114:117]
	v_mfma_f32_16x16x32_bf16 v[102:105], v[216:219], v[102:105], v[122:125]
	v_mfma_f32_16x16x32_bf16 v[98:101], v[212:215], v[106:109], v[98:101]
	v_mfma_f32_16x16x32_bf16 v[102:105], v[220:223], v[106:109], v[102:105]
	v_mfma_f32_16x16x32_bf16 v[106:109], v[208:211], v[110:113], v[176:179]
	v_mfma_f32_16x16x32_bf16 v[110:113], v[216:219], v[110:113], v[180:183]
	v_mfma_f32_16x16x32_bf16 v[114:117], v[208:211], v[228:231], v[184:187]
	v_mfma_f32_16x16x32_bf16 v[118:121], v[216:219], v[228:231], v[118:121]
	s_setprio 0
	s_setprio 1
	v_mfma_f32_16x16x32_bf16 v[122:125], v[208:211], v[236:239], v[188:191]
	v_mfma_f32_16x16x32_bf16 v[126:129], v[216:219], v[236:239], v[126:129]
	v_mfma_f32_16x16x32_bf16 v[106:109], v[212:215], v[224:227], v[106:109]
	v_mfma_f32_16x16x32_bf16 v[110:113], v[220:223], v[224:227], v[110:113]
	v_mfma_f32_16x16x32_bf16 v[114:117], v[212:215], v[232:235], v[114:117]
	v_mfma_f32_16x16x32_bf16 v[118:121], v[220:223], v[232:235], v[118:121]
	s_setprio 2
	s_barrier
	v_mfma_f32_16x16x32_bf16 v[122:125], v[212:215], v[240:243], v[122:125]
	v_mfma_f32_16x16x32_bf16 v[126:129], v[220:223], v[240:243], v[126:129]
	s_setprio 0
	s_add_i32 s27, s27, 2
	s_cmp_ge_i32 s27, s15
	s_cbranch_scc0 .LBB0_495
	v_mov_b32_e32 v136, v130
	s_branch .LBB0_498

.LBB0_499:
	v_add_u32_e32 v133, s58, v140
	ds_read_b128 v[142:145], v133
	ds_read_b128 v[148:151], v133 offset:1024
	ds_read_b128 v[152:155], v133 offset:2048
	ds_read_b128 v[156:159], v133 offset:3072
	v_add_u32_e32 v133, s59, v140
	ds_read_b128 v[160:163], v133
	ds_read_b128 v[164:167], v133 offset:1024
	ds_read_b128 v[168:171], v133 offset:2048
	ds_read_b128 v[172:175], v133 offset:3072
	s_add_u32 s38, s36, 0xfff80080
	s_addc_u32 s39, s37, -1
	s_cmp_eq_u32 s42, 4
	s_cselect_b32 s41, s31, s39
	s_cselect_b32 s40, s30, s38
	s_cselect_b32 s39, s35, s27
	s_cselect_b32 s38, s34, s15
	s_mov_b32 m0, s56
	v_add_u32_e32 v141, 0, v1
	ds_read_b128 v[176:179], v141
	ds_read_b128 v[180:183], v141 offset:1024
	ds_read_b128 v[184:187], v141 offset:2048
	ds_read_b128 v[188:191], v141 offset:3072
	ds_read_b128 v[192:195], v141 offset:4096
	ds_read_b128 v[196:199], v141 offset:5120
	ds_read_b128 v[200:203], v141 offset:6144
	ds_read_b128 v[204:207], v141 offset:7168
	global_load_lds_dwordx4 v130, s[36:37]
	s_mov_b32 m0, s57
	v_mov_b32_e32 v133, v131
	global_load_lds_dwordx4 v132, s[36:37]
	s_waitcnt vmcnt(8)
	s_waitcnt lgkmcnt(0)
	s_barrier
	s_setprio 1
	s_waitcnt lgkmcnt(0)
	v_mfma_f32_16x16x32_bf16 v[2:5], v[142:145], v[176:179], v[2:5]
	v_mfma_f32_16x16x32_bf16 v[2:5], v[148:151], v[180:183], v[2:5]
	v_mfma_f32_16x16x32_bf16 v[6:9], v[156:159], v[180:183], v[6:9]
	v_mfma_f32_16x16x32_bf16 v[6:9], v[152:155], v[176:179], v[6:9]
	v_mfma_f32_16x16x32_bf16 v[14:17], v[152:155], v[184:187], v[14:17]
	v_mfma_f32_16x16x32_bf16 v[14:17], v[156:159], v[188:191], v[14:17]
	v_mfma_f32_16x16x32_bf16 v[10:13], v[148:151], v[188:191], v[10:13]
	v_mfma_f32_16x16x32_bf16 v[10:13], v[142:145], v[184:187], v[10:13]
	s_setprio 0
	s_setprio 1
	v_mfma_f32_16x16x32_bf16 v[18:21], v[142:145], v[192:195], v[18:21]
	v_mfma_f32_16x16x32_bf16 v[18:21], v[148:151], v[196:199], v[18:21]
	v_mfma_f32_16x16x32_bf16 v[22:25], v[156:159], v[196:199], v[22:25]
	v_mfma_f32_16x16x32_bf16 v[22:25], v[152:155], v[192:195], v[22:25]
	v_mfma_f32_16x16x32_bf16 v[30:33], v[152:155], v[200:203], v[30:33]
	v_mfma_f32_16x16x32_bf16 v[30:33], v[156:159], v[204:207], v[30:33]
	v_mfma_f32_16x16x32_bf16 v[26:29], v[148:151], v[204:207], v[26:29]
	v_mfma_f32_16x16x32_bf16 v[26:29], v[142:145], v[200:203], v[26:29]
	s_setprio 0
	s_setprio 1
	v_mfma_f32_16x16x32_bf16 v[34:37], v[160:163], v[176:179], v[34:37]
	v_mfma_f32_16x16x32_bf16 v[34:37], v[164:167], v[180:183], v[34:37]
	v_mfma_f32_16x16x32_bf16 v[38:41], v[172:175], v[180:183], v[38:41]
	v_mfma_f32_16x16x32_bf16 v[38:41], v[168:171], v[176:179], v[38:41]
	v_mfma_f32_16x16x32_bf16 v[46:49], v[168:171], v[184:187], v[46:49]
	v_mfma_f32_16x16x32_bf16 v[46:49], v[172:175], v[188:191], v[46:49]
	v_mfma_f32_16x16x32_bf16 v[42:45], v[164:167], v[188:191], v[42:45]
	v_mfma_f32_16x16x32_bf16 v[42:45], v[160:163], v[184:187], v[42:45]
	s_setprio 0
	s_setprio 1
	v_mfma_f32_16x16x32_bf16 v[50:53], v[160:163], v[192:195], v[50:53]
	v_mfma_f32_16x16x32_bf16 v[50:53], v[164:167], v[196:199], v[50:53]
	v_mfma_f32_16x16x32_bf16 v[54:57], v[172:175], v[196:199], v[54:57]
	v_mfma_f32_16x16x32_bf16 v[54:57], v[168:171], v[192:195], v[54:57]
	v_mfma_f32_16x16x32_bf16 v[62:65], v[168:171], v[200:203], v[62:65]
	v_mfma_f32_16x16x32_bf16 v[62:65], v[172:175], v[204:207], v[62:65]
	s_setprio 2
	s_barrier
	v_mfma_f32_16x16x32_bf16 v[58:61], v[164:167], v[204:207], v[58:61]
	v_mfma_f32_16x16x32_bf16 v[58:61], v[160:163], v[200:203], v[58:61]
	s_setprio 0
	s_add_i32 s43, s58, s46
	s_mov_b32 m0, s43
	ds_read_b128 v[176:179], v141 offset:16384
	ds_read_b128 v[180:183], v141 offset:17408
	ds_read_b128 v[184:187], v141 offset:18432
	ds_read_b128 v[188:191], v141 offset:19456
	ds_read_b128 v[192:195], v141 offset:20480
	ds_read_b128 v[196:199], v141 offset:21504
	ds_read_b128 v[200:203], v141 offset:22528
	ds_read_b128 v[204:207], v141 offset:23552
	global_load_lds_dwordx4 v136, s[38:39]
	s_add_i32 m0, s43, 0x2000
	s_add_u32 s44, s38, 0x400000
	s_addc_u32 s45, s39, 0
	s_add_i32 s43, s59, s46
	global_load_lds_dwordx4 v134, s[38:39]
	s_mov_b32 m0, s43
	v_mov_b32_e32 v137, v131
	global_load_lds_dwordx4 v136, s[44:45]
	s_add_i32 m0, s43, 0x2000
	v_mov_b32_e32 v135, v131
	global_load_lds_dwordx4 v134, s[44:45]
	s_mov_b32 m0, s47
	v_lshl_add_u64 v[138:139], s[38:39], 0, v[136:137]
	global_load_lds_dwordx4 v130, s[40:41]
	s_mov_b32 m0, s48
	v_lshl_add_u64 v[208:209], s[38:39], 0, v[134:135]
	global_load_lds_dwordx4 v132, s[40:41]
	s_waitcnt vmcnt(8)
	s_waitcnt lgkmcnt(0)
	v_lshl_add_u64 v[210:211], s[40:41], 0, v[130:131]
	v_lshl_add_u64 v[212:213], s[40:41], 0, v[132:133]
	s_barrier
	s_setprio 1
	s_waitcnt lgkmcnt(0)
	v_mfma_f32_16x16x32_bf16 v[66:69], v[142:145], v[176:179], v[66:69]
	v_mfma_f32_16x16x32_bf16 v[66:69], v[148:151], v[180:183], v[66:69]
	v_mfma_f32_16x16x32_bf16 v[70:73], v[156:159], v[180:183], v[70:73]
	v_mfma_f32_16x16x32_bf16 v[70:73], v[152:155], v[176:179], v[70:73]
	v_mfma_f32_16x16x32_bf16 v[78:81], v[152:155], v[184:187], v[78:81]
	v_mfma_f32_16x16x32_bf16 v[78:81], v[156:159], v[188:191], v[78:81]
	v_mfma_f32_16x16x32_bf16 v[74:77], v[148:151], v[188:191], v[74:77]
	v_mfma_f32_16x16x32_bf16 v[74:77], v[142:145], v[184:187], v[74:77]
	s_setprio 0
	s_setprio 1
	v_mfma_f32_16x16x32_bf16 v[82:85], v[142:145], v[192:195], v[82:85]
	v_mfma_f32_16x16x32_bf16 v[82:85], v[148:151], v[196:199], v[82:85]
	v_mfma_f32_16x16x32_bf16 v[86:89], v[156:159], v[196:199], v[86:89]
	v_mfma_f32_16x16x32_bf16 v[86:89], v[152:155], v[192:195], v[86:89]
	v_mfma_f32_16x16x32_bf16 v[94:97], v[152:155], v[200:203], v[94:97]
	v_mfma_f32_16x16x32_bf16 v[94:97], v[156:159], v[204:207], v[94:97]
	v_mfma_f32_16x16x32_bf16 v[90:93], v[148:151], v[204:207], v[90:93]
	v_mfma_f32_16x16x32_bf16 v[90:93], v[142:145], v[200:203], v[90:93]
	s_setprio 0
	s_setprio 1
	v_mfma_f32_16x16x32_bf16 v[98:101], v[160:163], v[176:179], v[98:101]
	v_mfma_f32_16x16x32_bf16 v[98:101], v[164:167], v[180:183], v[98:101]
	v_mfma_f32_16x16x32_bf16 v[102:105], v[172:175], v[180:183], v[102:105]
	v_mfma_f32_16x16x32_bf16 v[102:105], v[168:171], v[176:179], v[102:105]
	v_mfma_f32_16x16x32_bf16 v[110:113], v[168:171], v[184:187], v[110:113]
	v_mfma_f32_16x16x32_bf16 v[110:113], v[172:175], v[188:191], v[110:113]
	v_mfma_f32_16x16x32_bf16 v[106:109], v[164:167], v[188:191], v[106:109]
	v_mfma_f32_16x16x32_bf16 v[106:109], v[160:163], v[184:187], v[106:109]
	s_setprio 0
	s_setprio 1
	v_mfma_f32_16x16x32_bf16 v[114:117], v[160:163], v[192:195], v[114:117]
	v_mfma_f32_16x16x32_bf16 v[114:117], v[164:167], v[196:199], v[114:117]
	v_mfma_f32_16x16x32_bf16 v[118:121], v[172:175], v[196:199], v[118:121]
	v_mfma_f32_16x16x32_bf16 v[118:121], v[168:171], v[192:195], v[118:121]
	v_mfma_f32_16x16x32_bf16 v[126:129], v[168:171], v[200:203], v[126:129]
	v_mfma_f32_16x16x32_bf16 v[126:129], v[172:175], v[204:207], v[126:129]
	s_setprio 2
	s_barrier
	v_mfma_f32_16x16x32_bf16 v[122:125], v[164:167], v[204:207], v[122:125]
	v_mfma_f32_16x16x32_bf16 v[122:125], v[160:163], v[200:203], v[122:125]
	s_setprio 0
	s_add_i32 s43, 0, 0x18000
	v_add_u32_e32 v135, s43, v140
	s_add_i32 s44, 0, 0x1c000
	ds_read_b128 v[142:145], v135
	ds_read_b128 v[148:151], v135 offset:1024
	ds_read_b128 v[152:155], v135 offset:2048
	ds_read_b128 v[156:159], v135 offset:3072
	v_add_u32_e32 v135, s44, v140
	ds_read_b128 v[160:163], v135
	ds_read_b128 v[164:167], v135 offset:1024
	ds_read_b128 v[168:171], v135 offset:2048
	ds_read_b128 v[172:175], v135 offset:3072
	s_add_u32 s40, s40, 0x80000
	s_addc_u32 s41, s41, 0
	s_mov_b32 m0, s49
	ds_read_b128 v[176:179], v141 offset:32768
	ds_read_b128 v[180:183], v141 offset:33792
	ds_read_b128 v[184:187], v141 offset:34816
	ds_read_b128 v[188:191], v141 offset:35840
	ds_read_b128 v[192:195], v141 offset:36864
	ds_read_b128 v[196:199], v141 offset:37888
	ds_read_b128 v[200:203], v141 offset:38912
	ds_read_b128 v[204:207], v141 offset:39936
	global_load_lds_dwordx4 v130, s[40:41]
	s_mov_b32 m0, s50
	s_nop 0
	global_load_lds_dwordx4 v132, s[40:41]
	s_waitcnt vmcnt(8)
	s_waitcnt lgkmcnt(0)
	s_barrier
	s_setprio 1
	s_waitcnt lgkmcnt(0)
	v_mfma_f32_16x16x32_bf16 v[2:5], v[142:145], v[176:179], v[2:5]
	v_mfma_f32_16x16x32_bf16 v[2:5], v[148:151], v[180:183], v[2:5]
	v_mfma_f32_16x16x32_bf16 v[6:9], v[156:159], v[180:183], v[6:9]
	v_mfma_f32_16x16x32_bf16 v[6:9], v[152:155], v[176:179], v[6:9]
	v_mfma_f32_16x16x32_bf16 v[14:17], v[152:155], v[184:187], v[14:17]
	v_mfma_f32_16x16x32_bf16 v[14:17], v[156:159], v[188:191], v[14:17]
	v_mfma_f32_16x16x32_bf16 v[10:13], v[148:151], v[188:191], v[10:13]
	v_mfma_f32_16x16x32_bf16 v[10:13], v[142:145], v[184:187], v[10:13]
	s_setprio 0
	s_setprio 1
	v_mfma_f32_16x16x32_bf16 v[18:21], v[142:145], v[192:195], v[18:21]
	v_mfma_f32_16x16x32_bf16 v[18:21], v[148:151], v[196:199], v[18:21]
	v_mfma_f32_16x16x32_bf16 v[22:25], v[156:159], v[196:199], v[22:25]
	v_mfma_f32_16x16x32_bf16 v[22:25], v[152:155], v[192:195], v[22:25]
	v_mfma_f32_16x16x32_bf16 v[30:33], v[152:155], v[200:203], v[30:33]
	v_mfma_f32_16x16x32_bf16 v[30:33], v[156:159], v[204:207], v[30:33]
	v_mfma_f32_16x16x32_bf16 v[26:29], v[148:151], v[204:207], v[26:29]
	v_mfma_f32_16x16x32_bf16 v[26:29], v[142:145], v[200:203], v[26:29]
	s_setprio 0
	s_setprio 1
	v_mfma_f32_16x16x32_bf16 v[34:37], v[160:163], v[176:179], v[34:37]
	v_mfma_f32_16x16x32_bf16 v[34:37], v[164:167], v[180:183], v[34:37]
	v_mfma_f32_16x16x32_bf16 v[38:41], v[172:175], v[180:183], v[38:41]
	v_mfma_f32_16x16x32_bf16 v[38:41], v[168:171], v[176:179], v[38:41]
	v_mfma_f32_16x16x32_bf16 v[46:49], v[168:171], v[184:187], v[46:49]
	v_mfma_f32_16x16x32_bf16 v[46:49], v[172:175], v[188:191], v[46:49]
	v_mfma_f32_16x16x32_bf16 v[42:45], v[164:167], v[188:191], v[42:45]
	v_mfma_f32_16x16x32_bf16 v[42:45], v[160:163], v[184:187], v[42:45]
	s_setprio 0
	s_setprio 1
	v_mfma_f32_16x16x32_bf16 v[50:53], v[160:163], v[192:195], v[50:53]
	v_mfma_f32_16x16x32_bf16 v[50:53], v[164:167], v[196:199], v[50:53]
	v_mfma_f32_16x16x32_bf16 v[54:57], v[172:175], v[196:199], v[54:57]
	v_mfma_f32_16x16x32_bf16 v[54:57], v[168:171], v[192:195], v[54:57]
	v_mfma_f32_16x16x32_bf16 v[62:65], v[168:171], v[200:203], v[62:65]
	v_mfma_f32_16x16x32_bf16 v[62:65], v[172:175], v[204:207], v[62:65]
	s_setprio 2
	s_barrier
	v_mfma_f32_16x16x32_bf16 v[58:61], v[164:167], v[204:207], v[58:61]
	v_mfma_f32_16x16x32_bf16 v[58:61], v[160:163], v[200:203], v[58:61]
	s_setprio 0
	s_add_i32 s40, s43, s46
	v_lshl_add_u64 v[138:139], v[138:139], 0, s[6:7]
	s_mov_b32 m0, s40
	ds_read_b128 v[176:179], v141 offset:49152
	ds_read_b128 v[180:183], v141 offset:50176
	ds_read_b128 v[184:187], v141 offset:51200
	ds_read_b128 v[188:191], v141 offset:52224
	ds_read_b128 v[192:195], v141 offset:53248
	ds_read_b128 v[196:199], v141 offset:54272
	ds_read_b128 v[200:203], v141 offset:55296
	ds_read_b128 v[204:207], v141 offset:56320
	global_load_lds_dwordx4 v[138:139], off
	s_add_i32 m0, s40, 0x2000
	s_add_u32 s38, s38, 0x400080
	v_lshl_add_u64 v[138:139], v[208:209], 0, s[6:7]
	s_addc_u32 s39, s39, 0
	s_add_i32 s40, s44, s46
	global_load_lds_dwordx4 v[138:139], off
	s_mov_b32 m0, s40
	v_lshl_add_u64 v[138:139], v[210:211], 0, s[6:7]
	global_load_lds_dwordx4 v136, s[38:39]
	s_add_i32 m0, s40, 0x2000
	s_nop 0
	global_load_lds_dwordx4 v134, s[38:39]
	s_mov_b32 m0, s54
	s_nop 0
	global_load_lds_dwordx4 v[138:139], off
	v_lshl_add_u64 v[138:139], v[212:213], 0, s[6:7]
	s_mov_b32 m0, s55
	s_nop 0
	global_load_lds_dwordx4 v[138:139], off
	s_waitcnt vmcnt(8)
	s_waitcnt lgkmcnt(0)
	s_barrier
	s_setprio 1
	s_waitcnt lgkmcnt(0)
	v_mfma_f32_16x16x32_bf16 v[66:69], v[142:145], v[176:179], v[66:69]
	v_mfma_f32_16x16x32_bf16 v[66:69], v[148:151], v[180:183], v[66:69]
	v_mfma_f32_16x16x32_bf16 v[70:73], v[156:159], v[180:183], v[70:73]
	v_mfma_f32_16x16x32_bf16 v[70:73], v[152:155], v[176:179], v[70:73]
	v_mfma_f32_16x16x32_bf16 v[78:81], v[152:155], v[184:187], v[78:81]
	v_mfma_f32_16x16x32_bf16 v[78:81], v[156:159], v[188:191], v[78:81]
	v_mfma_f32_16x16x32_bf16 v[74:77], v[148:151], v[188:191], v[74:77]
	v_mfma_f32_16x16x32_bf16 v[74:77], v[142:145], v[184:187], v[74:77]
	s_setprio 0
	s_setprio 1
	v_mfma_f32_16x16x32_bf16 v[82:85], v[142:145], v[192:195], v[82:85]
	v_mfma_f32_16x16x32_bf16 v[82:85], v[148:151], v[196:199], v[82:85]
	v_mfma_f32_16x16x32_bf16 v[86:89], v[156:159], v[196:199], v[86:89]
	v_mfma_f32_16x16x32_bf16 v[86:89], v[152:155], v[192:195], v[86:89]
	v_mfma_f32_16x16x32_bf16 v[94:97], v[152:155], v[200:203], v[94:97]
	v_mfma_f32_16x16x32_bf16 v[94:97], v[156:159], v[204:207], v[94:97]
	v_mfma_f32_16x16x32_bf16 v[90:93], v[148:151], v[204:207], v[90:93]
	v_mfma_f32_16x16x32_bf16 v[90:93], v[142:145], v[200:203], v[90:93]
	s_setprio 0
	s_setprio 1
	v_mfma_f32_16x16x32_bf16 v[98:101], v[160:163], v[176:179], v[98:101]
	v_mfma_f32_16x16x32_bf16 v[98:101], v[164:167], v[180:183], v[98:101]
	v_mfma_f32_16x16x32_bf16 v[102:105], v[172:175], v[180:183], v[102:105]
	v_mfma_f32_16x16x32_bf16 v[102:105], v[168:171], v[176:179], v[102:105]
	v_mfma_f32_16x16x32_bf16 v[110:113], v[168:171], v[184:187], v[110:113]
	v_mfma_f32_16x16x32_bf16 v[110:113], v[172:175], v[188:191], v[110:113]
	v_mfma_f32_16x16x32_bf16 v[106:109], v[164:167], v[188:191], v[106:109]
	v_mfma_f32_16x16x32_bf16 v[106:109], v[160:163], v[184:187], v[106:109]
	s_setprio 0
	s_setprio 1
	v_mfma_f32_16x16x32_bf16 v[114:117], v[160:163], v[192:195], v[114:117]
	v_mfma_f32_16x16x32_bf16 v[114:117], v[164:167], v[196:199], v[114:117]
	v_mfma_f32_16x16x32_bf16 v[118:121], v[172:175], v[196:199], v[118:121]
	v_mfma_f32_16x16x32_bf16 v[118:121], v[168:171], v[192:195], v[118:121]
	v_mfma_f32_16x16x32_bf16 v[126:129], v[168:171], v[200:203], v[126:129]
	v_mfma_f32_16x16x32_bf16 v[126:129], v[172:175], v[204:207], v[126:129]
	s_setprio 2
	s_barrier
	v_mfma_f32_16x16x32_bf16 v[122:125], v[164:167], v[204:207], v[122:125]
	v_mfma_f32_16x16x32_bf16 v[122:125], v[160:163], v[200:203], v[122:125]
	s_setprio 0
	s_add_i32 s42, s42, 2
	s_add_u32 s36, s36, 0x100
	s_addc_u32 s37, s37, 0
	s_add_u32 s15, s15, 0x100
	s_addc_u32 s27, s27, 0
	s_cmp_gt_u32 s42, 5
	s_cbranch_scc0 .LBB0_499
	s_and_b64 vcc, exec, s[8:9]
	s_cbranch_vccz .LBB0_502
	s_barrier

.LBB0_528:
	s_add_i32 s53, 0, 0x10000
	s_add_i32 s72, 0, 0x14000
	v_add_u32_e32 v16, s53, v147
	v_add_u32_e32 v32, s72, v147
	ds_read_b128 v[4:7], v16
	ds_read_b128 v[8:11], v16 offset:1024
	ds_read_b128 v[12:15], v16 offset:2048
	ds_read_b128 v[16:19], v16 offset:3072
	ds_read_b128 v[20:23], v32
	ds_read_b128 v[24:27], v32 offset:1024
	ds_read_b128 v[28:31], v32 offset:2048
	ds_read_b128 v[32:35], v32 offset:3072
	v_add_u32_e32 v231, 0, v146
	ds_read_b128 v[36:39], v231
	ds_read_b128 v[40:43], v231 offset:1024
	ds_read_b128 v[44:47], v231 offset:2048
	ds_read_b128 v[48:51], v231 offset:3072
	ds_read_b128 v[52:55], v231 offset:4096
	ds_read_b128 v[56:59], v231 offset:5120
	ds_read_b128 v[60:63], v231 offset:6144
	ds_read_b128 v[64:67], v231 offset:7168
	s_waitcnt vmcnt(8)
	s_waitcnt lgkmcnt(0)
	s_barrier
	s_setprio 1
	s_waitcnt lgkmcnt(0)
	v_mfma_f32_16x16x32_f16 v[68:71], v[4:7], v[36:39], 0
	v_mfma_f32_16x16x32_f16 v[68:71], v[8:11], v[40:43], v[68:71]
	v_mfma_f32_16x16x32_f16 v[72:75], v[12:15], v[36:39], 0
	v_mfma_f32_16x16x32_f16 v[72:75], v[16:19], v[40:43], v[72:75]
	v_mfma_f32_16x16x32_f16 v[80:83], v[12:15], v[44:47], 0
	v_mfma_f32_16x16x32_f16 v[80:83], v[16:19], v[48:51], v[80:83]
	v_mfma_f32_16x16x32_f16 v[76:79], v[4:7], v[44:47], 0
	v_mfma_f32_16x16x32_f16 v[76:79], v[8:11], v[48:51], v[76:79]
	s_setprio 0
	s_setprio 1
	v_mfma_f32_16x16x32_f16 v[84:87], v[4:7], v[52:55], 0
	v_mfma_f32_16x16x32_f16 v[84:87], v[8:11], v[56:59], v[84:87]
	v_mfma_f32_16x16x32_f16 v[88:91], v[12:15], v[52:55], 0
	v_mfma_f32_16x16x32_f16 v[88:91], v[16:19], v[56:59], v[88:91]
	v_mfma_f32_16x16x32_f16 v[96:99], v[12:15], v[60:63], 0
	v_mfma_f32_16x16x32_f16 v[96:99], v[16:19], v[64:67], v[96:99]
	v_mfma_f32_16x16x32_f16 v[92:95], v[4:7], v[60:63], 0
	v_mfma_f32_16x16x32_f16 v[92:95], v[8:11], v[64:67], v[92:95]
	s_setprio 0
	s_setprio 1
	v_mfma_f32_16x16x32_f16 v[100:103], v[20:23], v[36:39], 0
	v_mfma_f32_16x16x32_f16 v[36:39], v[28:31], v[36:39], 0
	v_mfma_f32_16x16x32_f16 v[104:107], v[20:23], v[44:47], 0
	v_mfma_f32_16x16x32_f16 v[44:47], v[28:31], v[44:47], 0
	v_mfma_f32_16x16x32_f16 v[108:111], v[20:23], v[52:55], 0
	v_mfma_f32_16x16x32_f16 v[52:55], v[28:31], v[52:55], 0
	v_mfma_f32_16x16x32_f16 v[112:115], v[20:23], v[60:63], 0
	v_mfma_f32_16x16x32_f16 v[60:63], v[28:31], v[60:63], 0
	s_setprio 0
	s_setprio 1
	v_mfma_f32_16x16x32_f16 v[100:103], v[24:27], v[40:43], v[100:103]
	v_mfma_f32_16x16x32_f16 v[40:43], v[32:35], v[40:43], v[36:39]
	v_mfma_f32_16x16x32_f16 v[104:107], v[24:27], v[48:51], v[104:107]
	v_mfma_f32_16x16x32_f16 v[48:51], v[32:35], v[48:51], v[44:47]
	v_mfma_f32_16x16x32_f16 v[108:111], v[24:27], v[56:59], v[108:111]
	v_mfma_f32_16x16x32_f16 v[56:59], v[32:35], v[56:59], v[52:55]
	s_setprio 2
	s_barrier
	v_mfma_f32_16x16x32_f16 v[112:115], v[24:27], v[64:67], v[112:115]
	v_mfma_f32_16x16x32_f16 v[64:67], v[32:35], v[64:67], v[60:63]
	s_setprio 0
	v_lshl_add_u64 v[136:137], s[6:7], 0, v[2:3]
	s_add_i32 s53, s53, s38
	v_mov_b32_e32 v135, v3
	v_lshl_add_u64 v[140:141], v[136:137], 0, s[74:75]
	s_mov_b32 m0, s53
	v_lshl_add_u64 v[144:145], s[6:7], 0, v[134:135]
	ds_read_b128 v[36:39], v231 offset:16384
	ds_read_b128 v[44:47], v231 offset:17408
	ds_read_b128 v[52:55], v231 offset:18432
	ds_read_b128 v[60:63], v231 offset:19456
	ds_read_b128 v[116:119], v231 offset:20480
	ds_read_b128 v[120:123], v231 offset:21504
	ds_read_b128 v[124:127], v231 offset:22528
	ds_read_b128 v[128:131], v231 offset:23552
	global_load_lds_dwordx4 v[140:141], off
	v_lshl_add_u64 v[140:141], v[144:145], 0, s[74:75]
	s_add_i32 m0, s53, 0x2000
	s_add_i32 s53, s72, s38
	global_load_lds_dwordx4 v[140:141], off
	s_mov_b32 m0, s53
	v_mov_b32_e32 v139, v3
	global_load_lds_dwordx4 v2, s[16:17]
	s_add_i32 m0, s53, 0x2000
	v_lshl_add_u64 v[248:249], s[8:9], 0, v[138:139]
	v_mov_b32_e32 v133, v3
	global_load_lds_dwordx4 v134, s[16:17]
	v_lshl_add_u64 v[140:141], v[248:249], 0, s[74:75]
	s_mov_b32 m0, s58
	v_lshl_add_u64 v[250:251], s[8:9], 0, v[132:133]
	global_load_lds_dwordx4 v[140:141], off
	v_lshl_add_u64 v[140:141], v[250:251], 0, s[74:75]
	s_mov_b32 m0, s59
	s_nop 0
	global_load_lds_dwordx4 v[140:141], off
	s_waitcnt vmcnt(8)
	s_waitcnt lgkmcnt(0)
	s_barrier
	s_setprio 1
	s_waitcnt lgkmcnt(0)
	v_mfma_f32_16x16x32_f16 v[140:143], v[4:7], v[36:39], 0
	v_mfma_f32_16x16x32_f16 v[148:151], v[12:15], v[36:39], 0
	v_mfma_f32_16x16x32_f16 v[152:155], v[4:7], v[52:55], 0
	v_mfma_f32_16x16x32_f16 v[156:159], v[12:15], v[52:55], 0
	v_mfma_f32_16x16x32_f16 v[160:163], v[4:7], v[116:119], 0
	v_mfma_f32_16x16x32_f16 v[164:167], v[12:15], v[116:119], 0
	v_mfma_f32_16x16x32_f16 v[4:7], v[4:7], v[124:127], 0
	v_mfma_f32_16x16x32_f16 v[12:15], v[12:15], v[124:127], 0
	s_setprio 0
	s_setprio 1
	v_mfma_f32_16x16x32_f16 v[140:143], v[8:11], v[44:47], v[140:143]
	v_mfma_f32_16x16x32_f16 v[148:151], v[16:19], v[44:47], v[148:151]
	v_mfma_f32_16x16x32_f16 v[152:155], v[8:11], v[60:63], v[152:155]
	v_mfma_f32_16x16x32_f16 v[156:159], v[16:19], v[60:63], v[156:159]
	v_mfma_f32_16x16x32_f16 v[160:163], v[8:11], v[120:123], v[160:163]
	v_mfma_f32_16x16x32_f16 v[164:167], v[16:19], v[120:123], v[164:167]
	v_mfma_f32_16x16x32_f16 v[168:171], v[8:11], v[128:131], v[4:7]
	v_mfma_f32_16x16x32_f16 v[172:175], v[16:19], v[128:131], v[12:15]
	s_setprio 0
	s_setprio 1
	v_mfma_f32_16x16x32_f16 v[4:7], v[20:23], v[36:39], 0
	v_mfma_f32_16x16x32_f16 v[8:11], v[28:31], v[36:39], 0
	v_mfma_f32_16x16x32_f16 v[12:15], v[20:23], v[52:55], 0
	v_mfma_f32_16x16x32_f16 v[16:19], v[28:31], v[52:55], 0
	v_mfma_f32_16x16x32_f16 v[36:39], v[20:23], v[116:119], 0
	v_mfma_f32_16x16x32_f16 v[52:55], v[28:31], v[116:119], 0
	v_mfma_f32_16x16x32_f16 v[20:23], v[20:23], v[124:127], 0
	v_mfma_f32_16x16x32_f16 v[28:31], v[28:31], v[124:127], 0
	s_setprio 0
	s_setprio 1
	v_mfma_f32_16x16x32_f16 v[116:119], v[24:27], v[44:47], v[4:7]
	v_mfma_f32_16x16x32_f16 v[124:127], v[32:35], v[44:47], v[8:11]
	v_mfma_f32_16x16x32_f16 v[184:187], v[24:27], v[120:123], v[36:39]
	v_mfma_f32_16x16x32_f16 v[120:123], v[32:35], v[120:123], v[52:55]
	v_mfma_f32_16x16x32_f16 v[188:191], v[24:27], v[128:131], v[20:23]
	v_mfma_f32_16x16x32_f16 v[128:131], v[32:35], v[128:131], v[28:31]
	s_setprio 2
	s_barrier
	v_mfma_f32_16x16x32_f16 v[176:179], v[24:27], v[60:63], v[12:15]
	v_mfma_f32_16x16x32_f16 v[180:183], v[32:35], v[60:63], v[16:19]
	s_setprio 0
	s_add_i32 s53, 0, 0x18000
	v_add_u32_e32 v4, s53, v147
	s_add_i32 s72, 0, 0x1c000
	ds_read_b128 v[192:195], v4
	ds_read_b128 v[196:199], v4 offset:1024
	ds_read_b128 v[200:203], v4 offset:2048
	ds_read_b128 v[204:207], v4 offset:3072
	v_add_u32_e32 v4, s72, v147
	ds_read_b128 v[208:211], v4
	ds_read_b128 v[212:215], v4 offset:1024
	ds_read_b128 v[216:219], v4 offset:2048
	ds_read_b128 v[220:223], v4 offset:3072
	s_mov_b32 m0, s60
	ds_read_b128 v[44:47], v231 offset:32768
	ds_read_b128 v[52:55], v231 offset:33792
	ds_read_b128 v[60:63], v231 offset:34816
	ds_read_b128 v[224:227], v231 offset:35840
	ds_read_b128 v[232:235], v231 offset:36864
	ds_read_b128 v[236:239], v231 offset:37888
	ds_read_b128 v[240:243], v231 offset:38912
	ds_read_b128 v[244:247], v231 offset:39936
	global_load_lds_dwordx4 v138, s[26:27]
	s_mov_b32 m0, s61
	s_nop 0
	global_load_lds_dwordx4 v132, s[26:27]
	s_waitcnt vmcnt(8)
	s_waitcnt lgkmcnt(0)
	s_barrier
	s_setprio 1
	s_waitcnt lgkmcnt(0)
	v_mfma_f32_16x16x32_f16 v[4:7], v[192:195], v[44:47], v[68:71]
	v_mfma_f32_16x16x32_f16 v[8:11], v[200:203], v[44:47], v[72:75]
	v_mfma_f32_16x16x32_f16 v[12:15], v[192:195], v[60:63], v[76:79]
	v_mfma_f32_16x16x32_f16 v[16:19], v[200:203], v[60:63], v[80:83]
	v_mfma_f32_16x16x32_f16 v[20:23], v[192:195], v[232:235], v[84:87]
	v_mfma_f32_16x16x32_f16 v[24:27], v[200:203], v[232:235], v[88:91]
	v_mfma_f32_16x16x32_f16 v[28:31], v[192:195], v[240:243], v[92:95]
	v_mfma_f32_16x16x32_f16 v[32:35], v[200:203], v[240:243], v[96:99]
	s_setprio 0
	s_setprio 1
	v_mfma_f32_16x16x32_f16 v[4:7], v[196:199], v[52:55], v[4:7]
	v_mfma_f32_16x16x32_f16 v[8:11], v[204:207], v[52:55], v[8:11]
	v_mfma_f32_16x16x32_f16 v[12:15], v[196:199], v[224:227], v[12:15]
	v_mfma_f32_16x16x32_f16 v[16:19], v[204:207], v[224:227], v[16:19]
	v_mfma_f32_16x16x32_f16 v[20:23], v[196:199], v[236:239], v[20:23]
	v_mfma_f32_16x16x32_f16 v[24:27], v[204:207], v[236:239], v[24:27]
	v_mfma_f32_16x16x32_f16 v[28:31], v[196:199], v[244:247], v[28:31]
	v_mfma_f32_16x16x32_f16 v[32:35], v[204:207], v[244:247], v[32:35]
	s_setprio 0
	s_setprio 1
	v_mfma_f32_16x16x32_f16 v[36:39], v[208:211], v[44:47], v[100:103]
	v_mfma_f32_16x16x32_f16 v[40:43], v[216:219], v[44:47], v[40:43]
	v_mfma_f32_16x16x32_f16 v[36:39], v[212:215], v[52:55], v[36:39]
	v_mfma_f32_16x16x32_f16 v[40:43], v[220:223], v[52:55], v[40:43]
	v_mfma_f32_16x16x32_f16 v[44:47], v[208:211], v[60:63], v[104:107]
	v_mfma_f32_16x16x32_f16 v[48:51], v[216:219], v[60:63], v[48:51]
	v_mfma_f32_16x16x32_f16 v[52:55], v[208:211], v[232:235], v[108:111]
	v_mfma_f32_16x16x32_f16 v[56:59], v[216:219], v[232:235], v[56:59]
	s_setprio 0
	s_setprio 1
	v_mfma_f32_16x16x32_f16 v[60:63], v[208:211], v[240:243], v[112:115]
	v_mfma_f32_16x16x32_f16 v[64:67], v[216:219], v[240:243], v[64:67]
	v_mfma_f32_16x16x32_f16 v[44:47], v[212:215], v[224:227], v[44:47]
	v_mfma_f32_16x16x32_f16 v[48:51], v[220:223], v[224:227], v[48:51]
	v_mfma_f32_16x16x32_f16 v[52:55], v[212:215], v[236:239], v[52:55]
	v_mfma_f32_16x16x32_f16 v[56:59], v[220:223], v[236:239], v[56:59]
	s_setprio 2
	s_barrier
	v_mfma_f32_16x16x32_f16 v[60:63], v[212:215], v[244:247], v[60:63]
	v_mfma_f32_16x16x32_f16 v[64:67], v[220:223], v[244:247], v[64:67]
	s_setprio 0
	s_add_i32 s53, s53, s38
	v_lshl_add_u64 v[68:69], v[136:137], 0, s[24:25]
	s_mov_b32 m0, s53
	ds_read_b128 v[104:107], v231 offset:49152
	ds_read_b128 v[108:111], v231 offset:50176
	ds_read_b128 v[112:115], v231 offset:51200
	ds_read_b128 v[224:227], v231 offset:52224
	ds_read_b128 v[232:235], v231 offset:53248
	ds_read_b128 v[236:239], v231 offset:54272
	ds_read_b128 v[240:243], v231 offset:55296
	ds_read_b128 v[244:247], v231 offset:56320
	global_load_lds_dwordx4 v[68:69], off
	v_lshl_add_u64 v[68:69], v[144:145], 0, s[24:25]
	s_add_i32 m0, s53, 0x2000
	s_add_i32 s53, s72, s38
	global_load_lds_dwordx4 v[68:69], off
	s_mov_b32 m0, s53
	v_lshl_add_u64 v[68:69], v[248:249], 0, s[24:25]
	global_load_lds_dwordx4 v2, s[28:29]
	s_add_i32 m0, s53, 0x2000
	s_nop 0
	global_load_lds_dwordx4 v134, s[28:29]
	s_mov_b32 m0, s64
	s_nop 0
	global_load_lds_dwordx4 v[68:69], off
	v_lshl_add_u64 v[68:69], v[250:251], 0, s[24:25]
	s_mov_b32 m0, s65
	s_nop 0
	global_load_lds_dwordx4 v[68:69], off
	s_waitcnt vmcnt(8)
	s_waitcnt lgkmcnt(0)
	s_barrier
	s_setprio 1
	s_waitcnt lgkmcnt(0)
	v_mfma_f32_16x16x32_f16 v[68:71], v[192:195], v[104:107], v[140:143]
	v_mfma_f32_16x16x32_f16 v[72:75], v[200:203], v[104:107], v[148:151]
	v_mfma_f32_16x16x32_f16 v[76:79], v[192:195], v[112:115], v[152:155]
	v_mfma_f32_16x16x32_f16 v[80:83], v[200:203], v[112:115], v[156:159]
	v_mfma_f32_16x16x32_f16 v[84:87], v[192:195], v[232:235], v[160:163]
	v_mfma_f32_16x16x32_f16 v[88:91], v[200:203], v[232:235], v[164:167]
	v_mfma_f32_16x16x32_f16 v[92:95], v[192:195], v[240:243], v[168:171]
	v_mfma_f32_16x16x32_f16 v[96:99], v[200:203], v[240:243], v[172:175]
	s_setprio 0
	s_setprio 1
	v_mfma_f32_16x16x32_f16 v[68:71], v[196:199], v[108:111], v[68:71]
	v_mfma_f32_16x16x32_f16 v[72:75], v[204:207], v[108:111], v[72:75]
	v_mfma_f32_16x16x32_f16 v[76:79], v[196:199], v[224:227], v[76:79]
	v_mfma_f32_16x16x32_f16 v[80:83], v[204:207], v[224:227], v[80:83]
	v_mfma_f32_16x16x32_f16 v[84:87], v[196:199], v[236:239], v[84:87]
	v_mfma_f32_16x16x32_f16 v[88:91], v[204:207], v[236:239], v[88:91]
	v_mfma_f32_16x16x32_f16 v[92:95], v[196:199], v[244:247], v[92:95]
	v_mfma_f32_16x16x32_f16 v[96:99], v[204:207], v[244:247], v[96:99]
	s_setprio 0
	s_setprio 1
	v_mfma_f32_16x16x32_f16 v[100:103], v[208:211], v[104:107], v[116:119]
	v_mfma_f32_16x16x32_f16 v[104:107], v[216:219], v[104:107], v[124:127]
	v_mfma_f32_16x16x32_f16 v[100:103], v[212:215], v[108:111], v[100:103]
	v_mfma_f32_16x16x32_f16 v[104:107], v[220:223], v[108:111], v[104:107]
	v_mfma_f32_16x16x32_f16 v[108:111], v[208:211], v[112:115], v[176:179]
	v_mfma_f32_16x16x32_f16 v[112:115], v[216:219], v[112:115], v[180:183]
	v_mfma_f32_16x16x32_f16 v[116:119], v[208:211], v[232:235], v[184:187]
	v_mfma_f32_16x16x32_f16 v[120:123], v[216:219], v[232:235], v[120:123]
	s_setprio 0
	s_setprio 1
	v_mfma_f32_16x16x32_f16 v[124:127], v[208:211], v[240:243], v[188:191]
	v_mfma_f32_16x16x32_f16 v[128:131], v[216:219], v[240:243], v[128:131]
	v_mfma_f32_16x16x32_f16 v[108:111], v[212:215], v[224:227], v[108:111]
	v_mfma_f32_16x16x32_f16 v[112:115], v[220:223], v[224:227], v[112:115]
	v_mfma_f32_16x16x32_f16 v[116:119], v[212:215], v[236:239], v[116:119]
	v_mfma_f32_16x16x32_f16 v[120:123], v[220:223], v[236:239], v[120:123]
	s_setprio 2
	s_barrier
	v_mfma_f32_16x16x32_f16 v[124:127], v[212:215], v[244:247], v[124:127]
	v_mfma_f32_16x16x32_f16 v[128:131], v[220:223], v[244:247], v[128:131]
	s_setprio 0
	s_add_i32 s41, s41, 2
	s_cmp_ge_i32 s41, s40
	s_cbranch_scc0 .LBB0_528
	v_mov_b32_e32 v136, v2
	s_branch .LBB0_531

.LBB0_532:
	s_add_u32 s6, s8, 0xfff80080
	s_addc_u32 s7, s9, -1
	s_add_i32 s29, 0, 0x10000
	s_cmp_eq_u32 s28, 28
	s_cselect_b32 s17, s13, s7
	s_cselect_b32 s16, s12, s6
	v_add_u32_e32 v133, s29, v147
	s_cselect_b32 s7, s15, s27
	s_cselect_b32 s6, s14, s26
	s_add_i32 s53, 0, 0x14000
	ds_read_b128 v[138:141], v133
	ds_read_b128 v[142:145], v133 offset:1024
	ds_read_b128 v[148:151], v133 offset:2048
	ds_read_b128 v[152:155], v133 offset:3072
	v_add_u32_e32 v133, s53, v147
	ds_read_b128 v[156:159], v133
	ds_read_b128 v[160:163], v133 offset:1024
	ds_read_b128 v[164:167], v133 offset:2048
	ds_read_b128 v[168:171], v133 offset:3072
	s_mov_b32 m0, s66
	v_add_u32_e32 v212, 0, v146
	ds_read_b128 v[172:175], v212
	ds_read_b128 v[176:179], v212 offset:1024
	ds_read_b128 v[180:183], v212 offset:2048
	ds_read_b128 v[184:187], v212 offset:3072
	ds_read_b128 v[188:191], v212 offset:4096
	ds_read_b128 v[192:195], v212 offset:5120
	ds_read_b128 v[196:199], v212 offset:6144
	ds_read_b128 v[200:203], v212 offset:7168
	global_load_lds_dwordx4 v2, s[8:9]
	s_mov_b32 m0, s67
	v_mov_b32_e32 v133, v3
	global_load_lds_dwordx4 v132, s[8:9]
	s_waitcnt vmcnt(8)
	s_waitcnt lgkmcnt(0)
	s_barrier
	s_setprio 1
	s_waitcnt lgkmcnt(0)
	v_mfma_f32_16x16x32_f16 v[4:7], v[138:141], v[172:175], v[4:7]
	v_mfma_f32_16x16x32_f16 v[4:7], v[142:145], v[176:179], v[4:7]
	v_mfma_f32_16x16x32_f16 v[8:11], v[152:155], v[176:179], v[8:11]
	v_mfma_f32_16x16x32_f16 v[8:11], v[148:151], v[172:175], v[8:11]
	v_mfma_f32_16x16x32_f16 v[16:19], v[148:151], v[180:183], v[16:19]
	v_mfma_f32_16x16x32_f16 v[16:19], v[152:155], v[184:187], v[16:19]
	v_mfma_f32_16x16x32_f16 v[12:15], v[142:145], v[184:187], v[12:15]
	v_mfma_f32_16x16x32_f16 v[12:15], v[138:141], v[180:183], v[12:15]
	s_setprio 0
	s_setprio 1
	v_mfma_f32_16x16x32_f16 v[20:23], v[138:141], v[188:191], v[20:23]
	v_mfma_f32_16x16x32_f16 v[20:23], v[142:145], v[192:195], v[20:23]
	v_mfma_f32_16x16x32_f16 v[24:27], v[152:155], v[192:195], v[24:27]
	v_mfma_f32_16x16x32_f16 v[24:27], v[148:151], v[188:191], v[24:27]
	v_mfma_f32_16x16x32_f16 v[32:35], v[148:151], v[196:199], v[32:35]
	v_mfma_f32_16x16x32_f16 v[32:35], v[152:155], v[200:203], v[32:35]
	v_mfma_f32_16x16x32_f16 v[28:31], v[142:145], v[200:203], v[28:31]
	v_mfma_f32_16x16x32_f16 v[28:31], v[138:141], v[196:199], v[28:31]
	s_setprio 0
	s_setprio 1
	v_mfma_f32_16x16x32_f16 v[36:39], v[156:159], v[172:175], v[36:39]
	v_mfma_f32_16x16x32_f16 v[36:39], v[160:163], v[176:179], v[36:39]
	v_mfma_f32_16x16x32_f16 v[40:43], v[168:171], v[176:179], v[40:43]
	v_mfma_f32_16x16x32_f16 v[40:43], v[164:167], v[172:175], v[40:43]
	v_mfma_f32_16x16x32_f16 v[48:51], v[164:167], v[180:183], v[48:51]
	v_mfma_f32_16x16x32_f16 v[48:51], v[168:171], v[184:187], v[48:51]
	v_mfma_f32_16x16x32_f16 v[44:47], v[160:163], v[184:187], v[44:47]
	v_mfma_f32_16x16x32_f16 v[44:47], v[156:159], v[180:183], v[44:47]
	s_setprio 0
	s_setprio 1
	v_mfma_f32_16x16x32_f16 v[52:55], v[156:159], v[188:191], v[52:55]
	v_mfma_f32_16x16x32_f16 v[52:55], v[160:163], v[192:195], v[52:55]
	v_mfma_f32_16x16x32_f16 v[56:59], v[168:171], v[192:195], v[56:59]
	v_mfma_f32_16x16x32_f16 v[56:59], v[164:167], v[188:191], v[56:59]
	v_mfma_f32_16x16x32_f16 v[64:67], v[164:167], v[196:199], v[64:67]
	v_mfma_f32_16x16x32_f16 v[64:67], v[168:171], v[200:203], v[64:67]
	s_setprio 2
	s_barrier
	v_mfma_f32_16x16x32_f16 v[60:63], v[160:163], v[200:203], v[60:63]
	v_mfma_f32_16x16x32_f16 v[60:63], v[156:159], v[196:199], v[60:63]
	s_setprio 0
	s_add_i32 s29, s29, s38
	s_mov_b32 m0, s29
	ds_read_b128 v[172:175], v212 offset:16384
	ds_read_b128 v[176:179], v212 offset:17408
	ds_read_b128 v[180:183], v212 offset:18432
	ds_read_b128 v[184:187], v212 offset:19456
	ds_read_b128 v[188:191], v212 offset:20480
	ds_read_b128 v[192:195], v212 offset:21504
	ds_read_b128 v[196:199], v212 offset:22528
	ds_read_b128 v[200:203], v212 offset:23552
	global_load_lds_dwordx4 v136, s[6:7]
	s_add_i32 m0, s29, 0x2000
	s_add_u32 s40, s6, 0x80000
	s_addc_u32 s41, s7, 0
	s_add_i32 s29, s53, s38
	global_load_lds_dwordx4 v134, s[6:7]
	s_mov_b32 m0, s29
	v_mov_b32_e32 v137, v3
	global_load_lds_dwordx4 v136, s[40:41]
	s_add_i32 m0, s29, 0x2000
	v_mov_b32_e32 v135, v3
	global_load_lds_dwordx4 v134, s[40:41]
	s_mov_b32 m0, s58
	v_lshl_add_u64 v[204:205], s[6:7], 0, v[136:137]
	global_load_lds_dwordx4 v2, s[16:17]
	s_mov_b32 m0, s59
	v_lshl_add_u64 v[206:207], s[6:7], 0, v[134:135]
	global_load_lds_dwordx4 v132, s[16:17]
	s_waitcnt vmcnt(8)
	s_waitcnt lgkmcnt(0)
	v_lshl_add_u64 v[208:209], s[16:17], 0, v[2:3]
	v_lshl_add_u64 v[210:211], s[16:17], 0, v[132:133]
	s_barrier
	s_setprio 1
	s_waitcnt lgkmcnt(0)
	v_mfma_f32_16x16x32_f16 v[68:71], v[138:141], v[172:175], v[68:71]
	v_mfma_f32_16x16x32_f16 v[68:71], v[142:145], v[176:179], v[68:71]
	v_mfma_f32_16x16x32_f16 v[72:75], v[152:155], v[176:179], v[72:75]
	v_mfma_f32_16x16x32_f16 v[72:75], v[148:151], v[172:175], v[72:75]
	v_mfma_f32_16x16x32_f16 v[80:83], v[148:151], v[180:183], v[80:83]
	v_mfma_f32_16x16x32_f16 v[80:83], v[152:155], v[184:187], v[80:83]
	v_mfma_f32_16x16x32_f16 v[76:79], v[142:145], v[184:187], v[76:79]
	v_mfma_f32_16x16x32_f16 v[76:79], v[138:141], v[180:183], v[76:79]
	s_setprio 0
	s_setprio 1
	v_mfma_f32_16x16x32_f16 v[84:87], v[138:141], v[188:191], v[84:87]
	v_mfma_f32_16x16x32_f16 v[84:87], v[142:145], v[192:195], v[84:87]
	v_mfma_f32_16x16x32_f16 v[88:91], v[152:155], v[192:195], v[88:91]
	v_mfma_f32_16x16x32_f16 v[88:91], v[148:151], v[188:191], v[88:91]
	v_mfma_f32_16x16x32_f16 v[96:99], v[148:151], v[196:199], v[96:99]
	v_mfma_f32_16x16x32_f16 v[96:99], v[152:155], v[200:203], v[96:99]
	v_mfma_f32_16x16x32_f16 v[92:95], v[142:145], v[200:203], v[92:95]
	v_mfma_f32_16x16x32_f16 v[92:95], v[138:141], v[196:199], v[92:95]
	s_setprio 0
	s_setprio 1
	v_mfma_f32_16x16x32_f16 v[100:103], v[156:159], v[172:175], v[100:103]
	v_mfma_f32_16x16x32_f16 v[100:103], v[160:163], v[176:179], v[100:103]
	v_mfma_f32_16x16x32_f16 v[104:107], v[168:171], v[176:179], v[104:107]
	v_mfma_f32_16x16x32_f16 v[104:107], v[164:167], v[172:175], v[104:107]
	v_mfma_f32_16x16x32_f16 v[112:115], v[164:167], v[180:183], v[112:115]
	v_mfma_f32_16x16x32_f16 v[112:115], v[168:171], v[184:187], v[112:115]
	v_mfma_f32_16x16x32_f16 v[108:111], v[160:163], v[184:187], v[108:111]
	v_mfma_f32_16x16x32_f16 v[108:111], v[156:159], v[180:183], v[108:111]
	s_setprio 0
	s_setprio 1
	v_mfma_f32_16x16x32_f16 v[116:119], v[156:159], v[188:191], v[116:119]
	v_mfma_f32_16x16x32_f16 v[116:119], v[160:163], v[192:195], v[116:119]
	v_mfma_f32_16x16x32_f16 v[120:123], v[168:171], v[192:195], v[120:123]
	v_mfma_f32_16x16x32_f16 v[120:123], v[164:167], v[188:191], v[120:123]
	v_mfma_f32_16x16x32_f16 v[128:131], v[164:167], v[196:199], v[128:131]
	v_mfma_f32_16x16x32_f16 v[128:131], v[168:171], v[200:203], v[128:131]
	s_setprio 2
	s_barrier
	v_mfma_f32_16x16x32_f16 v[124:127], v[160:163], v[200:203], v[124:127]
	v_mfma_f32_16x16x32_f16 v[124:127], v[156:159], v[196:199], v[124:127]
	s_setprio 0
	s_add_i32 s29, 0, 0x18000
	v_add_u32_e32 v135, s29, v147
	s_add_i32 s40, 0, 0x1c000
	ds_read_b128 v[138:141], v135
	ds_read_b128 v[142:145], v135 offset:1024
	ds_read_b128 v[148:151], v135 offset:2048
	ds_read_b128 v[152:155], v135 offset:3072
	v_add_u32_e32 v135, s40, v147
	ds_read_b128 v[156:159], v135
	ds_read_b128 v[160:163], v135 offset:1024
	ds_read_b128 v[164:167], v135 offset:2048
	ds_read_b128 v[168:171], v135 offset:3072
	s_add_u32 s16, s16, 0x80000
	s_addc_u32 s17, s17, 0
	s_mov_b32 m0, s60
	ds_read_b128 v[172:175], v212 offset:32768
	ds_read_b128 v[176:179], v212 offset:33792
	ds_read_b128 v[180:183], v212 offset:34816
	ds_read_b128 v[184:187], v212 offset:35840
	ds_read_b128 v[188:191], v212 offset:36864
	ds_read_b128 v[192:195], v212 offset:37888
	ds_read_b128 v[196:199], v212 offset:38912
	ds_read_b128 v[200:203], v212 offset:39936
	global_load_lds_dwordx4 v2, s[16:17]
	s_mov_b32 m0, s61
	s_nop 0
	global_load_lds_dwordx4 v132, s[16:17]
	s_waitcnt vmcnt(8)
	s_waitcnt lgkmcnt(0)
	s_barrier
	s_setprio 1
	s_waitcnt lgkmcnt(0)
	v_mfma_f32_16x16x32_f16 v[4:7], v[138:141], v[172:175], v[4:7]
	v_mfma_f32_16x16x32_f16 v[4:7], v[142:145], v[176:179], v[4:7]
	v_mfma_f32_16x16x32_f16 v[8:11], v[152:155], v[176:179], v[8:11]
	v_mfma_f32_16x16x32_f16 v[8:11], v[148:151], v[172:175], v[8:11]
	v_mfma_f32_16x16x32_f16 v[16:19], v[148:151], v[180:183], v[16:19]
	v_mfma_f32_16x16x32_f16 v[16:19], v[152:155], v[184:187], v[16:19]
	v_mfma_f32_16x16x32_f16 v[12:15], v[142:145], v[184:187], v[12:15]
	v_mfma_f32_16x16x32_f16 v[12:15], v[138:141], v[180:183], v[12:15]
	s_setprio 0
	s_setprio 1
	v_mfma_f32_16x16x32_f16 v[20:23], v[138:141], v[188:191], v[20:23]
	v_mfma_f32_16x16x32_f16 v[20:23], v[142:145], v[192:195], v[20:23]
	v_mfma_f32_16x16x32_f16 v[24:27], v[152:155], v[192:195], v[24:27]
	v_mfma_f32_16x16x32_f16 v[24:27], v[148:151], v[188:191], v[24:27]
	v_mfma_f32_16x16x32_f16 v[32:35], v[148:151], v[196:199], v[32:35]
	v_mfma_f32_16x16x32_f16 v[32:35], v[152:155], v[200:203], v[32:35]
	v_mfma_f32_16x16x32_f16 v[28:31], v[142:145], v[200:203], v[28:31]
	v_mfma_f32_16x16x32_f16 v[28:31], v[138:141], v[196:199], v[28:31]
	s_setprio 0
	s_setprio 1
	v_mfma_f32_16x16x32_f16 v[36:39], v[156:159], v[172:175], v[36:39]
	v_mfma_f32_16x16x32_f16 v[36:39], v[160:163], v[176:179], v[36:39]
	v_mfma_f32_16x16x32_f16 v[40:43], v[168:171], v[176:179], v[40:43]
	v_mfma_f32_16x16x32_f16 v[40:43], v[164:167], v[172:175], v[40:43]
	v_mfma_f32_16x16x32_f16 v[48:51], v[164:167], v[180:183], v[48:51]
	v_mfma_f32_16x16x32_f16 v[48:51], v[168:171], v[184:187], v[48:51]
	v_mfma_f32_16x16x32_f16 v[44:47], v[160:163], v[184:187], v[44:47]
	v_mfma_f32_16x16x32_f16 v[44:47], v[156:159], v[180:183], v[44:47]
	s_setprio 0
	s_setprio 1
	v_mfma_f32_16x16x32_f16 v[52:55], v[156:159], v[188:191], v[52:55]
	v_mfma_f32_16x16x32_f16 v[52:55], v[160:163], v[192:195], v[52:55]
	v_mfma_f32_16x16x32_f16 v[56:59], v[168:171], v[192:195], v[56:59]
	v_mfma_f32_16x16x32_f16 v[56:59], v[164:167], v[188:191], v[56:59]
	v_mfma_f32_16x16x32_f16 v[64:67], v[164:167], v[196:199], v[64:67]
	v_mfma_f32_16x16x32_f16 v[64:67], v[168:171], v[200:203], v[64:67]
	s_setprio 2
	s_barrier
	v_mfma_f32_16x16x32_f16 v[60:63], v[160:163], v[200:203], v[60:63]
	v_mfma_f32_16x16x32_f16 v[60:63], v[156:159], v[196:199], v[60:63]
	s_setprio 0
	s_add_i32 s16, s29, s38
	v_lshl_add_u64 v[204:205], v[204:205], 0, s[86:87]
	s_mov_b32 m0, s16
	ds_read_b128 v[172:175], v212 offset:49152
	ds_read_b128 v[176:179], v212 offset:50176
	ds_read_b128 v[180:183], v212 offset:51200
	ds_read_b128 v[184:187], v212 offset:52224
	ds_read_b128 v[188:191], v212 offset:53248
	ds_read_b128 v[192:195], v212 offset:54272
	ds_read_b128 v[196:199], v212 offset:55296
	ds_read_b128 v[200:203], v212 offset:56320
	global_load_lds_dwordx4 v[204:205], off
	s_add_i32 m0, s16, 0x2000
	s_add_u32 s6, s6, 0x80080
	v_lshl_add_u64 v[204:205], v[206:207], 0, s[86:87]
	s_addc_u32 s7, s7, 0
	s_add_i32 s16, s40, s38
	global_load_lds_dwordx4 v[204:205], off
	s_mov_b32 m0, s16
	v_lshl_add_u64 v[204:205], v[208:209], 0, s[86:87]
	global_load_lds_dwordx4 v136, s[6:7]
	s_add_i32 m0, s16, 0x2000
	s_nop 0
	global_load_lds_dwordx4 v134, s[6:7]
	s_mov_b32 m0, s64
	s_nop 0
	global_load_lds_dwordx4 v[204:205], off
	v_lshl_add_u64 v[204:205], v[210:211], 0, s[86:87]
	s_mov_b32 m0, s65
	s_nop 0
	global_load_lds_dwordx4 v[204:205], off
	s_waitcnt vmcnt(8)
	s_waitcnt lgkmcnt(0)
	s_barrier
	s_setprio 1
	s_waitcnt lgkmcnt(0)
	v_mfma_f32_16x16x32_f16 v[68:71], v[138:141], v[172:175], v[68:71]
	v_mfma_f32_16x16x32_f16 v[68:71], v[142:145], v[176:179], v[68:71]
	v_mfma_f32_16x16x32_f16 v[72:75], v[152:155], v[176:179], v[72:75]
	v_mfma_f32_16x16x32_f16 v[72:75], v[148:151], v[172:175], v[72:75]
	v_mfma_f32_16x16x32_f16 v[80:83], v[148:151], v[180:183], v[80:83]
	v_mfma_f32_16x16x32_f16 v[80:83], v[152:155], v[184:187], v[80:83]
	v_mfma_f32_16x16x32_f16 v[76:79], v[142:145], v[184:187], v[76:79]
	v_mfma_f32_16x16x32_f16 v[76:79], v[138:141], v[180:183], v[76:79]
	s_setprio 0
	s_setprio 1
	v_mfma_f32_16x16x32_f16 v[84:87], v[138:141], v[188:191], v[84:87]
	v_mfma_f32_16x16x32_f16 v[84:87], v[142:145], v[192:195], v[84:87]
	v_mfma_f32_16x16x32_f16 v[88:91], v[152:155], v[192:195], v[88:91]
	v_mfma_f32_16x16x32_f16 v[88:91], v[148:151], v[188:191], v[88:91]
	v_mfma_f32_16x16x32_f16 v[96:99], v[148:151], v[196:199], v[96:99]
	v_mfma_f32_16x16x32_f16 v[96:99], v[152:155], v[200:203], v[96:99]
	v_mfma_f32_16x16x32_f16 v[92:95], v[142:145], v[200:203], v[92:95]
	v_mfma_f32_16x16x32_f16 v[92:95], v[138:141], v[196:199], v[92:95]
	s_setprio 0
	s_setprio 1
	v_mfma_f32_16x16x32_f16 v[100:103], v[156:159], v[172:175], v[100:103]
	v_mfma_f32_16x16x32_f16 v[100:103], v[160:163], v[176:179], v[100:103]
	v_mfma_f32_16x16x32_f16 v[104:107], v[168:171], v[176:179], v[104:107]
	v_mfma_f32_16x16x32_f16 v[104:107], v[164:167], v[172:175], v[104:107]
	v_mfma_f32_16x16x32_f16 v[112:115], v[164:167], v[180:183], v[112:115]
	v_mfma_f32_16x16x32_f16 v[112:115], v[168:171], v[184:187], v[112:115]
	v_mfma_f32_16x16x32_f16 v[108:111], v[160:163], v[184:187], v[108:111]
	v_mfma_f32_16x16x32_f16 v[108:111], v[156:159], v[180:183], v[108:111]
	s_setprio 0
	s_setprio 1
	v_mfma_f32_16x16x32_f16 v[116:119], v[156:159], v[188:191], v[116:119]
	v_mfma_f32_16x16x32_f16 v[116:119], v[160:163], v[192:195], v[116:119]
	v_mfma_f32_16x16x32_f16 v[120:123], v[168:171], v[192:195], v[120:123]
	v_mfma_f32_16x16x32_f16 v[120:123], v[164:167], v[188:191], v[120:123]
	v_mfma_f32_16x16x32_f16 v[128:131], v[164:167], v[196:199], v[128:131]
	v_mfma_f32_16x16x32_f16 v[128:131], v[168:171], v[200:203], v[128:131]
	s_setprio 2
	s_barrier
	v_mfma_f32_16x16x32_f16 v[124:127], v[160:163], v[200:203], v[124:127]
	v_mfma_f32_16x16x32_f16 v[124:127], v[156:159], v[196:199], v[124:127]
	s_setprio 0
	s_add_i32 s28, s28, 2
	s_add_u32 s8, s8, 0x100
	s_addc_u32 s9, s9, 0
	s_add_u32 s26, s26, 0x100
	s_addc_u32 s27, s27, 0
	s_cmp_gt_u32 s28, 29
	s_cbranch_scc0 .LBB0_532
	s_and_b64 vcc, exec, s[50:51]
	s_cbranch_vccz .LBB0_535
	s_barrier

.LBB0_641:
	s_add_i32 s43, 0, 0x10000
	s_add_i32 s71, 0, 0x14000
	v_add_u32_e32 v16, s43, v232
	v_add_u32_e32 v32, s71, v232
	ds_read_b128 v[4:7], v16
	ds_read_b128 v[8:11], v16 offset:1024
	ds_read_b128 v[12:15], v16 offset:2048
	ds_read_b128 v[16:19], v16 offset:3072
	ds_read_b128 v[20:23], v32
	ds_read_b128 v[24:27], v32 offset:1024
	ds_read_b128 v[28:31], v32 offset:2048
	ds_read_b128 v[32:35], v32 offset:3072
	v_add_u32_e32 v233, 0, v231
	ds_read_b128 v[36:39], v233
	ds_read_b128 v[40:43], v233 offset:1024
	ds_read_b128 v[44:47], v233 offset:2048
	ds_read_b128 v[48:51], v233 offset:3072
	ds_read_b128 v[52:55], v233 offset:4096
	ds_read_b128 v[56:59], v233 offset:5120
	ds_read_b128 v[60:63], v233 offset:6144
	ds_read_b128 v[64:67], v233 offset:7168
	s_waitcnt vmcnt(8)
	s_waitcnt lgkmcnt(0)
	s_barrier
	s_setprio 1
	s_waitcnt lgkmcnt(0)
	v_mfma_f32_16x16x32_bf16 v[68:71], v[4:7], v[36:39], 0
	v_mfma_f32_16x16x32_bf16 v[68:71], v[8:11], v[40:43], v[68:71]
	v_mfma_f32_16x16x32_bf16 v[72:75], v[12:15], v[36:39], 0
	v_mfma_f32_16x16x32_bf16 v[72:75], v[16:19], v[40:43], v[72:75]
	v_mfma_f32_16x16x32_bf16 v[80:83], v[12:15], v[44:47], 0
	v_mfma_f32_16x16x32_bf16 v[80:83], v[16:19], v[48:51], v[80:83]
	v_mfma_f32_16x16x32_bf16 v[76:79], v[4:7], v[44:47], 0
	v_mfma_f32_16x16x32_bf16 v[76:79], v[8:11], v[48:51], v[76:79]
	s_setprio 0
	s_setprio 1
	v_mfma_f32_16x16x32_bf16 v[84:87], v[4:7], v[52:55], 0
	v_mfma_f32_16x16x32_bf16 v[84:87], v[8:11], v[56:59], v[84:87]
	v_mfma_f32_16x16x32_bf16 v[88:91], v[12:15], v[52:55], 0
	v_mfma_f32_16x16x32_bf16 v[88:91], v[16:19], v[56:59], v[88:91]
	v_mfma_f32_16x16x32_bf16 v[96:99], v[12:15], v[60:63], 0
	v_mfma_f32_16x16x32_bf16 v[96:99], v[16:19], v[64:67], v[96:99]
	v_mfma_f32_16x16x32_bf16 v[92:95], v[4:7], v[60:63], 0
	v_mfma_f32_16x16x32_bf16 v[92:95], v[8:11], v[64:67], v[92:95]
	s_setprio 0
	s_setprio 1
	v_mfma_f32_16x16x32_bf16 v[100:103], v[20:23], v[36:39], 0
	v_mfma_f32_16x16x32_bf16 v[36:39], v[28:31], v[36:39], 0
	v_mfma_f32_16x16x32_bf16 v[104:107], v[20:23], v[44:47], 0
	v_mfma_f32_16x16x32_bf16 v[44:47], v[28:31], v[44:47], 0
	v_mfma_f32_16x16x32_bf16 v[108:111], v[20:23], v[52:55], 0
	v_mfma_f32_16x16x32_bf16 v[52:55], v[28:31], v[52:55], 0
	v_mfma_f32_16x16x32_bf16 v[112:115], v[20:23], v[60:63], 0
	v_mfma_f32_16x16x32_bf16 v[60:63], v[28:31], v[60:63], 0
	s_setprio 0
	s_setprio 1
	v_mfma_f32_16x16x32_bf16 v[100:103], v[24:27], v[40:43], v[100:103]
	v_mfma_f32_16x16x32_bf16 v[40:43], v[32:35], v[40:43], v[36:39]
	v_mfma_f32_16x16x32_bf16 v[104:107], v[24:27], v[48:51], v[104:107]
	v_mfma_f32_16x16x32_bf16 v[48:51], v[32:35], v[48:51], v[44:47]
	v_mfma_f32_16x16x32_bf16 v[108:111], v[24:27], v[56:59], v[108:111]
	v_mfma_f32_16x16x32_bf16 v[56:59], v[32:35], v[56:59], v[52:55]
	s_setprio 2
	s_barrier
	v_mfma_f32_16x16x32_bf16 v[112:115], v[24:27], v[64:67], v[112:115]
	v_mfma_f32_16x16x32_bf16 v[64:67], v[32:35], v[64:67], v[60:63]
	s_setprio 0
	v_lshl_add_u64 v[186:187], s[8:9], 0, v[2:3]
	s_add_i32 s43, s43, s54
	v_mov_b32_e32 v191, v3
	v_lshl_add_u64 v[134:135], v[186:187], 0, s[80:81]
	s_mov_b32 m0, s43
	v_lshl_add_u64 v[246:247], s[8:9], 0, v[190:191]
	ds_read_b128 v[36:39], v233 offset:16384
	ds_read_b128 v[44:47], v233 offset:17408
	ds_read_b128 v[52:55], v233 offset:18432
	ds_read_b128 v[60:63], v233 offset:19456
	ds_read_b128 v[116:119], v233 offset:20480
	ds_read_b128 v[120:123], v233 offset:21504
	ds_read_b128 v[124:127], v233 offset:22528
	ds_read_b128 v[128:131], v233 offset:23552
	global_load_lds_dwordx4 v[134:135], off
	v_lshl_add_u64 v[134:135], v[246:247], 0, s[80:81]
	s_add_i32 m0, s43, 0x2000
	s_add_i32 s43, s71, s54
	global_load_lds_dwordx4 v[134:135], off
	s_mov_b32 m0, s43
	v_mov_b32_e32 v133, v3
	global_load_lds_dwordx4 v2, s[16:17]
	s_add_i32 m0, s43, 0x2000
	v_lshl_add_u64 v[248:249], s[6:7], 0, v[132:133]
	v_mov_b32_e32 v189, v3
	global_load_lds_dwordx4 v190, s[16:17]
	v_lshl_add_u64 v[134:135], v[248:249], 0, s[80:81]
	s_mov_b32 m0, s55
	v_lshl_add_u64 v[250:251], s[6:7], 0, v[188:189]
	global_load_lds_dwordx4 v[134:135], off
	v_lshl_add_u64 v[134:135], v[250:251], 0, s[80:81]
	s_mov_b32 m0, s56
	s_nop 0
	global_load_lds_dwordx4 v[134:135], off
	s_waitcnt vmcnt(8)
	s_waitcnt lgkmcnt(0)
	s_barrier
	s_setprio 1
	s_waitcnt lgkmcnt(0)
	v_mfma_f32_16x16x32_bf16 v[134:137], v[4:7], v[36:39], 0
	v_mfma_f32_16x16x32_bf16 v[138:141], v[12:15], v[36:39], 0
	v_mfma_f32_16x16x32_bf16 v[142:145], v[4:7], v[52:55], 0
	v_mfma_f32_16x16x32_bf16 v[146:149], v[12:15], v[52:55], 0
	v_mfma_f32_16x16x32_bf16 v[150:153], v[4:7], v[116:119], 0
	v_mfma_f32_16x16x32_bf16 v[154:157], v[12:15], v[116:119], 0
	v_mfma_f32_16x16x32_bf16 v[4:7], v[4:7], v[124:127], 0
	v_mfma_f32_16x16x32_bf16 v[12:15], v[12:15], v[124:127], 0
	s_setprio 0
	s_setprio 1
	v_mfma_f32_16x16x32_bf16 v[134:137], v[8:11], v[44:47], v[134:137]
	v_mfma_f32_16x16x32_bf16 v[138:141], v[16:19], v[44:47], v[138:141]
	v_mfma_f32_16x16x32_bf16 v[142:145], v[8:11], v[60:63], v[142:145]
	v_mfma_f32_16x16x32_bf16 v[146:149], v[16:19], v[60:63], v[146:149]
	v_mfma_f32_16x16x32_bf16 v[150:153], v[8:11], v[120:123], v[150:153]
	v_mfma_f32_16x16x32_bf16 v[154:157], v[16:19], v[120:123], v[154:157]
	v_mfma_f32_16x16x32_bf16 v[158:161], v[8:11], v[128:131], v[4:7]
	v_mfma_f32_16x16x32_bf16 v[162:165], v[16:19], v[128:131], v[12:15]
	s_setprio 0
	s_setprio 1
	v_mfma_f32_16x16x32_bf16 v[4:7], v[20:23], v[36:39], 0
	v_mfma_f32_16x16x32_bf16 v[8:11], v[28:31], v[36:39], 0
	v_mfma_f32_16x16x32_bf16 v[12:15], v[20:23], v[52:55], 0
	v_mfma_f32_16x16x32_bf16 v[16:19], v[28:31], v[52:55], 0
	v_mfma_f32_16x16x32_bf16 v[36:39], v[20:23], v[116:119], 0
	v_mfma_f32_16x16x32_bf16 v[52:55], v[28:31], v[116:119], 0
	v_mfma_f32_16x16x32_bf16 v[20:23], v[20:23], v[124:127], 0
	v_mfma_f32_16x16x32_bf16 v[28:31], v[28:31], v[124:127], 0
	s_setprio 0
	s_setprio 1
	v_mfma_f32_16x16x32_bf16 v[116:119], v[24:27], v[44:47], v[4:7]
	v_mfma_f32_16x16x32_bf16 v[124:127], v[32:35], v[44:47], v[8:11]
	v_mfma_f32_16x16x32_bf16 v[174:177], v[24:27], v[120:123], v[36:39]
	v_mfma_f32_16x16x32_bf16 v[120:123], v[32:35], v[120:123], v[52:55]
	v_mfma_f32_16x16x32_bf16 v[178:181], v[24:27], v[128:131], v[20:23]
	v_mfma_f32_16x16x32_bf16 v[128:131], v[32:35], v[128:131], v[28:31]
	s_setprio 2
	s_barrier
	v_mfma_f32_16x16x32_bf16 v[166:169], v[24:27], v[60:63], v[12:15]
	v_mfma_f32_16x16x32_bf16 v[170:173], v[32:35], v[60:63], v[16:19]
	s_setprio 0
	s_add_i32 s43, 0, 0x18000
	v_add_u32_e32 v4, s43, v232
	s_add_i32 s71, 0, 0x1c000
	ds_read_b128 v[182:185], v4
	ds_read_b128 v[192:195], v4 offset:1024
	ds_read_b128 v[196:199], v4 offset:2048
	ds_read_b128 v[200:203], v4 offset:3072
	v_add_u32_e32 v4, s71, v232
	ds_read_b128 v[204:207], v4
	ds_read_b128 v[208:211], v4 offset:1024
	ds_read_b128 v[212:215], v4 offset:2048
	ds_read_b128 v[216:219], v4 offset:3072
	s_mov_b32 m0, s57
	ds_read_b128 v[44:47], v233 offset:32768
	ds_read_b128 v[52:55], v233 offset:33792
	ds_read_b128 v[60:63], v233 offset:34816
	ds_read_b128 v[220:223], v233 offset:35840
	ds_read_b128 v[224:227], v233 offset:36864
	ds_read_b128 v[234:237], v233 offset:37888
	ds_read_b128 v[238:241], v233 offset:38912
	ds_read_b128 v[242:245], v233 offset:39936
	global_load_lds_dwordx4 v132, s[26:27]
	s_mov_b32 m0, s58
	s_nop 0
	global_load_lds_dwordx4 v188, s[26:27]
	s_waitcnt vmcnt(8)
	s_waitcnt lgkmcnt(0)
	s_barrier
	s_setprio 1
	s_waitcnt lgkmcnt(0)
	v_mfma_f32_16x16x32_bf16 v[4:7], v[182:185], v[44:47], v[68:71]
	v_mfma_f32_16x16x32_bf16 v[8:11], v[196:199], v[44:47], v[72:75]
	v_mfma_f32_16x16x32_bf16 v[12:15], v[182:185], v[60:63], v[76:79]
	v_mfma_f32_16x16x32_bf16 v[16:19], v[196:199], v[60:63], v[80:83]
	v_mfma_f32_16x16x32_bf16 v[20:23], v[182:185], v[224:227], v[84:87]
	v_mfma_f32_16x16x32_bf16 v[24:27], v[196:199], v[224:227], v[88:91]
	v_mfma_f32_16x16x32_bf16 v[28:31], v[182:185], v[238:241], v[92:95]
	v_mfma_f32_16x16x32_bf16 v[32:35], v[196:199], v[238:241], v[96:99]
	s_setprio 0
	s_setprio 1
	v_mfma_f32_16x16x32_bf16 v[4:7], v[192:195], v[52:55], v[4:7]
	v_mfma_f32_16x16x32_bf16 v[8:11], v[200:203], v[52:55], v[8:11]
	v_mfma_f32_16x16x32_bf16 v[12:15], v[192:195], v[220:223], v[12:15]
	v_mfma_f32_16x16x32_bf16 v[16:19], v[200:203], v[220:223], v[16:19]
	v_mfma_f32_16x16x32_bf16 v[20:23], v[192:195], v[234:237], v[20:23]
	v_mfma_f32_16x16x32_bf16 v[24:27], v[200:203], v[234:237], v[24:27]
	v_mfma_f32_16x16x32_bf16 v[28:31], v[192:195], v[242:245], v[28:31]
	v_mfma_f32_16x16x32_bf16 v[32:35], v[200:203], v[242:245], v[32:35]
	s_setprio 0
	s_setprio 1
	v_mfma_f32_16x16x32_bf16 v[36:39], v[204:207], v[44:47], v[100:103]
	v_mfma_f32_16x16x32_bf16 v[40:43], v[212:215], v[44:47], v[40:43]
	v_mfma_f32_16x16x32_bf16 v[36:39], v[208:211], v[52:55], v[36:39]
	v_mfma_f32_16x16x32_bf16 v[40:43], v[216:219], v[52:55], v[40:43]
	v_mfma_f32_16x16x32_bf16 v[44:47], v[204:207], v[60:63], v[104:107]
	v_mfma_f32_16x16x32_bf16 v[48:51], v[212:215], v[60:63], v[48:51]
	v_mfma_f32_16x16x32_bf16 v[52:55], v[204:207], v[224:227], v[108:111]
	v_mfma_f32_16x16x32_bf16 v[56:59], v[212:215], v[224:227], v[56:59]
	s_setprio 0
	s_setprio 1
	v_mfma_f32_16x16x32_bf16 v[60:63], v[204:207], v[238:241], v[112:115]
	v_mfma_f32_16x16x32_bf16 v[64:67], v[212:215], v[238:241], v[64:67]
	v_mfma_f32_16x16x32_bf16 v[44:47], v[208:211], v[220:223], v[44:47]
	v_mfma_f32_16x16x32_bf16 v[48:51], v[216:219], v[220:223], v[48:51]
	v_mfma_f32_16x16x32_bf16 v[52:55], v[208:211], v[234:237], v[52:55]
	v_mfma_f32_16x16x32_bf16 v[56:59], v[216:219], v[234:237], v[56:59]
	s_setprio 2
	s_barrier
	v_mfma_f32_16x16x32_bf16 v[60:63], v[208:211], v[242:245], v[60:63]
	v_mfma_f32_16x16x32_bf16 v[64:67], v[216:219], v[242:245], v[64:67]
	s_setprio 0
	s_add_i32 s43, s43, s54
	v_lshl_add_u64 v[68:69], v[186:187], 0, s[0:1]
	s_mov_b32 m0, s43
	ds_read_b128 v[104:107], v233 offset:49152
	ds_read_b128 v[108:111], v233 offset:50176
	ds_read_b128 v[112:115], v233 offset:51200
	ds_read_b128 v[220:223], v233 offset:52224
	ds_read_b128 v[224:227], v233 offset:53248
	ds_read_b128 v[234:237], v233 offset:54272
	ds_read_b128 v[238:241], v233 offset:55296
	ds_read_b128 v[242:245], v233 offset:56320
	global_load_lds_dwordx4 v[68:69], off
	v_lshl_add_u64 v[68:69], v[246:247], 0, s[0:1]
	s_add_i32 m0, s43, 0x2000
	s_add_i32 s43, s71, s54
	global_load_lds_dwordx4 v[68:69], off
	s_mov_b32 m0, s43
	v_lshl_add_u64 v[68:69], v[248:249], 0, s[0:1]
	global_load_lds_dwordx4 v2, s[28:29]
	s_add_i32 m0, s43, 0x2000
	s_nop 0
	global_load_lds_dwordx4 v190, s[28:29]
	s_mov_b32 m0, s62
	s_nop 0
	global_load_lds_dwordx4 v[68:69], off
	v_lshl_add_u64 v[68:69], v[250:251], 0, s[0:1]
	s_mov_b32 m0, s63
	s_nop 0
	global_load_lds_dwordx4 v[68:69], off
	s_waitcnt vmcnt(8)
	s_waitcnt lgkmcnt(0)
	s_barrier
	s_setprio 1
	s_waitcnt lgkmcnt(0)
	v_mfma_f32_16x16x32_bf16 v[68:71], v[182:185], v[104:107], v[134:137]
	v_mfma_f32_16x16x32_bf16 v[72:75], v[196:199], v[104:107], v[138:141]
	v_mfma_f32_16x16x32_bf16 v[76:79], v[182:185], v[112:115], v[142:145]
	v_mfma_f32_16x16x32_bf16 v[80:83], v[196:199], v[112:115], v[146:149]
	v_mfma_f32_16x16x32_bf16 v[84:87], v[182:185], v[224:227], v[150:153]
	v_mfma_f32_16x16x32_bf16 v[88:91], v[196:199], v[224:227], v[154:157]
	v_mfma_f32_16x16x32_bf16 v[92:95], v[182:185], v[238:241], v[158:161]
	v_mfma_f32_16x16x32_bf16 v[96:99], v[196:199], v[238:241], v[162:165]
	s_setprio 0
	s_setprio 1
	v_mfma_f32_16x16x32_bf16 v[68:71], v[192:195], v[108:111], v[68:71]
	v_mfma_f32_16x16x32_bf16 v[72:75], v[200:203], v[108:111], v[72:75]
	v_mfma_f32_16x16x32_bf16 v[76:79], v[192:195], v[220:223], v[76:79]
	v_mfma_f32_16x16x32_bf16 v[80:83], v[200:203], v[220:223], v[80:83]
	v_mfma_f32_16x16x32_bf16 v[84:87], v[192:195], v[234:237], v[84:87]
	v_mfma_f32_16x16x32_bf16 v[88:91], v[200:203], v[234:237], v[88:91]
	v_mfma_f32_16x16x32_bf16 v[92:95], v[192:195], v[242:245], v[92:95]
	v_mfma_f32_16x16x32_bf16 v[96:99], v[200:203], v[242:245], v[96:99]
	s_setprio 0
	s_setprio 1
	v_mfma_f32_16x16x32_bf16 v[100:103], v[204:207], v[104:107], v[116:119]
	v_mfma_f32_16x16x32_bf16 v[104:107], v[212:215], v[104:107], v[124:127]
	v_mfma_f32_16x16x32_bf16 v[100:103], v[208:211], v[108:111], v[100:103]
	v_mfma_f32_16x16x32_bf16 v[104:107], v[216:219], v[108:111], v[104:107]
	v_mfma_f32_16x16x32_bf16 v[108:111], v[204:207], v[112:115], v[166:169]
	v_mfma_f32_16x16x32_bf16 v[112:115], v[212:215], v[112:115], v[170:173]
	v_mfma_f32_16x16x32_bf16 v[116:119], v[204:207], v[224:227], v[174:177]
	v_mfma_f32_16x16x32_bf16 v[120:123], v[212:215], v[224:227], v[120:123]
	s_setprio 0
	s_setprio 1
	v_mfma_f32_16x16x32_bf16 v[124:127], v[204:207], v[238:241], v[178:181]
	v_mfma_f32_16x16x32_bf16 v[128:131], v[212:215], v[238:241], v[128:131]
	v_mfma_f32_16x16x32_bf16 v[108:111], v[208:211], v[220:223], v[108:111]
	v_mfma_f32_16x16x32_bf16 v[112:115], v[216:219], v[220:223], v[112:115]
	v_mfma_f32_16x16x32_bf16 v[116:119], v[208:211], v[234:237], v[116:119]
	v_mfma_f32_16x16x32_bf16 v[120:123], v[216:219], v[234:237], v[120:123]
	s_setprio 2
	s_barrier
	v_mfma_f32_16x16x32_bf16 v[124:127], v[208:211], v[242:245], v[124:127]
	v_mfma_f32_16x16x32_bf16 v[128:131], v[216:219], v[242:245], v[128:131]
	s_setprio 0
	s_add_i32 s42, s42, 2
	s_cmp_ge_i32 s42, s38
	s_cbranch_scc0 .LBB0_641
	v_mov_b32_e32 v192, v2
	s_branch .LBB0_644

.LBB0_649:
	s_or_b32 s38, s28, 1
	s_lshl_b64 s[42:43], s[38:39], 7
	s_sub_u32 s38, 0, s42
	s_subb_u32 s42, 0, s43
	s_add_u32 s38, s6, s38
	s_addc_u32 s43, s7, s42
	s_add_i32 s71, 0, 0x10000
	s_add_i32 s72, 0, 0x14000
	v_add_u32_e32 v144, s71, v232
	v_add_u32_e32 v160, s72, v232
	s_waitcnt lgkmcnt(0)
	ds_read_b128 v[132:135], v144
	ds_read_b128 v[136:139], v144 offset:1024
	ds_read_b128 v[140:143], v144 offset:2048
	ds_read_b128 v[144:147], v144 offset:3072
	ds_read_b128 v[148:151], v160
	ds_read_b128 v[152:155], v160 offset:1024
	ds_read_b128 v[156:159], v160 offset:2048
	ds_read_b128 v[160:163], v160 offset:3072
	s_add_u32 s42, s38, 0x160000
	s_mov_b32 m0, s64
	v_add_u32_e32 v210, 0, v231
	s_addc_u32 s43, s43, 0
	ds_read_b128 v[164:167], v210
	ds_read_b128 v[168:171], v210 offset:1024
	ds_read_b128 v[172:175], v210 offset:2048
	ds_read_b128 v[176:179], v210 offset:3072
	ds_read_b128 v[180:183], v210 offset:4096
	ds_read_b128 v[184:187], v210 offset:5120
	ds_read_b128 v[194:197], v210 offset:6144
	ds_read_b128 v[198:201], v210 offset:7168
	global_load_lds_dwordx4 v2, s[42:43]
	s_mov_b32 m0, s65
	v_mov_b32_e32 v189, v3
	global_load_lds_dwordx4 v188, s[42:43]
	s_waitcnt vmcnt(8)
	s_waitcnt lgkmcnt(0)
	s_barrier
	s_setprio 1
	s_waitcnt lgkmcnt(0)
	v_mfma_f32_16x16x32_bf16 v[4:7], v[132:135], v[164:167], v[4:7]
	v_mfma_f32_16x16x32_bf16 v[4:7], v[136:139], v[168:171], v[4:7]
	v_mfma_f32_16x16x32_bf16 v[8:11], v[144:147], v[168:171], v[8:11]
	v_mfma_f32_16x16x32_bf16 v[8:11], v[140:143], v[164:167], v[8:11]
	v_mfma_f32_16x16x32_bf16 v[16:19], v[140:143], v[172:175], v[16:19]
	v_mfma_f32_16x16x32_bf16 v[16:19], v[144:147], v[176:179], v[16:19]
	v_mfma_f32_16x16x32_bf16 v[12:15], v[136:139], v[176:179], v[12:15]
	v_mfma_f32_16x16x32_bf16 v[12:15], v[132:135], v[172:175], v[12:15]
	s_setprio 0
	s_setprio 1
	v_mfma_f32_16x16x32_bf16 v[20:23], v[132:135], v[180:183], v[20:23]
	v_mfma_f32_16x16x32_bf16 v[20:23], v[136:139], v[184:187], v[20:23]
	v_mfma_f32_16x16x32_bf16 v[24:27], v[144:147], v[184:187], v[24:27]
	v_mfma_f32_16x16x32_bf16 v[24:27], v[140:143], v[180:183], v[24:27]
	v_mfma_f32_16x16x32_bf16 v[32:35], v[140:143], v[194:197], v[32:35]
	v_mfma_f32_16x16x32_bf16 v[32:35], v[144:147], v[198:201], v[32:35]
	v_mfma_f32_16x16x32_bf16 v[28:31], v[136:139], v[198:201], v[28:31]
	v_mfma_f32_16x16x32_bf16 v[28:31], v[132:135], v[194:197], v[28:31]
	s_setprio 0
	s_setprio 1
	v_mfma_f32_16x16x32_bf16 v[36:39], v[148:151], v[164:167], v[36:39]
	v_mfma_f32_16x16x32_bf16 v[36:39], v[152:155], v[168:171], v[36:39]
	v_mfma_f32_16x16x32_bf16 v[40:43], v[160:163], v[168:171], v[40:43]
	v_mfma_f32_16x16x32_bf16 v[40:43], v[156:159], v[164:167], v[40:43]
	v_mfma_f32_16x16x32_bf16 v[48:51], v[156:159], v[172:175], v[48:51]
	v_mfma_f32_16x16x32_bf16 v[48:51], v[160:163], v[176:179], v[48:51]
	v_mfma_f32_16x16x32_bf16 v[44:47], v[152:155], v[176:179], v[44:47]
	v_mfma_f32_16x16x32_bf16 v[44:47], v[148:151], v[172:175], v[44:47]
	s_setprio 0
	s_setprio 1
	v_mfma_f32_16x16x32_bf16 v[52:55], v[148:151], v[180:183], v[52:55]
	v_mfma_f32_16x16x32_bf16 v[52:55], v[152:155], v[184:187], v[52:55]
	v_mfma_f32_16x16x32_bf16 v[56:59], v[160:163], v[184:187], v[56:59]
	v_mfma_f32_16x16x32_bf16 v[56:59], v[156:159], v[180:183], v[56:59]
	v_mfma_f32_16x16x32_bf16 v[64:67], v[156:159], v[194:197], v[64:67]
	v_mfma_f32_16x16x32_bf16 v[64:67], v[160:163], v[198:201], v[64:67]
	s_setprio 2
	s_barrier
	v_mfma_f32_16x16x32_bf16 v[60:63], v[152:155], v[198:201], v[60:63]
	v_mfma_f32_16x16x32_bf16 v[60:63], v[148:151], v[194:197], v[60:63]
	s_setprio 0
	s_add_i32 s38, s71, s54
	s_mov_b32 m0, s38
	ds_read_b128 v[164:167], v210 offset:16384
	ds_read_b128 v[168:171], v210 offset:17408
	ds_read_b128 v[172:175], v210 offset:18432
	ds_read_b128 v[176:179], v210 offset:19456
	ds_read_b128 v[180:183], v210 offset:20480
	ds_read_b128 v[184:187], v210 offset:21504
	ds_read_b128 v[194:197], v210 offset:22528
	ds_read_b128 v[198:201], v210 offset:23552
	global_load_lds_dwordx4 v192, s[16:17]
	s_add_i32 m0, s38, 0x2000
	s_add_u32 s42, s16, 0x160000
	s_addc_u32 s43, s17, 0
	s_add_i32 s38, s72, s54
	global_load_lds_dwordx4 v190, s[16:17]
	s_mov_b32 m0, s38
	v_mov_b32_e32 v193, v3
	global_load_lds_dwordx4 v192, s[42:43]
	s_add_i32 m0, s38, 0x2000
	v_mov_b32_e32 v191, v3
	global_load_lds_dwordx4 v190, s[42:43]
	s_mov_b32 m0, s55
	v_lshl_add_u64 v[202:203], s[16:17], 0, v[192:193]
	global_load_lds_dwordx4 v2, s[26:27]
	s_mov_b32 m0, s56
	v_lshl_add_u64 v[204:205], s[16:17], 0, v[190:191]
	global_load_lds_dwordx4 v188, s[26:27]
	s_waitcnt vmcnt(8)
	s_waitcnt lgkmcnt(0)
	v_lshl_add_u64 v[206:207], s[26:27], 0, v[2:3]
	v_lshl_add_u64 v[208:209], s[26:27], 0, v[188:189]
	s_barrier
	s_setprio 1
	s_waitcnt lgkmcnt(0)
	v_mfma_f32_16x16x32_bf16 v[68:71], v[132:135], v[164:167], v[68:71]
	v_mfma_f32_16x16x32_bf16 v[68:71], v[136:139], v[168:171], v[68:71]
	v_mfma_f32_16x16x32_bf16 v[72:75], v[144:147], v[168:171], v[72:75]
	v_mfma_f32_16x16x32_bf16 v[72:75], v[140:143], v[164:167], v[72:75]
	v_mfma_f32_16x16x32_bf16 v[80:83], v[140:143], v[172:175], v[80:83]
	v_mfma_f32_16x16x32_bf16 v[80:83], v[144:147], v[176:179], v[80:83]
	v_mfma_f32_16x16x32_bf16 v[76:79], v[136:139], v[176:179], v[76:79]
	v_mfma_f32_16x16x32_bf16 v[76:79], v[132:135], v[172:175], v[76:79]
	s_setprio 0
	s_setprio 1
	v_mfma_f32_16x16x32_bf16 v[84:87], v[132:135], v[180:183], v[84:87]
	v_mfma_f32_16x16x32_bf16 v[84:87], v[136:139], v[184:187], v[84:87]
	v_mfma_f32_16x16x32_bf16 v[88:91], v[144:147], v[184:187], v[88:91]
	v_mfma_f32_16x16x32_bf16 v[88:91], v[140:143], v[180:183], v[88:91]
	v_mfma_f32_16x16x32_bf16 v[96:99], v[140:143], v[194:197], v[96:99]
	v_mfma_f32_16x16x32_bf16 v[96:99], v[144:147], v[198:201], v[96:99]
	v_mfma_f32_16x16x32_bf16 v[92:95], v[136:139], v[198:201], v[92:95]
	v_mfma_f32_16x16x32_bf16 v[92:95], v[132:135], v[194:197], v[92:95]
	s_setprio 0
	s_setprio 1
	v_mfma_f32_16x16x32_bf16 v[100:103], v[148:151], v[164:167], v[100:103]
	v_mfma_f32_16x16x32_bf16 v[100:103], v[152:155], v[168:171], v[100:103]
	v_mfma_f32_16x16x32_bf16 v[104:107], v[160:163], v[168:171], v[104:107]
	v_mfma_f32_16x16x32_bf16 v[104:107], v[156:159], v[164:167], v[104:107]
	v_mfma_f32_16x16x32_bf16 v[112:115], v[156:159], v[172:175], v[112:115]
	v_mfma_f32_16x16x32_bf16 v[112:115], v[160:163], v[176:179], v[112:115]
	v_mfma_f32_16x16x32_bf16 v[108:111], v[152:155], v[176:179], v[108:111]
	v_mfma_f32_16x16x32_bf16 v[108:111], v[148:151], v[172:175], v[108:111]
	s_setprio 0
	s_setprio 1
	v_mfma_f32_16x16x32_bf16 v[116:119], v[148:151], v[180:183], v[116:119]
	v_mfma_f32_16x16x32_bf16 v[116:119], v[152:155], v[184:187], v[116:119]
	v_mfma_f32_16x16x32_bf16 v[120:123], v[160:163], v[184:187], v[120:123]
	v_mfma_f32_16x16x32_bf16 v[120:123], v[156:159], v[180:183], v[120:123]
	v_mfma_f32_16x16x32_bf16 v[128:131], v[156:159], v[194:197], v[128:131]
	v_mfma_f32_16x16x32_bf16 v[128:131], v[160:163], v[198:201], v[128:131]
	s_setprio 2
	s_barrier
	v_mfma_f32_16x16x32_bf16 v[124:127], v[152:155], v[198:201], v[124:127]
	v_mfma_f32_16x16x32_bf16 v[124:127], v[148:151], v[194:197], v[124:127]
	s_setprio 0
	s_add_i32 s38, 0, 0x18000
	s_add_i32 s42, 0, 0x1c000
	v_add_u32_e32 v144, s38, v232
	v_add_u32_e32 v160, s42, v232
	ds_read_b128 v[132:135], v144
	ds_read_b128 v[136:139], v144 offset:1024
	ds_read_b128 v[140:143], v144 offset:2048
	ds_read_b128 v[144:147], v144 offset:3072
	ds_read_b128 v[148:151], v160
	ds_read_b128 v[152:155], v160 offset:1024
	ds_read_b128 v[156:159], v160 offset:2048
	ds_read_b128 v[160:163], v160 offset:3072
	s_add_u32 s26, s26, 0x160000
	s_addc_u32 s27, s27, 0
	s_mov_b32 m0, s57
	ds_read_b128 v[164:167], v210 offset:32768
	ds_read_b128 v[168:171], v210 offset:33792
	ds_read_b128 v[172:175], v210 offset:34816
	ds_read_b128 v[176:179], v210 offset:35840
	ds_read_b128 v[180:183], v210 offset:36864
	ds_read_b128 v[184:187], v210 offset:37888
	ds_read_b128 v[194:197], v210 offset:38912
	ds_read_b128 v[198:201], v210 offset:39936
	global_load_lds_dwordx4 v2, s[26:27]
	s_mov_b32 m0, s58
	s_nop 0
	global_load_lds_dwordx4 v188, s[26:27]
	s_waitcnt vmcnt(8)
	s_waitcnt lgkmcnt(0)
	s_barrier
	s_setprio 1
	s_waitcnt lgkmcnt(0)
	v_mfma_f32_16x16x32_bf16 v[4:7], v[132:135], v[164:167], v[4:7]
	v_mfma_f32_16x16x32_bf16 v[4:7], v[136:139], v[168:171], v[4:7]
	v_mfma_f32_16x16x32_bf16 v[8:11], v[144:147], v[168:171], v[8:11]
	v_mfma_f32_16x16x32_bf16 v[8:11], v[140:143], v[164:167], v[8:11]
	v_mfma_f32_16x16x32_bf16 v[16:19], v[140:143], v[172:175], v[16:19]
	v_mfma_f32_16x16x32_bf16 v[16:19], v[144:147], v[176:179], v[16:19]
	v_mfma_f32_16x16x32_bf16 v[12:15], v[136:139], v[176:179], v[12:15]
	v_mfma_f32_16x16x32_bf16 v[12:15], v[132:135], v[172:175], v[12:15]
	s_setprio 0
	s_setprio 1
	v_mfma_f32_16x16x32_bf16 v[20:23], v[132:135], v[180:183], v[20:23]
	v_mfma_f32_16x16x32_bf16 v[20:23], v[136:139], v[184:187], v[20:23]
	v_mfma_f32_16x16x32_bf16 v[24:27], v[144:147], v[184:187], v[24:27]
	v_mfma_f32_16x16x32_bf16 v[24:27], v[140:143], v[180:183], v[24:27]
	v_mfma_f32_16x16x32_bf16 v[32:35], v[140:143], v[194:197], v[32:35]
	v_mfma_f32_16x16x32_bf16 v[32:35], v[144:147], v[198:201], v[32:35]
	v_mfma_f32_16x16x32_bf16 v[28:31], v[136:139], v[198:201], v[28:31]
	v_mfma_f32_16x16x32_bf16 v[28:31], v[132:135], v[194:197], v[28:31]
	s_setprio 0
	s_setprio 1
	v_mfma_f32_16x16x32_bf16 v[36:39], v[148:151], v[164:167], v[36:39]
	v_mfma_f32_16x16x32_bf16 v[36:39], v[152:155], v[168:171], v[36:39]
	v_mfma_f32_16x16x32_bf16 v[40:43], v[160:163], v[168:171], v[40:43]
	v_mfma_f32_16x16x32_bf16 v[40:43], v[156:159], v[164:167], v[40:43]
	v_mfma_f32_16x16x32_bf16 v[48:51], v[156:159], v[172:175], v[48:51]
	v_mfma_f32_16x16x32_bf16 v[48:51], v[160:163], v[176:179], v[48:51]
	v_mfma_f32_16x16x32_bf16 v[44:47], v[152:155], v[176:179], v[44:47]
	v_mfma_f32_16x16x32_bf16 v[44:47], v[148:151], v[172:175], v[44:47]
	s_setprio 0
	s_setprio 1
	v_mfma_f32_16x16x32_bf16 v[52:55], v[148:151], v[180:183], v[52:55]
	v_mfma_f32_16x16x32_bf16 v[52:55], v[152:155], v[184:187], v[52:55]
	v_mfma_f32_16x16x32_bf16 v[56:59], v[160:163], v[184:187], v[56:59]
	v_mfma_f32_16x16x32_bf16 v[56:59], v[156:159], v[180:183], v[56:59]
	v_mfma_f32_16x16x32_bf16 v[64:67], v[156:159], v[194:197], v[64:67]
	v_mfma_f32_16x16x32_bf16 v[64:67], v[160:163], v[198:201], v[64:67]
	s_setprio 2
	s_barrier
	v_mfma_f32_16x16x32_bf16 v[60:63], v[152:155], v[198:201], v[60:63]
	v_mfma_f32_16x16x32_bf16 v[60:63], v[148:151], v[194:197], v[60:63]
	s_setprio 0
	s_add_i32 s26, s38, s54
	v_lshl_add_u64 v[202:203], v[202:203], 0, s[4:5]
	s_mov_b32 m0, s26
	ds_read_b128 v[164:167], v210 offset:49152
	ds_read_b128 v[168:171], v210 offset:50176
	ds_read_b128 v[172:175], v210 offset:51200
	ds_read_b128 v[176:179], v210 offset:52224
	ds_read_b128 v[180:183], v210 offset:53248
	ds_read_b128 v[184:187], v210 offset:54272
	ds_read_b128 v[194:197], v210 offset:55296
	ds_read_b128 v[198:201], v210 offset:56320
	global_load_lds_dwordx4 v[202:203], off
	s_add_i32 m0, s26, 0x2000
	s_add_u32 s16, s16, 0x15ff80
	v_lshl_add_u64 v[202:203], v[204:205], 0, s[4:5]
	s_addc_u32 s17, s17, 0
	s_add_i32 s26, s42, s54
	global_load_lds_dwordx4 v[202:203], off
	s_mov_b32 m0, s26
	v_lshl_add_u64 v[202:203], v[206:207], 0, s[4:5]
	global_load_lds_dwordx4 v192, s[16:17]
	s_add_i32 m0, s26, 0x2000
	s_nop 0
	global_load_lds_dwordx4 v190, s[16:17]
	s_mov_b32 m0, s62
	s_nop 0
	global_load_lds_dwordx4 v[202:203], off
	v_lshl_add_u64 v[202:203], v[208:209], 0, s[4:5]
	s_mov_b32 m0, s63
	s_nop 0
	global_load_lds_dwordx4 v[202:203], off
	s_waitcnt vmcnt(8)
	s_waitcnt lgkmcnt(0)
	s_barrier
	s_setprio 1
	s_waitcnt lgkmcnt(0)
	v_mfma_f32_16x16x32_bf16 v[68:71], v[132:135], v[164:167], v[68:71]
	v_mfma_f32_16x16x32_bf16 v[68:71], v[136:139], v[168:171], v[68:71]
	v_mfma_f32_16x16x32_bf16 v[72:75], v[144:147], v[168:171], v[72:75]
	v_mfma_f32_16x16x32_bf16 v[72:75], v[140:143], v[164:167], v[72:75]
	v_mfma_f32_16x16x32_bf16 v[80:83], v[140:143], v[172:175], v[80:83]
	v_mfma_f32_16x16x32_bf16 v[80:83], v[144:147], v[176:179], v[80:83]
	v_mfma_f32_16x16x32_bf16 v[76:79], v[136:139], v[176:179], v[76:79]
	v_mfma_f32_16x16x32_bf16 v[76:79], v[132:135], v[172:175], v[76:79]
	s_setprio 0
	s_setprio 1
	v_mfma_f32_16x16x32_bf16 v[84:87], v[132:135], v[180:183], v[84:87]
	v_mfma_f32_16x16x32_bf16 v[84:87], v[136:139], v[184:187], v[84:87]
	v_mfma_f32_16x16x32_bf16 v[88:91], v[144:147], v[184:187], v[88:91]
	v_mfma_f32_16x16x32_bf16 v[88:91], v[140:143], v[180:183], v[88:91]
	v_mfma_f32_16x16x32_bf16 v[96:99], v[140:143], v[194:197], v[96:99]
	v_mfma_f32_16x16x32_bf16 v[96:99], v[144:147], v[198:201], v[96:99]
	v_mfma_f32_16x16x32_bf16 v[92:95], v[136:139], v[198:201], v[92:95]
	v_mfma_f32_16x16x32_bf16 v[92:95], v[132:135], v[194:197], v[92:95]
	s_setprio 0
	s_setprio 1
	v_mfma_f32_16x16x32_bf16 v[100:103], v[148:151], v[164:167], v[100:103]
	v_mfma_f32_16x16x32_bf16 v[100:103], v[152:155], v[168:171], v[100:103]
	v_mfma_f32_16x16x32_bf16 v[104:107], v[160:163], v[168:171], v[104:107]
	v_mfma_f32_16x16x32_bf16 v[104:107], v[156:159], v[164:167], v[104:107]
	v_mfma_f32_16x16x32_bf16 v[112:115], v[156:159], v[172:175], v[112:115]
	v_mfma_f32_16x16x32_bf16 v[112:115], v[160:163], v[176:179], v[112:115]
	v_mfma_f32_16x16x32_bf16 v[108:111], v[152:155], v[176:179], v[108:111]
	v_mfma_f32_16x16x32_bf16 v[108:111], v[148:151], v[172:175], v[108:111]
	s_setprio 0
	s_setprio 1
	v_mfma_f32_16x16x32_bf16 v[116:119], v[148:151], v[180:183], v[116:119]
	v_mfma_f32_16x16x32_bf16 v[116:119], v[152:155], v[184:187], v[116:119]
	v_mfma_f32_16x16x32_bf16 v[120:123], v[160:163], v[184:187], v[120:123]
	v_mfma_f32_16x16x32_bf16 v[120:123], v[156:159], v[180:183], v[120:123]
	v_mfma_f32_16x16x32_bf16 v[128:131], v[156:159], v[194:197], v[128:131]
	v_mfma_f32_16x16x32_bf16 v[128:131], v[160:163], v[198:201], v[128:131]
	s_setprio 2
	s_barrier
	v_mfma_f32_16x16x32_bf16 v[124:127], v[152:155], v[198:201], v[124:127]
	v_mfma_f32_16x16x32_bf16 v[124:127], v[148:151], v[194:197], v[124:127]
	s_setprio 0
	s_cmpk_gt_u32 s28, 0x55
	s_cbranch_scc1 .LBB0_651
	s_mov_b32 s28, s29
	s_branch .LBB0_645

.LBB0_749:
	s_add_i32 s47, 0, 0x10000
	s_add_i32 s49, 0, 0x14000
	v_add_u32_e32 v16, s47, v147
	v_add_u32_e32 v32, s49, v147
	ds_read_b128 v[4:7], v16
	ds_read_b128 v[8:11], v16 offset:1024
	ds_read_b128 v[12:15], v16 offset:2048
	ds_read_b128 v[16:19], v16 offset:3072
	ds_read_b128 v[20:23], v32
	ds_read_b128 v[24:27], v32 offset:1024
	ds_read_b128 v[28:31], v32 offset:2048
	ds_read_b128 v[32:35], v32 offset:3072
	v_add_u32_e32 v231, 0, v146
	ds_read_b128 v[36:39], v231
	ds_read_b128 v[40:43], v231 offset:1024
	ds_read_b128 v[44:47], v231 offset:2048
	ds_read_b128 v[48:51], v231 offset:3072
	ds_read_b128 v[52:55], v231 offset:4096
	ds_read_b128 v[56:59], v231 offset:5120
	ds_read_b128 v[60:63], v231 offset:6144
	ds_read_b128 v[64:67], v231 offset:7168
	s_waitcnt vmcnt(8)
	s_waitcnt lgkmcnt(0)
	s_barrier
	s_setprio 1
	s_waitcnt lgkmcnt(0)
	v_mfma_f32_16x16x32_f16 v[68:71], v[4:7], v[36:39], 0
	v_mfma_f32_16x16x32_f16 v[68:71], v[8:11], v[40:43], v[68:71]
	v_mfma_f32_16x16x32_f16 v[72:75], v[12:15], v[36:39], 0
	v_mfma_f32_16x16x32_f16 v[72:75], v[16:19], v[40:43], v[72:75]
	v_mfma_f32_16x16x32_f16 v[80:83], v[12:15], v[44:47], 0
	v_mfma_f32_16x16x32_f16 v[80:83], v[16:19], v[48:51], v[80:83]
	v_mfma_f32_16x16x32_f16 v[76:79], v[4:7], v[44:47], 0
	v_mfma_f32_16x16x32_f16 v[76:79], v[8:11], v[48:51], v[76:79]
	s_setprio 0
	s_setprio 1
	v_mfma_f32_16x16x32_f16 v[84:87], v[4:7], v[52:55], 0
	v_mfma_f32_16x16x32_f16 v[84:87], v[8:11], v[56:59], v[84:87]
	v_mfma_f32_16x16x32_f16 v[88:91], v[12:15], v[52:55], 0
	v_mfma_f32_16x16x32_f16 v[88:91], v[16:19], v[56:59], v[88:91]
	v_mfma_f32_16x16x32_f16 v[96:99], v[12:15], v[60:63], 0
	v_mfma_f32_16x16x32_f16 v[96:99], v[16:19], v[64:67], v[96:99]
	v_mfma_f32_16x16x32_f16 v[92:95], v[4:7], v[60:63], 0
	v_mfma_f32_16x16x32_f16 v[92:95], v[8:11], v[64:67], v[92:95]
	s_setprio 0
	s_setprio 1
	v_mfma_f32_16x16x32_f16 v[100:103], v[20:23], v[36:39], 0
	v_mfma_f32_16x16x32_f16 v[36:39], v[28:31], v[36:39], 0
	v_mfma_f32_16x16x32_f16 v[104:107], v[20:23], v[44:47], 0
	v_mfma_f32_16x16x32_f16 v[44:47], v[28:31], v[44:47], 0
	v_mfma_f32_16x16x32_f16 v[108:111], v[20:23], v[52:55], 0
	v_mfma_f32_16x16x32_f16 v[52:55], v[28:31], v[52:55], 0
	v_mfma_f32_16x16x32_f16 v[112:115], v[20:23], v[60:63], 0
	v_mfma_f32_16x16x32_f16 v[60:63], v[28:31], v[60:63], 0
	s_setprio 0
	s_setprio 1
	v_mfma_f32_16x16x32_f16 v[100:103], v[24:27], v[40:43], v[100:103]
	v_mfma_f32_16x16x32_f16 v[40:43], v[32:35], v[40:43], v[36:39]
	v_mfma_f32_16x16x32_f16 v[104:107], v[24:27], v[48:51], v[104:107]
	v_mfma_f32_16x16x32_f16 v[48:51], v[32:35], v[48:51], v[44:47]
	v_mfma_f32_16x16x32_f16 v[108:111], v[24:27], v[56:59], v[108:111]
	v_mfma_f32_16x16x32_f16 v[56:59], v[32:35], v[56:59], v[52:55]
	s_setprio 2
	s_barrier
	v_mfma_f32_16x16x32_f16 v[112:115], v[24:27], v[64:67], v[112:115]
	v_mfma_f32_16x16x32_f16 v[64:67], v[32:35], v[64:67], v[60:63]
	s_setprio 0
	v_lshl_add_u64 v[136:137], s[6:7], 0, v[2:3]
	s_add_i32 s47, s47, s62
	v_mov_b32_e32 v135, v3
	v_lshl_add_u64 v[140:141], v[136:137], 0, s[74:75]
	s_mov_b32 m0, s47
	v_lshl_add_u64 v[144:145], s[6:7], 0, v[134:135]
	ds_read_b128 v[36:39], v231 offset:16384
	ds_read_b128 v[44:47], v231 offset:17408
	ds_read_b128 v[52:55], v231 offset:18432
	ds_read_b128 v[60:63], v231 offset:19456
	ds_read_b128 v[116:119], v231 offset:20480
	ds_read_b128 v[120:123], v231 offset:21504
	ds_read_b128 v[124:127], v231 offset:22528
	ds_read_b128 v[128:131], v231 offset:23552
	global_load_lds_dwordx4 v[140:141], off
	v_lshl_add_u64 v[140:141], v[144:145], 0, s[74:75]
	s_add_i32 m0, s47, 0x2000
	s_add_i32 s47, s49, s62
	global_load_lds_dwordx4 v[140:141], off
	s_mov_b32 m0, s47
	v_mov_b32_e32 v139, v3
	global_load_lds_dwordx4 v2, s[16:17]
	s_add_i32 m0, s47, 0x2000
	v_lshl_add_u64 v[248:249], s[8:9], 0, v[138:139]
	v_mov_b32_e32 v133, v3
	global_load_lds_dwordx4 v134, s[16:17]
	v_lshl_add_u64 v[140:141], v[248:249], 0, s[74:75]
	s_mov_b32 m0, s63
	v_lshl_add_u64 v[250:251], s[8:9], 0, v[132:133]
	global_load_lds_dwordx4 v[140:141], off
	v_lshl_add_u64 v[140:141], v[250:251], 0, s[74:75]
	s_mov_b32 m0, s64
	s_nop 0
	global_load_lds_dwordx4 v[140:141], off
	s_waitcnt vmcnt(8)
	s_waitcnt lgkmcnt(0)
	s_barrier
	s_setprio 1
	s_waitcnt lgkmcnt(0)
	v_mfma_f32_16x16x32_f16 v[140:143], v[4:7], v[36:39], 0
	v_mfma_f32_16x16x32_f16 v[148:151], v[12:15], v[36:39], 0
	v_mfma_f32_16x16x32_f16 v[152:155], v[4:7], v[52:55], 0
	v_mfma_f32_16x16x32_f16 v[156:159], v[12:15], v[52:55], 0
	v_mfma_f32_16x16x32_f16 v[160:163], v[4:7], v[116:119], 0
	v_mfma_f32_16x16x32_f16 v[164:167], v[12:15], v[116:119], 0
	v_mfma_f32_16x16x32_f16 v[4:7], v[4:7], v[124:127], 0
	v_mfma_f32_16x16x32_f16 v[12:15], v[12:15], v[124:127], 0
	s_setprio 0
	s_setprio 1
	v_mfma_f32_16x16x32_f16 v[140:143], v[8:11], v[44:47], v[140:143]
	v_mfma_f32_16x16x32_f16 v[148:151], v[16:19], v[44:47], v[148:151]
	v_mfma_f32_16x16x32_f16 v[152:155], v[8:11], v[60:63], v[152:155]
	v_mfma_f32_16x16x32_f16 v[156:159], v[16:19], v[60:63], v[156:159]
	v_mfma_f32_16x16x32_f16 v[160:163], v[8:11], v[120:123], v[160:163]
	v_mfma_f32_16x16x32_f16 v[164:167], v[16:19], v[120:123], v[164:167]
	v_mfma_f32_16x16x32_f16 v[168:171], v[8:11], v[128:131], v[4:7]
	v_mfma_f32_16x16x32_f16 v[172:175], v[16:19], v[128:131], v[12:15]
	s_setprio 0
	s_setprio 1
	v_mfma_f32_16x16x32_f16 v[4:7], v[20:23], v[36:39], 0
	v_mfma_f32_16x16x32_f16 v[8:11], v[28:31], v[36:39], 0
	v_mfma_f32_16x16x32_f16 v[12:15], v[20:23], v[52:55], 0
	v_mfma_f32_16x16x32_f16 v[16:19], v[28:31], v[52:55], 0
	v_mfma_f32_16x16x32_f16 v[36:39], v[20:23], v[116:119], 0
	v_mfma_f32_16x16x32_f16 v[52:55], v[28:31], v[116:119], 0
	v_mfma_f32_16x16x32_f16 v[20:23], v[20:23], v[124:127], 0
	v_mfma_f32_16x16x32_f16 v[28:31], v[28:31], v[124:127], 0
	s_setprio 0
	s_setprio 1
	v_mfma_f32_16x16x32_f16 v[116:119], v[24:27], v[44:47], v[4:7]
	v_mfma_f32_16x16x32_f16 v[124:127], v[32:35], v[44:47], v[8:11]
	v_mfma_f32_16x16x32_f16 v[184:187], v[24:27], v[120:123], v[36:39]
	v_mfma_f32_16x16x32_f16 v[120:123], v[32:35], v[120:123], v[52:55]
	v_mfma_f32_16x16x32_f16 v[188:191], v[24:27], v[128:131], v[20:23]
	v_mfma_f32_16x16x32_f16 v[128:131], v[32:35], v[128:131], v[28:31]
	s_setprio 2
	s_barrier
	v_mfma_f32_16x16x32_f16 v[176:179], v[24:27], v[60:63], v[12:15]
	v_mfma_f32_16x16x32_f16 v[180:183], v[32:35], v[60:63], v[16:19]
	s_setprio 0
	s_add_i32 s47, 0, 0x18000
	v_add_u32_e32 v4, s47, v147
	s_add_i32 s49, 0, 0x1c000
	ds_read_b128 v[192:195], v4
	ds_read_b128 v[196:199], v4 offset:1024
	ds_read_b128 v[200:203], v4 offset:2048
	ds_read_b128 v[204:207], v4 offset:3072
	v_add_u32_e32 v4, s49, v147
	ds_read_b128 v[208:211], v4
	ds_read_b128 v[212:215], v4 offset:1024
	ds_read_b128 v[216:219], v4 offset:2048
	ds_read_b128 v[220:223], v4 offset:3072
	s_mov_b32 m0, s65
	ds_read_b128 v[44:47], v231 offset:32768
	ds_read_b128 v[52:55], v231 offset:33792
	ds_read_b128 v[60:63], v231 offset:34816
	ds_read_b128 v[224:227], v231 offset:35840
	ds_read_b128 v[232:235], v231 offset:36864
	ds_read_b128 v[236:239], v231 offset:37888
	ds_read_b128 v[240:243], v231 offset:38912
	ds_read_b128 v[244:247], v231 offset:39936
	global_load_lds_dwordx4 v138, s[26:27]
	s_mov_b32 m0, s66
	s_nop 0
	global_load_lds_dwordx4 v132, s[26:27]
	s_waitcnt vmcnt(8)
	s_waitcnt lgkmcnt(0)
	s_barrier
	s_setprio 1
	s_waitcnt lgkmcnt(0)
	v_mfma_f32_16x16x32_f16 v[4:7], v[192:195], v[44:47], v[68:71]
	v_mfma_f32_16x16x32_f16 v[8:11], v[200:203], v[44:47], v[72:75]
	v_mfma_f32_16x16x32_f16 v[12:15], v[192:195], v[60:63], v[76:79]
	v_mfma_f32_16x16x32_f16 v[16:19], v[200:203], v[60:63], v[80:83]
	v_mfma_f32_16x16x32_f16 v[20:23], v[192:195], v[232:235], v[84:87]
	v_mfma_f32_16x16x32_f16 v[24:27], v[200:203], v[232:235], v[88:91]
	v_mfma_f32_16x16x32_f16 v[28:31], v[192:195], v[240:243], v[92:95]
	v_mfma_f32_16x16x32_f16 v[32:35], v[200:203], v[240:243], v[96:99]
	s_setprio 0
	s_setprio 1
	v_mfma_f32_16x16x32_f16 v[4:7], v[196:199], v[52:55], v[4:7]
	v_mfma_f32_16x16x32_f16 v[8:11], v[204:207], v[52:55], v[8:11]
	v_mfma_f32_16x16x32_f16 v[12:15], v[196:199], v[224:227], v[12:15]
	v_mfma_f32_16x16x32_f16 v[16:19], v[204:207], v[224:227], v[16:19]
	v_mfma_f32_16x16x32_f16 v[20:23], v[196:199], v[236:239], v[20:23]
	v_mfma_f32_16x16x32_f16 v[24:27], v[204:207], v[236:239], v[24:27]
	v_mfma_f32_16x16x32_f16 v[28:31], v[196:199], v[244:247], v[28:31]
	v_mfma_f32_16x16x32_f16 v[32:35], v[204:207], v[244:247], v[32:35]
	s_setprio 0
	s_setprio 1
	v_mfma_f32_16x16x32_f16 v[36:39], v[208:211], v[44:47], v[100:103]
	v_mfma_f32_16x16x32_f16 v[40:43], v[216:219], v[44:47], v[40:43]
	v_mfma_f32_16x16x32_f16 v[36:39], v[212:215], v[52:55], v[36:39]
	v_mfma_f32_16x16x32_f16 v[40:43], v[220:223], v[52:55], v[40:43]
	v_mfma_f32_16x16x32_f16 v[44:47], v[208:211], v[60:63], v[104:107]
	v_mfma_f32_16x16x32_f16 v[48:51], v[216:219], v[60:63], v[48:51]
	v_mfma_f32_16x16x32_f16 v[52:55], v[208:211], v[232:235], v[108:111]
	v_mfma_f32_16x16x32_f16 v[56:59], v[216:219], v[232:235], v[56:59]
	s_setprio 0
	s_setprio 1
	v_mfma_f32_16x16x32_f16 v[60:63], v[208:211], v[240:243], v[112:115]
	v_mfma_f32_16x16x32_f16 v[64:67], v[216:219], v[240:243], v[64:67]
	v_mfma_f32_16x16x32_f16 v[44:47], v[212:215], v[224:227], v[44:47]
	v_mfma_f32_16x16x32_f16 v[48:51], v[220:223], v[224:227], v[48:51]
	v_mfma_f32_16x16x32_f16 v[52:55], v[212:215], v[236:239], v[52:55]
	v_mfma_f32_16x16x32_f16 v[56:59], v[220:223], v[236:239], v[56:59]
	s_setprio 2
	s_barrier
	v_mfma_f32_16x16x32_f16 v[60:63], v[212:215], v[244:247], v[60:63]
	v_mfma_f32_16x16x32_f16 v[64:67], v[220:223], v[244:247], v[64:67]
	s_setprio 0
	s_add_i32 s47, s47, s62
	v_lshl_add_u64 v[68:69], v[136:137], 0, s[24:25]
	s_mov_b32 m0, s47
	ds_read_b128 v[104:107], v231 offset:49152
	ds_read_b128 v[108:111], v231 offset:50176
	ds_read_b128 v[112:115], v231 offset:51200
	ds_read_b128 v[224:227], v231 offset:52224
	ds_read_b128 v[232:235], v231 offset:53248
	ds_read_b128 v[236:239], v231 offset:54272
	ds_read_b128 v[240:243], v231 offset:55296
	ds_read_b128 v[244:247], v231 offset:56320
	global_load_lds_dwordx4 v[68:69], off
	v_lshl_add_u64 v[68:69], v[144:145], 0, s[24:25]
	s_add_i32 m0, s47, 0x2000
	s_add_i32 s47, s49, s62
	global_load_lds_dwordx4 v[68:69], off
	s_mov_b32 m0, s47
	v_lshl_add_u64 v[68:69], v[248:249], 0, s[24:25]
	global_load_lds_dwordx4 v2, s[28:29]
	s_add_i32 m0, s47, 0x2000
	s_nop 0
	global_load_lds_dwordx4 v134, s[28:29]
	s_mov_b32 m0, s69
	s_nop 0
	global_load_lds_dwordx4 v[68:69], off
	v_lshl_add_u64 v[68:69], v[250:251], 0, s[24:25]
	s_mov_b32 m0, s70
	s_nop 0
	global_load_lds_dwordx4 v[68:69], off
	s_waitcnt vmcnt(8)
	s_waitcnt lgkmcnt(0)
	s_barrier
	s_setprio 1
	s_waitcnt lgkmcnt(0)
	v_mfma_f32_16x16x32_f16 v[68:71], v[192:195], v[104:107], v[140:143]
	v_mfma_f32_16x16x32_f16 v[72:75], v[200:203], v[104:107], v[148:151]
	v_mfma_f32_16x16x32_f16 v[76:79], v[192:195], v[112:115], v[152:155]
	v_mfma_f32_16x16x32_f16 v[80:83], v[200:203], v[112:115], v[156:159]
	v_mfma_f32_16x16x32_f16 v[84:87], v[192:195], v[232:235], v[160:163]
	v_mfma_f32_16x16x32_f16 v[88:91], v[200:203], v[232:235], v[164:167]
	v_mfma_f32_16x16x32_f16 v[92:95], v[192:195], v[240:243], v[168:171]
	v_mfma_f32_16x16x32_f16 v[96:99], v[200:203], v[240:243], v[172:175]
	s_setprio 0
	s_setprio 1
	v_mfma_f32_16x16x32_f16 v[68:71], v[196:199], v[108:111], v[68:71]
	v_mfma_f32_16x16x32_f16 v[72:75], v[204:207], v[108:111], v[72:75]
	v_mfma_f32_16x16x32_f16 v[76:79], v[196:199], v[224:227], v[76:79]
	v_mfma_f32_16x16x32_f16 v[80:83], v[204:207], v[224:227], v[80:83]
	v_mfma_f32_16x16x32_f16 v[84:87], v[196:199], v[236:239], v[84:87]
	v_mfma_f32_16x16x32_f16 v[88:91], v[204:207], v[236:239], v[88:91]
	v_mfma_f32_16x16x32_f16 v[92:95], v[196:199], v[244:247], v[92:95]
	v_mfma_f32_16x16x32_f16 v[96:99], v[204:207], v[244:247], v[96:99]
	s_setprio 0
	s_setprio 1
	v_mfma_f32_16x16x32_f16 v[100:103], v[208:211], v[104:107], v[116:119]
	v_mfma_f32_16x16x32_f16 v[104:107], v[216:219], v[104:107], v[124:127]
	v_mfma_f32_16x16x32_f16 v[100:103], v[212:215], v[108:111], v[100:103]
	v_mfma_f32_16x16x32_f16 v[104:107], v[220:223], v[108:111], v[104:107]
	v_mfma_f32_16x16x32_f16 v[108:111], v[208:211], v[112:115], v[176:179]
	v_mfma_f32_16x16x32_f16 v[112:115], v[216:219], v[112:115], v[180:183]
	v_mfma_f32_16x16x32_f16 v[116:119], v[208:211], v[232:235], v[184:187]
	v_mfma_f32_16x16x32_f16 v[120:123], v[216:219], v[232:235], v[120:123]
	s_setprio 0
	s_setprio 1
	v_mfma_f32_16x16x32_f16 v[124:127], v[208:211], v[240:243], v[188:191]
	v_mfma_f32_16x16x32_f16 v[128:131], v[216:219], v[240:243], v[128:131]
	v_mfma_f32_16x16x32_f16 v[108:111], v[212:215], v[224:227], v[108:111]
	v_mfma_f32_16x16x32_f16 v[112:115], v[220:223], v[224:227], v[112:115]
	v_mfma_f32_16x16x32_f16 v[116:119], v[212:215], v[236:239], v[116:119]
	v_mfma_f32_16x16x32_f16 v[120:123], v[220:223], v[236:239], v[120:123]
	s_setprio 2
	s_barrier
	v_mfma_f32_16x16x32_f16 v[124:127], v[212:215], v[244:247], v[124:127]
	v_mfma_f32_16x16x32_f16 v[128:131], v[220:223], v[244:247], v[128:131]
	s_setprio 0
	s_add_i32 s45, s45, 2
	s_cmp_ge_i32 s45, s44
	s_cbranch_scc0 .LBB0_749
	v_mov_b32_e32 v136, v2
	s_branch .LBB0_752

.LBB0_753:
	s_add_u32 s6, s8, 0xfff80080
	s_addc_u32 s7, s9, -1
	s_add_i32 s29, 0, 0x10000
	s_cmp_eq_u32 s28, 28
	s_cselect_b32 s17, s13, s7
	s_cselect_b32 s16, s12, s6
	v_add_u32_e32 v133, s29, v147
	s_cselect_b32 s7, s15, s27
	s_cselect_b32 s6, s14, s26
	s_add_i32 s47, 0, 0x14000
	ds_read_b128 v[138:141], v133
	ds_read_b128 v[142:145], v133 offset:1024
	ds_read_b128 v[148:151], v133 offset:2048
	ds_read_b128 v[152:155], v133 offset:3072
	v_add_u32_e32 v133, s47, v147
	ds_read_b128 v[156:159], v133
	ds_read_b128 v[160:163], v133 offset:1024
	ds_read_b128 v[164:167], v133 offset:2048
	ds_read_b128 v[168:171], v133 offset:3072
	s_mov_b32 m0, s71
	v_add_u32_e32 v212, 0, v146
	ds_read_b128 v[172:175], v212
	ds_read_b128 v[176:179], v212 offset:1024
	ds_read_b128 v[180:183], v212 offset:2048
	ds_read_b128 v[184:187], v212 offset:3072
	ds_read_b128 v[188:191], v212 offset:4096
	ds_read_b128 v[192:195], v212 offset:5120
	ds_read_b128 v[196:199], v212 offset:6144
	ds_read_b128 v[200:203], v212 offset:7168
	global_load_lds_dwordx4 v2, s[8:9]
	s_mov_b32 m0, s72
	v_mov_b32_e32 v133, v3
	global_load_lds_dwordx4 v132, s[8:9]
	s_waitcnt vmcnt(8)
	s_waitcnt lgkmcnt(0)
	s_barrier
	s_setprio 1
	s_waitcnt lgkmcnt(0)
	v_mfma_f32_16x16x32_f16 v[4:7], v[138:141], v[172:175], v[4:7]
	v_mfma_f32_16x16x32_f16 v[4:7], v[142:145], v[176:179], v[4:7]
	v_mfma_f32_16x16x32_f16 v[8:11], v[152:155], v[176:179], v[8:11]
	v_mfma_f32_16x16x32_f16 v[8:11], v[148:151], v[172:175], v[8:11]
	v_mfma_f32_16x16x32_f16 v[16:19], v[148:151], v[180:183], v[16:19]
	v_mfma_f32_16x16x32_f16 v[16:19], v[152:155], v[184:187], v[16:19]
	v_mfma_f32_16x16x32_f16 v[12:15], v[142:145], v[184:187], v[12:15]
	v_mfma_f32_16x16x32_f16 v[12:15], v[138:141], v[180:183], v[12:15]
	s_setprio 0
	s_setprio 1
	v_mfma_f32_16x16x32_f16 v[20:23], v[138:141], v[188:191], v[20:23]
	v_mfma_f32_16x16x32_f16 v[20:23], v[142:145], v[192:195], v[20:23]
	v_mfma_f32_16x16x32_f16 v[24:27], v[152:155], v[192:195], v[24:27]
	v_mfma_f32_16x16x32_f16 v[24:27], v[148:151], v[188:191], v[24:27]
	v_mfma_f32_16x16x32_f16 v[32:35], v[148:151], v[196:199], v[32:35]
	v_mfma_f32_16x16x32_f16 v[32:35], v[152:155], v[200:203], v[32:35]
	v_mfma_f32_16x16x32_f16 v[28:31], v[142:145], v[200:203], v[28:31]
	v_mfma_f32_16x16x32_f16 v[28:31], v[138:141], v[196:199], v[28:31]
	s_setprio 0
	s_setprio 1
	v_mfma_f32_16x16x32_f16 v[36:39], v[156:159], v[172:175], v[36:39]
	v_mfma_f32_16x16x32_f16 v[36:39], v[160:163], v[176:179], v[36:39]
	v_mfma_f32_16x16x32_f16 v[40:43], v[168:171], v[176:179], v[40:43]
	v_mfma_f32_16x16x32_f16 v[40:43], v[164:167], v[172:175], v[40:43]
	v_mfma_f32_16x16x32_f16 v[48:51], v[164:167], v[180:183], v[48:51]
	v_mfma_f32_16x16x32_f16 v[48:51], v[168:171], v[184:187], v[48:51]
	v_mfma_f32_16x16x32_f16 v[44:47], v[160:163], v[184:187], v[44:47]
	v_mfma_f32_16x16x32_f16 v[44:47], v[156:159], v[180:183], v[44:47]
	s_setprio 0
	s_setprio 1
	v_mfma_f32_16x16x32_f16 v[52:55], v[156:159], v[188:191], v[52:55]
	v_mfma_f32_16x16x32_f16 v[52:55], v[160:163], v[192:195], v[52:55]
	v_mfma_f32_16x16x32_f16 v[56:59], v[168:171], v[192:195], v[56:59]
	v_mfma_f32_16x16x32_f16 v[56:59], v[164:167], v[188:191], v[56:59]
	v_mfma_f32_16x16x32_f16 v[64:67], v[164:167], v[196:199], v[64:67]
	v_mfma_f32_16x16x32_f16 v[64:67], v[168:171], v[200:203], v[64:67]
	s_setprio 2
	s_barrier
	v_mfma_f32_16x16x32_f16 v[60:63], v[160:163], v[200:203], v[60:63]
	v_mfma_f32_16x16x32_f16 v[60:63], v[156:159], v[196:199], v[60:63]
	s_setprio 0
	s_add_i32 s29, s29, s62
	s_mov_b32 m0, s29
	ds_read_b128 v[172:175], v212 offset:16384
	ds_read_b128 v[176:179], v212 offset:17408
	ds_read_b128 v[180:183], v212 offset:18432
	ds_read_b128 v[184:187], v212 offset:19456
	ds_read_b128 v[188:191], v212 offset:20480
	ds_read_b128 v[192:195], v212 offset:21504
	ds_read_b128 v[196:199], v212 offset:22528
	ds_read_b128 v[200:203], v212 offset:23552
	global_load_lds_dwordx4 v136, s[6:7]
	s_add_i32 m0, s29, 0x2000
	s_add_u32 s44, s6, 0x80000
	s_addc_u32 s45, s7, 0
	s_add_i32 s29, s47, s62
	global_load_lds_dwordx4 v134, s[6:7]
	s_mov_b32 m0, s29
	v_mov_b32_e32 v137, v3
	global_load_lds_dwordx4 v136, s[44:45]
	s_add_i32 m0, s29, 0x2000
	v_mov_b32_e32 v135, v3
	global_load_lds_dwordx4 v134, s[44:45]
	s_mov_b32 m0, s63
	v_lshl_add_u64 v[204:205], s[6:7], 0, v[136:137]
	global_load_lds_dwordx4 v2, s[16:17]
	s_mov_b32 m0, s64
	v_lshl_add_u64 v[206:207], s[6:7], 0, v[134:135]
	global_load_lds_dwordx4 v132, s[16:17]
	s_waitcnt vmcnt(8)
	s_waitcnt lgkmcnt(0)
	v_lshl_add_u64 v[208:209], s[16:17], 0, v[2:3]
	v_lshl_add_u64 v[210:211], s[16:17], 0, v[132:133]
	s_barrier
	s_setprio 1
	s_waitcnt lgkmcnt(0)
	v_mfma_f32_16x16x32_f16 v[68:71], v[138:141], v[172:175], v[68:71]
	v_mfma_f32_16x16x32_f16 v[68:71], v[142:145], v[176:179], v[68:71]
	v_mfma_f32_16x16x32_f16 v[72:75], v[152:155], v[176:179], v[72:75]
	v_mfma_f32_16x16x32_f16 v[72:75], v[148:151], v[172:175], v[72:75]
	v_mfma_f32_16x16x32_f16 v[80:83], v[148:151], v[180:183], v[80:83]
	v_mfma_f32_16x16x32_f16 v[80:83], v[152:155], v[184:187], v[80:83]
	v_mfma_f32_16x16x32_f16 v[76:79], v[142:145], v[184:187], v[76:79]
	v_mfma_f32_16x16x32_f16 v[76:79], v[138:141], v[180:183], v[76:79]
	s_setprio 0
	s_setprio 1
	v_mfma_f32_16x16x32_f16 v[84:87], v[138:141], v[188:191], v[84:87]
	v_mfma_f32_16x16x32_f16 v[84:87], v[142:145], v[192:195], v[84:87]
	v_mfma_f32_16x16x32_f16 v[88:91], v[152:155], v[192:195], v[88:91]
	v_mfma_f32_16x16x32_f16 v[88:91], v[148:151], v[188:191], v[88:91]
	v_mfma_f32_16x16x32_f16 v[96:99], v[148:151], v[196:199], v[96:99]
	v_mfma_f32_16x16x32_f16 v[96:99], v[152:155], v[200:203], v[96:99]
	v_mfma_f32_16x16x32_f16 v[92:95], v[142:145], v[200:203], v[92:95]
	v_mfma_f32_16x16x32_f16 v[92:95], v[138:141], v[196:199], v[92:95]
	s_setprio 0
	s_setprio 1
	v_mfma_f32_16x16x32_f16 v[100:103], v[156:159], v[172:175], v[100:103]
	v_mfma_f32_16x16x32_f16 v[100:103], v[160:163], v[176:179], v[100:103]
	v_mfma_f32_16x16x32_f16 v[104:107], v[168:171], v[176:179], v[104:107]
	v_mfma_f32_16x16x32_f16 v[104:107], v[164:167], v[172:175], v[104:107]
	v_mfma_f32_16x16x32_f16 v[112:115], v[164:167], v[180:183], v[112:115]
	v_mfma_f32_16x16x32_f16 v[112:115], v[168:171], v[184:187], v[112:115]
	v_mfma_f32_16x16x32_f16 v[108:111], v[160:163], v[184:187], v[108:111]
	v_mfma_f32_16x16x32_f16 v[108:111], v[156:159], v[180:183], v[108:111]
	s_setprio 0
	s_setprio 1
	v_mfma_f32_16x16x32_f16 v[116:119], v[156:159], v[188:191], v[116:119]
	v_mfma_f32_16x16x32_f16 v[116:119], v[160:163], v[192:195], v[116:119]
	v_mfma_f32_16x16x32_f16 v[120:123], v[168:171], v[192:195], v[120:123]
	v_mfma_f32_16x16x32_f16 v[120:123], v[164:167], v[188:191], v[120:123]
	v_mfma_f32_16x16x32_f16 v[128:131], v[164:167], v[196:199], v[128:131]
	v_mfma_f32_16x16x32_f16 v[128:131], v[168:171], v[200:203], v[128:131]
	s_setprio 2
	s_barrier
	v_mfma_f32_16x16x32_f16 v[124:127], v[160:163], v[200:203], v[124:127]
	v_mfma_f32_16x16x32_f16 v[124:127], v[156:159], v[196:199], v[124:127]
	s_setprio 0
	s_add_i32 s29, 0, 0x18000
	v_add_u32_e32 v135, s29, v147
	s_add_i32 s44, 0, 0x1c000
	ds_read_b128 v[138:141], v135
	ds_read_b128 v[142:145], v135 offset:1024
	ds_read_b128 v[148:151], v135 offset:2048
	ds_read_b128 v[152:155], v135 offset:3072
	v_add_u32_e32 v135, s44, v147
	ds_read_b128 v[156:159], v135
	ds_read_b128 v[160:163], v135 offset:1024
	ds_read_b128 v[164:167], v135 offset:2048
	ds_read_b128 v[168:171], v135 offset:3072
	s_add_u32 s16, s16, 0x80000
	s_addc_u32 s17, s17, 0
	s_mov_b32 m0, s65
	ds_read_b128 v[172:175], v212 offset:32768
	ds_read_b128 v[176:179], v212 offset:33792
	ds_read_b128 v[180:183], v212 offset:34816
	ds_read_b128 v[184:187], v212 offset:35840
	ds_read_b128 v[188:191], v212 offset:36864
	ds_read_b128 v[192:195], v212 offset:37888
	ds_read_b128 v[196:199], v212 offset:38912
	ds_read_b128 v[200:203], v212 offset:39936
	global_load_lds_dwordx4 v2, s[16:17]
	s_mov_b32 m0, s66
	s_nop 0
	global_load_lds_dwordx4 v132, s[16:17]
	s_waitcnt vmcnt(8)
	s_waitcnt lgkmcnt(0)
	s_barrier
	s_setprio 1
	s_waitcnt lgkmcnt(0)
	v_mfma_f32_16x16x32_f16 v[4:7], v[138:141], v[172:175], v[4:7]
	v_mfma_f32_16x16x32_f16 v[4:7], v[142:145], v[176:179], v[4:7]
	v_mfma_f32_16x16x32_f16 v[8:11], v[152:155], v[176:179], v[8:11]
	v_mfma_f32_16x16x32_f16 v[8:11], v[148:151], v[172:175], v[8:11]
	v_mfma_f32_16x16x32_f16 v[16:19], v[148:151], v[180:183], v[16:19]
	v_mfma_f32_16x16x32_f16 v[16:19], v[152:155], v[184:187], v[16:19]
	v_mfma_f32_16x16x32_f16 v[12:15], v[142:145], v[184:187], v[12:15]
	v_mfma_f32_16x16x32_f16 v[12:15], v[138:141], v[180:183], v[12:15]
	s_setprio 0
	s_setprio 1
	v_mfma_f32_16x16x32_f16 v[20:23], v[138:141], v[188:191], v[20:23]
	v_mfma_f32_16x16x32_f16 v[20:23], v[142:145], v[192:195], v[20:23]
	v_mfma_f32_16x16x32_f16 v[24:27], v[152:155], v[192:195], v[24:27]
	v_mfma_f32_16x16x32_f16 v[24:27], v[148:151], v[188:191], v[24:27]
	v_mfma_f32_16x16x32_f16 v[32:35], v[148:151], v[196:199], v[32:35]
	v_mfma_f32_16x16x32_f16 v[32:35], v[152:155], v[200:203], v[32:35]
	v_mfma_f32_16x16x32_f16 v[28:31], v[142:145], v[200:203], v[28:31]
	v_mfma_f32_16x16x32_f16 v[28:31], v[138:141], v[196:199], v[28:31]
	s_setprio 0
	s_setprio 1
	v_mfma_f32_16x16x32_f16 v[36:39], v[156:159], v[172:175], v[36:39]
	v_mfma_f32_16x16x32_f16 v[36:39], v[160:163], v[176:179], v[36:39]
	v_mfma_f32_16x16x32_f16 v[40:43], v[168:171], v[176:179], v[40:43]
	v_mfma_f32_16x16x32_f16 v[40:43], v[164:167], v[172:175], v[40:43]
	v_mfma_f32_16x16x32_f16 v[48:51], v[164:167], v[180:183], v[48:51]
	v_mfma_f32_16x16x32_f16 v[48:51], v[168:171], v[184:187], v[48:51]
	v_mfma_f32_16x16x32_f16 v[44:47], v[160:163], v[184:187], v[44:47]
	v_mfma_f32_16x16x32_f16 v[44:47], v[156:159], v[180:183], v[44:47]
	s_setprio 0
	s_setprio 1
	v_mfma_f32_16x16x32_f16 v[52:55], v[156:159], v[188:191], v[52:55]
	v_mfma_f32_16x16x32_f16 v[52:55], v[160:163], v[192:195], v[52:55]
	v_mfma_f32_16x16x32_f16 v[56:59], v[168:171], v[192:195], v[56:59]
	v_mfma_f32_16x16x32_f16 v[56:59], v[164:167], v[188:191], v[56:59]
	v_mfma_f32_16x16x32_f16 v[64:67], v[164:167], v[196:199], v[64:67]
	v_mfma_f32_16x16x32_f16 v[64:67], v[168:171], v[200:203], v[64:67]
	s_setprio 2
	s_barrier
	v_mfma_f32_16x16x32_f16 v[60:63], v[160:163], v[200:203], v[60:63]
	v_mfma_f32_16x16x32_f16 v[60:63], v[156:159], v[196:199], v[60:63]
	s_setprio 0
	s_add_i32 s16, s29, s62
	v_lshl_add_u64 v[204:205], v[204:205], 0, s[86:87]
	s_mov_b32 m0, s16
	ds_read_b128 v[172:175], v212 offset:49152
	ds_read_b128 v[176:179], v212 offset:50176
	ds_read_b128 v[180:183], v212 offset:51200
	ds_read_b128 v[184:187], v212 offset:52224
	ds_read_b128 v[188:191], v212 offset:53248
	ds_read_b128 v[192:195], v212 offset:54272
	ds_read_b128 v[196:199], v212 offset:55296
	ds_read_b128 v[200:203], v212 offset:56320
	global_load_lds_dwordx4 v[204:205], off
	s_add_i32 m0, s16, 0x2000
	s_add_u32 s6, s6, 0x80080
	v_lshl_add_u64 v[204:205], v[206:207], 0, s[86:87]
	s_addc_u32 s7, s7, 0
	s_add_i32 s16, s44, s62
	global_load_lds_dwordx4 v[204:205], off
	s_mov_b32 m0, s16
	v_lshl_add_u64 v[204:205], v[208:209], 0, s[86:87]
	global_load_lds_dwordx4 v136, s[6:7]
	s_add_i32 m0, s16, 0x2000
	s_nop 0
	global_load_lds_dwordx4 v134, s[6:7]
	s_mov_b32 m0, s69
	s_nop 0
	global_load_lds_dwordx4 v[204:205], off
	v_lshl_add_u64 v[204:205], v[210:211], 0, s[86:87]
	s_mov_b32 m0, s70
	s_nop 0
	global_load_lds_dwordx4 v[204:205], off
	s_waitcnt vmcnt(8)
	s_waitcnt lgkmcnt(0)
	s_barrier
	s_setprio 1
	s_waitcnt lgkmcnt(0)
	v_mfma_f32_16x16x32_f16 v[68:71], v[138:141], v[172:175], v[68:71]
	v_mfma_f32_16x16x32_f16 v[68:71], v[142:145], v[176:179], v[68:71]
	v_mfma_f32_16x16x32_f16 v[72:75], v[152:155], v[176:179], v[72:75]
	v_mfma_f32_16x16x32_f16 v[72:75], v[148:151], v[172:175], v[72:75]
	v_mfma_f32_16x16x32_f16 v[80:83], v[148:151], v[180:183], v[80:83]
	v_mfma_f32_16x16x32_f16 v[80:83], v[152:155], v[184:187], v[80:83]
	v_mfma_f32_16x16x32_f16 v[76:79], v[142:145], v[184:187], v[76:79]
	v_mfma_f32_16x16x32_f16 v[76:79], v[138:141], v[180:183], v[76:79]
	s_setprio 0
	s_setprio 1
	v_mfma_f32_16x16x32_f16 v[84:87], v[138:141], v[188:191], v[84:87]
	v_mfma_f32_16x16x32_f16 v[84:87], v[142:145], v[192:195], v[84:87]
	v_mfma_f32_16x16x32_f16 v[88:91], v[152:155], v[192:195], v[88:91]
	v_mfma_f32_16x16x32_f16 v[88:91], v[148:151], v[188:191], v[88:91]
	v_mfma_f32_16x16x32_f16 v[96:99], v[148:151], v[196:199], v[96:99]
	v_mfma_f32_16x16x32_f16 v[96:99], v[152:155], v[200:203], v[96:99]
	v_mfma_f32_16x16x32_f16 v[92:95], v[142:145], v[200:203], v[92:95]
	v_mfma_f32_16x16x32_f16 v[92:95], v[138:141], v[196:199], v[92:95]
	s_setprio 0
	s_setprio 1
	v_mfma_f32_16x16x32_f16 v[100:103], v[156:159], v[172:175], v[100:103]
	v_mfma_f32_16x16x32_f16 v[100:103], v[160:163], v[176:179], v[100:103]
	v_mfma_f32_16x16x32_f16 v[104:107], v[168:171], v[176:179], v[104:107]
	v_mfma_f32_16x16x32_f16 v[104:107], v[164:167], v[172:175], v[104:107]
	v_mfma_f32_16x16x32_f16 v[112:115], v[164:167], v[180:183], v[112:115]
	v_mfma_f32_16x16x32_f16 v[112:115], v[168:171], v[184:187], v[112:115]
	v_mfma_f32_16x16x32_f16 v[108:111], v[160:163], v[184:187], v[108:111]
	v_mfma_f32_16x16x32_f16 v[108:111], v[156:159], v[180:183], v[108:111]
	s_setprio 0
	s_setprio 1
	v_mfma_f32_16x16x32_f16 v[116:119], v[156:159], v[188:191], v[116:119]
	v_mfma_f32_16x16x32_f16 v[116:119], v[160:163], v[192:195], v[116:119]
	v_mfma_f32_16x16x32_f16 v[120:123], v[168:171], v[192:195], v[120:123]
	v_mfma_f32_16x16x32_f16 v[120:123], v[164:167], v[188:191], v[120:123]
	v_mfma_f32_16x16x32_f16 v[128:131], v[164:167], v[196:199], v[128:131]
	v_mfma_f32_16x16x32_f16 v[128:131], v[168:171], v[200:203], v[128:131]
	s_setprio 2
	s_barrier
	v_mfma_f32_16x16x32_f16 v[124:127], v[160:163], v[200:203], v[124:127]
	v_mfma_f32_16x16x32_f16 v[124:127], v[156:159], v[196:199], v[124:127]
	s_setprio 0
	s_add_i32 s28, s28, 2
	s_add_u32 s8, s8, 0x100
	s_addc_u32 s9, s9, 0
	s_add_u32 s26, s26, 0x100
	s_addc_u32 s27, s27, 0
	s_cmp_gt_u32 s28, 29
	s_cbranch_scc0 .LBB0_753
	s_and_b64 vcc, exec, s[52:53]
	s_cbranch_vccz .LBB0_756
	s_barrier

.LBB0_1175:
	s_add_i32 s61, 0, 0x10000
	s_add_i32 s79, 0, 0x14000
	v_add_u32_e32 v16, s61, v209
	v_add_u32_e32 v32, s79, v209
	ds_read_b128 v[4:7], v16
	ds_read_b128 v[8:11], v16 offset:1024
	ds_read_b128 v[12:15], v16 offset:2048
	ds_read_b128 v[16:19], v16 offset:3072
	ds_read_b128 v[20:23], v32
	ds_read_b128 v[24:27], v32 offset:1024
	ds_read_b128 v[28:31], v32 offset:2048
	ds_read_b128 v[32:35], v32 offset:3072
	v_add_u32_e32 v231, 0, v208
	ds_read_b128 v[36:39], v231
	ds_read_b128 v[40:43], v231 offset:1024
	ds_read_b128 v[44:47], v231 offset:2048
	ds_read_b128 v[48:51], v231 offset:3072
	ds_read_b128 v[52:55], v231 offset:4096
	ds_read_b128 v[56:59], v231 offset:5120
	ds_read_b128 v[60:63], v231 offset:6144
	ds_read_b128 v[64:67], v231 offset:7168
	s_waitcnt vmcnt(8)
	s_waitcnt lgkmcnt(0)
	s_barrier
	s_setprio 1
	s_waitcnt lgkmcnt(0)
	v_mfma_f32_16x16x32_bf16 v[68:71], v[4:7], v[36:39], 0
	v_mfma_f32_16x16x32_bf16 v[68:71], v[8:11], v[40:43], v[68:71]
	v_mfma_f32_16x16x32_bf16 v[72:75], v[12:15], v[36:39], 0
	v_mfma_f32_16x16x32_bf16 v[72:75], v[16:19], v[40:43], v[72:75]
	v_mfma_f32_16x16x32_bf16 v[80:83], v[12:15], v[44:47], 0
	v_mfma_f32_16x16x32_bf16 v[80:83], v[16:19], v[48:51], v[80:83]
	v_mfma_f32_16x16x32_bf16 v[76:79], v[4:7], v[44:47], 0
	v_mfma_f32_16x16x32_bf16 v[76:79], v[8:11], v[48:51], v[76:79]
	s_setprio 0
	s_setprio 1
	v_mfma_f32_16x16x32_bf16 v[84:87], v[4:7], v[52:55], 0
	v_mfma_f32_16x16x32_bf16 v[84:87], v[8:11], v[56:59], v[84:87]
	v_mfma_f32_16x16x32_bf16 v[88:91], v[12:15], v[52:55], 0
	v_mfma_f32_16x16x32_bf16 v[88:91], v[16:19], v[56:59], v[88:91]
	v_mfma_f32_16x16x32_bf16 v[96:99], v[12:15], v[60:63], 0
	v_mfma_f32_16x16x32_bf16 v[96:99], v[16:19], v[64:67], v[96:99]
	v_mfma_f32_16x16x32_bf16 v[92:95], v[4:7], v[60:63], 0
	v_mfma_f32_16x16x32_bf16 v[92:95], v[8:11], v[64:67], v[92:95]
	s_setprio 0
	s_setprio 1
	v_mfma_f32_16x16x32_bf16 v[100:103], v[20:23], v[36:39], 0
	v_mfma_f32_16x16x32_bf16 v[36:39], v[28:31], v[36:39], 0
	v_mfma_f32_16x16x32_bf16 v[104:107], v[20:23], v[44:47], 0
	v_mfma_f32_16x16x32_bf16 v[44:47], v[28:31], v[44:47], 0
	v_mfma_f32_16x16x32_bf16 v[108:111], v[20:23], v[52:55], 0
	v_mfma_f32_16x16x32_bf16 v[52:55], v[28:31], v[52:55], 0
	v_mfma_f32_16x16x32_bf16 v[112:115], v[20:23], v[60:63], 0
	v_mfma_f32_16x16x32_bf16 v[60:63], v[28:31], v[60:63], 0
	s_setprio 0
	s_setprio 1
	v_mfma_f32_16x16x32_bf16 v[100:103], v[24:27], v[40:43], v[100:103]
	v_mfma_f32_16x16x32_bf16 v[40:43], v[32:35], v[40:43], v[36:39]
	v_mfma_f32_16x16x32_bf16 v[104:107], v[24:27], v[48:51], v[104:107]
	v_mfma_f32_16x16x32_bf16 v[48:51], v[32:35], v[48:51], v[44:47]
	v_mfma_f32_16x16x32_bf16 v[108:111], v[24:27], v[56:59], v[108:111]
	v_mfma_f32_16x16x32_bf16 v[56:59], v[32:35], v[56:59], v[52:55]
	s_setprio 2
	s_barrier
	v_mfma_f32_16x16x32_bf16 v[112:115], v[24:27], v[64:67], v[112:115]
	v_mfma_f32_16x16x32_bf16 v[64:67], v[32:35], v[64:67], v[60:63]
	s_setprio 0
	v_lshl_add_u64 v[186:187], s[12:13], 0, v[2:3]
	s_add_i32 s61, s61, s36
	v_mov_b32_e32 v191, v3
	v_lshl_add_u64 v[134:135], v[186:187], 0, s[74:75]
	s_mov_b32 m0, s61
	v_lshl_add_u64 v[226:227], s[12:13], 0, v[190:191]
	ds_read_b128 v[36:39], v231 offset:16384
	ds_read_b128 v[44:47], v231 offset:17408
	ds_read_b128 v[52:55], v231 offset:18432
	ds_read_b128 v[60:63], v231 offset:19456
	ds_read_b128 v[116:119], v231 offset:20480
	ds_read_b128 v[120:123], v231 offset:21504
	ds_read_b128 v[124:127], v231 offset:22528
	ds_read_b128 v[128:131], v231 offset:23552
	global_load_lds_dwordx4 v[134:135], off
	v_lshl_add_u64 v[134:135], v[226:227], 0, s[74:75]
	s_add_i32 m0, s61, 0x2000
	s_add_i32 s61, s79, s36
	global_load_lds_dwordx4 v[134:135], off
	s_mov_b32 m0, s61
	v_mov_b32_e32 v133, v3
	global_load_lds_dwordx4 v2, s[16:17]
	s_add_i32 m0, s61, 0x2000
	v_lshl_add_u64 v[248:249], s[6:7], 0, v[132:133]
	v_mov_b32_e32 v189, v3
	global_load_lds_dwordx4 v190, s[16:17]
	v_lshl_add_u64 v[134:135], v[248:249], 0, s[74:75]
	s_mov_b32 m0, s37
	v_lshl_add_u64 v[250:251], s[6:7], 0, v[188:189]
	global_load_lds_dwordx4 v[134:135], off
	v_lshl_add_u64 v[134:135], v[250:251], 0, s[74:75]
	s_mov_b32 m0, s66
	s_nop 0
	global_load_lds_dwordx4 v[134:135], off
	s_waitcnt vmcnt(8)
	s_waitcnt lgkmcnt(0)
	s_barrier
	s_setprio 1
	s_waitcnt lgkmcnt(0)
	v_mfma_f32_16x16x32_bf16 v[134:137], v[4:7], v[36:39], 0
	v_mfma_f32_16x16x32_bf16 v[138:141], v[12:15], v[36:39], 0
	v_mfma_f32_16x16x32_bf16 v[142:145], v[4:7], v[52:55], 0
	v_mfma_f32_16x16x32_bf16 v[146:149], v[12:15], v[52:55], 0
	v_mfma_f32_16x16x32_bf16 v[150:153], v[4:7], v[116:119], 0
	v_mfma_f32_16x16x32_bf16 v[154:157], v[12:15], v[116:119], 0
	v_mfma_f32_16x16x32_bf16 v[4:7], v[4:7], v[124:127], 0
	v_mfma_f32_16x16x32_bf16 v[12:15], v[12:15], v[124:127], 0
	s_setprio 0
	s_setprio 1
	v_mfma_f32_16x16x32_bf16 v[134:137], v[8:11], v[44:47], v[134:137]
	v_mfma_f32_16x16x32_bf16 v[138:141], v[16:19], v[44:47], v[138:141]
	v_mfma_f32_16x16x32_bf16 v[142:145], v[8:11], v[60:63], v[142:145]
	v_mfma_f32_16x16x32_bf16 v[146:149], v[16:19], v[60:63], v[146:149]
	v_mfma_f32_16x16x32_bf16 v[150:153], v[8:11], v[120:123], v[150:153]
	v_mfma_f32_16x16x32_bf16 v[154:157], v[16:19], v[120:123], v[154:157]
	v_mfma_f32_16x16x32_bf16 v[158:161], v[8:11], v[128:131], v[4:7]
	v_mfma_f32_16x16x32_bf16 v[162:165], v[16:19], v[128:131], v[12:15]
	s_setprio 0
	s_setprio 1
	v_mfma_f32_16x16x32_bf16 v[4:7], v[20:23], v[36:39], 0
	v_mfma_f32_16x16x32_bf16 v[8:11], v[28:31], v[36:39], 0
	v_mfma_f32_16x16x32_bf16 v[12:15], v[20:23], v[52:55], 0
	v_mfma_f32_16x16x32_bf16 v[16:19], v[28:31], v[52:55], 0
	v_mfma_f32_16x16x32_bf16 v[36:39], v[20:23], v[116:119], 0
	v_mfma_f32_16x16x32_bf16 v[52:55], v[28:31], v[116:119], 0
	v_mfma_f32_16x16x32_bf16 v[20:23], v[20:23], v[124:127], 0
	v_mfma_f32_16x16x32_bf16 v[28:31], v[28:31], v[124:127], 0
	s_setprio 0
	s_setprio 1
	v_mfma_f32_16x16x32_bf16 v[116:119], v[24:27], v[44:47], v[4:7]
	v_mfma_f32_16x16x32_bf16 v[124:127], v[32:35], v[44:47], v[8:11]
	v_mfma_f32_16x16x32_bf16 v[174:177], v[24:27], v[120:123], v[36:39]
	v_mfma_f32_16x16x32_bf16 v[120:123], v[32:35], v[120:123], v[52:55]
	v_mfma_f32_16x16x32_bf16 v[178:181], v[24:27], v[128:131], v[20:23]
	v_mfma_f32_16x16x32_bf16 v[128:131], v[32:35], v[128:131], v[28:31]
	s_setprio 2
	s_barrier
	v_mfma_f32_16x16x32_bf16 v[166:169], v[24:27], v[60:63], v[12:15]
	v_mfma_f32_16x16x32_bf16 v[170:173], v[32:35], v[60:63], v[16:19]
	s_setprio 0
	s_add_i32 s61, 0, 0x18000
	v_add_u32_e32 v4, s61, v209
	s_add_i32 s79, 0, 0x1c000
	ds_read_b128 v[182:185], v4
	ds_read_b128 v[192:195], v4 offset:1024
	ds_read_b128 v[196:199], v4 offset:2048
	ds_read_b128 v[200:203], v4 offset:3072
	v_add_u32_e32 v4, s79, v209
	ds_read_b128 v[204:207], v4
	ds_read_b128 v[210:213], v4 offset:1024
	ds_read_b128 v[214:217], v4 offset:2048
	ds_read_b128 v[218:221], v4 offset:3072
	s_mov_b32 m0, s67
	ds_read_b128 v[44:47], v231 offset:32768
	ds_read_b128 v[52:55], v231 offset:33792
	ds_read_b128 v[60:63], v231 offset:34816
	ds_read_b128 v[222:225], v231 offset:35840
	ds_read_b128 v[232:235], v231 offset:36864
	ds_read_b128 v[236:239], v231 offset:37888
	ds_read_b128 v[240:243], v231 offset:38912
	ds_read_b128 v[244:247], v231 offset:39936
	global_load_lds_dwordx4 v132, s[26:27]
	s_mov_b32 m0, s68
	s_nop 0
	global_load_lds_dwordx4 v188, s[26:27]
	s_waitcnt vmcnt(8)
	s_waitcnt lgkmcnt(0)
	s_barrier
	s_setprio 1
	s_waitcnt lgkmcnt(0)
	v_mfma_f32_16x16x32_bf16 v[4:7], v[182:185], v[44:47], v[68:71]
	v_mfma_f32_16x16x32_bf16 v[8:11], v[196:199], v[44:47], v[72:75]
	v_mfma_f32_16x16x32_bf16 v[12:15], v[182:185], v[60:63], v[76:79]
	v_mfma_f32_16x16x32_bf16 v[16:19], v[196:199], v[60:63], v[80:83]
	v_mfma_f32_16x16x32_bf16 v[20:23], v[182:185], v[232:235], v[84:87]
	v_mfma_f32_16x16x32_bf16 v[24:27], v[196:199], v[232:235], v[88:91]
	v_mfma_f32_16x16x32_bf16 v[28:31], v[182:185], v[240:243], v[92:95]
	v_mfma_f32_16x16x32_bf16 v[32:35], v[196:199], v[240:243], v[96:99]
	s_setprio 0
	s_setprio 1
	v_mfma_f32_16x16x32_bf16 v[4:7], v[192:195], v[52:55], v[4:7]
	v_mfma_f32_16x16x32_bf16 v[8:11], v[200:203], v[52:55], v[8:11]
	v_mfma_f32_16x16x32_bf16 v[12:15], v[192:195], v[222:225], v[12:15]
	v_mfma_f32_16x16x32_bf16 v[16:19], v[200:203], v[222:225], v[16:19]
	v_mfma_f32_16x16x32_bf16 v[20:23], v[192:195], v[236:239], v[20:23]
	v_mfma_f32_16x16x32_bf16 v[24:27], v[200:203], v[236:239], v[24:27]
	v_mfma_f32_16x16x32_bf16 v[28:31], v[192:195], v[244:247], v[28:31]
	v_mfma_f32_16x16x32_bf16 v[32:35], v[200:203], v[244:247], v[32:35]
	s_setprio 0
	s_setprio 1
	v_mfma_f32_16x16x32_bf16 v[36:39], v[204:207], v[44:47], v[100:103]
	v_mfma_f32_16x16x32_bf16 v[40:43], v[214:217], v[44:47], v[40:43]
	v_mfma_f32_16x16x32_bf16 v[36:39], v[210:213], v[52:55], v[36:39]
	v_mfma_f32_16x16x32_bf16 v[40:43], v[218:221], v[52:55], v[40:43]
	v_mfma_f32_16x16x32_bf16 v[44:47], v[204:207], v[60:63], v[104:107]
	v_mfma_f32_16x16x32_bf16 v[48:51], v[214:217], v[60:63], v[48:51]
	v_mfma_f32_16x16x32_bf16 v[52:55], v[204:207], v[232:235], v[108:111]
	v_mfma_f32_16x16x32_bf16 v[56:59], v[214:217], v[232:235], v[56:59]
	s_setprio 0
	s_setprio 1
	v_mfma_f32_16x16x32_bf16 v[60:63], v[204:207], v[240:243], v[112:115]
	v_mfma_f32_16x16x32_bf16 v[64:67], v[214:217], v[240:243], v[64:67]
	v_mfma_f32_16x16x32_bf16 v[44:47], v[210:213], v[222:225], v[44:47]
	v_mfma_f32_16x16x32_bf16 v[48:51], v[218:221], v[222:225], v[48:51]
	v_mfma_f32_16x16x32_bf16 v[52:55], v[210:213], v[236:239], v[52:55]
	v_mfma_f32_16x16x32_bf16 v[56:59], v[218:221], v[236:239], v[56:59]
	s_setprio 2
	s_barrier
	v_mfma_f32_16x16x32_bf16 v[60:63], v[210:213], v[244:247], v[60:63]
	v_mfma_f32_16x16x32_bf16 v[64:67], v[218:221], v[244:247], v[64:67]
	s_setprio 0
	s_add_i32 s61, s61, s36
	v_lshl_add_u64 v[68:69], v[186:187], 0, s[24:25]
	s_mov_b32 m0, s61
	ds_read_b128 v[104:107], v231 offset:49152
	ds_read_b128 v[108:111], v231 offset:50176
	ds_read_b128 v[112:115], v231 offset:51200
	ds_read_b128 v[222:225], v231 offset:52224
	ds_read_b128 v[232:235], v231 offset:53248
	ds_read_b128 v[236:239], v231 offset:54272
	ds_read_b128 v[240:243], v231 offset:55296
	ds_read_b128 v[244:247], v231 offset:56320
	global_load_lds_dwordx4 v[68:69], off
	v_lshl_add_u64 v[68:69], v[226:227], 0, s[24:25]
	s_add_i32 m0, s61, 0x2000
	s_add_i32 s61, s79, s36
	global_load_lds_dwordx4 v[68:69], off
	s_mov_b32 m0, s61
	v_lshl_add_u64 v[68:69], v[248:249], 0, s[24:25]
	global_load_lds_dwordx4 v2, s[28:29]
	s_add_i32 m0, s61, 0x2000
	s_nop 0
	global_load_lds_dwordx4 v190, s[28:29]
	s_mov_b32 m0, s71
	s_nop 0
	global_load_lds_dwordx4 v[68:69], off
	v_lshl_add_u64 v[68:69], v[250:251], 0, s[24:25]
	s_mov_b32 m0, s72
	s_nop 0
	global_load_lds_dwordx4 v[68:69], off
	s_waitcnt vmcnt(8)
	s_waitcnt lgkmcnt(0)
	s_barrier
	s_setprio 1
	s_waitcnt lgkmcnt(0)
	v_mfma_f32_16x16x32_bf16 v[68:71], v[182:185], v[104:107], v[134:137]
	v_mfma_f32_16x16x32_bf16 v[72:75], v[196:199], v[104:107], v[138:141]
	v_mfma_f32_16x16x32_bf16 v[76:79], v[182:185], v[112:115], v[142:145]
	v_mfma_f32_16x16x32_bf16 v[80:83], v[196:199], v[112:115], v[146:149]
	v_mfma_f32_16x16x32_bf16 v[84:87], v[182:185], v[232:235], v[150:153]
	v_mfma_f32_16x16x32_bf16 v[88:91], v[196:199], v[232:235], v[154:157]
	v_mfma_f32_16x16x32_bf16 v[92:95], v[182:185], v[240:243], v[158:161]
	v_mfma_f32_16x16x32_bf16 v[96:99], v[196:199], v[240:243], v[162:165]
	s_setprio 0
	s_setprio 1
	v_mfma_f32_16x16x32_bf16 v[68:71], v[192:195], v[108:111], v[68:71]
	v_mfma_f32_16x16x32_bf16 v[72:75], v[200:203], v[108:111], v[72:75]
	v_mfma_f32_16x16x32_bf16 v[76:79], v[192:195], v[222:225], v[76:79]
	v_mfma_f32_16x16x32_bf16 v[80:83], v[200:203], v[222:225], v[80:83]
	v_mfma_f32_16x16x32_bf16 v[84:87], v[192:195], v[236:239], v[84:87]
	v_mfma_f32_16x16x32_bf16 v[88:91], v[200:203], v[236:239], v[88:91]
	v_mfma_f32_16x16x32_bf16 v[92:95], v[192:195], v[244:247], v[92:95]
	v_mfma_f32_16x16x32_bf16 v[96:99], v[200:203], v[244:247], v[96:99]
	s_setprio 0
	s_setprio 1
	v_mfma_f32_16x16x32_bf16 v[100:103], v[204:207], v[104:107], v[116:119]
	v_mfma_f32_16x16x32_bf16 v[104:107], v[214:217], v[104:107], v[124:127]
	v_mfma_f32_16x16x32_bf16 v[100:103], v[210:213], v[108:111], v[100:103]
	v_mfma_f32_16x16x32_bf16 v[104:107], v[218:221], v[108:111], v[104:107]
	v_mfma_f32_16x16x32_bf16 v[108:111], v[204:207], v[112:115], v[166:169]
	v_mfma_f32_16x16x32_bf16 v[112:115], v[214:217], v[112:115], v[170:173]
	v_mfma_f32_16x16x32_bf16 v[116:119], v[204:207], v[232:235], v[174:177]
	v_mfma_f32_16x16x32_bf16 v[120:123], v[214:217], v[232:235], v[120:123]
	s_setprio 0
	s_setprio 1
	v_mfma_f32_16x16x32_bf16 v[124:127], v[204:207], v[240:243], v[178:181]
	v_mfma_f32_16x16x32_bf16 v[128:131], v[214:217], v[240:243], v[128:131]
	v_mfma_f32_16x16x32_bf16 v[108:111], v[210:213], v[222:225], v[108:111]
	v_mfma_f32_16x16x32_bf16 v[112:115], v[218:221], v[222:225], v[112:115]
	v_mfma_f32_16x16x32_bf16 v[116:119], v[210:213], v[236:239], v[116:119]
	v_mfma_f32_16x16x32_bf16 v[120:123], v[218:221], v[236:239], v[120:123]
	s_setprio 2
	s_barrier
	v_mfma_f32_16x16x32_bf16 v[124:127], v[210:213], v[244:247], v[124:127]
	v_mfma_f32_16x16x32_bf16 v[128:131], v[218:221], v[244:247], v[128:131]
	s_setprio 0
	s_add_i32 s43, s43, 2
	s_cmp_ge_i32 s43, s42
	s_cbranch_scc0 .LBB0_1175
.LBB0_1176:
	s_add_i32 s12, 0, 0x10000
	s_add_i32 s13, 0, 0x14000
	v_mov_b32_e32 v192, v2
	v_mov_b32_e32 v2, v132
	v_add_u32_e32 v144, s12, v209
	v_add_u32_e32 v160, s13, v209
	ds_read_b128 v[132:135], v144
	ds_read_b128 v[136:139], v144 offset:1024
	ds_read_b128 v[140:143], v144 offset:2048
	ds_read_b128 v[144:147], v144 offset:3072
	ds_read_b128 v[148:151], v160
	ds_read_b128 v[152:155], v160 offset:1024
	ds_read_b128 v[156:159], v160 offset:2048
	ds_read_b128 v[160:163], v160 offset:3072
	s_add_u32 s6, s6, 0x80180
	s_mov_b32 m0, s73
	v_add_u32_e32 v212, 0, v208
	s_addc_u32 s7, s7, 0
	ds_read_b128 v[164:167], v212
	ds_read_b128 v[168:171], v212 offset:1024
	ds_read_b128 v[172:175], v212 offset:2048
	ds_read_b128 v[176:179], v212 offset:3072
	ds_read_b128 v[180:183], v212 offset:4096
	ds_read_b128 v[184:187], v212 offset:5120
	ds_read_b128 v[194:197], v212 offset:6144
	ds_read_b128 v[198:201], v212 offset:7168
	global_load_lds_dwordx4 v2, s[6:7]
	s_mov_b32 m0, s76
	v_mov_b32_e32 v189, v3
	global_load_lds_dwordx4 v188, s[6:7]
	s_waitcnt vmcnt(8)
	s_waitcnt lgkmcnt(0)
	s_barrier
	s_setprio 1
	s_waitcnt lgkmcnt(0)
	v_mfma_f32_16x16x32_bf16 v[4:7], v[132:135], v[164:167], v[4:7]
	v_mfma_f32_16x16x32_bf16 v[4:7], v[136:139], v[168:171], v[4:7]
	v_mfma_f32_16x16x32_bf16 v[8:11], v[144:147], v[168:171], v[8:11]
	v_mfma_f32_16x16x32_bf16 v[8:11], v[140:143], v[164:167], v[8:11]
	v_mfma_f32_16x16x32_bf16 v[16:19], v[140:143], v[172:175], v[16:19]
	v_mfma_f32_16x16x32_bf16 v[16:19], v[144:147], v[176:179], v[16:19]
	v_mfma_f32_16x16x32_bf16 v[12:15], v[136:139], v[176:179], v[12:15]
	v_mfma_f32_16x16x32_bf16 v[12:15], v[132:135], v[172:175], v[12:15]
	s_setprio 0
	s_setprio 1
	v_mfma_f32_16x16x32_bf16 v[20:23], v[132:135], v[180:183], v[20:23]
	v_mfma_f32_16x16x32_bf16 v[20:23], v[136:139], v[184:187], v[20:23]
	v_mfma_f32_16x16x32_bf16 v[24:27], v[144:147], v[184:187], v[24:27]
	v_mfma_f32_16x16x32_bf16 v[24:27], v[140:143], v[180:183], v[24:27]
	v_mfma_f32_16x16x32_bf16 v[32:35], v[140:143], v[194:197], v[32:35]
	v_mfma_f32_16x16x32_bf16 v[32:35], v[144:147], v[198:201], v[32:35]
	v_mfma_f32_16x16x32_bf16 v[28:31], v[136:139], v[198:201], v[28:31]
	v_mfma_f32_16x16x32_bf16 v[28:31], v[132:135], v[194:197], v[28:31]
	s_setprio 0
	s_setprio 1
	v_mfma_f32_16x16x32_bf16 v[36:39], v[148:151], v[164:167], v[36:39]
	v_mfma_f32_16x16x32_bf16 v[36:39], v[152:155], v[168:171], v[36:39]
	v_mfma_f32_16x16x32_bf16 v[40:43], v[160:163], v[168:171], v[40:43]
	v_mfma_f32_16x16x32_bf16 v[40:43], v[156:159], v[164:167], v[40:43]
	v_mfma_f32_16x16x32_bf16 v[48:51], v[156:159], v[172:175], v[48:51]
	v_mfma_f32_16x16x32_bf16 v[48:51], v[160:163], v[176:179], v[48:51]
	v_mfma_f32_16x16x32_bf16 v[44:47], v[152:155], v[176:179], v[44:47]
	v_mfma_f32_16x16x32_bf16 v[44:47], v[148:151], v[172:175], v[44:47]
	s_setprio 0
	s_setprio 1
	v_mfma_f32_16x16x32_bf16 v[52:55], v[148:151], v[180:183], v[52:55]
	v_mfma_f32_16x16x32_bf16 v[52:55], v[152:155], v[184:187], v[52:55]
	v_mfma_f32_16x16x32_bf16 v[56:59], v[160:163], v[184:187], v[56:59]
	v_mfma_f32_16x16x32_bf16 v[56:59], v[156:159], v[180:183], v[56:59]
	v_mfma_f32_16x16x32_bf16 v[64:67], v[156:159], v[194:197], v[64:67]
	v_mfma_f32_16x16x32_bf16 v[64:67], v[160:163], v[198:201], v[64:67]
	s_setprio 2
	s_barrier
	v_mfma_f32_16x16x32_bf16 v[60:63], v[152:155], v[198:201], v[60:63]
	v_mfma_f32_16x16x32_bf16 v[60:63], v[148:151], v[194:197], v[60:63]
	s_setprio 0
	s_add_i32 s6, s12, s36
	s_mov_b32 m0, s6
	ds_read_b128 v[164:167], v212 offset:16384
	ds_read_b128 v[168:171], v212 offset:17408
	ds_read_b128 v[172:175], v212 offset:18432
	ds_read_b128 v[176:179], v212 offset:19456
	ds_read_b128 v[180:183], v212 offset:20480
	ds_read_b128 v[184:187], v212 offset:21504
	ds_read_b128 v[194:197], v212 offset:22528
	ds_read_b128 v[198:201], v212 offset:23552
	global_load_lds_dwordx4 v192, s[14:15]
	s_add_i32 m0, s6, 0x2000
	s_add_u32 s6, s14, 0x10000
	s_addc_u32 s7, s15, 0
	s_add_i32 s12, s13, s36
	global_load_lds_dwordx4 v190, s[14:15]
	s_mov_b32 m0, s12
	v_mov_b32_e32 v193, v3
	global_load_lds_dwordx4 v192, s[6:7]
	s_add_i32 m0, s12, 0x2000
	v_mov_b32_e32 v191, v3
	global_load_lds_dwordx4 v190, s[6:7]
	s_mov_b32 m0, s37
	v_lshl_add_u64 v[202:203], s[14:15], 0, v[192:193]
	global_load_lds_dwordx4 v2, s[10:11]
	s_mov_b32 m0, s66
	v_lshl_add_u64 v[204:205], s[14:15], 0, v[190:191]
	global_load_lds_dwordx4 v188, s[10:11]
	s_waitcnt vmcnt(8)
	s_waitcnt lgkmcnt(0)
	v_lshl_add_u64 v[206:207], s[10:11], 0, v[2:3]
	v_lshl_add_u64 v[210:211], s[10:11], 0, v[188:189]
	s_barrier
	s_setprio 1
	s_waitcnt lgkmcnt(0)
	v_mfma_f32_16x16x32_bf16 v[68:71], v[132:135], v[164:167], v[68:71]
	v_mfma_f32_16x16x32_bf16 v[68:71], v[136:139], v[168:171], v[68:71]
	v_mfma_f32_16x16x32_bf16 v[72:75], v[144:147], v[168:171], v[72:75]
	v_mfma_f32_16x16x32_bf16 v[72:75], v[140:143], v[164:167], v[72:75]
	v_mfma_f32_16x16x32_bf16 v[80:83], v[140:143], v[172:175], v[80:83]
	v_mfma_f32_16x16x32_bf16 v[80:83], v[144:147], v[176:179], v[80:83]
	v_mfma_f32_16x16x32_bf16 v[76:79], v[136:139], v[176:179], v[76:79]
	v_mfma_f32_16x16x32_bf16 v[76:79], v[132:135], v[172:175], v[76:79]
	s_setprio 0
	s_setprio 1
	v_mfma_f32_16x16x32_bf16 v[84:87], v[132:135], v[180:183], v[84:87]
	v_mfma_f32_16x16x32_bf16 v[84:87], v[136:139], v[184:187], v[84:87]
	v_mfma_f32_16x16x32_bf16 v[88:91], v[144:147], v[184:187], v[88:91]
	v_mfma_f32_16x16x32_bf16 v[88:91], v[140:143], v[180:183], v[88:91]
	v_mfma_f32_16x16x32_bf16 v[96:99], v[140:143], v[194:197], v[96:99]
	v_mfma_f32_16x16x32_bf16 v[96:99], v[144:147], v[198:201], v[96:99]
	v_mfma_f32_16x16x32_bf16 v[92:95], v[136:139], v[198:201], v[92:95]
	v_mfma_f32_16x16x32_bf16 v[92:95], v[132:135], v[194:197], v[92:95]
	s_setprio 0
	s_setprio 1
	v_mfma_f32_16x16x32_bf16 v[100:103], v[148:151], v[164:167], v[100:103]
	v_mfma_f32_16x16x32_bf16 v[100:103], v[152:155], v[168:171], v[100:103]
	v_mfma_f32_16x16x32_bf16 v[104:107], v[160:163], v[168:171], v[104:107]
	v_mfma_f32_16x16x32_bf16 v[104:107], v[156:159], v[164:167], v[104:107]
	v_mfma_f32_16x16x32_bf16 v[112:115], v[156:159], v[172:175], v[112:115]
	v_mfma_f32_16x16x32_bf16 v[112:115], v[160:163], v[176:179], v[112:115]
	v_mfma_f32_16x16x32_bf16 v[108:111], v[152:155], v[176:179], v[108:111]
	v_mfma_f32_16x16x32_bf16 v[108:111], v[148:151], v[172:175], v[108:111]
	s_setprio 0
	s_setprio 1
	v_mfma_f32_16x16x32_bf16 v[116:119], v[148:151], v[180:183], v[116:119]
	v_mfma_f32_16x16x32_bf16 v[116:119], v[152:155], v[184:187], v[116:119]
	v_mfma_f32_16x16x32_bf16 v[120:123], v[160:163], v[184:187], v[120:123]
	v_mfma_f32_16x16x32_bf16 v[120:123], v[156:159], v[180:183], v[120:123]
	v_mfma_f32_16x16x32_bf16 v[128:131], v[156:159], v[194:197], v[128:131]
	v_mfma_f32_16x16x32_bf16 v[128:131], v[160:163], v[198:201], v[128:131]
	s_setprio 2
	s_barrier
	v_mfma_f32_16x16x32_bf16 v[124:127], v[152:155], v[198:201], v[124:127]
	v_mfma_f32_16x16x32_bf16 v[124:127], v[148:151], v[194:197], v[124:127]
	s_setprio 0
	s_add_i32 s12, 0, 0x18000
	s_add_i32 s13, 0, 0x1c000
	v_add_u32_e32 v144, s12, v209
	v_add_u32_e32 v160, s13, v209
	ds_read_b128 v[132:135], v144
	ds_read_b128 v[136:139], v144 offset:1024
	ds_read_b128 v[140:143], v144 offset:2048
	ds_read_b128 v[144:147], v144 offset:3072
	ds_read_b128 v[148:151], v160
	ds_read_b128 v[152:155], v160 offset:1024
	ds_read_b128 v[156:159], v160 offset:2048
	ds_read_b128 v[160:163], v160 offset:3072
	s_add_u32 s6, s10, 0x80000
	s_addc_u32 s7, s11, 0
	s_mov_b32 m0, s67
	ds_read_b128 v[164:167], v212 offset:32768
	ds_read_b128 v[168:171], v212 offset:33792
	ds_read_b128 v[172:175], v212 offset:34816
	ds_read_b128 v[176:179], v212 offset:35840
	ds_read_b128 v[180:183], v212 offset:36864
	ds_read_b128 v[184:187], v212 offset:37888
	ds_read_b128 v[194:197], v212 offset:38912
	ds_read_b128 v[198:201], v212 offset:39936
	global_load_lds_dwordx4 v2, s[6:7]
	s_mov_b32 m0, s68
	s_nop 0
	global_load_lds_dwordx4 v188, s[6:7]
	s_waitcnt vmcnt(8)
	s_waitcnt lgkmcnt(0)
	s_barrier
	s_setprio 1
	s_waitcnt lgkmcnt(0)
	v_mfma_f32_16x16x32_bf16 v[4:7], v[132:135], v[164:167], v[4:7]
	v_mfma_f32_16x16x32_bf16 v[4:7], v[136:139], v[168:171], v[4:7]
	v_mfma_f32_16x16x32_bf16 v[8:11], v[144:147], v[168:171], v[8:11]
	v_mfma_f32_16x16x32_bf16 v[8:11], v[140:143], v[164:167], v[8:11]
	v_mfma_f32_16x16x32_bf16 v[16:19], v[140:143], v[172:175], v[16:19]
	v_mfma_f32_16x16x32_bf16 v[16:19], v[144:147], v[176:179], v[16:19]
	v_mfma_f32_16x16x32_bf16 v[12:15], v[136:139], v[176:179], v[12:15]
	v_mfma_f32_16x16x32_bf16 v[12:15], v[132:135], v[172:175], v[12:15]
	s_setprio 0
	s_setprio 1
	v_mfma_f32_16x16x32_bf16 v[20:23], v[132:135], v[180:183], v[20:23]
	v_mfma_f32_16x16x32_bf16 v[20:23], v[136:139], v[184:187], v[20:23]
	v_mfma_f32_16x16x32_bf16 v[24:27], v[144:147], v[184:187], v[24:27]
	v_mfma_f32_16x16x32_bf16 v[24:27], v[140:143], v[180:183], v[24:27]
	v_mfma_f32_16x16x32_bf16 v[32:35], v[140:143], v[194:197], v[32:35]
	v_mfma_f32_16x16x32_bf16 v[32:35], v[144:147], v[198:201], v[32:35]
	v_mfma_f32_16x16x32_bf16 v[28:31], v[136:139], v[198:201], v[28:31]
	v_mfma_f32_16x16x32_bf16 v[28:31], v[132:135], v[194:197], v[28:31]
	s_setprio 0
	s_setprio 1
	v_mfma_f32_16x16x32_bf16 v[36:39], v[148:151], v[164:167], v[36:39]
	v_mfma_f32_16x16x32_bf16 v[36:39], v[152:155], v[168:171], v[36:39]
	v_mfma_f32_16x16x32_bf16 v[40:43], v[160:163], v[168:171], v[40:43]
	v_mfma_f32_16x16x32_bf16 v[40:43], v[156:159], v[164:167], v[40:43]
	v_mfma_f32_16x16x32_bf16 v[48:51], v[156:159], v[172:175], v[48:51]
	v_mfma_f32_16x16x32_bf16 v[48:51], v[160:163], v[176:179], v[48:51]
	v_mfma_f32_16x16x32_bf16 v[44:47], v[152:155], v[176:179], v[44:47]
	v_mfma_f32_16x16x32_bf16 v[44:47], v[148:151], v[172:175], v[44:47]
	s_setprio 0
	s_setprio 1
	v_mfma_f32_16x16x32_bf16 v[52:55], v[148:151], v[180:183], v[52:55]
	v_mfma_f32_16x16x32_bf16 v[52:55], v[152:155], v[184:187], v[52:55]
	v_mfma_f32_16x16x32_bf16 v[56:59], v[160:163], v[184:187], v[56:59]
	v_mfma_f32_16x16x32_bf16 v[56:59], v[156:159], v[180:183], v[56:59]
	v_mfma_f32_16x16x32_bf16 v[64:67], v[156:159], v[194:197], v[64:67]
	v_mfma_f32_16x16x32_bf16 v[64:67], v[160:163], v[198:201], v[64:67]
	s_setprio 2
	s_barrier
	v_mfma_f32_16x16x32_bf16 v[60:63], v[152:155], v[198:201], v[60:63]
	v_mfma_f32_16x16x32_bf16 v[60:63], v[148:151], v[194:197], v[60:63]
	s_setprio 0
	s_add_i32 s6, s12, s36
	v_lshl_add_u64 v[202:203], v[202:203], 0, s[86:87]
	s_mov_b32 m0, s6
	ds_read_b128 v[164:167], v212 offset:49152
	ds_read_b128 v[168:171], v212 offset:50176
	ds_read_b128 v[172:175], v212 offset:51200
	ds_read_b128 v[176:179], v212 offset:52224
	ds_read_b128 v[180:183], v212 offset:53248
	ds_read_b128 v[184:187], v212 offset:54272
	ds_read_b128 v[194:197], v212 offset:55296
	ds_read_b128 v[198:201], v212 offset:56320
	global_load_lds_dwordx4 v[202:203], off
	s_add_i32 m0, s6, 0x2000
	s_add_u32 s6, s14, 0x10080
	v_lshl_add_u64 v[202:203], v[204:205], 0, s[86:87]
	s_addc_u32 s7, s15, 0
	s_add_i32 s12, s13, s36
	global_load_lds_dwordx4 v[202:203], off
	s_mov_b32 m0, s12
	v_lshl_add_u64 v[202:203], v[206:207], 0, s[86:87]
	global_load_lds_dwordx4 v192, s[6:7]
	s_add_i32 m0, s12, 0x2000
	s_nop 0
	global_load_lds_dwordx4 v190, s[6:7]
	s_mov_b32 m0, s71
	s_nop 0
	global_load_lds_dwordx4 v[202:203], off
	v_lshl_add_u64 v[202:203], v[210:211], 0, s[86:87]
	s_mov_b32 m0, s72
	s_nop 0
	global_load_lds_dwordx4 v[202:203], off
	s_waitcnt vmcnt(8)
	s_waitcnt lgkmcnt(0)
	s_barrier
	s_setprio 1
	s_waitcnt lgkmcnt(0)
	v_mfma_f32_16x16x32_bf16 v[68:71], v[132:135], v[164:167], v[68:71]
	v_mfma_f32_16x16x32_bf16 v[68:71], v[136:139], v[168:171], v[68:71]
	v_mfma_f32_16x16x32_bf16 v[72:75], v[144:147], v[168:171], v[72:75]
	v_mfma_f32_16x16x32_bf16 v[72:75], v[140:143], v[164:167], v[72:75]
	v_mfma_f32_16x16x32_bf16 v[80:83], v[140:143], v[172:175], v[80:83]
	v_mfma_f32_16x16x32_bf16 v[80:83], v[144:147], v[176:179], v[80:83]
	v_mfma_f32_16x16x32_bf16 v[76:79], v[136:139], v[176:179], v[76:79]
	v_mfma_f32_16x16x32_bf16 v[76:79], v[132:135], v[172:175], v[76:79]
	s_setprio 0
	s_setprio 1
	v_mfma_f32_16x16x32_bf16 v[84:87], v[132:135], v[180:183], v[84:87]
	v_mfma_f32_16x16x32_bf16 v[84:87], v[136:139], v[184:187], v[84:87]
	v_mfma_f32_16x16x32_bf16 v[88:91], v[144:147], v[184:187], v[88:91]
	v_mfma_f32_16x16x32_bf16 v[88:91], v[140:143], v[180:183], v[88:91]
	v_mfma_f32_16x16x32_bf16 v[96:99], v[140:143], v[194:197], v[96:99]
	v_mfma_f32_16x16x32_bf16 v[96:99], v[144:147], v[198:201], v[96:99]
	v_mfma_f32_16x16x32_bf16 v[92:95], v[136:139], v[198:201], v[92:95]
	v_mfma_f32_16x16x32_bf16 v[92:95], v[132:135], v[194:197], v[92:95]
	s_setprio 0
	s_setprio 1
	v_mfma_f32_16x16x32_bf16 v[100:103], v[148:151], v[164:167], v[100:103]
	v_mfma_f32_16x16x32_bf16 v[100:103], v[152:155], v[168:171], v[100:103]
	v_mfma_f32_16x16x32_bf16 v[104:107], v[160:163], v[168:171], v[104:107]
	v_mfma_f32_16x16x32_bf16 v[104:107], v[156:159], v[164:167], v[104:107]
	v_mfma_f32_16x16x32_bf16 v[112:115], v[156:159], v[172:175], v[112:115]
	v_mfma_f32_16x16x32_bf16 v[112:115], v[160:163], v[176:179], v[112:115]
	v_mfma_f32_16x16x32_bf16 v[108:111], v[152:155], v[176:179], v[108:111]
	v_mfma_f32_16x16x32_bf16 v[108:111], v[148:151], v[172:175], v[108:111]
	s_setprio 0
	s_setprio 1
	v_mfma_f32_16x16x32_bf16 v[116:119], v[148:151], v[180:183], v[116:119]
	v_mfma_f32_16x16x32_bf16 v[116:119], v[152:155], v[184:187], v[116:119]
	v_mfma_f32_16x16x32_bf16 v[120:123], v[160:163], v[184:187], v[120:123]
	v_mfma_f32_16x16x32_bf16 v[120:123], v[156:159], v[180:183], v[120:123]
	v_mfma_f32_16x16x32_bf16 v[128:131], v[156:159], v[194:197], v[128:131]
	v_mfma_f32_16x16x32_bf16 v[128:131], v[160:163], v[198:201], v[128:131]
	s_setprio 2
	s_barrier
	v_mfma_f32_16x16x32_bf16 v[124:127], v[152:155], v[198:201], v[124:127]
	v_mfma_f32_16x16x32_bf16 v[124:127], v[148:151], v[194:197], v[124:127]
	s_setprio 0
	s_and_b64 vcc, exec, s[58:59]
	s_cbranch_vccz .LBB0_1178
	s_barrier

.LBB0_1625:
	s_add_i32 s51, 0, 0x10000
	s_add_i32 s72, 0, 0x14000
	v_add_u32_e32 v16, s51, v232
	v_add_u32_e32 v32, s72, v232
	ds_read_b128 v[4:7], v16
	ds_read_b128 v[8:11], v16 offset:1024
	ds_read_b128 v[12:15], v16 offset:2048
	ds_read_b128 v[16:19], v16 offset:3072
	ds_read_b128 v[20:23], v32
	ds_read_b128 v[24:27], v32 offset:1024
	ds_read_b128 v[28:31], v32 offset:2048
	ds_read_b128 v[32:35], v32 offset:3072
	v_add_u32_e32 v233, 0, v231
	ds_read_b128 v[36:39], v233
	ds_read_b128 v[40:43], v233 offset:1024
	ds_read_b128 v[44:47], v233 offset:2048
	ds_read_b128 v[48:51], v233 offset:3072
	ds_read_b128 v[52:55], v233 offset:4096
	ds_read_b128 v[56:59], v233 offset:5120
	ds_read_b128 v[60:63], v233 offset:6144
	ds_read_b128 v[64:67], v233 offset:7168
	s_waitcnt vmcnt(8)
	s_waitcnt lgkmcnt(0)
	s_barrier
	s_setprio 1
	s_waitcnt lgkmcnt(0)
	v_mfma_f32_16x16x32_bf16 v[68:71], v[4:7], v[36:39], 0
	v_mfma_f32_16x16x32_bf16 v[68:71], v[8:11], v[40:43], v[68:71]
	v_mfma_f32_16x16x32_bf16 v[72:75], v[12:15], v[36:39], 0
	v_mfma_f32_16x16x32_bf16 v[72:75], v[16:19], v[40:43], v[72:75]
	v_mfma_f32_16x16x32_bf16 v[80:83], v[12:15], v[44:47], 0
	v_mfma_f32_16x16x32_bf16 v[80:83], v[16:19], v[48:51], v[80:83]
	v_mfma_f32_16x16x32_bf16 v[76:79], v[4:7], v[44:47], 0
	v_mfma_f32_16x16x32_bf16 v[76:79], v[8:11], v[48:51], v[76:79]
	s_setprio 0
	s_setprio 1
	v_mfma_f32_16x16x32_bf16 v[84:87], v[4:7], v[52:55], 0
	v_mfma_f32_16x16x32_bf16 v[84:87], v[8:11], v[56:59], v[84:87]
	v_mfma_f32_16x16x32_bf16 v[88:91], v[12:15], v[52:55], 0
	v_mfma_f32_16x16x32_bf16 v[88:91], v[16:19], v[56:59], v[88:91]
	v_mfma_f32_16x16x32_bf16 v[96:99], v[12:15], v[60:63], 0
	v_mfma_f32_16x16x32_bf16 v[96:99], v[16:19], v[64:67], v[96:99]
	v_mfma_f32_16x16x32_bf16 v[92:95], v[4:7], v[60:63], 0
	v_mfma_f32_16x16x32_bf16 v[92:95], v[8:11], v[64:67], v[92:95]
	s_setprio 0
	s_setprio 1
	v_mfma_f32_16x16x32_bf16 v[100:103], v[20:23], v[36:39], 0
	v_mfma_f32_16x16x32_bf16 v[36:39], v[28:31], v[36:39], 0
	v_mfma_f32_16x16x32_bf16 v[104:107], v[20:23], v[44:47], 0
	v_mfma_f32_16x16x32_bf16 v[44:47], v[28:31], v[44:47], 0
	v_mfma_f32_16x16x32_bf16 v[108:111], v[20:23], v[52:55], 0
	v_mfma_f32_16x16x32_bf16 v[52:55], v[28:31], v[52:55], 0
	v_mfma_f32_16x16x32_bf16 v[112:115], v[20:23], v[60:63], 0
	v_mfma_f32_16x16x32_bf16 v[60:63], v[28:31], v[60:63], 0
	s_setprio 0
	s_setprio 1
	v_mfma_f32_16x16x32_bf16 v[100:103], v[24:27], v[40:43], v[100:103]
	v_mfma_f32_16x16x32_bf16 v[40:43], v[32:35], v[40:43], v[36:39]
	v_mfma_f32_16x16x32_bf16 v[104:107], v[24:27], v[48:51], v[104:107]
	v_mfma_f32_16x16x32_bf16 v[48:51], v[32:35], v[48:51], v[44:47]
	v_mfma_f32_16x16x32_bf16 v[108:111], v[24:27], v[56:59], v[108:111]
	v_mfma_f32_16x16x32_bf16 v[56:59], v[32:35], v[56:59], v[52:55]
	s_setprio 2
	s_barrier
	v_mfma_f32_16x16x32_bf16 v[112:115], v[24:27], v[64:67], v[112:115]
	v_mfma_f32_16x16x32_bf16 v[64:67], v[32:35], v[64:67], v[60:63]
	s_setprio 0
	v_lshl_add_u64 v[186:187], s[12:13], 0, v[2:3]
	s_add_i32 s51, s51, s56
	v_mov_b32_e32 v191, v3
	v_lshl_add_u64 v[134:135], v[186:187], 0, s[74:75]
	s_mov_b32 m0, s51
	v_lshl_add_u64 v[246:247], s[12:13], 0, v[190:191]
	ds_read_b128 v[36:39], v233 offset:16384
	ds_read_b128 v[44:47], v233 offset:17408
	ds_read_b128 v[52:55], v233 offset:18432
	ds_read_b128 v[60:63], v233 offset:19456
	ds_read_b128 v[116:119], v233 offset:20480
	ds_read_b128 v[120:123], v233 offset:21504
	ds_read_b128 v[124:127], v233 offset:22528
	ds_read_b128 v[128:131], v233 offset:23552
	global_load_lds_dwordx4 v[134:135], off
	v_lshl_add_u64 v[134:135], v[246:247], 0, s[74:75]
	s_add_i32 m0, s51, 0x2000
	s_add_i32 s51, s72, s56
	global_load_lds_dwordx4 v[134:135], off
	s_mov_b32 m0, s51
	v_mov_b32_e32 v133, v3
	global_load_lds_dwordx4 v2, s[16:17]
	s_add_i32 m0, s51, 0x2000
	v_lshl_add_u64 v[248:249], s[14:15], 0, v[132:133]
	v_mov_b32_e32 v189, v3
	global_load_lds_dwordx4 v190, s[16:17]
	v_lshl_add_u64 v[134:135], v[248:249], 0, s[74:75]
	s_mov_b32 m0, s57
	v_lshl_add_u64 v[250:251], s[14:15], 0, v[188:189]
	global_load_lds_dwordx4 v[134:135], off
	v_lshl_add_u64 v[134:135], v[250:251], 0, s[74:75]
	s_mov_b32 m0, s58
	s_nop 0
	global_load_lds_dwordx4 v[134:135], off
	s_waitcnt vmcnt(8)
	s_waitcnt lgkmcnt(0)
	s_barrier
	s_setprio 1
	s_waitcnt lgkmcnt(0)
	v_mfma_f32_16x16x32_bf16 v[134:137], v[4:7], v[36:39], 0
	v_mfma_f32_16x16x32_bf16 v[138:141], v[12:15], v[36:39], 0
	v_mfma_f32_16x16x32_bf16 v[142:145], v[4:7], v[52:55], 0
	v_mfma_f32_16x16x32_bf16 v[146:149], v[12:15], v[52:55], 0
	v_mfma_f32_16x16x32_bf16 v[150:153], v[4:7], v[116:119], 0
	v_mfma_f32_16x16x32_bf16 v[154:157], v[12:15], v[116:119], 0
	v_mfma_f32_16x16x32_bf16 v[4:7], v[4:7], v[124:127], 0
	v_mfma_f32_16x16x32_bf16 v[12:15], v[12:15], v[124:127], 0
	s_setprio 0
	s_setprio 1
	v_mfma_f32_16x16x32_bf16 v[134:137], v[8:11], v[44:47], v[134:137]
	v_mfma_f32_16x16x32_bf16 v[138:141], v[16:19], v[44:47], v[138:141]
	v_mfma_f32_16x16x32_bf16 v[142:145], v[8:11], v[60:63], v[142:145]
	v_mfma_f32_16x16x32_bf16 v[146:149], v[16:19], v[60:63], v[146:149]
	v_mfma_f32_16x16x32_bf16 v[150:153], v[8:11], v[120:123], v[150:153]
	v_mfma_f32_16x16x32_bf16 v[154:157], v[16:19], v[120:123], v[154:157]
	v_mfma_f32_16x16x32_bf16 v[158:161], v[8:11], v[128:131], v[4:7]
	v_mfma_f32_16x16x32_bf16 v[162:165], v[16:19], v[128:131], v[12:15]
	s_setprio 0
	s_setprio 1
	v_mfma_f32_16x16x32_bf16 v[4:7], v[20:23], v[36:39], 0
	v_mfma_f32_16x16x32_bf16 v[8:11], v[28:31], v[36:39], 0
	v_mfma_f32_16x16x32_bf16 v[12:15], v[20:23], v[52:55], 0
	v_mfma_f32_16x16x32_bf16 v[16:19], v[28:31], v[52:55], 0
	v_mfma_f32_16x16x32_bf16 v[36:39], v[20:23], v[116:119], 0
	v_mfma_f32_16x16x32_bf16 v[52:55], v[28:31], v[116:119], 0
	v_mfma_f32_16x16x32_bf16 v[20:23], v[20:23], v[124:127], 0
	v_mfma_f32_16x16x32_bf16 v[28:31], v[28:31], v[124:127], 0
	s_setprio 0
	s_setprio 1
	v_mfma_f32_16x16x32_bf16 v[116:119], v[24:27], v[44:47], v[4:7]
	v_mfma_f32_16x16x32_bf16 v[124:127], v[32:35], v[44:47], v[8:11]
	v_mfma_f32_16x16x32_bf16 v[174:177], v[24:27], v[120:123], v[36:39]
	v_mfma_f32_16x16x32_bf16 v[120:123], v[32:35], v[120:123], v[52:55]
	v_mfma_f32_16x16x32_bf16 v[178:181], v[24:27], v[128:131], v[20:23]
	v_mfma_f32_16x16x32_bf16 v[128:131], v[32:35], v[128:131], v[28:31]
	s_setprio 2
	s_barrier
	v_mfma_f32_16x16x32_bf16 v[166:169], v[24:27], v[60:63], v[12:15]
	v_mfma_f32_16x16x32_bf16 v[170:173], v[32:35], v[60:63], v[16:19]
	s_setprio 0
	s_add_i32 s51, 0, 0x18000
	v_add_u32_e32 v4, s51, v232
	s_add_i32 s72, 0, 0x1c000
	ds_read_b128 v[182:185], v4
	ds_read_b128 v[192:195], v4 offset:1024
	ds_read_b128 v[196:199], v4 offset:2048
	ds_read_b128 v[200:203], v4 offset:3072
	v_add_u32_e32 v4, s72, v232
	ds_read_b128 v[204:207], v4
	ds_read_b128 v[208:211], v4 offset:1024
	ds_read_b128 v[212:215], v4 offset:2048
	ds_read_b128 v[216:219], v4 offset:3072
	s_mov_b32 m0, s59
	ds_read_b128 v[44:47], v233 offset:32768
	ds_read_b128 v[52:55], v233 offset:33792
	ds_read_b128 v[60:63], v233 offset:34816
	ds_read_b128 v[220:223], v233 offset:35840
	ds_read_b128 v[224:227], v233 offset:36864
	ds_read_b128 v[234:237], v233 offset:37888
	ds_read_b128 v[238:241], v233 offset:38912
	ds_read_b128 v[242:245], v233 offset:39936
	global_load_lds_dwordx4 v132, s[26:27]
	s_mov_b32 m0, s60
	s_nop 0
	global_load_lds_dwordx4 v188, s[26:27]
	s_waitcnt vmcnt(8)
	s_waitcnt lgkmcnt(0)
	s_barrier
	s_setprio 1
	s_waitcnt lgkmcnt(0)
	v_mfma_f32_16x16x32_bf16 v[4:7], v[182:185], v[44:47], v[68:71]
	v_mfma_f32_16x16x32_bf16 v[8:11], v[196:199], v[44:47], v[72:75]
	v_mfma_f32_16x16x32_bf16 v[12:15], v[182:185], v[60:63], v[76:79]
	v_mfma_f32_16x16x32_bf16 v[16:19], v[196:199], v[60:63], v[80:83]
	v_mfma_f32_16x16x32_bf16 v[20:23], v[182:185], v[224:227], v[84:87]
	v_mfma_f32_16x16x32_bf16 v[24:27], v[196:199], v[224:227], v[88:91]
	v_mfma_f32_16x16x32_bf16 v[28:31], v[182:185], v[238:241], v[92:95]
	v_mfma_f32_16x16x32_bf16 v[32:35], v[196:199], v[238:241], v[96:99]
	s_setprio 0
	s_setprio 1
	v_mfma_f32_16x16x32_bf16 v[4:7], v[192:195], v[52:55], v[4:7]
	v_mfma_f32_16x16x32_bf16 v[8:11], v[200:203], v[52:55], v[8:11]
	v_mfma_f32_16x16x32_bf16 v[12:15], v[192:195], v[220:223], v[12:15]
	v_mfma_f32_16x16x32_bf16 v[16:19], v[200:203], v[220:223], v[16:19]
	v_mfma_f32_16x16x32_bf16 v[20:23], v[192:195], v[234:237], v[20:23]
	v_mfma_f32_16x16x32_bf16 v[24:27], v[200:203], v[234:237], v[24:27]
	v_mfma_f32_16x16x32_bf16 v[28:31], v[192:195], v[242:245], v[28:31]
	v_mfma_f32_16x16x32_bf16 v[32:35], v[200:203], v[242:245], v[32:35]
	s_setprio 0
	s_setprio 1
	v_mfma_f32_16x16x32_bf16 v[36:39], v[204:207], v[44:47], v[100:103]
	v_mfma_f32_16x16x32_bf16 v[40:43], v[212:215], v[44:47], v[40:43]
	v_mfma_f32_16x16x32_bf16 v[36:39], v[208:211], v[52:55], v[36:39]
	v_mfma_f32_16x16x32_bf16 v[40:43], v[216:219], v[52:55], v[40:43]
	v_mfma_f32_16x16x32_bf16 v[44:47], v[204:207], v[60:63], v[104:107]
	v_mfma_f32_16x16x32_bf16 v[48:51], v[212:215], v[60:63], v[48:51]
	v_mfma_f32_16x16x32_bf16 v[52:55], v[204:207], v[224:227], v[108:111]
	v_mfma_f32_16x16x32_bf16 v[56:59], v[212:215], v[224:227], v[56:59]
	s_setprio 0
	s_setprio 1
	v_mfma_f32_16x16x32_bf16 v[60:63], v[204:207], v[238:241], v[112:115]
	v_mfma_f32_16x16x32_bf16 v[64:67], v[212:215], v[238:241], v[64:67]
	v_mfma_f32_16x16x32_bf16 v[44:47], v[208:211], v[220:223], v[44:47]
	v_mfma_f32_16x16x32_bf16 v[48:51], v[216:219], v[220:223], v[48:51]
	v_mfma_f32_16x16x32_bf16 v[52:55], v[208:211], v[234:237], v[52:55]
	v_mfma_f32_16x16x32_bf16 v[56:59], v[216:219], v[234:237], v[56:59]
	s_setprio 2
	s_barrier
	v_mfma_f32_16x16x32_bf16 v[60:63], v[208:211], v[242:245], v[60:63]
	v_mfma_f32_16x16x32_bf16 v[64:67], v[216:219], v[242:245], v[64:67]
	s_setprio 0
	s_add_i32 s51, s51, s56
	v_lshl_add_u64 v[68:69], v[186:187], 0, s[24:25]
	s_mov_b32 m0, s51
	ds_read_b128 v[104:107], v233 offset:49152
	ds_read_b128 v[108:111], v233 offset:50176
	ds_read_b128 v[112:115], v233 offset:51200
	ds_read_b128 v[220:223], v233 offset:52224
	ds_read_b128 v[224:227], v233 offset:53248
	ds_read_b128 v[234:237], v233 offset:54272
	ds_read_b128 v[238:241], v233 offset:55296
	ds_read_b128 v[242:245], v233 offset:56320
	global_load_lds_dwordx4 v[68:69], off
	v_lshl_add_u64 v[68:69], v[246:247], 0, s[24:25]
	s_add_i32 m0, s51, 0x2000
	s_add_i32 s51, s72, s56
	global_load_lds_dwordx4 v[68:69], off
	s_mov_b32 m0, s51
	v_lshl_add_u64 v[68:69], v[248:249], 0, s[24:25]
	global_load_lds_dwordx4 v2, s[28:29]
	s_add_i32 m0, s51, 0x2000
	s_nop 0
	global_load_lds_dwordx4 v190, s[28:29]
	s_mov_b32 m0, s64
	s_nop 0
	global_load_lds_dwordx4 v[68:69], off
	v_lshl_add_u64 v[68:69], v[250:251], 0, s[24:25]
	s_mov_b32 m0, s65
	s_nop 0
	global_load_lds_dwordx4 v[68:69], off
	s_waitcnt vmcnt(8)
	s_waitcnt lgkmcnt(0)
	s_barrier
	s_setprio 1
	s_waitcnt lgkmcnt(0)
	v_mfma_f32_16x16x32_bf16 v[68:71], v[182:185], v[104:107], v[134:137]
	v_mfma_f32_16x16x32_bf16 v[72:75], v[196:199], v[104:107], v[138:141]
	v_mfma_f32_16x16x32_bf16 v[76:79], v[182:185], v[112:115], v[142:145]
	v_mfma_f32_16x16x32_bf16 v[80:83], v[196:199], v[112:115], v[146:149]
	v_mfma_f32_16x16x32_bf16 v[84:87], v[182:185], v[224:227], v[150:153]
	v_mfma_f32_16x16x32_bf16 v[88:91], v[196:199], v[224:227], v[154:157]
	v_mfma_f32_16x16x32_bf16 v[92:95], v[182:185], v[238:241], v[158:161]
	v_mfma_f32_16x16x32_bf16 v[96:99], v[196:199], v[238:241], v[162:165]
	s_setprio 0
	s_setprio 1
	v_mfma_f32_16x16x32_bf16 v[68:71], v[192:195], v[108:111], v[68:71]
	v_mfma_f32_16x16x32_bf16 v[72:75], v[200:203], v[108:111], v[72:75]
	v_mfma_f32_16x16x32_bf16 v[76:79], v[192:195], v[220:223], v[76:79]
	v_mfma_f32_16x16x32_bf16 v[80:83], v[200:203], v[220:223], v[80:83]
	v_mfma_f32_16x16x32_bf16 v[84:87], v[192:195], v[234:237], v[84:87]
	v_mfma_f32_16x16x32_bf16 v[88:91], v[200:203], v[234:237], v[88:91]
	v_mfma_f32_16x16x32_bf16 v[92:95], v[192:195], v[242:245], v[92:95]
	v_mfma_f32_16x16x32_bf16 v[96:99], v[200:203], v[242:245], v[96:99]
	s_setprio 0
	s_setprio 1
	v_mfma_f32_16x16x32_bf16 v[100:103], v[204:207], v[104:107], v[116:119]
	v_mfma_f32_16x16x32_bf16 v[104:107], v[212:215], v[104:107], v[124:127]
	v_mfma_f32_16x16x32_bf16 v[100:103], v[208:211], v[108:111], v[100:103]
	v_mfma_f32_16x16x32_bf16 v[104:107], v[216:219], v[108:111], v[104:107]
	v_mfma_f32_16x16x32_bf16 v[108:111], v[204:207], v[112:115], v[166:169]
	v_mfma_f32_16x16x32_bf16 v[112:115], v[212:215], v[112:115], v[170:173]
	v_mfma_f32_16x16x32_bf16 v[116:119], v[204:207], v[224:227], v[174:177]
	v_mfma_f32_16x16x32_bf16 v[120:123], v[212:215], v[224:227], v[120:123]
	s_setprio 0
	s_setprio 1
	v_mfma_f32_16x16x32_bf16 v[124:127], v[204:207], v[238:241], v[178:181]
	v_mfma_f32_16x16x32_bf16 v[128:131], v[212:215], v[238:241], v[128:131]
	v_mfma_f32_16x16x32_bf16 v[108:111], v[208:211], v[220:223], v[108:111]
	v_mfma_f32_16x16x32_bf16 v[112:115], v[216:219], v[220:223], v[112:115]
	v_mfma_f32_16x16x32_bf16 v[116:119], v[208:211], v[234:237], v[116:119]
	v_mfma_f32_16x16x32_bf16 v[120:123], v[216:219], v[234:237], v[120:123]
	s_setprio 2
	s_barrier
	v_mfma_f32_16x16x32_bf16 v[124:127], v[208:211], v[242:245], v[124:127]
	v_mfma_f32_16x16x32_bf16 v[128:131], v[216:219], v[242:245], v[128:131]
	s_setprio 0
	s_add_i32 s43, s43, 2
	s_cmp_ge_i32 s43, s42
	s_cbranch_scc0 .LBB0_1625
	v_mov_b32_e32 v192, v2
	s_branch .LBB0_1628

.LBB0_1629:
	s_add_u32 s12, s14, 0xfff80080
	s_addc_u32 s13, s15, -1
	s_add_i32 s29, 0, 0x10000
	s_cmp_eq_u32 s28, 28
	s_cselect_b32 s17, s9, s13
	s_cselect_b32 s16, s8, s12
	s_cselect_b32 s13, s11, s27
	s_cselect_b32 s12, s10, s26
	s_add_i32 s51, 0, 0x14000
	v_add_u32_e32 v144, s29, v232
	v_add_u32_e32 v160, s51, v232
	s_waitcnt lgkmcnt(0)
	ds_read_b128 v[132:135], v144
	ds_read_b128 v[136:139], v144 offset:1024
	ds_read_b128 v[140:143], v144 offset:2048
	ds_read_b128 v[144:147], v144 offset:3072
	ds_read_b128 v[148:151], v160
	ds_read_b128 v[152:155], v160 offset:1024
	ds_read_b128 v[156:159], v160 offset:2048
	ds_read_b128 v[160:163], v160 offset:3072
	s_mov_b32 m0, s66
	v_add_u32_e32 v210, 0, v231
	ds_read_b128 v[164:167], v210
	ds_read_b128 v[168:171], v210 offset:1024
	ds_read_b128 v[172:175], v210 offset:2048
	ds_read_b128 v[176:179], v210 offset:3072
	ds_read_b128 v[180:183], v210 offset:4096
	ds_read_b128 v[184:187], v210 offset:5120
	ds_read_b128 v[194:197], v210 offset:6144
	ds_read_b128 v[198:201], v210 offset:7168
	global_load_lds_dwordx4 v2, s[14:15]
	s_mov_b32 m0, s67
	v_mov_b32_e32 v189, v3
	global_load_lds_dwordx4 v188, s[14:15]
	s_waitcnt vmcnt(8)
	s_waitcnt lgkmcnt(0)
	s_barrier
	s_setprio 1
	s_waitcnt lgkmcnt(0)
	v_mfma_f32_16x16x32_bf16 v[4:7], v[132:135], v[164:167], v[4:7]
	v_mfma_f32_16x16x32_bf16 v[4:7], v[136:139], v[168:171], v[4:7]
	v_mfma_f32_16x16x32_bf16 v[8:11], v[144:147], v[168:171], v[8:11]
	v_mfma_f32_16x16x32_bf16 v[8:11], v[140:143], v[164:167], v[8:11]
	v_mfma_f32_16x16x32_bf16 v[16:19], v[140:143], v[172:175], v[16:19]
	v_mfma_f32_16x16x32_bf16 v[16:19], v[144:147], v[176:179], v[16:19]
	v_mfma_f32_16x16x32_bf16 v[12:15], v[136:139], v[176:179], v[12:15]
	v_mfma_f32_16x16x32_bf16 v[12:15], v[132:135], v[172:175], v[12:15]
	s_setprio 0
	s_setprio 1
	v_mfma_f32_16x16x32_bf16 v[20:23], v[132:135], v[180:183], v[20:23]
	v_mfma_f32_16x16x32_bf16 v[20:23], v[136:139], v[184:187], v[20:23]
	v_mfma_f32_16x16x32_bf16 v[24:27], v[144:147], v[184:187], v[24:27]
	v_mfma_f32_16x16x32_bf16 v[24:27], v[140:143], v[180:183], v[24:27]
	v_mfma_f32_16x16x32_bf16 v[32:35], v[140:143], v[194:197], v[32:35]
	v_mfma_f32_16x16x32_bf16 v[32:35], v[144:147], v[198:201], v[32:35]
	v_mfma_f32_16x16x32_bf16 v[28:31], v[136:139], v[198:201], v[28:31]
	v_mfma_f32_16x16x32_bf16 v[28:31], v[132:135], v[194:197], v[28:31]
	s_setprio 0
	s_setprio 1
	v_mfma_f32_16x16x32_bf16 v[36:39], v[148:151], v[164:167], v[36:39]
	v_mfma_f32_16x16x32_bf16 v[36:39], v[152:155], v[168:171], v[36:39]
	v_mfma_f32_16x16x32_bf16 v[40:43], v[160:163], v[168:171], v[40:43]
	v_mfma_f32_16x16x32_bf16 v[40:43], v[156:159], v[164:167], v[40:43]
	v_mfma_f32_16x16x32_bf16 v[48:51], v[156:159], v[172:175], v[48:51]
	v_mfma_f32_16x16x32_bf16 v[48:51], v[160:163], v[176:179], v[48:51]
	v_mfma_f32_16x16x32_bf16 v[44:47], v[152:155], v[176:179], v[44:47]
	v_mfma_f32_16x16x32_bf16 v[44:47], v[148:151], v[172:175], v[44:47]
	s_setprio 0
	s_setprio 1
	v_mfma_f32_16x16x32_bf16 v[52:55], v[148:151], v[180:183], v[52:55]
	v_mfma_f32_16x16x32_bf16 v[52:55], v[152:155], v[184:187], v[52:55]
	v_mfma_f32_16x16x32_bf16 v[56:59], v[160:163], v[184:187], v[56:59]
	v_mfma_f32_16x16x32_bf16 v[56:59], v[156:159], v[180:183], v[56:59]
	v_mfma_f32_16x16x32_bf16 v[64:67], v[156:159], v[194:197], v[64:67]
	v_mfma_f32_16x16x32_bf16 v[64:67], v[160:163], v[198:201], v[64:67]
	s_setprio 2
	s_barrier
	v_mfma_f32_16x16x32_bf16 v[60:63], v[152:155], v[198:201], v[60:63]
	v_mfma_f32_16x16x32_bf16 v[60:63], v[148:151], v[194:197], v[60:63]
	s_setprio 0
	s_add_i32 s29, s29, s56
	s_mov_b32 m0, s29
	ds_read_b128 v[164:167], v210 offset:16384
	ds_read_b128 v[168:171], v210 offset:17408
	ds_read_b128 v[172:175], v210 offset:18432
	ds_read_b128 v[176:179], v210 offset:19456
	ds_read_b128 v[180:183], v210 offset:20480
	ds_read_b128 v[184:187], v210 offset:21504
	ds_read_b128 v[194:197], v210 offset:22528
	ds_read_b128 v[198:201], v210 offset:23552
	global_load_lds_dwordx4 v192, s[12:13]
	s_add_i32 m0, s29, 0x2000
	s_add_u32 s42, s12, 0x80000
	s_addc_u32 s43, s13, 0
	s_add_i32 s29, s51, s56
	global_load_lds_dwordx4 v190, s[12:13]
	s_mov_b32 m0, s29
	v_mov_b32_e32 v193, v3
	global_load_lds_dwordx4 v192, s[42:43]
	s_add_i32 m0, s29, 0x2000
	v_mov_b32_e32 v191, v3
	global_load_lds_dwordx4 v190, s[42:43]
	s_mov_b32 m0, s57
	v_lshl_add_u64 v[202:203], s[12:13], 0, v[192:193]
	global_load_lds_dwordx4 v2, s[16:17]
	s_mov_b32 m0, s58
	v_lshl_add_u64 v[204:205], s[12:13], 0, v[190:191]
	global_load_lds_dwordx4 v188, s[16:17]
	s_waitcnt vmcnt(8)
	s_waitcnt lgkmcnt(0)
	v_lshl_add_u64 v[206:207], s[16:17], 0, v[2:3]
	v_lshl_add_u64 v[208:209], s[16:17], 0, v[188:189]
	s_barrier
	s_setprio 1
	s_waitcnt lgkmcnt(0)
	v_mfma_f32_16x16x32_bf16 v[68:71], v[132:135], v[164:167], v[68:71]
	v_mfma_f32_16x16x32_bf16 v[68:71], v[136:139], v[168:171], v[68:71]
	v_mfma_f32_16x16x32_bf16 v[72:75], v[144:147], v[168:171], v[72:75]
	v_mfma_f32_16x16x32_bf16 v[72:75], v[140:143], v[164:167], v[72:75]
	v_mfma_f32_16x16x32_bf16 v[80:83], v[140:143], v[172:175], v[80:83]
	v_mfma_f32_16x16x32_bf16 v[80:83], v[144:147], v[176:179], v[80:83]
	v_mfma_f32_16x16x32_bf16 v[76:79], v[136:139], v[176:179], v[76:79]
	v_mfma_f32_16x16x32_bf16 v[76:79], v[132:135], v[172:175], v[76:79]
	s_setprio 0
	s_setprio 1
	v_mfma_f32_16x16x32_bf16 v[84:87], v[132:135], v[180:183], v[84:87]
	v_mfma_f32_16x16x32_bf16 v[84:87], v[136:139], v[184:187], v[84:87]
	v_mfma_f32_16x16x32_bf16 v[88:91], v[144:147], v[184:187], v[88:91]
	v_mfma_f32_16x16x32_bf16 v[88:91], v[140:143], v[180:183], v[88:91]
	v_mfma_f32_16x16x32_bf16 v[96:99], v[140:143], v[194:197], v[96:99]
	v_mfma_f32_16x16x32_bf16 v[96:99], v[144:147], v[198:201], v[96:99]
	v_mfma_f32_16x16x32_bf16 v[92:95], v[136:139], v[198:201], v[92:95]
	v_mfma_f32_16x16x32_bf16 v[92:95], v[132:135], v[194:197], v[92:95]
	s_setprio 0
	s_setprio 1
	v_mfma_f32_16x16x32_bf16 v[100:103], v[148:151], v[164:167], v[100:103]
	v_mfma_f32_16x16x32_bf16 v[100:103], v[152:155], v[168:171], v[100:103]
	v_mfma_f32_16x16x32_bf16 v[104:107], v[160:163], v[168:171], v[104:107]
	v_mfma_f32_16x16x32_bf16 v[104:107], v[156:159], v[164:167], v[104:107]
	v_mfma_f32_16x16x32_bf16 v[112:115], v[156:159], v[172:175], v[112:115]
	v_mfma_f32_16x16x32_bf16 v[112:115], v[160:163], v[176:179], v[112:115]
	v_mfma_f32_16x16x32_bf16 v[108:111], v[152:155], v[176:179], v[108:111]
	v_mfma_f32_16x16x32_bf16 v[108:111], v[148:151], v[172:175], v[108:111]
	s_setprio 0
	s_setprio 1
	v_mfma_f32_16x16x32_bf16 v[116:119], v[148:151], v[180:183], v[116:119]
	v_mfma_f32_16x16x32_bf16 v[116:119], v[152:155], v[184:187], v[116:119]
	v_mfma_f32_16x16x32_bf16 v[120:123], v[160:163], v[184:187], v[120:123]
	v_mfma_f32_16x16x32_bf16 v[120:123], v[156:159], v[180:183], v[120:123]
	v_mfma_f32_16x16x32_bf16 v[128:131], v[156:159], v[194:197], v[128:131]
	v_mfma_f32_16x16x32_bf16 v[128:131], v[160:163], v[198:201], v[128:131]
	s_setprio 2
	s_barrier
	v_mfma_f32_16x16x32_bf16 v[124:127], v[152:155], v[198:201], v[124:127]
	v_mfma_f32_16x16x32_bf16 v[124:127], v[148:151], v[194:197], v[124:127]
	s_setprio 0
	s_add_i32 s29, 0, 0x18000
	s_add_i32 s42, 0, 0x1c000
	v_add_u32_e32 v144, s29, v232
	v_add_u32_e32 v160, s42, v232
	ds_read_b128 v[132:135], v144
	ds_read_b128 v[136:139], v144 offset:1024
	ds_read_b128 v[140:143], v144 offset:2048
	ds_read_b128 v[144:147], v144 offset:3072
	ds_read_b128 v[148:151], v160
	ds_read_b128 v[152:155], v160 offset:1024
	ds_read_b128 v[156:159], v160 offset:2048
	ds_read_b128 v[160:163], v160 offset:3072
	s_add_u32 s16, s16, 0x80000
	s_addc_u32 s17, s17, 0
	s_mov_b32 m0, s59
	ds_read_b128 v[164:167], v210 offset:32768
	ds_read_b128 v[168:171], v210 offset:33792
	ds_read_b128 v[172:175], v210 offset:34816
	ds_read_b128 v[176:179], v210 offset:35840
	ds_read_b128 v[180:183], v210 offset:36864
	ds_read_b128 v[184:187], v210 offset:37888
	ds_read_b128 v[194:197], v210 offset:38912
	ds_read_b128 v[198:201], v210 offset:39936
	global_load_lds_dwordx4 v2, s[16:17]
	s_mov_b32 m0, s60
	s_nop 0
	global_load_lds_dwordx4 v188, s[16:17]
	s_waitcnt vmcnt(8)
	s_waitcnt lgkmcnt(0)
	s_barrier
	s_setprio 1
	s_waitcnt lgkmcnt(0)
	v_mfma_f32_16x16x32_bf16 v[4:7], v[132:135], v[164:167], v[4:7]
	v_mfma_f32_16x16x32_bf16 v[4:7], v[136:139], v[168:171], v[4:7]
	v_mfma_f32_16x16x32_bf16 v[8:11], v[144:147], v[168:171], v[8:11]
	v_mfma_f32_16x16x32_bf16 v[8:11], v[140:143], v[164:167], v[8:11]
	v_mfma_f32_16x16x32_bf16 v[16:19], v[140:143], v[172:175], v[16:19]
	v_mfma_f32_16x16x32_bf16 v[16:19], v[144:147], v[176:179], v[16:19]
	v_mfma_f32_16x16x32_bf16 v[12:15], v[136:139], v[176:179], v[12:15]
	v_mfma_f32_16x16x32_bf16 v[12:15], v[132:135], v[172:175], v[12:15]
	s_setprio 0
	s_setprio 1
	v_mfma_f32_16x16x32_bf16 v[20:23], v[132:135], v[180:183], v[20:23]
	v_mfma_f32_16x16x32_bf16 v[20:23], v[136:139], v[184:187], v[20:23]
	v_mfma_f32_16x16x32_bf16 v[24:27], v[144:147], v[184:187], v[24:27]
	v_mfma_f32_16x16x32_bf16 v[24:27], v[140:143], v[180:183], v[24:27]
	v_mfma_f32_16x16x32_bf16 v[32:35], v[140:143], v[194:197], v[32:35]
	v_mfma_f32_16x16x32_bf16 v[32:35], v[144:147], v[198:201], v[32:35]
	v_mfma_f32_16x16x32_bf16 v[28:31], v[136:139], v[198:201], v[28:31]
	v_mfma_f32_16x16x32_bf16 v[28:31], v[132:135], v[194:197], v[28:31]
	s_setprio 0
	s_setprio 1
	v_mfma_f32_16x16x32_bf16 v[36:39], v[148:151], v[164:167], v[36:39]
	v_mfma_f32_16x16x32_bf16 v[36:39], v[152:155], v[168:171], v[36:39]
	v_mfma_f32_16x16x32_bf16 v[40:43], v[160:163], v[168:171], v[40:43]
	v_mfma_f32_16x16x32_bf16 v[40:43], v[156:159], v[164:167], v[40:43]
	v_mfma_f32_16x16x32_bf16 v[48:51], v[156:159], v[172:175], v[48:51]
	v_mfma_f32_16x16x32_bf16 v[48:51], v[160:163], v[176:179], v[48:51]
	v_mfma_f32_16x16x32_bf16 v[44:47], v[152:155], v[176:179], v[44:47]
	v_mfma_f32_16x16x32_bf16 v[44:47], v[148:151], v[172:175], v[44:47]
	s_setprio 0
	s_setprio 1
	v_mfma_f32_16x16x32_bf16 v[52:55], v[148:151], v[180:183], v[52:55]
	v_mfma_f32_16x16x32_bf16 v[52:55], v[152:155], v[184:187], v[52:55]
	v_mfma_f32_16x16x32_bf16 v[56:59], v[160:163], v[184:187], v[56:59]
	v_mfma_f32_16x16x32_bf16 v[56:59], v[156:159], v[180:183], v[56:59]
	v_mfma_f32_16x16x32_bf16 v[64:67], v[156:159], v[194:197], v[64:67]
	v_mfma_f32_16x16x32_bf16 v[64:67], v[160:163], v[198:201], v[64:67]
	s_setprio 2
	s_barrier
	v_mfma_f32_16x16x32_bf16 v[60:63], v[152:155], v[198:201], v[60:63]
	v_mfma_f32_16x16x32_bf16 v[60:63], v[148:151], v[194:197], v[60:63]
	s_setprio 0
	s_add_i32 s16, s29, s56
	v_lshl_add_u64 v[202:203], v[202:203], 0, s[86:87]
	s_mov_b32 m0, s16
	ds_read_b128 v[164:167], v210 offset:49152
	ds_read_b128 v[168:171], v210 offset:50176
	ds_read_b128 v[172:175], v210 offset:51200
	ds_read_b128 v[176:179], v210 offset:52224
	ds_read_b128 v[180:183], v210 offset:53248
	ds_read_b128 v[184:187], v210 offset:54272
	ds_read_b128 v[194:197], v210 offset:55296
	ds_read_b128 v[198:201], v210 offset:56320
	global_load_lds_dwordx4 v[202:203], off
	s_add_i32 m0, s16, 0x2000
	s_add_u32 s12, s12, 0x80080
	v_lshl_add_u64 v[202:203], v[204:205], 0, s[86:87]
	s_addc_u32 s13, s13, 0
	s_add_i32 s16, s42, s56
	global_load_lds_dwordx4 v[202:203], off
	s_mov_b32 m0, s16
	v_lshl_add_u64 v[202:203], v[206:207], 0, s[86:87]
	global_load_lds_dwordx4 v192, s[12:13]
	s_add_i32 m0, s16, 0x2000
	s_nop 0
	global_load_lds_dwordx4 v190, s[12:13]
	s_mov_b32 m0, s64
	s_nop 0
	global_load_lds_dwordx4 v[202:203], off
	v_lshl_add_u64 v[202:203], v[208:209], 0, s[86:87]
	s_mov_b32 m0, s65
	s_nop 0
	global_load_lds_dwordx4 v[202:203], off
	s_waitcnt vmcnt(8)
	s_waitcnt lgkmcnt(0)
	s_barrier
	s_setprio 1
	s_waitcnt lgkmcnt(0)
	v_mfma_f32_16x16x32_bf16 v[68:71], v[132:135], v[164:167], v[68:71]
	v_mfma_f32_16x16x32_bf16 v[68:71], v[136:139], v[168:171], v[68:71]
	v_mfma_f32_16x16x32_bf16 v[72:75], v[144:147], v[168:171], v[72:75]
	v_mfma_f32_16x16x32_bf16 v[72:75], v[140:143], v[164:167], v[72:75]
	v_mfma_f32_16x16x32_bf16 v[80:83], v[140:143], v[172:175], v[80:83]
	v_mfma_f32_16x16x32_bf16 v[80:83], v[144:147], v[176:179], v[80:83]
	v_mfma_f32_16x16x32_bf16 v[76:79], v[136:139], v[176:179], v[76:79]
	v_mfma_f32_16x16x32_bf16 v[76:79], v[132:135], v[172:175], v[76:79]
	s_setprio 0
	s_setprio 1
	v_mfma_f32_16x16x32_bf16 v[84:87], v[132:135], v[180:183], v[84:87]
	v_mfma_f32_16x16x32_bf16 v[84:87], v[136:139], v[184:187], v[84:87]
	v_mfma_f32_16x16x32_bf16 v[88:91], v[144:147], v[184:187], v[88:91]
	v_mfma_f32_16x16x32_bf16 v[88:91], v[140:143], v[180:183], v[88:91]
	v_mfma_f32_16x16x32_bf16 v[96:99], v[140:143], v[194:197], v[96:99]
	v_mfma_f32_16x16x32_bf16 v[96:99], v[144:147], v[198:201], v[96:99]
	v_mfma_f32_16x16x32_bf16 v[92:95], v[136:139], v[198:201], v[92:95]
	v_mfma_f32_16x16x32_bf16 v[92:95], v[132:135], v[194:197], v[92:95]
	s_setprio 0
	s_setprio 1
	v_mfma_f32_16x16x32_bf16 v[100:103], v[148:151], v[164:167], v[100:103]
	v_mfma_f32_16x16x32_bf16 v[100:103], v[152:155], v[168:171], v[100:103]
	v_mfma_f32_16x16x32_bf16 v[104:107], v[160:163], v[168:171], v[104:107]
	v_mfma_f32_16x16x32_bf16 v[104:107], v[156:159], v[164:167], v[104:107]
	v_mfma_f32_16x16x32_bf16 v[112:115], v[156:159], v[172:175], v[112:115]
	v_mfma_f32_16x16x32_bf16 v[112:115], v[160:163], v[176:179], v[112:115]
	v_mfma_f32_16x16x32_bf16 v[108:111], v[152:155], v[176:179], v[108:111]
	v_mfma_f32_16x16x32_bf16 v[108:111], v[148:151], v[172:175], v[108:111]
	s_setprio 0
	s_setprio 1
	v_mfma_f32_16x16x32_bf16 v[116:119], v[148:151], v[180:183], v[116:119]
	v_mfma_f32_16x16x32_bf16 v[116:119], v[152:155], v[184:187], v[116:119]
	v_mfma_f32_16x16x32_bf16 v[120:123], v[160:163], v[184:187], v[120:123]
	v_mfma_f32_16x16x32_bf16 v[120:123], v[156:159], v[180:183], v[120:123]
	v_mfma_f32_16x16x32_bf16 v[128:131], v[156:159], v[194:197], v[128:131]
	v_mfma_f32_16x16x32_bf16 v[128:131], v[160:163], v[198:201], v[128:131]
	s_setprio 2
	s_barrier
	v_mfma_f32_16x16x32_bf16 v[124:127], v[152:155], v[198:201], v[124:127]
	v_mfma_f32_16x16x32_bf16 v[124:127], v[148:151], v[194:197], v[124:127]
	s_setprio 0
	s_add_i32 s28, s28, 2
	s_add_u32 s14, s14, 0x100
	s_addc_u32 s15, s15, 0
	s_add_u32 s26, s26, 0x100
	s_addc_u32 s27, s27, 0
	s_cmp_gt_u32 s28, 29
	s_cbranch_scc0 .LBB0_1629
	s_and_b64 vcc, exec, s[48:49]
	s_cbranch_vccz .LBB0_1632
	s_barrier

.LBB0_2065:
	s_add_i32 s51, 0, 0x10000
	s_add_i32 s71, 0, 0x14000
	v_add_u32_e32 v16, s51, v232
	v_add_u32_e32 v32, s71, v232
	ds_read_b128 v[4:7], v16
	ds_read_b128 v[8:11], v16 offset:1024
	ds_read_b128 v[12:15], v16 offset:2048
	ds_read_b128 v[16:19], v16 offset:3072
	ds_read_b128 v[20:23], v32
	ds_read_b128 v[24:27], v32 offset:1024
	ds_read_b128 v[28:31], v32 offset:2048
	ds_read_b128 v[32:35], v32 offset:3072
	v_add_u32_e32 v233, 0, v231
	ds_read_b128 v[36:39], v233
	ds_read_b128 v[40:43], v233 offset:1024
	ds_read_b128 v[44:47], v233 offset:2048
	ds_read_b128 v[48:51], v233 offset:3072
	ds_read_b128 v[52:55], v233 offset:4096
	ds_read_b128 v[56:59], v233 offset:5120
	ds_read_b128 v[60:63], v233 offset:6144
	ds_read_b128 v[64:67], v233 offset:7168
	s_waitcnt vmcnt(8)
	s_waitcnt lgkmcnt(0)
	s_barrier
	s_setprio 1
	s_waitcnt lgkmcnt(0)
	v_mfma_f32_16x16x32_bf16 v[68:71], v[4:7], v[36:39], 0
	v_mfma_f32_16x16x32_bf16 v[68:71], v[8:11], v[40:43], v[68:71]
	v_mfma_f32_16x16x32_bf16 v[72:75], v[12:15], v[36:39], 0
	v_mfma_f32_16x16x32_bf16 v[72:75], v[16:19], v[40:43], v[72:75]
	v_mfma_f32_16x16x32_bf16 v[80:83], v[12:15], v[44:47], 0
	v_mfma_f32_16x16x32_bf16 v[80:83], v[16:19], v[48:51], v[80:83]
	v_mfma_f32_16x16x32_bf16 v[76:79], v[4:7], v[44:47], 0
	v_mfma_f32_16x16x32_bf16 v[76:79], v[8:11], v[48:51], v[76:79]
	s_setprio 0
	s_setprio 1
	v_mfma_f32_16x16x32_bf16 v[84:87], v[4:7], v[52:55], 0
	v_mfma_f32_16x16x32_bf16 v[84:87], v[8:11], v[56:59], v[84:87]
	v_mfma_f32_16x16x32_bf16 v[88:91], v[12:15], v[52:55], 0
	v_mfma_f32_16x16x32_bf16 v[88:91], v[16:19], v[56:59], v[88:91]
	v_mfma_f32_16x16x32_bf16 v[96:99], v[12:15], v[60:63], 0
	v_mfma_f32_16x16x32_bf16 v[96:99], v[16:19], v[64:67], v[96:99]
	v_mfma_f32_16x16x32_bf16 v[92:95], v[4:7], v[60:63], 0
	v_mfma_f32_16x16x32_bf16 v[92:95], v[8:11], v[64:67], v[92:95]
	s_setprio 0
	s_setprio 1
	v_mfma_f32_16x16x32_bf16 v[100:103], v[20:23], v[36:39], 0
	v_mfma_f32_16x16x32_bf16 v[36:39], v[28:31], v[36:39], 0
	v_mfma_f32_16x16x32_bf16 v[104:107], v[20:23], v[44:47], 0
	v_mfma_f32_16x16x32_bf16 v[44:47], v[28:31], v[44:47], 0
	v_mfma_f32_16x16x32_bf16 v[108:111], v[20:23], v[52:55], 0
	v_mfma_f32_16x16x32_bf16 v[52:55], v[28:31], v[52:55], 0
	v_mfma_f32_16x16x32_bf16 v[112:115], v[20:23], v[60:63], 0
	v_mfma_f32_16x16x32_bf16 v[60:63], v[28:31], v[60:63], 0
	s_setprio 0
	s_setprio 1
	v_mfma_f32_16x16x32_bf16 v[100:103], v[24:27], v[40:43], v[100:103]
	v_mfma_f32_16x16x32_bf16 v[40:43], v[32:35], v[40:43], v[36:39]
	v_mfma_f32_16x16x32_bf16 v[104:107], v[24:27], v[48:51], v[104:107]
	v_mfma_f32_16x16x32_bf16 v[48:51], v[32:35], v[48:51], v[44:47]
	v_mfma_f32_16x16x32_bf16 v[108:111], v[24:27], v[56:59], v[108:111]
	v_mfma_f32_16x16x32_bf16 v[56:59], v[32:35], v[56:59], v[52:55]
	s_setprio 2
	s_barrier
	v_mfma_f32_16x16x32_bf16 v[112:115], v[24:27], v[64:67], v[112:115]
	v_mfma_f32_16x16x32_bf16 v[64:67], v[32:35], v[64:67], v[60:63]
	s_setprio 0
	v_lshl_add_u64 v[186:187], s[12:13], 0, v[2:3]
	s_add_i32 s51, s51, s38
	v_mov_b32_e32 v191, v3
	v_lshl_add_u64 v[134:135], v[186:187], 0, s[74:75]
	s_mov_b32 m0, s51
	v_lshl_add_u64 v[246:247], s[12:13], 0, v[190:191]
	ds_read_b128 v[36:39], v233 offset:16384
	ds_read_b128 v[44:47], v233 offset:17408
	ds_read_b128 v[52:55], v233 offset:18432
	ds_read_b128 v[60:63], v233 offset:19456
	ds_read_b128 v[116:119], v233 offset:20480
	ds_read_b128 v[120:123], v233 offset:21504
	ds_read_b128 v[124:127], v233 offset:22528
	ds_read_b128 v[128:131], v233 offset:23552
	global_load_lds_dwordx4 v[134:135], off
	v_lshl_add_u64 v[134:135], v[246:247], 0, s[74:75]
	s_add_i32 m0, s51, 0x2000
	s_add_i32 s51, s71, s38
	global_load_lds_dwordx4 v[134:135], off
	s_mov_b32 m0, s51
	v_mov_b32_e32 v133, v3
	global_load_lds_dwordx4 v2, s[16:17]
	s_add_i32 m0, s51, 0x2000
	v_lshl_add_u64 v[248:249], s[14:15], 0, v[132:133]
	v_mov_b32_e32 v189, v3
	global_load_lds_dwordx4 v190, s[16:17]
	v_lshl_add_u64 v[134:135], v[248:249], 0, s[74:75]
	s_mov_b32 m0, s56
	v_lshl_add_u64 v[250:251], s[14:15], 0, v[188:189]
	global_load_lds_dwordx4 v[134:135], off
	v_lshl_add_u64 v[134:135], v[250:251], 0, s[74:75]
	s_mov_b32 m0, s57
	s_nop 0
	global_load_lds_dwordx4 v[134:135], off
	s_waitcnt vmcnt(8)
	s_waitcnt lgkmcnt(0)
	s_barrier
	s_setprio 1
	s_waitcnt lgkmcnt(0)
	v_mfma_f32_16x16x32_bf16 v[134:137], v[4:7], v[36:39], 0
	v_mfma_f32_16x16x32_bf16 v[138:141], v[12:15], v[36:39], 0
	v_mfma_f32_16x16x32_bf16 v[142:145], v[4:7], v[52:55], 0
	v_mfma_f32_16x16x32_bf16 v[146:149], v[12:15], v[52:55], 0
	v_mfma_f32_16x16x32_bf16 v[150:153], v[4:7], v[116:119], 0
	v_mfma_f32_16x16x32_bf16 v[154:157], v[12:15], v[116:119], 0
	v_mfma_f32_16x16x32_bf16 v[4:7], v[4:7], v[124:127], 0
	v_mfma_f32_16x16x32_bf16 v[12:15], v[12:15], v[124:127], 0
	s_setprio 0
	s_setprio 1
	v_mfma_f32_16x16x32_bf16 v[134:137], v[8:11], v[44:47], v[134:137]
	v_mfma_f32_16x16x32_bf16 v[138:141], v[16:19], v[44:47], v[138:141]
	v_mfma_f32_16x16x32_bf16 v[142:145], v[8:11], v[60:63], v[142:145]
	v_mfma_f32_16x16x32_bf16 v[146:149], v[16:19], v[60:63], v[146:149]
	v_mfma_f32_16x16x32_bf16 v[150:153], v[8:11], v[120:123], v[150:153]
	v_mfma_f32_16x16x32_bf16 v[154:157], v[16:19], v[120:123], v[154:157]
	v_mfma_f32_16x16x32_bf16 v[158:161], v[8:11], v[128:131], v[4:7]
	v_mfma_f32_16x16x32_bf16 v[162:165], v[16:19], v[128:131], v[12:15]
	s_setprio 0
	s_setprio 1
	v_mfma_f32_16x16x32_bf16 v[4:7], v[20:23], v[36:39], 0
	v_mfma_f32_16x16x32_bf16 v[8:11], v[28:31], v[36:39], 0
	v_mfma_f32_16x16x32_bf16 v[12:15], v[20:23], v[52:55], 0
	v_mfma_f32_16x16x32_bf16 v[16:19], v[28:31], v[52:55], 0
	v_mfma_f32_16x16x32_bf16 v[36:39], v[20:23], v[116:119], 0
	v_mfma_f32_16x16x32_bf16 v[52:55], v[28:31], v[116:119], 0
	v_mfma_f32_16x16x32_bf16 v[20:23], v[20:23], v[124:127], 0
	v_mfma_f32_16x16x32_bf16 v[28:31], v[28:31], v[124:127], 0
	s_setprio 0
	s_setprio 1
	v_mfma_f32_16x16x32_bf16 v[116:119], v[24:27], v[44:47], v[4:7]
	v_mfma_f32_16x16x32_bf16 v[124:127], v[32:35], v[44:47], v[8:11]
	v_mfma_f32_16x16x32_bf16 v[174:177], v[24:27], v[120:123], v[36:39]
	v_mfma_f32_16x16x32_bf16 v[120:123], v[32:35], v[120:123], v[52:55]
	v_mfma_f32_16x16x32_bf16 v[178:181], v[24:27], v[128:131], v[20:23]
	v_mfma_f32_16x16x32_bf16 v[128:131], v[32:35], v[128:131], v[28:31]
	s_setprio 2
	s_barrier
	v_mfma_f32_16x16x32_bf16 v[166:169], v[24:27], v[60:63], v[12:15]
	v_mfma_f32_16x16x32_bf16 v[170:173], v[32:35], v[60:63], v[16:19]
	s_setprio 0
	s_add_i32 s51, 0, 0x18000
	v_add_u32_e32 v4, s51, v232
	s_add_i32 s71, 0, 0x1c000
	ds_read_b128 v[182:185], v4
	ds_read_b128 v[192:195], v4 offset:1024
	ds_read_b128 v[196:199], v4 offset:2048
	ds_read_b128 v[200:203], v4 offset:3072
	v_add_u32_e32 v4, s71, v232
	ds_read_b128 v[204:207], v4
	ds_read_b128 v[208:211], v4 offset:1024
	ds_read_b128 v[212:215], v4 offset:2048
	ds_read_b128 v[216:219], v4 offset:3072
	s_mov_b32 m0, s58
	ds_read_b128 v[44:47], v233 offset:32768
	ds_read_b128 v[52:55], v233 offset:33792
	ds_read_b128 v[60:63], v233 offset:34816
	ds_read_b128 v[220:223], v233 offset:35840
	ds_read_b128 v[224:227], v233 offset:36864
	ds_read_b128 v[234:237], v233 offset:37888
	ds_read_b128 v[238:241], v233 offset:38912
	ds_read_b128 v[242:245], v233 offset:39936
	global_load_lds_dwordx4 v132, s[26:27]
	s_mov_b32 m0, s59
	s_nop 0
	global_load_lds_dwordx4 v188, s[26:27]
	s_waitcnt vmcnt(8)
	s_waitcnt lgkmcnt(0)
	s_barrier
	s_setprio 1
	s_waitcnt lgkmcnt(0)
	v_mfma_f32_16x16x32_bf16 v[4:7], v[182:185], v[44:47], v[68:71]
	v_mfma_f32_16x16x32_bf16 v[8:11], v[196:199], v[44:47], v[72:75]
	v_mfma_f32_16x16x32_bf16 v[12:15], v[182:185], v[60:63], v[76:79]
	v_mfma_f32_16x16x32_bf16 v[16:19], v[196:199], v[60:63], v[80:83]
	v_mfma_f32_16x16x32_bf16 v[20:23], v[182:185], v[224:227], v[84:87]
	v_mfma_f32_16x16x32_bf16 v[24:27], v[196:199], v[224:227], v[88:91]
	v_mfma_f32_16x16x32_bf16 v[28:31], v[182:185], v[238:241], v[92:95]
	v_mfma_f32_16x16x32_bf16 v[32:35], v[196:199], v[238:241], v[96:99]
	s_setprio 0
	s_setprio 1
	v_mfma_f32_16x16x32_bf16 v[4:7], v[192:195], v[52:55], v[4:7]
	v_mfma_f32_16x16x32_bf16 v[8:11], v[200:203], v[52:55], v[8:11]
	v_mfma_f32_16x16x32_bf16 v[12:15], v[192:195], v[220:223], v[12:15]
	v_mfma_f32_16x16x32_bf16 v[16:19], v[200:203], v[220:223], v[16:19]
	v_mfma_f32_16x16x32_bf16 v[20:23], v[192:195], v[234:237], v[20:23]
	v_mfma_f32_16x16x32_bf16 v[24:27], v[200:203], v[234:237], v[24:27]
	v_mfma_f32_16x16x32_bf16 v[28:31], v[192:195], v[242:245], v[28:31]
	v_mfma_f32_16x16x32_bf16 v[32:35], v[200:203], v[242:245], v[32:35]
	s_setprio 0
	s_setprio 1
	v_mfma_f32_16x16x32_bf16 v[36:39], v[204:207], v[44:47], v[100:103]
	v_mfma_f32_16x16x32_bf16 v[40:43], v[212:215], v[44:47], v[40:43]
	v_mfma_f32_16x16x32_bf16 v[36:39], v[208:211], v[52:55], v[36:39]
	v_mfma_f32_16x16x32_bf16 v[40:43], v[216:219], v[52:55], v[40:43]
	v_mfma_f32_16x16x32_bf16 v[44:47], v[204:207], v[60:63], v[104:107]
	v_mfma_f32_16x16x32_bf16 v[48:51], v[212:215], v[60:63], v[48:51]
	v_mfma_f32_16x16x32_bf16 v[52:55], v[204:207], v[224:227], v[108:111]
	v_mfma_f32_16x16x32_bf16 v[56:59], v[212:215], v[224:227], v[56:59]
	s_setprio 0
	s_setprio 1
	v_mfma_f32_16x16x32_bf16 v[60:63], v[204:207], v[238:241], v[112:115]
	v_mfma_f32_16x16x32_bf16 v[64:67], v[212:215], v[238:241], v[64:67]
	v_mfma_f32_16x16x32_bf16 v[44:47], v[208:211], v[220:223], v[44:47]
	v_mfma_f32_16x16x32_bf16 v[48:51], v[216:219], v[220:223], v[48:51]
	v_mfma_f32_16x16x32_bf16 v[52:55], v[208:211], v[234:237], v[52:55]
	v_mfma_f32_16x16x32_bf16 v[56:59], v[216:219], v[234:237], v[56:59]
	s_setprio 2
	s_barrier
	v_mfma_f32_16x16x32_bf16 v[60:63], v[208:211], v[242:245], v[60:63]
	v_mfma_f32_16x16x32_bf16 v[64:67], v[216:219], v[242:245], v[64:67]
	s_setprio 0
	s_add_i32 s51, s51, s38
	v_lshl_add_u64 v[68:69], v[186:187], 0, s[24:25]
	s_mov_b32 m0, s51
	ds_read_b128 v[104:107], v233 offset:49152
	ds_read_b128 v[108:111], v233 offset:50176
	ds_read_b128 v[112:115], v233 offset:51200
	ds_read_b128 v[220:223], v233 offset:52224
	ds_read_b128 v[224:227], v233 offset:53248
	ds_read_b128 v[234:237], v233 offset:54272
	ds_read_b128 v[238:241], v233 offset:55296
	ds_read_b128 v[242:245], v233 offset:56320
	global_load_lds_dwordx4 v[68:69], off
	v_lshl_add_u64 v[68:69], v[246:247], 0, s[24:25]
	s_add_i32 m0, s51, 0x2000
	s_add_i32 s51, s71, s38
	global_load_lds_dwordx4 v[68:69], off
	s_mov_b32 m0, s51
	v_lshl_add_u64 v[68:69], v[248:249], 0, s[24:25]
	global_load_lds_dwordx4 v2, s[28:29]
	s_add_i32 m0, s51, 0x2000
	s_nop 0
	global_load_lds_dwordx4 v190, s[28:29]
	s_mov_b32 m0, s63
	s_nop 0
	global_load_lds_dwordx4 v[68:69], off
	v_lshl_add_u64 v[68:69], v[250:251], 0, s[24:25]
	s_mov_b32 m0, s64
	s_nop 0
	global_load_lds_dwordx4 v[68:69], off
	s_waitcnt vmcnt(8)
	s_waitcnt lgkmcnt(0)
	s_barrier
	s_setprio 1
	s_waitcnt lgkmcnt(0)
	v_mfma_f32_16x16x32_bf16 v[68:71], v[182:185], v[104:107], v[134:137]
	v_mfma_f32_16x16x32_bf16 v[72:75], v[196:199], v[104:107], v[138:141]
	v_mfma_f32_16x16x32_bf16 v[76:79], v[182:185], v[112:115], v[142:145]
	v_mfma_f32_16x16x32_bf16 v[80:83], v[196:199], v[112:115], v[146:149]
	v_mfma_f32_16x16x32_bf16 v[84:87], v[182:185], v[224:227], v[150:153]
	v_mfma_f32_16x16x32_bf16 v[88:91], v[196:199], v[224:227], v[154:157]
	v_mfma_f32_16x16x32_bf16 v[92:95], v[182:185], v[238:241], v[158:161]
	v_mfma_f32_16x16x32_bf16 v[96:99], v[196:199], v[238:241], v[162:165]
	s_setprio 0
	s_setprio 1
	v_mfma_f32_16x16x32_bf16 v[68:71], v[192:195], v[108:111], v[68:71]
	v_mfma_f32_16x16x32_bf16 v[72:75], v[200:203], v[108:111], v[72:75]
	v_mfma_f32_16x16x32_bf16 v[76:79], v[192:195], v[220:223], v[76:79]
	v_mfma_f32_16x16x32_bf16 v[80:83], v[200:203], v[220:223], v[80:83]
	v_mfma_f32_16x16x32_bf16 v[84:87], v[192:195], v[234:237], v[84:87]
	v_mfma_f32_16x16x32_bf16 v[88:91], v[200:203], v[234:237], v[88:91]
	v_mfma_f32_16x16x32_bf16 v[92:95], v[192:195], v[242:245], v[92:95]
	v_mfma_f32_16x16x32_bf16 v[96:99], v[200:203], v[242:245], v[96:99]
	s_setprio 0
	s_setprio 1
	v_mfma_f32_16x16x32_bf16 v[100:103], v[204:207], v[104:107], v[116:119]
	v_mfma_f32_16x16x32_bf16 v[104:107], v[212:215], v[104:107], v[124:127]
	v_mfma_f32_16x16x32_bf16 v[100:103], v[208:211], v[108:111], v[100:103]
	v_mfma_f32_16x16x32_bf16 v[104:107], v[216:219], v[108:111], v[104:107]
	v_mfma_f32_16x16x32_bf16 v[108:111], v[204:207], v[112:115], v[166:169]
	v_mfma_f32_16x16x32_bf16 v[112:115], v[212:215], v[112:115], v[170:173]
	v_mfma_f32_16x16x32_bf16 v[116:119], v[204:207], v[224:227], v[174:177]
	v_mfma_f32_16x16x32_bf16 v[120:123], v[212:215], v[224:227], v[120:123]
	s_setprio 0
	s_setprio 1
	v_mfma_f32_16x16x32_bf16 v[124:127], v[204:207], v[238:241], v[178:181]
	v_mfma_f32_16x16x32_bf16 v[128:131], v[212:215], v[238:241], v[128:131]
	v_mfma_f32_16x16x32_bf16 v[108:111], v[208:211], v[220:223], v[108:111]
	v_mfma_f32_16x16x32_bf16 v[112:115], v[216:219], v[220:223], v[112:115]
	v_mfma_f32_16x16x32_bf16 v[116:119], v[208:211], v[234:237], v[116:119]
	v_mfma_f32_16x16x32_bf16 v[120:123], v[216:219], v[234:237], v[120:123]
	s_setprio 2
	s_barrier
	v_mfma_f32_16x16x32_bf16 v[124:127], v[208:211], v[242:245], v[124:127]
	v_mfma_f32_16x16x32_bf16 v[128:131], v[216:219], v[242:245], v[128:131]
	s_setprio 0
	s_add_i32 s45, s45, 2
	s_cmp_ge_i32 s45, s44
	s_cbranch_scc0 .LBB0_2065
	v_mov_b32_e32 v192, v2
	s_branch .LBB0_2068

.LBB0_2069:
	s_add_u32 s12, s14, 0xfff80080
	s_addc_u32 s13, s15, -1
	s_add_i32 s29, 0, 0x10000
	s_cmp_eq_u32 s28, 4
	s_cselect_b32 s17, s9, s13
	s_cselect_b32 s16, s8, s12
	s_cselect_b32 s13, s11, s27
	s_cselect_b32 s12, s10, s26
	s_add_i32 s51, 0, 0x14000
	v_add_u32_e32 v144, s29, v232
	v_add_u32_e32 v160, s51, v232
	s_waitcnt lgkmcnt(0)
	ds_read_b128 v[132:135], v144
	ds_read_b128 v[136:139], v144 offset:1024
	ds_read_b128 v[140:143], v144 offset:2048
	ds_read_b128 v[144:147], v144 offset:3072
	ds_read_b128 v[148:151], v160
	ds_read_b128 v[152:155], v160 offset:1024
	ds_read_b128 v[156:159], v160 offset:2048
	ds_read_b128 v[160:163], v160 offset:3072
	s_mov_b32 m0, s65
	v_add_u32_e32 v210, 0, v231
	ds_read_b128 v[164:167], v210
	ds_read_b128 v[168:171], v210 offset:1024
	ds_read_b128 v[172:175], v210 offset:2048
	ds_read_b128 v[176:179], v210 offset:3072
	ds_read_b128 v[180:183], v210 offset:4096
	ds_read_b128 v[184:187], v210 offset:5120
	ds_read_b128 v[194:197], v210 offset:6144
	ds_read_b128 v[198:201], v210 offset:7168
	global_load_lds_dwordx4 v2, s[14:15]
	s_mov_b32 m0, s66
	v_mov_b32_e32 v189, v3
	global_load_lds_dwordx4 v188, s[14:15]
	s_waitcnt vmcnt(8)
	s_waitcnt lgkmcnt(0)
	s_barrier
	s_setprio 1
	s_waitcnt lgkmcnt(0)
	v_mfma_f32_16x16x32_bf16 v[4:7], v[132:135], v[164:167], v[4:7]
	v_mfma_f32_16x16x32_bf16 v[4:7], v[136:139], v[168:171], v[4:7]
	v_mfma_f32_16x16x32_bf16 v[8:11], v[144:147], v[168:171], v[8:11]
	v_mfma_f32_16x16x32_bf16 v[8:11], v[140:143], v[164:167], v[8:11]
	v_mfma_f32_16x16x32_bf16 v[16:19], v[140:143], v[172:175], v[16:19]
	v_mfma_f32_16x16x32_bf16 v[16:19], v[144:147], v[176:179], v[16:19]
	v_mfma_f32_16x16x32_bf16 v[12:15], v[136:139], v[176:179], v[12:15]
	v_mfma_f32_16x16x32_bf16 v[12:15], v[132:135], v[172:175], v[12:15]
	s_setprio 0
	s_setprio 1
	v_mfma_f32_16x16x32_bf16 v[20:23], v[132:135], v[180:183], v[20:23]
	v_mfma_f32_16x16x32_bf16 v[20:23], v[136:139], v[184:187], v[20:23]
	v_mfma_f32_16x16x32_bf16 v[24:27], v[144:147], v[184:187], v[24:27]
	v_mfma_f32_16x16x32_bf16 v[24:27], v[140:143], v[180:183], v[24:27]
	v_mfma_f32_16x16x32_bf16 v[32:35], v[140:143], v[194:197], v[32:35]
	v_mfma_f32_16x16x32_bf16 v[32:35], v[144:147], v[198:201], v[32:35]
	v_mfma_f32_16x16x32_bf16 v[28:31], v[136:139], v[198:201], v[28:31]
	v_mfma_f32_16x16x32_bf16 v[28:31], v[132:135], v[194:197], v[28:31]
	s_setprio 0
	s_setprio 1
	v_mfma_f32_16x16x32_bf16 v[36:39], v[148:151], v[164:167], v[36:39]
	v_mfma_f32_16x16x32_bf16 v[36:39], v[152:155], v[168:171], v[36:39]
	v_mfma_f32_16x16x32_bf16 v[40:43], v[160:163], v[168:171], v[40:43]
	v_mfma_f32_16x16x32_bf16 v[40:43], v[156:159], v[164:167], v[40:43]
	v_mfma_f32_16x16x32_bf16 v[48:51], v[156:159], v[172:175], v[48:51]
	v_mfma_f32_16x16x32_bf16 v[48:51], v[160:163], v[176:179], v[48:51]
	v_mfma_f32_16x16x32_bf16 v[44:47], v[152:155], v[176:179], v[44:47]
	v_mfma_f32_16x16x32_bf16 v[44:47], v[148:151], v[172:175], v[44:47]
	s_setprio 0
	s_setprio 1
	v_mfma_f32_16x16x32_bf16 v[52:55], v[148:151], v[180:183], v[52:55]
	v_mfma_f32_16x16x32_bf16 v[52:55], v[152:155], v[184:187], v[52:55]
	v_mfma_f32_16x16x32_bf16 v[56:59], v[160:163], v[184:187], v[56:59]
	v_mfma_f32_16x16x32_bf16 v[56:59], v[156:159], v[180:183], v[56:59]
	v_mfma_f32_16x16x32_bf16 v[64:67], v[156:159], v[194:197], v[64:67]
	v_mfma_f32_16x16x32_bf16 v[64:67], v[160:163], v[198:201], v[64:67]
	s_setprio 2
	s_barrier
	v_mfma_f32_16x16x32_bf16 v[60:63], v[152:155], v[198:201], v[60:63]
	v_mfma_f32_16x16x32_bf16 v[60:63], v[148:151], v[194:197], v[60:63]
	s_setprio 0
	s_add_i32 s29, s29, s38
	s_mov_b32 m0, s29
	ds_read_b128 v[164:167], v210 offset:16384
	ds_read_b128 v[168:171], v210 offset:17408
	ds_read_b128 v[172:175], v210 offset:18432
	ds_read_b128 v[176:179], v210 offset:19456
	ds_read_b128 v[180:183], v210 offset:20480
	ds_read_b128 v[184:187], v210 offset:21504
	ds_read_b128 v[194:197], v210 offset:22528
	ds_read_b128 v[198:201], v210 offset:23552
	global_load_lds_dwordx4 v192, s[12:13]
	s_add_i32 m0, s29, 0x2000
	s_add_u32 s44, s12, 0x20000
	s_addc_u32 s45, s13, 0
	s_add_i32 s29, s51, s38
	global_load_lds_dwordx4 v190, s[12:13]
	s_mov_b32 m0, s29
	v_mov_b32_e32 v193, v3
	global_load_lds_dwordx4 v192, s[44:45]
	s_add_i32 m0, s29, 0x2000
	v_mov_b32_e32 v191, v3
	global_load_lds_dwordx4 v190, s[44:45]
	s_mov_b32 m0, s56
	v_lshl_add_u64 v[202:203], s[12:13], 0, v[192:193]
	global_load_lds_dwordx4 v2, s[16:17]
	s_mov_b32 m0, s57
	v_lshl_add_u64 v[204:205], s[12:13], 0, v[190:191]
	global_load_lds_dwordx4 v188, s[16:17]
	s_waitcnt vmcnt(8)
	s_waitcnt lgkmcnt(0)
	v_lshl_add_u64 v[206:207], s[16:17], 0, v[2:3]
	v_lshl_add_u64 v[208:209], s[16:17], 0, v[188:189]
	s_barrier
	s_setprio 1
	s_waitcnt lgkmcnt(0)
	v_mfma_f32_16x16x32_bf16 v[68:71], v[132:135], v[164:167], v[68:71]
	v_mfma_f32_16x16x32_bf16 v[68:71], v[136:139], v[168:171], v[68:71]
	v_mfma_f32_16x16x32_bf16 v[72:75], v[144:147], v[168:171], v[72:75]
	v_mfma_f32_16x16x32_bf16 v[72:75], v[140:143], v[164:167], v[72:75]
	v_mfma_f32_16x16x32_bf16 v[80:83], v[140:143], v[172:175], v[80:83]
	v_mfma_f32_16x16x32_bf16 v[80:83], v[144:147], v[176:179], v[80:83]
	v_mfma_f32_16x16x32_bf16 v[76:79], v[136:139], v[176:179], v[76:79]
	v_mfma_f32_16x16x32_bf16 v[76:79], v[132:135], v[172:175], v[76:79]
	s_setprio 0
	s_setprio 1
	v_mfma_f32_16x16x32_bf16 v[84:87], v[132:135], v[180:183], v[84:87]
	v_mfma_f32_16x16x32_bf16 v[84:87], v[136:139], v[184:187], v[84:87]
	v_mfma_f32_16x16x32_bf16 v[88:91], v[144:147], v[184:187], v[88:91]
	v_mfma_f32_16x16x32_bf16 v[88:91], v[140:143], v[180:183], v[88:91]
	v_mfma_f32_16x16x32_bf16 v[96:99], v[140:143], v[194:197], v[96:99]
	v_mfma_f32_16x16x32_bf16 v[96:99], v[144:147], v[198:201], v[96:99]
	v_mfma_f32_16x16x32_bf16 v[92:95], v[136:139], v[198:201], v[92:95]
	v_mfma_f32_16x16x32_bf16 v[92:95], v[132:135], v[194:197], v[92:95]
	s_setprio 0
	s_setprio 1
	v_mfma_f32_16x16x32_bf16 v[100:103], v[148:151], v[164:167], v[100:103]
	v_mfma_f32_16x16x32_bf16 v[100:103], v[152:155], v[168:171], v[100:103]
	v_mfma_f32_16x16x32_bf16 v[104:107], v[160:163], v[168:171], v[104:107]
	v_mfma_f32_16x16x32_bf16 v[104:107], v[156:159], v[164:167], v[104:107]
	v_mfma_f32_16x16x32_bf16 v[112:115], v[156:159], v[172:175], v[112:115]
	v_mfma_f32_16x16x32_bf16 v[112:115], v[160:163], v[176:179], v[112:115]
	v_mfma_f32_16x16x32_bf16 v[108:111], v[152:155], v[176:179], v[108:111]
	v_mfma_f32_16x16x32_bf16 v[108:111], v[148:151], v[172:175], v[108:111]
	s_setprio 0
	s_setprio 1
	v_mfma_f32_16x16x32_bf16 v[116:119], v[148:151], v[180:183], v[116:119]
	v_mfma_f32_16x16x32_bf16 v[116:119], v[152:155], v[184:187], v[116:119]
	v_mfma_f32_16x16x32_bf16 v[120:123], v[160:163], v[184:187], v[120:123]
	v_mfma_f32_16x16x32_bf16 v[120:123], v[156:159], v[180:183], v[120:123]
	v_mfma_f32_16x16x32_bf16 v[128:131], v[156:159], v[194:197], v[128:131]
	v_mfma_f32_16x16x32_bf16 v[128:131], v[160:163], v[198:201], v[128:131]
	s_setprio 2
	s_barrier
	v_mfma_f32_16x16x32_bf16 v[124:127], v[152:155], v[198:201], v[124:127]
	v_mfma_f32_16x16x32_bf16 v[124:127], v[148:151], v[194:197], v[124:127]
	s_setprio 0
	s_add_i32 s29, 0, 0x18000
	s_add_i32 s44, 0, 0x1c000
	v_add_u32_e32 v144, s29, v232
	v_add_u32_e32 v160, s44, v232
	ds_read_b128 v[132:135], v144
	ds_read_b128 v[136:139], v144 offset:1024
	ds_read_b128 v[140:143], v144 offset:2048
	ds_read_b128 v[144:147], v144 offset:3072
	ds_read_b128 v[148:151], v160
	ds_read_b128 v[152:155], v160 offset:1024
	ds_read_b128 v[156:159], v160 offset:2048
	ds_read_b128 v[160:163], v160 offset:3072
	s_add_u32 s16, s16, 0x80000
	s_addc_u32 s17, s17, 0
	s_mov_b32 m0, s58
	ds_read_b128 v[164:167], v210 offset:32768
	ds_read_b128 v[168:171], v210 offset:33792
	ds_read_b128 v[172:175], v210 offset:34816
	ds_read_b128 v[176:179], v210 offset:35840
	ds_read_b128 v[180:183], v210 offset:36864
	ds_read_b128 v[184:187], v210 offset:37888
	ds_read_b128 v[194:197], v210 offset:38912
	ds_read_b128 v[198:201], v210 offset:39936
	global_load_lds_dwordx4 v2, s[16:17]
	s_mov_b32 m0, s59
	s_nop 0
	global_load_lds_dwordx4 v188, s[16:17]
	s_waitcnt vmcnt(8)
	s_waitcnt lgkmcnt(0)
	s_barrier
	s_setprio 1
	s_waitcnt lgkmcnt(0)
	v_mfma_f32_16x16x32_bf16 v[4:7], v[132:135], v[164:167], v[4:7]
	v_mfma_f32_16x16x32_bf16 v[4:7], v[136:139], v[168:171], v[4:7]
	v_mfma_f32_16x16x32_bf16 v[8:11], v[144:147], v[168:171], v[8:11]
	v_mfma_f32_16x16x32_bf16 v[8:11], v[140:143], v[164:167], v[8:11]
	v_mfma_f32_16x16x32_bf16 v[16:19], v[140:143], v[172:175], v[16:19]
	v_mfma_f32_16x16x32_bf16 v[16:19], v[144:147], v[176:179], v[16:19]
	v_mfma_f32_16x16x32_bf16 v[12:15], v[136:139], v[176:179], v[12:15]
	v_mfma_f32_16x16x32_bf16 v[12:15], v[132:135], v[172:175], v[12:15]
	s_setprio 0
	s_setprio 1
	v_mfma_f32_16x16x32_bf16 v[20:23], v[132:135], v[180:183], v[20:23]
	v_mfma_f32_16x16x32_bf16 v[20:23], v[136:139], v[184:187], v[20:23]
	v_mfma_f32_16x16x32_bf16 v[24:27], v[144:147], v[184:187], v[24:27]
	v_mfma_f32_16x16x32_bf16 v[24:27], v[140:143], v[180:183], v[24:27]
	v_mfma_f32_16x16x32_bf16 v[32:35], v[140:143], v[194:197], v[32:35]
	v_mfma_f32_16x16x32_bf16 v[32:35], v[144:147], v[198:201], v[32:35]
	v_mfma_f32_16x16x32_bf16 v[28:31], v[136:139], v[198:201], v[28:31]
	v_mfma_f32_16x16x32_bf16 v[28:31], v[132:135], v[194:197], v[28:31]
	s_setprio 0
	s_setprio 1
	v_mfma_f32_16x16x32_bf16 v[36:39], v[148:151], v[164:167], v[36:39]
	v_mfma_f32_16x16x32_bf16 v[36:39], v[152:155], v[168:171], v[36:39]
	v_mfma_f32_16x16x32_bf16 v[40:43], v[160:163], v[168:171], v[40:43]
	v_mfma_f32_16x16x32_bf16 v[40:43], v[156:159], v[164:167], v[40:43]
	v_mfma_f32_16x16x32_bf16 v[48:51], v[156:159], v[172:175], v[48:51]
	v_mfma_f32_16x16x32_bf16 v[48:51], v[160:163], v[176:179], v[48:51]
	v_mfma_f32_16x16x32_bf16 v[44:47], v[152:155], v[176:179], v[44:47]
	v_mfma_f32_16x16x32_bf16 v[44:47], v[148:151], v[172:175], v[44:47]
	s_setprio 0
	s_setprio 1
	v_mfma_f32_16x16x32_bf16 v[52:55], v[148:151], v[180:183], v[52:55]
	v_mfma_f32_16x16x32_bf16 v[52:55], v[152:155], v[184:187], v[52:55]
	v_mfma_f32_16x16x32_bf16 v[56:59], v[160:163], v[184:187], v[56:59]
	v_mfma_f32_16x16x32_bf16 v[56:59], v[156:159], v[180:183], v[56:59]
	v_mfma_f32_16x16x32_bf16 v[64:67], v[156:159], v[194:197], v[64:67]
	v_mfma_f32_16x16x32_bf16 v[64:67], v[160:163], v[198:201], v[64:67]
	s_setprio 2
	s_barrier
	v_mfma_f32_16x16x32_bf16 v[60:63], v[152:155], v[198:201], v[60:63]
	v_mfma_f32_16x16x32_bf16 v[60:63], v[148:151], v[194:197], v[60:63]
	s_setprio 0
	s_add_i32 s16, s29, s38
	v_lshl_add_u64 v[202:203], v[202:203], 0, s[86:87]
	s_mov_b32 m0, s16
	ds_read_b128 v[164:167], v210 offset:49152
	ds_read_b128 v[168:171], v210 offset:50176
	ds_read_b128 v[172:175], v210 offset:51200
	ds_read_b128 v[176:179], v210 offset:52224
	ds_read_b128 v[180:183], v210 offset:53248
	ds_read_b128 v[184:187], v210 offset:54272
	ds_read_b128 v[194:197], v210 offset:55296
	ds_read_b128 v[198:201], v210 offset:56320
	global_load_lds_dwordx4 v[202:203], off
	s_add_i32 m0, s16, 0x2000
	s_add_u32 s12, s12, 0x20080
	v_lshl_add_u64 v[202:203], v[204:205], 0, s[86:87]
	s_addc_u32 s13, s13, 0
	s_add_i32 s16, s44, s38
	global_load_lds_dwordx4 v[202:203], off
	s_mov_b32 m0, s16
	v_lshl_add_u64 v[202:203], v[206:207], 0, s[86:87]
	global_load_lds_dwordx4 v192, s[12:13]
	s_add_i32 m0, s16, 0x2000
	s_nop 0
	global_load_lds_dwordx4 v190, s[12:13]
	s_mov_b32 m0, s63
	s_nop 0
	global_load_lds_dwordx4 v[202:203], off
	v_lshl_add_u64 v[202:203], v[208:209], 0, s[86:87]
	s_mov_b32 m0, s64
	s_nop 0
	global_load_lds_dwordx4 v[202:203], off
	s_waitcnt vmcnt(8)
	s_waitcnt lgkmcnt(0)
	s_barrier
	s_setprio 1
	s_waitcnt lgkmcnt(0)
	v_mfma_f32_16x16x32_bf16 v[68:71], v[132:135], v[164:167], v[68:71]
	v_mfma_f32_16x16x32_bf16 v[68:71], v[136:139], v[168:171], v[68:71]
	v_mfma_f32_16x16x32_bf16 v[72:75], v[144:147], v[168:171], v[72:75]
	v_mfma_f32_16x16x32_bf16 v[72:75], v[140:143], v[164:167], v[72:75]
	v_mfma_f32_16x16x32_bf16 v[80:83], v[140:143], v[172:175], v[80:83]
	v_mfma_f32_16x16x32_bf16 v[80:83], v[144:147], v[176:179], v[80:83]
	v_mfma_f32_16x16x32_bf16 v[76:79], v[136:139], v[176:179], v[76:79]
	v_mfma_f32_16x16x32_bf16 v[76:79], v[132:135], v[172:175], v[76:79]
	s_setprio 0
	s_setprio 1
	v_mfma_f32_16x16x32_bf16 v[84:87], v[132:135], v[180:183], v[84:87]
	v_mfma_f32_16x16x32_bf16 v[84:87], v[136:139], v[184:187], v[84:87]
	v_mfma_f32_16x16x32_bf16 v[88:91], v[144:147], v[184:187], v[88:91]
	v_mfma_f32_16x16x32_bf16 v[88:91], v[140:143], v[180:183], v[88:91]
	v_mfma_f32_16x16x32_bf16 v[96:99], v[140:143], v[194:197], v[96:99]
	v_mfma_f32_16x16x32_bf16 v[96:99], v[144:147], v[198:201], v[96:99]
	v_mfma_f32_16x16x32_bf16 v[92:95], v[136:139], v[198:201], v[92:95]
	v_mfma_f32_16x16x32_bf16 v[92:95], v[132:135], v[194:197], v[92:95]
	s_setprio 0
	s_setprio 1
	v_mfma_f32_16x16x32_bf16 v[100:103], v[148:151], v[164:167], v[100:103]
	v_mfma_f32_16x16x32_bf16 v[100:103], v[152:155], v[168:171], v[100:103]
	v_mfma_f32_16x16x32_bf16 v[104:107], v[160:163], v[168:171], v[104:107]
	v_mfma_f32_16x16x32_bf16 v[104:107], v[156:159], v[164:167], v[104:107]
	v_mfma_f32_16x16x32_bf16 v[112:115], v[156:159], v[172:175], v[112:115]
	v_mfma_f32_16x16x32_bf16 v[112:115], v[160:163], v[176:179], v[112:115]
	v_mfma_f32_16x16x32_bf16 v[108:111], v[152:155], v[176:179], v[108:111]
	v_mfma_f32_16x16x32_bf16 v[108:111], v[148:151], v[172:175], v[108:111]
	s_setprio 0
	s_setprio 1
	v_mfma_f32_16x16x32_bf16 v[116:119], v[148:151], v[180:183], v[116:119]
	v_mfma_f32_16x16x32_bf16 v[116:119], v[152:155], v[184:187], v[116:119]
	v_mfma_f32_16x16x32_bf16 v[120:123], v[160:163], v[184:187], v[120:123]
	v_mfma_f32_16x16x32_bf16 v[120:123], v[156:159], v[180:183], v[120:123]
	v_mfma_f32_16x16x32_bf16 v[128:131], v[156:159], v[194:197], v[128:131]
	v_mfma_f32_16x16x32_bf16 v[128:131], v[160:163], v[198:201], v[128:131]
	s_setprio 2
	s_barrier
	v_mfma_f32_16x16x32_bf16 v[124:127], v[152:155], v[198:201], v[124:127]
	v_mfma_f32_16x16x32_bf16 v[124:127], v[148:151], v[194:197], v[124:127]
	s_setprio 0
	s_add_i32 s28, s28, 2
	s_add_u32 s14, s14, 0x100
	s_addc_u32 s15, s15, 0
	s_add_u32 s26, s26, 0x100
	s_addc_u32 s27, s27, 0
	s_cmp_gt_u32 s28, 5
	s_cbranch_scc0 .LBB0_2069
	s_and_b64 vcc, exec, s[48:49]
	s_cbranch_vccz .LBB0_2072
	s_barrier

.LBB0_2159:
	s_add_i32 s68, 0, 0x10000
	s_add_i32 s69, 0, 0x14000
	v_add_u32_e32 v16, s68, v143
	v_add_u32_e32 v32, s69, v143
	ds_read_b128 v[4:7], v16
	ds_read_b128 v[8:11], v16 offset:1024
	ds_read_b128 v[12:15], v16 offset:2048
	ds_read_b128 v[16:19], v16 offset:3072
	ds_read_b128 v[20:23], v32
	ds_read_b128 v[24:27], v32 offset:1024
	ds_read_b128 v[28:31], v32 offset:2048
	ds_read_b128 v[32:35], v32 offset:3072
	v_add_u32_e32 v231, 0, v142
	ds_read_b128 v[36:39], v231
	ds_read_b128 v[40:43], v231 offset:1024
	ds_read_b128 v[44:47], v231 offset:2048
	ds_read_b128 v[48:51], v231 offset:3072
	ds_read_b128 v[52:55], v231 offset:4096
	ds_read_b128 v[56:59], v231 offset:5120
	ds_read_b128 v[60:63], v231 offset:6144
	ds_read_b128 v[64:67], v231 offset:7168
	s_waitcnt vmcnt(8)
	s_waitcnt lgkmcnt(0)
	s_barrier
	s_setprio 1
	s_waitcnt lgkmcnt(0)
	v_mfma_f32_16x16x32_f16 v[68:71], v[4:7], v[36:39], 0
	v_mfma_f32_16x16x32_f16 v[72:75], v[12:15], v[36:39], 0
	v_mfma_f32_16x16x32_f16 v[76:79], v[4:7], v[44:47], 0
	v_mfma_f32_16x16x32_f16 v[80:83], v[12:15], v[44:47], 0
	v_mfma_f32_16x16x32_f16 v[84:87], v[4:7], v[52:55], 0
	v_mfma_f32_16x16x32_f16 v[88:91], v[12:15], v[52:55], 0
	v_mfma_f32_16x16x32_f16 v[92:95], v[4:7], v[60:63], 0
	v_mfma_f32_16x16x32_f16 v[96:99], v[12:15], v[60:63], 0
	s_setprio 0
	s_setprio 1
	v_mfma_f32_16x16x32_f16 v[68:71], v[8:11], v[40:43], v[68:71]
	v_mfma_f32_16x16x32_f16 v[72:75], v[16:19], v[40:43], v[72:75]
	v_mfma_f32_16x16x32_f16 v[76:79], v[8:11], v[48:51], v[76:79]
	v_mfma_f32_16x16x32_f16 v[80:83], v[16:19], v[48:51], v[80:83]
	v_mfma_f32_16x16x32_f16 v[84:87], v[8:11], v[56:59], v[84:87]
	v_mfma_f32_16x16x32_f16 v[88:91], v[16:19], v[56:59], v[88:91]
	v_mfma_f32_16x16x32_f16 v[92:95], v[8:11], v[64:67], v[92:95]
	v_mfma_f32_16x16x32_f16 v[100:103], v[16:19], v[64:67], v[96:99]
	s_setprio 0
	s_setprio 1
	v_mfma_f32_16x16x32_f16 v[96:99], v[20:23], v[36:39], 0
	v_mfma_f32_16x16x32_f16 v[36:39], v[28:31], v[36:39], 0
	v_mfma_f32_16x16x32_f16 v[104:107], v[20:23], v[44:47], 0
	v_mfma_f32_16x16x32_f16 v[44:47], v[28:31], v[44:47], 0
	v_mfma_f32_16x16x32_f16 v[108:111], v[20:23], v[52:55], 0
	v_mfma_f32_16x16x32_f16 v[52:55], v[28:31], v[52:55], 0
	v_mfma_f32_16x16x32_f16 v[112:115], v[20:23], v[60:63], 0
	v_mfma_f32_16x16x32_f16 v[60:63], v[28:31], v[60:63], 0
	s_setprio 0
	s_setprio 1
	v_mfma_f32_16x16x32_f16 v[116:119], v[24:27], v[40:43], v[96:99]
	v_mfma_f32_16x16x32_f16 v[36:39], v[32:35], v[40:43], v[36:39]
	v_mfma_f32_16x16x32_f16 v[40:43], v[24:27], v[48:51], v[104:107]
	v_mfma_f32_16x16x32_f16 v[44:47], v[32:35], v[48:51], v[44:47]
	v_mfma_f32_16x16x32_f16 v[48:51], v[24:27], v[56:59], v[108:111]
	v_mfma_f32_16x16x32_f16 v[52:55], v[32:35], v[56:59], v[52:55]
	s_setprio 2
	s_barrier
	v_mfma_f32_16x16x32_f16 v[56:59], v[24:27], v[64:67], v[112:115]
	v_mfma_f32_16x16x32_f16 v[60:63], v[32:35], v[64:67], v[60:63]
	s_setprio 0
	v_lshl_add_u64 v[138:139], s[8:9], 0, v[2:3]
	s_add_i32 s68, s68, s53
	v_mov_b32_e32 v135, v3
	v_lshl_add_u64 v[144:145], v[138:139], 0, s[74:75]
	s_mov_b32 m0, s68
	v_lshl_add_u64 v[192:193], s[8:9], 0, v[134:135]
	ds_read_b128 v[64:67], v231 offset:16384
	ds_read_b128 v[96:99], v231 offset:17408
	ds_read_b128 v[104:107], v231 offset:18432
	ds_read_b128 v[108:111], v231 offset:19456
	ds_read_b128 v[112:115], v231 offset:20480
	ds_read_b128 v[120:123], v231 offset:21504
	ds_read_b128 v[124:127], v231 offset:22528
	ds_read_b128 v[128:131], v231 offset:23552
	global_load_lds_dwordx4 v[144:145], off
	v_lshl_add_u64 v[144:145], v[192:193], 0, s[74:75]
	s_add_i32 m0, s68, 0x2000
	s_add_i32 s68, s69, s53
	global_load_lds_dwordx4 v[144:145], off
	s_mov_b32 m0, s68
	v_mov_b32_e32 v137, v3
	global_load_lds_dwordx4 v2, s[40:41]
	s_add_i32 m0, s68, 0x2000
	v_lshl_add_u64 v[248:249], s[6:7], 0, v[136:137]
	v_mov_b32_e32 v133, v3
	global_load_lds_dwordx4 v134, s[40:41]
	v_lshl_add_u64 v[144:145], v[248:249], 0, s[74:75]
	s_mov_b32 m0, s54
	v_lshl_add_u64 v[250:251], s[6:7], 0, v[132:133]
	global_load_lds_dwordx4 v[144:145], off
	v_lshl_add_u64 v[144:145], v[250:251], 0, s[74:75]
	s_mov_b32 m0, s55
	s_nop 0
	global_load_lds_dwordx4 v[144:145], off
	s_waitcnt vmcnt(8)
	s_waitcnt lgkmcnt(0)
	s_barrier
	s_setprio 1
	s_waitcnt lgkmcnt(0)
	v_mfma_f32_16x16x32_f16 v[144:147], v[4:7], v[64:67], 0
	v_mfma_f32_16x16x32_f16 v[148:151], v[12:15], v[64:67], 0
	v_mfma_f32_16x16x32_f16 v[152:155], v[4:7], v[104:107], 0
	v_mfma_f32_16x16x32_f16 v[156:159], v[12:15], v[104:107], 0
	v_mfma_f32_16x16x32_f16 v[160:163], v[4:7], v[112:115], 0
	v_mfma_f32_16x16x32_f16 v[164:167], v[12:15], v[112:115], 0
	v_mfma_f32_16x16x32_f16 v[4:7], v[4:7], v[124:127], 0
	v_mfma_f32_16x16x32_f16 v[12:15], v[12:15], v[124:127], 0
	s_setprio 0
	s_setprio 1
	v_mfma_f32_16x16x32_f16 v[144:147], v[8:11], v[96:99], v[144:147]
	v_mfma_f32_16x16x32_f16 v[152:155], v[8:11], v[108:111], v[152:155]
	v_mfma_f32_16x16x32_f16 v[160:163], v[8:11], v[120:123], v[160:163]
	v_mfma_f32_16x16x32_f16 v[4:7], v[8:11], v[128:131], v[4:7]
	v_mfma_f32_16x16x32_f16 v[8:11], v[16:19], v[128:131], v[12:15]
	v_mfma_f32_16x16x32_f16 v[148:151], v[16:19], v[96:99], v[148:151]
	v_mfma_f32_16x16x32_f16 v[156:159], v[16:19], v[108:111], v[156:159]
	v_mfma_f32_16x16x32_f16 v[164:167], v[16:19], v[120:123], v[164:167]
	s_setprio 0
	s_setprio 1
	v_mfma_f32_16x16x32_f16 v[12:15], v[20:23], v[64:67], 0
	v_mfma_f32_16x16x32_f16 v[16:19], v[28:31], v[64:67], 0
	v_mfma_f32_16x16x32_f16 v[64:67], v[20:23], v[104:107], 0
	v_mfma_f32_16x16x32_f16 v[104:107], v[28:31], v[104:107], 0
	v_mfma_f32_16x16x32_f16 v[168:171], v[20:23], v[112:115], 0
	v_mfma_f32_16x16x32_f16 v[112:115], v[28:31], v[112:115], 0
	v_mfma_f32_16x16x32_f16 v[20:23], v[20:23], v[124:127], 0
	v_mfma_f32_16x16x32_f16 v[28:31], v[28:31], v[124:127], 0
	s_setprio 0
	s_setprio 1
	v_mfma_f32_16x16x32_f16 v[12:15], v[24:27], v[96:99], v[12:15]
	v_mfma_f32_16x16x32_f16 v[172:175], v[32:35], v[96:99], v[16:19]
	v_mfma_f32_16x16x32_f16 v[176:179], v[24:27], v[108:111], v[64:67]
	v_mfma_f32_16x16x32_f16 v[180:183], v[32:35], v[108:111], v[104:107]
	v_mfma_f32_16x16x32_f16 v[168:171], v[24:27], v[120:123], v[168:171]
	v_mfma_f32_16x16x32_f16 v[184:187], v[32:35], v[120:123], v[112:115]
	s_setprio 2
	s_barrier
	v_mfma_f32_16x16x32_f16 v[188:191], v[24:27], v[128:131], v[20:23]
	v_mfma_f32_16x16x32_f16 v[196:199], v[32:35], v[128:131], v[28:31]
	s_setprio 0
	s_add_i32 s68, 0, 0x18000
	v_add_u32_e32 v24, s68, v143
	s_add_i32 s69, 0, 0x1c000
	ds_read_b128 v[16:19], v24
	ds_read_b128 v[20:23], v24 offset:1024
	ds_read_b128 v[28:31], v24 offset:2048
	ds_read_b128 v[200:203], v24 offset:3072
	v_add_u32_e32 v24, s69, v143
	ds_read_b128 v[204:207], v24
	ds_read_b128 v[208:211], v24 offset:1024
	ds_read_b128 v[212:215], v24 offset:2048
	ds_read_b128 v[216:219], v24 offset:3072
	s_mov_b32 m0, s56
	ds_read_b128 v[24:27], v231 offset:32768
	ds_read_b128 v[32:35], v231 offset:33792
	ds_read_b128 v[64:67], v231 offset:34816
	ds_read_b128 v[220:223], v231 offset:35840
	ds_read_b128 v[224:227], v231 offset:36864
	ds_read_b128 v[232:235], v231 offset:37888
	ds_read_b128 v[236:239], v231 offset:38912
	ds_read_b128 v[240:243], v231 offset:39936
	global_load_lds_dwordx4 v136, s[42:43]
	s_mov_b32 m0, s57
	s_nop 0
	global_load_lds_dwordx4 v132, s[42:43]
	s_waitcnt vmcnt(8)
	s_waitcnt lgkmcnt(0)
	s_barrier
	s_setprio 1
	s_waitcnt lgkmcnt(0)
	v_mfma_f32_16x16x32_f16 v[68:71], v[16:19], v[24:27], v[68:71]
	v_mfma_f32_16x16x32_f16 v[128:131], v[20:23], v[32:35], v[68:71]
	v_mfma_f32_16x16x32_f16 v[68:71], v[28:31], v[24:27], v[72:75]
	v_mfma_f32_16x16x32_f16 v[120:123], v[200:203], v[32:35], v[68:71]
	v_mfma_f32_16x16x32_f16 v[68:71], v[16:19], v[64:67], v[76:79]
	v_mfma_f32_16x16x32_f16 v[112:115], v[20:23], v[220:223], v[68:71]
	v_mfma_f32_16x16x32_f16 v[68:71], v[28:31], v[64:67], v[80:83]
	v_mfma_f32_16x16x32_f16 v[104:107], v[200:203], v[220:223], v[68:71]
	s_setprio 0
	s_setprio 1
	v_mfma_f32_16x16x32_f16 v[68:71], v[16:19], v[224:227], v[84:87]
	v_mfma_f32_16x16x32_f16 v[96:99], v[20:23], v[232:235], v[68:71]
	v_mfma_f32_16x16x32_f16 v[68:71], v[28:31], v[224:227], v[88:91]
	v_mfma_f32_16x16x32_f16 v[88:91], v[200:203], v[232:235], v[68:71]
	v_mfma_f32_16x16x32_f16 v[68:71], v[16:19], v[236:239], v[92:95]
	v_mfma_f32_16x16x32_f16 v[80:83], v[20:23], v[240:243], v[68:71]
	v_mfma_f32_16x16x32_f16 v[68:71], v[28:31], v[236:239], v[100:103]
	v_mfma_f32_16x16x32_f16 v[72:75], v[200:203], v[240:243], v[68:71]
	s_setprio 0
	s_setprio 1
	v_mfma_f32_16x16x32_f16 v[68:71], v[204:207], v[24:27], v[116:119]
	v_mfma_f32_16x16x32_f16 v[24:27], v[212:215], v[24:27], v[36:39]
	v_mfma_f32_16x16x32_f16 v[116:119], v[216:219], v[32:35], v[24:27]
	v_mfma_f32_16x16x32_f16 v[24:27], v[204:207], v[64:67], v[40:43]
	v_mfma_f32_16x16x32_f16 v[108:111], v[208:211], v[220:223], v[24:27]
	v_mfma_f32_16x16x32_f16 v[24:27], v[212:215], v[64:67], v[44:47]
	v_mfma_f32_16x16x32_f16 v[100:103], v[216:219], v[220:223], v[24:27]
	v_mfma_f32_16x16x32_f16 v[24:27], v[204:207], v[224:227], v[48:51]
	s_setprio 0
	s_setprio 1
	v_mfma_f32_16x16x32_f16 v[92:95], v[208:211], v[232:235], v[24:27]
	v_mfma_f32_16x16x32_f16 v[24:27], v[212:215], v[224:227], v[52:55]
	v_mfma_f32_16x16x32_f16 v[84:87], v[216:219], v[232:235], v[24:27]
	v_mfma_f32_16x16x32_f16 v[24:27], v[204:207], v[236:239], v[56:59]
	v_mfma_f32_16x16x32_f16 v[76:79], v[208:211], v[240:243], v[24:27]
	v_mfma_f32_16x16x32_f16 v[24:27], v[212:215], v[236:239], v[60:63]
	s_setprio 2
	s_barrier
	v_mfma_f32_16x16x32_f16 v[124:127], v[208:211], v[32:35], v[68:71]
	v_mfma_f32_16x16x32_f16 v[68:71], v[216:219], v[240:243], v[24:27]
	s_setprio 0
	s_add_i32 s68, s68, s53
	s_nop 2
	v_lshl_add_u64 v[24:25], v[138:139], 0, s[24:25]
	s_mov_b32 m0, s68
	ds_read_b128 v[36:39], v231 offset:49152
	ds_read_b128 v[44:47], v231 offset:50176
	ds_read_b128 v[220:223], v231 offset:51200
	ds_read_b128 v[224:227], v231 offset:52224
	ds_read_b128 v[232:235], v231 offset:53248
	ds_read_b128 v[236:239], v231 offset:54272
	ds_read_b128 v[240:243], v231 offset:55296
	ds_read_b128 v[244:247], v231 offset:56320
	global_load_lds_dwordx4 v[24:25], off
	v_lshl_add_u64 v[24:25], v[192:193], 0, s[24:25]
	s_add_i32 m0, s68, 0x2000
	s_add_i32 s68, s69, s53
	global_load_lds_dwordx4 v[24:25], off
	s_mov_b32 m0, s68
	v_lshl_add_u64 v[24:25], v[248:249], 0, s[24:25]
	global_load_lds_dwordx4 v2, s[44:45]
	s_add_i32 m0, s68, 0x2000
	s_nop 0
	global_load_lds_dwordx4 v134, s[44:45]
	s_mov_b32 m0, s59
	s_nop 0
	global_load_lds_dwordx4 v[24:25], off
	v_lshl_add_u64 v[24:25], v[250:251], 0, s[24:25]
	s_mov_b32 m0, s60
	s_nop 0
	global_load_lds_dwordx4 v[24:25], off
	s_waitcnt vmcnt(8)
	s_waitcnt lgkmcnt(0)
	s_barrier
	s_setprio 1
	s_waitcnt lgkmcnt(0)
	v_mfma_f32_16x16x32_f16 v[24:27], v[16:19], v[36:39], v[144:147]
	v_mfma_f32_16x16x32_f16 v[64:67], v[20:23], v[44:47], v[24:27]
	v_mfma_f32_16x16x32_f16 v[24:27], v[28:31], v[36:39], v[148:151]
	v_mfma_f32_16x16x32_f16 v[56:59], v[200:203], v[44:47], v[24:27]
	v_mfma_f32_16x16x32_f16 v[24:27], v[16:19], v[220:223], v[152:155]
	v_mfma_f32_16x16x32_f16 v[48:51], v[20:23], v[224:227], v[24:27]
	v_mfma_f32_16x16x32_f16 v[24:27], v[28:31], v[220:223], v[156:159]
	v_mfma_f32_16x16x32_f16 v[40:43], v[200:203], v[224:227], v[24:27]
	s_setprio 0
	s_setprio 1
	v_mfma_f32_16x16x32_f16 v[24:27], v[16:19], v[232:235], v[160:163]
	v_mfma_f32_16x16x32_f16 v[4:7], v[16:19], v[240:243], v[4:7]
	v_mfma_f32_16x16x32_f16 v[32:35], v[20:23], v[236:239], v[24:27]
	v_mfma_f32_16x16x32_f16 v[24:27], v[28:31], v[232:235], v[164:167]
	v_mfma_f32_16x16x32_f16 v[16:19], v[20:23], v[244:247], v[4:7]
	v_mfma_f32_16x16x32_f16 v[4:7], v[28:31], v[240:243], v[8:11]
	v_mfma_f32_16x16x32_f16 v[24:27], v[200:203], v[236:239], v[24:27]
	v_mfma_f32_16x16x32_f16 v[8:11], v[200:203], v[244:247], v[4:7]
	s_setprio 0
	s_setprio 1
	v_mfma_f32_16x16x32_f16 v[4:7], v[204:207], v[36:39], v[12:15]
	v_mfma_f32_16x16x32_f16 v[60:63], v[208:211], v[44:47], v[4:7]
	v_mfma_f32_16x16x32_f16 v[4:7], v[212:215], v[36:39], v[172:175]
	v_mfma_f32_16x16x32_f16 v[52:55], v[216:219], v[44:47], v[4:7]
	v_mfma_f32_16x16x32_f16 v[4:7], v[204:207], v[220:223], v[176:179]
	v_mfma_f32_16x16x32_f16 v[44:47], v[208:211], v[224:227], v[4:7]
	v_mfma_f32_16x16x32_f16 v[4:7], v[212:215], v[220:223], v[180:183]
	v_mfma_f32_16x16x32_f16 v[36:39], v[216:219], v[224:227], v[4:7]
	s_setprio 0
	s_setprio 1
	v_mfma_f32_16x16x32_f16 v[4:7], v[204:207], v[232:235], v[168:171]
	v_mfma_f32_16x16x32_f16 v[28:31], v[208:211], v[236:239], v[4:7]
	v_mfma_f32_16x16x32_f16 v[4:7], v[212:215], v[232:235], v[184:187]
	v_mfma_f32_16x16x32_f16 v[20:23], v[216:219], v[236:239], v[4:7]
	v_mfma_f32_16x16x32_f16 v[4:7], v[204:207], v[240:243], v[188:191]
	v_mfma_f32_16x16x32_f16 v[12:15], v[208:211], v[244:247], v[4:7]
	s_setprio 2
	s_barrier
	v_mfma_f32_16x16x32_f16 v[4:7], v[212:215], v[240:243], v[196:199]
	v_mfma_f32_16x16x32_f16 v[4:7], v[216:219], v[244:247], v[4:7]
	s_setprio 0
	s_add_i32 s67, s67, 2
	s_cmp_ge_i32 s67, s11
	s_cbranch_scc0 .LBB0_2159

.LBB0_2161:
	s_add_u32 s68, s6, s40
	s_addc_u32 s69, s7, s41
	s_add_u32 s42, s68, 0x200
	s_addc_u32 s43, s69, 0
	s_add_u32 s44, s8, s40
	s_addc_u32 s45, s9, s41
	s_add_u32 s67, s44, 0x200
	s_addc_u32 s70, s45, 0
	s_add_i32 s71, 0, 0x10000
	s_cmp_eq_u32 s11, 28
	s_cselect_b32 s45, s29, s43
	s_cselect_b32 s44, s28, s42
	v_add_u32_e32 v133, s71, v143
	s_cselect_b32 s43, s37, s70
	s_cselect_b32 s42, s36, s67
	s_add_i32 s67, 0, 0x14000
	ds_read_b128 v[144:147], v133
	ds_read_b128 v[148:151], v133 offset:1024
	ds_read_b128 v[152:155], v133 offset:2048
	ds_read_b128 v[156:159], v133 offset:3072
	v_add_u32_e32 v133, s67, v143
	ds_read_b128 v[160:163], v133
	ds_read_b128 v[164:167], v133 offset:1024
	ds_read_b128 v[168:171], v133 offset:2048
	ds_read_b128 v[172:175], v133 offset:3072
	v_lshl_add_u64 v[136:137], s[68:69], 0, v[2:3]
	s_mov_b32 m0, s61
	v_add_u32_e32 v216, 0, v142
	v_lshl_add_u64 v[136:137], v[136:137], 0, s[34:35]
	v_mov_b32_e32 v133, v3
	ds_read_b128 v[176:179], v216
	ds_read_b128 v[180:183], v216 offset:1024
	ds_read_b128 v[184:187], v216 offset:2048
	ds_read_b128 v[188:191], v216 offset:3072
	ds_read_b128 v[196:199], v216 offset:4096
	ds_read_b128 v[200:203], v216 offset:5120
	ds_read_b128 v[204:207], v216 offset:6144
	ds_read_b128 v[208:211], v216 offset:7168
	global_load_lds_dwordx4 v[136:137], off
	v_lshl_add_u64 v[136:137], s[68:69], 0, v[132:133]
	v_lshl_add_u64 v[136:137], v[136:137], 0, s[34:35]
	s_mov_b32 m0, s62
	s_nop 0
	global_load_lds_dwordx4 v[136:137], off
	s_waitcnt vmcnt(8)
	s_waitcnt lgkmcnt(0)
	s_barrier
	s_setprio 1
	s_waitcnt lgkmcnt(0)
	v_mfma_f32_16x16x32_f16 v[128:131], v[144:147], v[176:179], v[128:131]
	v_mfma_f32_16x16x32_f16 v[128:131], v[148:151], v[180:183], v[128:131]
	v_mfma_f32_16x16x32_f16 v[120:123], v[156:159], v[180:183], v[120:123]
	v_mfma_f32_16x16x32_f16 v[120:123], v[152:155], v[176:179], v[120:123]
	v_mfma_f32_16x16x32_f16 v[104:107], v[152:155], v[184:187], v[104:107]
	v_mfma_f32_16x16x32_f16 v[104:107], v[156:159], v[188:191], v[104:107]
	v_mfma_f32_16x16x32_f16 v[112:115], v[148:151], v[188:191], v[112:115]
	v_mfma_f32_16x16x32_f16 v[112:115], v[144:147], v[184:187], v[112:115]
	s_setprio 0
	s_setprio 1
	v_mfma_f32_16x16x32_f16 v[96:99], v[144:147], v[196:199], v[96:99]
	v_mfma_f32_16x16x32_f16 v[96:99], v[148:151], v[200:203], v[96:99]
	v_mfma_f32_16x16x32_f16 v[88:91], v[156:159], v[200:203], v[88:91]
	v_mfma_f32_16x16x32_f16 v[88:91], v[152:155], v[196:199], v[88:91]
	v_mfma_f32_16x16x32_f16 v[72:75], v[152:155], v[204:207], v[72:75]
	v_mfma_f32_16x16x32_f16 v[72:75], v[156:159], v[208:211], v[72:75]
	v_mfma_f32_16x16x32_f16 v[80:83], v[148:151], v[208:211], v[80:83]
	v_mfma_f32_16x16x32_f16 v[80:83], v[144:147], v[204:207], v[80:83]
	s_setprio 0
	s_setprio 1
	v_mfma_f32_16x16x32_f16 v[124:127], v[160:163], v[176:179], v[124:127]
	v_mfma_f32_16x16x32_f16 v[124:127], v[164:167], v[180:183], v[124:127]
	v_mfma_f32_16x16x32_f16 v[116:119], v[172:175], v[180:183], v[116:119]
	v_mfma_f32_16x16x32_f16 v[116:119], v[168:171], v[176:179], v[116:119]
	v_mfma_f32_16x16x32_f16 v[100:103], v[168:171], v[184:187], v[100:103]
	v_mfma_f32_16x16x32_f16 v[100:103], v[172:175], v[188:191], v[100:103]
	v_mfma_f32_16x16x32_f16 v[108:111], v[164:167], v[188:191], v[108:111]
	v_mfma_f32_16x16x32_f16 v[108:111], v[160:163], v[184:187], v[108:111]
	s_setprio 0
	s_setprio 1
	v_mfma_f32_16x16x32_f16 v[92:95], v[160:163], v[196:199], v[92:95]
	v_mfma_f32_16x16x32_f16 v[92:95], v[164:167], v[200:203], v[92:95]
	v_mfma_f32_16x16x32_f16 v[84:87], v[172:175], v[200:203], v[84:87]
	v_mfma_f32_16x16x32_f16 v[84:87], v[168:171], v[196:199], v[84:87]
	v_mfma_f32_16x16x32_f16 v[68:71], v[168:171], v[204:207], v[68:71]
	v_mfma_f32_16x16x32_f16 v[68:71], v[172:175], v[208:211], v[68:71]
	s_setprio 2
	s_barrier
	v_mfma_f32_16x16x32_f16 v[76:79], v[164:167], v[208:211], v[76:79]
	v_mfma_f32_16x16x32_f16 v[76:79], v[160:163], v[204:207], v[76:79]
	s_setprio 0
	s_add_i32 s68, s71, s53
	s_mov_b32 m0, s68
	ds_read_b128 v[176:179], v216 offset:16384
	ds_read_b128 v[180:183], v216 offset:17408
	ds_read_b128 v[184:187], v216 offset:18432
	ds_read_b128 v[188:191], v216 offset:19456
	ds_read_b128 v[196:199], v216 offset:20480
	ds_read_b128 v[200:203], v216 offset:21504
	ds_read_b128 v[204:207], v216 offset:22528
	ds_read_b128 v[208:211], v216 offset:23552
	global_load_lds_dwordx4 v138, s[42:43]
	s_add_i32 m0, s68, 0x2000
	s_add_u32 s68, s42, 0x80000
	s_addc_u32 s69, s43, 0
	s_add_i32 s67, s67, s53
	global_load_lds_dwordx4 v134, s[42:43]
	s_mov_b32 m0, s67
	v_mov_b32_e32 v139, v3
	global_load_lds_dwordx4 v138, s[68:69]
	s_add_i32 m0, s67, 0x2000
	v_mov_b32_e32 v135, v3
	global_load_lds_dwordx4 v134, s[68:69]
	s_mov_b32 m0, s54
	v_lshl_add_u64 v[136:137], s[42:43], 0, v[138:139]
	global_load_lds_dwordx4 v2, s[44:45]
	s_mov_b32 m0, s55
	v_lshl_add_u64 v[192:193], s[42:43], 0, v[134:135]
	global_load_lds_dwordx4 v132, s[44:45]
	s_waitcnt vmcnt(8)
	s_waitcnt lgkmcnt(0)
	v_lshl_add_u64 v[212:213], s[44:45], 0, v[2:3]
	v_lshl_add_u64 v[214:215], s[44:45], 0, v[132:133]
	s_barrier
	s_setprio 1
	s_waitcnt lgkmcnt(0)
	v_mfma_f32_16x16x32_f16 v[64:67], v[144:147], v[176:179], v[64:67]
	v_mfma_f32_16x16x32_f16 v[64:67], v[148:151], v[180:183], v[64:67]
	v_mfma_f32_16x16x32_f16 v[56:59], v[156:159], v[180:183], v[56:59]
	v_mfma_f32_16x16x32_f16 v[56:59], v[152:155], v[176:179], v[56:59]
	v_mfma_f32_16x16x32_f16 v[40:43], v[152:155], v[184:187], v[40:43]
	v_mfma_f32_16x16x32_f16 v[40:43], v[156:159], v[188:191], v[40:43]
	v_mfma_f32_16x16x32_f16 v[48:51], v[148:151], v[188:191], v[48:51]
	v_mfma_f32_16x16x32_f16 v[48:51], v[144:147], v[184:187], v[48:51]
	s_setprio 0
	s_setprio 1
	v_mfma_f32_16x16x32_f16 v[32:35], v[144:147], v[196:199], v[32:35]
	v_mfma_f32_16x16x32_f16 v[32:35], v[148:151], v[200:203], v[32:35]
	v_mfma_f32_16x16x32_f16 v[24:27], v[156:159], v[200:203], v[24:27]
	v_mfma_f32_16x16x32_f16 v[24:27], v[152:155], v[196:199], v[24:27]
	v_mfma_f32_16x16x32_f16 v[8:11], v[152:155], v[204:207], v[8:11]
	v_mfma_f32_16x16x32_f16 v[8:11], v[156:159], v[208:211], v[8:11]
	v_mfma_f32_16x16x32_f16 v[16:19], v[148:151], v[208:211], v[16:19]
	v_mfma_f32_16x16x32_f16 v[16:19], v[144:147], v[204:207], v[16:19]
	s_setprio 0
	s_setprio 1
	v_mfma_f32_16x16x32_f16 v[60:63], v[160:163], v[176:179], v[60:63]
	v_mfma_f32_16x16x32_f16 v[60:63], v[164:167], v[180:183], v[60:63]
	v_mfma_f32_16x16x32_f16 v[52:55], v[172:175], v[180:183], v[52:55]
	v_mfma_f32_16x16x32_f16 v[52:55], v[168:171], v[176:179], v[52:55]
	v_mfma_f32_16x16x32_f16 v[36:39], v[168:171], v[184:187], v[36:39]
	v_mfma_f32_16x16x32_f16 v[36:39], v[172:175], v[188:191], v[36:39]
	v_mfma_f32_16x16x32_f16 v[44:47], v[164:167], v[188:191], v[44:47]
	v_mfma_f32_16x16x32_f16 v[44:47], v[160:163], v[184:187], v[44:47]
	s_setprio 0
	s_setprio 1
	v_mfma_f32_16x16x32_f16 v[28:31], v[160:163], v[196:199], v[28:31]
	v_mfma_f32_16x16x32_f16 v[28:31], v[164:167], v[200:203], v[28:31]
	v_mfma_f32_16x16x32_f16 v[20:23], v[172:175], v[200:203], v[20:23]
	v_mfma_f32_16x16x32_f16 v[20:23], v[168:171], v[196:199], v[20:23]
	v_mfma_f32_16x16x32_f16 v[4:7], v[168:171], v[204:207], v[4:7]
	v_mfma_f32_16x16x32_f16 v[4:7], v[172:175], v[208:211], v[4:7]
	s_setprio 2
	s_barrier
	v_mfma_f32_16x16x32_f16 v[12:15], v[164:167], v[208:211], v[12:15]
	v_mfma_f32_16x16x32_f16 v[12:15], v[160:163], v[204:207], v[12:15]
	s_setprio 0
	s_add_i32 s67, 0, 0x18000
	v_add_u32_e32 v135, s67, v143
	s_add_i32 s68, 0, 0x1c000
	ds_read_b128 v[144:147], v135
	ds_read_b128 v[148:151], v135 offset:1024
	ds_read_b128 v[152:155], v135 offset:2048
	ds_read_b128 v[156:159], v135 offset:3072
	v_add_u32_e32 v135, s68, v143
	ds_read_b128 v[160:163], v135
	ds_read_b128 v[164:167], v135 offset:1024
	ds_read_b128 v[168:171], v135 offset:2048
	ds_read_b128 v[172:175], v135 offset:3072
	s_add_u32 s44, s44, 0x80000
	s_addc_u32 s45, s45, 0
	s_mov_b32 m0, s56
	ds_read_b128 v[176:179], v216 offset:32768
	ds_read_b128 v[180:183], v216 offset:33792
	ds_read_b128 v[184:187], v216 offset:34816
	ds_read_b128 v[188:191], v216 offset:35840
	ds_read_b128 v[196:199], v216 offset:36864
	ds_read_b128 v[200:203], v216 offset:37888
	ds_read_b128 v[204:207], v216 offset:38912
	ds_read_b128 v[208:211], v216 offset:39936
	global_load_lds_dwordx4 v2, s[44:45]
	s_mov_b32 m0, s57
	s_nop 0
	global_load_lds_dwordx4 v132, s[44:45]
	s_waitcnt vmcnt(8)
	s_waitcnt lgkmcnt(0)
	s_barrier
	s_setprio 1
	s_waitcnt lgkmcnt(0)
	v_mfma_f32_16x16x32_f16 v[128:131], v[144:147], v[176:179], v[128:131]
	v_mfma_f32_16x16x32_f16 v[128:131], v[148:151], v[180:183], v[128:131]
	v_mfma_f32_16x16x32_f16 v[120:123], v[156:159], v[180:183], v[120:123]
	v_mfma_f32_16x16x32_f16 v[120:123], v[152:155], v[176:179], v[120:123]
	v_mfma_f32_16x16x32_f16 v[104:107], v[152:155], v[184:187], v[104:107]
	v_mfma_f32_16x16x32_f16 v[104:107], v[156:159], v[188:191], v[104:107]
	v_mfma_f32_16x16x32_f16 v[112:115], v[148:151], v[188:191], v[112:115]
	v_mfma_f32_16x16x32_f16 v[112:115], v[144:147], v[184:187], v[112:115]
	s_setprio 0
	s_setprio 1
	v_mfma_f32_16x16x32_f16 v[96:99], v[144:147], v[196:199], v[96:99]
	v_mfma_f32_16x16x32_f16 v[96:99], v[148:151], v[200:203], v[96:99]
	v_mfma_f32_16x16x32_f16 v[88:91], v[156:159], v[200:203], v[88:91]
	v_mfma_f32_16x16x32_f16 v[88:91], v[152:155], v[196:199], v[88:91]
	v_mfma_f32_16x16x32_f16 v[72:75], v[152:155], v[204:207], v[72:75]
	v_mfma_f32_16x16x32_f16 v[72:75], v[156:159], v[208:211], v[72:75]
	v_mfma_f32_16x16x32_f16 v[80:83], v[148:151], v[208:211], v[80:83]
	v_mfma_f32_16x16x32_f16 v[80:83], v[144:147], v[204:207], v[80:83]
	s_setprio 0
	s_setprio 1
	v_mfma_f32_16x16x32_f16 v[124:127], v[160:163], v[176:179], v[124:127]
	v_mfma_f32_16x16x32_f16 v[124:127], v[164:167], v[180:183], v[124:127]
	v_mfma_f32_16x16x32_f16 v[116:119], v[172:175], v[180:183], v[116:119]
	v_mfma_f32_16x16x32_f16 v[116:119], v[168:171], v[176:179], v[116:119]
	v_mfma_f32_16x16x32_f16 v[100:103], v[168:171], v[184:187], v[100:103]
	v_mfma_f32_16x16x32_f16 v[100:103], v[172:175], v[188:191], v[100:103]
	v_mfma_f32_16x16x32_f16 v[108:111], v[164:167], v[188:191], v[108:111]
	v_mfma_f32_16x16x32_f16 v[108:111], v[160:163], v[184:187], v[108:111]
	s_setprio 0
	s_setprio 1
	v_mfma_f32_16x16x32_f16 v[92:95], v[160:163], v[196:199], v[92:95]
	v_mfma_f32_16x16x32_f16 v[92:95], v[164:167], v[200:203], v[92:95]
	v_mfma_f32_16x16x32_f16 v[84:87], v[172:175], v[200:203], v[84:87]
	v_mfma_f32_16x16x32_f16 v[84:87], v[168:171], v[196:199], v[84:87]
	v_mfma_f32_16x16x32_f16 v[68:71], v[168:171], v[204:207], v[68:71]
	v_mfma_f32_16x16x32_f16 v[68:71], v[172:175], v[208:211], v[68:71]
	s_setprio 2
	s_barrier
	v_mfma_f32_16x16x32_f16 v[76:79], v[164:167], v[208:211], v[76:79]
	v_mfma_f32_16x16x32_f16 v[76:79], v[160:163], v[204:207], v[76:79]
	s_setprio 0
	s_add_i32 s44, s67, s53
	v_lshl_add_u64 v[136:137], v[136:137], 0, s[86:87]
	s_mov_b32 m0, s44
	ds_read_b128 v[176:179], v216 offset:49152
	ds_read_b128 v[180:183], v216 offset:50176
	ds_read_b128 v[184:187], v216 offset:51200
	ds_read_b128 v[188:191], v216 offset:52224
	ds_read_b128 v[196:199], v216 offset:53248
	ds_read_b128 v[200:203], v216 offset:54272
	ds_read_b128 v[204:207], v216 offset:55296
	ds_read_b128 v[208:211], v216 offset:56320
	global_load_lds_dwordx4 v[136:137], off
	s_add_i32 m0, s44, 0x2000
	s_add_u32 s42, s42, 0x80080
	v_lshl_add_u64 v[136:137], v[192:193], 0, s[86:87]
	s_addc_u32 s43, s43, 0
	s_add_i32 s44, s68, s53
	global_load_lds_dwordx4 v[136:137], off
	s_mov_b32 m0, s44
	v_lshl_add_u64 v[136:137], v[212:213], 0, s[86:87]
	global_load_lds_dwordx4 v138, s[42:43]
	s_add_i32 m0, s44, 0x2000
	s_nop 0
	global_load_lds_dwordx4 v134, s[42:43]
	s_mov_b32 m0, s59
	s_nop 0
	global_load_lds_dwordx4 v[136:137], off
	v_lshl_add_u64 v[136:137], v[214:215], 0, s[86:87]
	s_mov_b32 m0, s60
	s_nop 0
	global_load_lds_dwordx4 v[136:137], off
	s_waitcnt vmcnt(8)
	s_waitcnt lgkmcnt(0)
	s_barrier
	s_setprio 1
	s_waitcnt lgkmcnt(0)
	v_mfma_f32_16x16x32_f16 v[64:67], v[144:147], v[176:179], v[64:67]
	v_mfma_f32_16x16x32_f16 v[64:67], v[148:151], v[180:183], v[64:67]
	v_mfma_f32_16x16x32_f16 v[56:59], v[156:159], v[180:183], v[56:59]
	v_mfma_f32_16x16x32_f16 v[56:59], v[152:155], v[176:179], v[56:59]
	v_mfma_f32_16x16x32_f16 v[40:43], v[152:155], v[184:187], v[40:43]
	v_mfma_f32_16x16x32_f16 v[40:43], v[156:159], v[188:191], v[40:43]
	v_mfma_f32_16x16x32_f16 v[48:51], v[148:151], v[188:191], v[48:51]
	v_mfma_f32_16x16x32_f16 v[48:51], v[144:147], v[184:187], v[48:51]
	s_setprio 0
	s_setprio 1
	v_mfma_f32_16x16x32_f16 v[32:35], v[144:147], v[196:199], v[32:35]
	v_mfma_f32_16x16x32_f16 v[32:35], v[148:151], v[200:203], v[32:35]
	v_mfma_f32_16x16x32_f16 v[24:27], v[156:159], v[200:203], v[24:27]
	v_mfma_f32_16x16x32_f16 v[24:27], v[152:155], v[196:199], v[24:27]
	v_mfma_f32_16x16x32_f16 v[8:11], v[152:155], v[204:207], v[8:11]
	v_mfma_f32_16x16x32_f16 v[8:11], v[156:159], v[208:211], v[8:11]
	v_mfma_f32_16x16x32_f16 v[16:19], v[148:151], v[208:211], v[16:19]
	v_mfma_f32_16x16x32_f16 v[16:19], v[144:147], v[204:207], v[16:19]
	s_setprio 0
	s_setprio 1
	v_mfma_f32_16x16x32_f16 v[60:63], v[160:163], v[176:179], v[60:63]
	v_mfma_f32_16x16x32_f16 v[60:63], v[164:167], v[180:183], v[60:63]
	v_mfma_f32_16x16x32_f16 v[52:55], v[172:175], v[180:183], v[52:55]
	v_mfma_f32_16x16x32_f16 v[52:55], v[168:171], v[176:179], v[52:55]
	v_mfma_f32_16x16x32_f16 v[36:39], v[168:171], v[184:187], v[36:39]
	v_mfma_f32_16x16x32_f16 v[36:39], v[172:175], v[188:191], v[36:39]
	v_mfma_f32_16x16x32_f16 v[44:47], v[164:167], v[188:191], v[44:47]
	v_mfma_f32_16x16x32_f16 v[44:47], v[160:163], v[184:187], v[44:47]
	s_setprio 0
	s_setprio 1
	v_mfma_f32_16x16x32_f16 v[28:31], v[160:163], v[196:199], v[28:31]
	v_mfma_f32_16x16x32_f16 v[28:31], v[164:167], v[200:203], v[28:31]
	v_mfma_f32_16x16x32_f16 v[20:23], v[172:175], v[200:203], v[20:23]
	v_mfma_f32_16x16x32_f16 v[20:23], v[168:171], v[196:199], v[20:23]
	v_mfma_f32_16x16x32_f16 v[4:7], v[168:171], v[204:207], v[4:7]
	v_mfma_f32_16x16x32_f16 v[4:7], v[172:175], v[208:211], v[4:7]
	s_setprio 2
	s_barrier
	v_mfma_f32_16x16x32_f16 v[12:15], v[164:167], v[208:211], v[12:15]
	v_mfma_f32_16x16x32_f16 v[12:15], v[160:163], v[204:207], v[12:15]
	s_setprio 0
	s_add_i32 s11, s11, 2
	s_add_u32 s40, s40, 0x100
	s_addc_u32 s41, s41, 0
	s_cmp_gt_u32 s11, 29
	s_cbranch_scc0 .LBB0_2161
	s_andn2_b64 vcc, exec, s[26:27]
	s_cbranch_vccnz .LBB0_2164
	s_add_u32 s6, s28, 0x80080
	s_addc_u32 s7, s29, 0
	s_mov_b32 m0, s61
	v_lshl_add_u64 v[144:145], s[6:7], 0, v[2:3]
	v_lshl_add_u64 v[136:137], s[6:7], 0, v[132:133]
	global_load_lds_dwordx4 v[144:145], off
	s_mov_b32 m0, s62
	s_mov_b32 s47, s65
	global_load_lds_dwordx4 v[136:137], off
	s_mov_b32 s64, s10
	s_mov_b64 s[8:9], s[14:15]
	s_mov_b64 s[6:7], s[12:13]
	s_mov_b32 s63, s66

.LBB0_2269:
	s_add_i32 s51, 0, 0x10000
	s_add_i32 s71, 0, 0x14000
	v_add_u32_e32 v16, s51, v232
	v_add_u32_e32 v32, s71, v232
	ds_read_b128 v[4:7], v16
	ds_read_b128 v[8:11], v16 offset:1024
	ds_read_b128 v[12:15], v16 offset:2048
	ds_read_b128 v[16:19], v16 offset:3072
	ds_read_b128 v[20:23], v32
	ds_read_b128 v[24:27], v32 offset:1024
	ds_read_b128 v[28:31], v32 offset:2048
	ds_read_b128 v[32:35], v32 offset:3072
	v_add_u32_e32 v233, 0, v231
	ds_read_b128 v[36:39], v233
	ds_read_b128 v[40:43], v233 offset:1024
	ds_read_b128 v[44:47], v233 offset:2048
	ds_read_b128 v[48:51], v233 offset:3072
	ds_read_b128 v[52:55], v233 offset:4096
	ds_read_b128 v[56:59], v233 offset:5120
	ds_read_b128 v[60:63], v233 offset:6144
	ds_read_b128 v[64:67], v233 offset:7168
	s_waitcnt vmcnt(8)
	s_waitcnt lgkmcnt(0)
	s_barrier
	s_setprio 1
	s_waitcnt lgkmcnt(0)
	v_mfma_f32_16x16x32_bf16 v[68:71], v[4:7], v[36:39], 0
	v_mfma_f32_16x16x32_bf16 v[68:71], v[8:11], v[40:43], v[68:71]
	v_mfma_f32_16x16x32_bf16 v[72:75], v[12:15], v[36:39], 0
	v_mfma_f32_16x16x32_bf16 v[72:75], v[16:19], v[40:43], v[72:75]
	v_mfma_f32_16x16x32_bf16 v[80:83], v[12:15], v[44:47], 0
	v_mfma_f32_16x16x32_bf16 v[80:83], v[16:19], v[48:51], v[80:83]
	v_mfma_f32_16x16x32_bf16 v[76:79], v[4:7], v[44:47], 0
	v_mfma_f32_16x16x32_bf16 v[76:79], v[8:11], v[48:51], v[76:79]
	s_setprio 0
	s_setprio 1
	v_mfma_f32_16x16x32_bf16 v[84:87], v[4:7], v[52:55], 0
	v_mfma_f32_16x16x32_bf16 v[84:87], v[8:11], v[56:59], v[84:87]
	v_mfma_f32_16x16x32_bf16 v[88:91], v[12:15], v[52:55], 0
	v_mfma_f32_16x16x32_bf16 v[88:91], v[16:19], v[56:59], v[88:91]
	v_mfma_f32_16x16x32_bf16 v[96:99], v[12:15], v[60:63], 0
	v_mfma_f32_16x16x32_bf16 v[96:99], v[16:19], v[64:67], v[96:99]
	v_mfma_f32_16x16x32_bf16 v[92:95], v[4:7], v[60:63], 0
	v_mfma_f32_16x16x32_bf16 v[92:95], v[8:11], v[64:67], v[92:95]
	s_setprio 0
	s_setprio 1
	v_mfma_f32_16x16x32_bf16 v[100:103], v[20:23], v[36:39], 0
	v_mfma_f32_16x16x32_bf16 v[36:39], v[28:31], v[36:39], 0
	v_mfma_f32_16x16x32_bf16 v[104:107], v[20:23], v[44:47], 0
	v_mfma_f32_16x16x32_bf16 v[44:47], v[28:31], v[44:47], 0
	v_mfma_f32_16x16x32_bf16 v[108:111], v[20:23], v[52:55], 0
	v_mfma_f32_16x16x32_bf16 v[52:55], v[28:31], v[52:55], 0
	v_mfma_f32_16x16x32_bf16 v[112:115], v[20:23], v[60:63], 0
	v_mfma_f32_16x16x32_bf16 v[60:63], v[28:31], v[60:63], 0
	s_setprio 0
	s_setprio 1
	v_mfma_f32_16x16x32_bf16 v[100:103], v[24:27], v[40:43], v[100:103]
	v_mfma_f32_16x16x32_bf16 v[40:43], v[32:35], v[40:43], v[36:39]
	v_mfma_f32_16x16x32_bf16 v[104:107], v[24:27], v[48:51], v[104:107]
	v_mfma_f32_16x16x32_bf16 v[48:51], v[32:35], v[48:51], v[44:47]
	v_mfma_f32_16x16x32_bf16 v[108:111], v[24:27], v[56:59], v[108:111]
	v_mfma_f32_16x16x32_bf16 v[56:59], v[32:35], v[56:59], v[52:55]
	s_setprio 2
	s_barrier
	v_mfma_f32_16x16x32_bf16 v[112:115], v[24:27], v[64:67], v[112:115]
	v_mfma_f32_16x16x32_bf16 v[64:67], v[32:35], v[64:67], v[60:63]
	s_setprio 0
	v_lshl_add_u64 v[186:187], s[12:13], 0, v[2:3]
	s_add_i32 s51, s51, s38
	v_mov_b32_e32 v191, v3
	v_lshl_add_u64 v[134:135], v[186:187], 0, s[74:75]
	s_mov_b32 m0, s51
	v_lshl_add_u64 v[246:247], s[12:13], 0, v[190:191]
	ds_read_b128 v[36:39], v233 offset:16384
	ds_read_b128 v[44:47], v233 offset:17408
	ds_read_b128 v[52:55], v233 offset:18432
	ds_read_b128 v[60:63], v233 offset:19456
	ds_read_b128 v[116:119], v233 offset:20480
	ds_read_b128 v[120:123], v233 offset:21504
	ds_read_b128 v[124:127], v233 offset:22528
	ds_read_b128 v[128:131], v233 offset:23552
	global_load_lds_dwordx4 v[134:135], off
	v_lshl_add_u64 v[134:135], v[246:247], 0, s[74:75]
	s_add_i32 m0, s51, 0x2000
	s_add_i32 s51, s71, s38
	global_load_lds_dwordx4 v[134:135], off
	s_mov_b32 m0, s51
	v_mov_b32_e32 v133, v3
	global_load_lds_dwordx4 v2, s[16:17]
	s_add_i32 m0, s51, 0x2000
	v_lshl_add_u64 v[248:249], s[14:15], 0, v[132:133]
	v_mov_b32_e32 v189, v3
	global_load_lds_dwordx4 v190, s[16:17]
	v_lshl_add_u64 v[134:135], v[248:249], 0, s[74:75]
	s_mov_b32 m0, s56
	v_lshl_add_u64 v[250:251], s[14:15], 0, v[188:189]
	global_load_lds_dwordx4 v[134:135], off
	v_lshl_add_u64 v[134:135], v[250:251], 0, s[74:75]
	s_mov_b32 m0, s57
	s_nop 0
	global_load_lds_dwordx4 v[134:135], off
	s_waitcnt vmcnt(8)
	s_waitcnt lgkmcnt(0)
	s_barrier
	s_setprio 1
	s_waitcnt lgkmcnt(0)
	v_mfma_f32_16x16x32_bf16 v[134:137], v[4:7], v[36:39], 0
	v_mfma_f32_16x16x32_bf16 v[138:141], v[12:15], v[36:39], 0
	v_mfma_f32_16x16x32_bf16 v[142:145], v[4:7], v[52:55], 0
	v_mfma_f32_16x16x32_bf16 v[146:149], v[12:15], v[52:55], 0
	v_mfma_f32_16x16x32_bf16 v[150:153], v[4:7], v[116:119], 0
	v_mfma_f32_16x16x32_bf16 v[154:157], v[12:15], v[116:119], 0
	v_mfma_f32_16x16x32_bf16 v[4:7], v[4:7], v[124:127], 0
	v_mfma_f32_16x16x32_bf16 v[12:15], v[12:15], v[124:127], 0
	s_setprio 0
	s_setprio 1
	v_mfma_f32_16x16x32_bf16 v[134:137], v[8:11], v[44:47], v[134:137]
	v_mfma_f32_16x16x32_bf16 v[138:141], v[16:19], v[44:47], v[138:141]
	v_mfma_f32_16x16x32_bf16 v[142:145], v[8:11], v[60:63], v[142:145]
	v_mfma_f32_16x16x32_bf16 v[146:149], v[16:19], v[60:63], v[146:149]
	v_mfma_f32_16x16x32_bf16 v[150:153], v[8:11], v[120:123], v[150:153]
	v_mfma_f32_16x16x32_bf16 v[154:157], v[16:19], v[120:123], v[154:157]
	v_mfma_f32_16x16x32_bf16 v[158:161], v[8:11], v[128:131], v[4:7]
	v_mfma_f32_16x16x32_bf16 v[162:165], v[16:19], v[128:131], v[12:15]
	s_setprio 0
	s_setprio 1
	v_mfma_f32_16x16x32_bf16 v[4:7], v[20:23], v[36:39], 0
	v_mfma_f32_16x16x32_bf16 v[8:11], v[28:31], v[36:39], 0
	v_mfma_f32_16x16x32_bf16 v[12:15], v[20:23], v[52:55], 0
	v_mfma_f32_16x16x32_bf16 v[16:19], v[28:31], v[52:55], 0
	v_mfma_f32_16x16x32_bf16 v[36:39], v[20:23], v[116:119], 0
	v_mfma_f32_16x16x32_bf16 v[52:55], v[28:31], v[116:119], 0
	v_mfma_f32_16x16x32_bf16 v[20:23], v[20:23], v[124:127], 0
	v_mfma_f32_16x16x32_bf16 v[28:31], v[28:31], v[124:127], 0
	s_setprio 0
	s_setprio 1
	v_mfma_f32_16x16x32_bf16 v[116:119], v[24:27], v[44:47], v[4:7]
	v_mfma_f32_16x16x32_bf16 v[124:127], v[32:35], v[44:47], v[8:11]
	v_mfma_f32_16x16x32_bf16 v[174:177], v[24:27], v[120:123], v[36:39]
	v_mfma_f32_16x16x32_bf16 v[120:123], v[32:35], v[120:123], v[52:55]
	v_mfma_f32_16x16x32_bf16 v[178:181], v[24:27], v[128:131], v[20:23]
	v_mfma_f32_16x16x32_bf16 v[128:131], v[32:35], v[128:131], v[28:31]
	s_setprio 2
	s_barrier
	v_mfma_f32_16x16x32_bf16 v[166:169], v[24:27], v[60:63], v[12:15]
	v_mfma_f32_16x16x32_bf16 v[170:173], v[32:35], v[60:63], v[16:19]
	s_setprio 0
	s_add_i32 s51, 0, 0x18000
	v_add_u32_e32 v4, s51, v232
	s_add_i32 s71, 0, 0x1c000
	ds_read_b128 v[182:185], v4
	ds_read_b128 v[192:195], v4 offset:1024
	ds_read_b128 v[196:199], v4 offset:2048
	ds_read_b128 v[200:203], v4 offset:3072
	v_add_u32_e32 v4, s71, v232
	ds_read_b128 v[204:207], v4
	ds_read_b128 v[208:211], v4 offset:1024
	ds_read_b128 v[212:215], v4 offset:2048
	ds_read_b128 v[216:219], v4 offset:3072
	s_mov_b32 m0, s58
	ds_read_b128 v[44:47], v233 offset:32768
	ds_read_b128 v[52:55], v233 offset:33792
	ds_read_b128 v[60:63], v233 offset:34816
	ds_read_b128 v[220:223], v233 offset:35840
	ds_read_b128 v[224:227], v233 offset:36864
	ds_read_b128 v[234:237], v233 offset:37888
	ds_read_b128 v[238:241], v233 offset:38912
	ds_read_b128 v[242:245], v233 offset:39936
	global_load_lds_dwordx4 v132, s[26:27]
	s_mov_b32 m0, s59
	s_nop 0
	global_load_lds_dwordx4 v188, s[26:27]
	s_waitcnt vmcnt(8)
	s_waitcnt lgkmcnt(0)
	s_barrier
	s_setprio 1
	s_waitcnt lgkmcnt(0)
	v_mfma_f32_16x16x32_bf16 v[4:7], v[182:185], v[44:47], v[68:71]
	v_mfma_f32_16x16x32_bf16 v[8:11], v[196:199], v[44:47], v[72:75]
	v_mfma_f32_16x16x32_bf16 v[12:15], v[182:185], v[60:63], v[76:79]
	v_mfma_f32_16x16x32_bf16 v[16:19], v[196:199], v[60:63], v[80:83]
	v_mfma_f32_16x16x32_bf16 v[20:23], v[182:185], v[224:227], v[84:87]
	v_mfma_f32_16x16x32_bf16 v[24:27], v[196:199], v[224:227], v[88:91]
	v_mfma_f32_16x16x32_bf16 v[28:31], v[182:185], v[238:241], v[92:95]
	v_mfma_f32_16x16x32_bf16 v[32:35], v[196:199], v[238:241], v[96:99]
	s_setprio 0
	s_setprio 1
	v_mfma_f32_16x16x32_bf16 v[4:7], v[192:195], v[52:55], v[4:7]
	v_mfma_f32_16x16x32_bf16 v[8:11], v[200:203], v[52:55], v[8:11]
	v_mfma_f32_16x16x32_bf16 v[12:15], v[192:195], v[220:223], v[12:15]
	v_mfma_f32_16x16x32_bf16 v[16:19], v[200:203], v[220:223], v[16:19]
	v_mfma_f32_16x16x32_bf16 v[20:23], v[192:195], v[234:237], v[20:23]
	v_mfma_f32_16x16x32_bf16 v[24:27], v[200:203], v[234:237], v[24:27]
	v_mfma_f32_16x16x32_bf16 v[28:31], v[192:195], v[242:245], v[28:31]
	v_mfma_f32_16x16x32_bf16 v[32:35], v[200:203], v[242:245], v[32:35]
	s_setprio 0
	s_setprio 1
	v_mfma_f32_16x16x32_bf16 v[36:39], v[204:207], v[44:47], v[100:103]
	v_mfma_f32_16x16x32_bf16 v[40:43], v[212:215], v[44:47], v[40:43]
	v_mfma_f32_16x16x32_bf16 v[36:39], v[208:211], v[52:55], v[36:39]
	v_mfma_f32_16x16x32_bf16 v[40:43], v[216:219], v[52:55], v[40:43]
	v_mfma_f32_16x16x32_bf16 v[44:47], v[204:207], v[60:63], v[104:107]
	v_mfma_f32_16x16x32_bf16 v[48:51], v[212:215], v[60:63], v[48:51]
	v_mfma_f32_16x16x32_bf16 v[52:55], v[204:207], v[224:227], v[108:111]
	v_mfma_f32_16x16x32_bf16 v[56:59], v[212:215], v[224:227], v[56:59]
	s_setprio 0
	s_setprio 1
	v_mfma_f32_16x16x32_bf16 v[60:63], v[204:207], v[238:241], v[112:115]
	v_mfma_f32_16x16x32_bf16 v[64:67], v[212:215], v[238:241], v[64:67]
	v_mfma_f32_16x16x32_bf16 v[44:47], v[208:211], v[220:223], v[44:47]
	v_mfma_f32_16x16x32_bf16 v[48:51], v[216:219], v[220:223], v[48:51]
	v_mfma_f32_16x16x32_bf16 v[52:55], v[208:211], v[234:237], v[52:55]
	v_mfma_f32_16x16x32_bf16 v[56:59], v[216:219], v[234:237], v[56:59]
	s_setprio 2
	s_barrier
	v_mfma_f32_16x16x32_bf16 v[60:63], v[208:211], v[242:245], v[60:63]
	v_mfma_f32_16x16x32_bf16 v[64:67], v[216:219], v[242:245], v[64:67]
	s_setprio 0
	s_add_i32 s51, s51, s38
	v_lshl_add_u64 v[68:69], v[186:187], 0, s[24:25]
	s_mov_b32 m0, s51
	ds_read_b128 v[104:107], v233 offset:49152
	ds_read_b128 v[108:111], v233 offset:50176
	ds_read_b128 v[112:115], v233 offset:51200
	ds_read_b128 v[220:223], v233 offset:52224
	ds_read_b128 v[224:227], v233 offset:53248
	ds_read_b128 v[234:237], v233 offset:54272
	ds_read_b128 v[238:241], v233 offset:55296
	ds_read_b128 v[242:245], v233 offset:56320
	global_load_lds_dwordx4 v[68:69], off
	v_lshl_add_u64 v[68:69], v[246:247], 0, s[24:25]
	s_add_i32 m0, s51, 0x2000
	s_add_i32 s51, s71, s38
	global_load_lds_dwordx4 v[68:69], off
	s_mov_b32 m0, s51
	v_lshl_add_u64 v[68:69], v[248:249], 0, s[24:25]
	global_load_lds_dwordx4 v2, s[28:29]
	s_add_i32 m0, s51, 0x2000
	s_nop 0
	global_load_lds_dwordx4 v190, s[28:29]
	s_mov_b32 m0, s63
	s_nop 0
	global_load_lds_dwordx4 v[68:69], off
	v_lshl_add_u64 v[68:69], v[250:251], 0, s[24:25]
	s_mov_b32 m0, s64
	s_nop 0
	global_load_lds_dwordx4 v[68:69], off
	s_waitcnt vmcnt(8)
	s_waitcnt lgkmcnt(0)
	s_barrier
	s_setprio 1
	s_waitcnt lgkmcnt(0)
	v_mfma_f32_16x16x32_bf16 v[68:71], v[182:185], v[104:107], v[134:137]
	v_mfma_f32_16x16x32_bf16 v[72:75], v[196:199], v[104:107], v[138:141]
	v_mfma_f32_16x16x32_bf16 v[76:79], v[182:185], v[112:115], v[142:145]
	v_mfma_f32_16x16x32_bf16 v[80:83], v[196:199], v[112:115], v[146:149]
	v_mfma_f32_16x16x32_bf16 v[84:87], v[182:185], v[224:227], v[150:153]
	v_mfma_f32_16x16x32_bf16 v[88:91], v[196:199], v[224:227], v[154:157]
	v_mfma_f32_16x16x32_bf16 v[92:95], v[182:185], v[238:241], v[158:161]
	v_mfma_f32_16x16x32_bf16 v[96:99], v[196:199], v[238:241], v[162:165]
	s_setprio 0
	s_setprio 1
	v_mfma_f32_16x16x32_bf16 v[68:71], v[192:195], v[108:111], v[68:71]
	v_mfma_f32_16x16x32_bf16 v[72:75], v[200:203], v[108:111], v[72:75]
	v_mfma_f32_16x16x32_bf16 v[76:79], v[192:195], v[220:223], v[76:79]
	v_mfma_f32_16x16x32_bf16 v[80:83], v[200:203], v[220:223], v[80:83]
	v_mfma_f32_16x16x32_bf16 v[84:87], v[192:195], v[234:237], v[84:87]
	v_mfma_f32_16x16x32_bf16 v[88:91], v[200:203], v[234:237], v[88:91]
	v_mfma_f32_16x16x32_bf16 v[92:95], v[192:195], v[242:245], v[92:95]
	v_mfma_f32_16x16x32_bf16 v[96:99], v[200:203], v[242:245], v[96:99]
	s_setprio 0
	s_setprio 1
	v_mfma_f32_16x16x32_bf16 v[100:103], v[204:207], v[104:107], v[116:119]
	v_mfma_f32_16x16x32_bf16 v[104:107], v[212:215], v[104:107], v[124:127]
	v_mfma_f32_16x16x32_bf16 v[100:103], v[208:211], v[108:111], v[100:103]
	v_mfma_f32_16x16x32_bf16 v[104:107], v[216:219], v[108:111], v[104:107]
	v_mfma_f32_16x16x32_bf16 v[108:111], v[204:207], v[112:115], v[166:169]
	v_mfma_f32_16x16x32_bf16 v[112:115], v[212:215], v[112:115], v[170:173]
	v_mfma_f32_16x16x32_bf16 v[116:119], v[204:207], v[224:227], v[174:177]
	v_mfma_f32_16x16x32_bf16 v[120:123], v[212:215], v[224:227], v[120:123]
	s_setprio 0
	s_setprio 1
	v_mfma_f32_16x16x32_bf16 v[124:127], v[204:207], v[238:241], v[178:181]
	v_mfma_f32_16x16x32_bf16 v[128:131], v[212:215], v[238:241], v[128:131]
	v_mfma_f32_16x16x32_bf16 v[108:111], v[208:211], v[220:223], v[108:111]
	v_mfma_f32_16x16x32_bf16 v[112:115], v[216:219], v[220:223], v[112:115]
	v_mfma_f32_16x16x32_bf16 v[116:119], v[208:211], v[234:237], v[116:119]
	v_mfma_f32_16x16x32_bf16 v[120:123], v[216:219], v[234:237], v[120:123]
	s_setprio 2
	s_barrier
	v_mfma_f32_16x16x32_bf16 v[124:127], v[208:211], v[242:245], v[124:127]
	v_mfma_f32_16x16x32_bf16 v[128:131], v[216:219], v[242:245], v[128:131]
	s_setprio 0
	s_add_i32 s41, s41, 2
	s_cmp_ge_i32 s41, s40
	s_cbranch_scc0 .LBB0_2269
	v_mov_b32_e32 v192, v2
	s_branch .LBB0_2272

.LBB0_2273:
	s_add_u32 s12, s14, 0xfffc0080
	s_addc_u32 s13, s15, -1
	s_add_i32 s29, 0, 0x10000
	s_cmp_eq_u32 s28, 12
	s_cselect_b32 s17, s9, s13
	s_cselect_b32 s16, s8, s12
	s_cselect_b32 s13, s11, s27
	s_cselect_b32 s12, s10, s26
	s_add_i32 s51, 0, 0x14000
	v_add_u32_e32 v144, s29, v232
	v_add_u32_e32 v160, s51, v232
	s_waitcnt lgkmcnt(0)
	ds_read_b128 v[132:135], v144
	ds_read_b128 v[136:139], v144 offset:1024
	ds_read_b128 v[140:143], v144 offset:2048
	ds_read_b128 v[144:147], v144 offset:3072
	ds_read_b128 v[148:151], v160
	ds_read_b128 v[152:155], v160 offset:1024
	ds_read_b128 v[156:159], v160 offset:2048
	ds_read_b128 v[160:163], v160 offset:3072
	s_mov_b32 m0, s65
	v_add_u32_e32 v210, 0, v231
	ds_read_b128 v[164:167], v210
	ds_read_b128 v[168:171], v210 offset:1024
	ds_read_b128 v[172:175], v210 offset:2048
	ds_read_b128 v[176:179], v210 offset:3072
	ds_read_b128 v[180:183], v210 offset:4096
	ds_read_b128 v[184:187], v210 offset:5120
	ds_read_b128 v[194:197], v210 offset:6144
	ds_read_b128 v[198:201], v210 offset:7168
	global_load_lds_dwordx4 v2, s[14:15]
	s_mov_b32 m0, s66
	v_mov_b32_e32 v189, v3
	global_load_lds_dwordx4 v188, s[14:15]
	s_waitcnt vmcnt(8)
	s_waitcnt lgkmcnt(0)
	s_barrier
	s_setprio 1
	s_waitcnt lgkmcnt(0)
	v_mfma_f32_16x16x32_bf16 v[4:7], v[132:135], v[164:167], v[4:7]
	v_mfma_f32_16x16x32_bf16 v[4:7], v[136:139], v[168:171], v[4:7]
	v_mfma_f32_16x16x32_bf16 v[8:11], v[144:147], v[168:171], v[8:11]
	v_mfma_f32_16x16x32_bf16 v[8:11], v[140:143], v[164:167], v[8:11]
	v_mfma_f32_16x16x32_bf16 v[16:19], v[140:143], v[172:175], v[16:19]
	v_mfma_f32_16x16x32_bf16 v[16:19], v[144:147], v[176:179], v[16:19]
	v_mfma_f32_16x16x32_bf16 v[12:15], v[136:139], v[176:179], v[12:15]
	v_mfma_f32_16x16x32_bf16 v[12:15], v[132:135], v[172:175], v[12:15]
	s_setprio 0
	s_setprio 1
	v_mfma_f32_16x16x32_bf16 v[20:23], v[132:135], v[180:183], v[20:23]
	v_mfma_f32_16x16x32_bf16 v[20:23], v[136:139], v[184:187], v[20:23]
	v_mfma_f32_16x16x32_bf16 v[24:27], v[144:147], v[184:187], v[24:27]
	v_mfma_f32_16x16x32_bf16 v[24:27], v[140:143], v[180:183], v[24:27]
	v_mfma_f32_16x16x32_bf16 v[32:35], v[140:143], v[194:197], v[32:35]
	v_mfma_f32_16x16x32_bf16 v[32:35], v[144:147], v[198:201], v[32:35]
	v_mfma_f32_16x16x32_bf16 v[28:31], v[136:139], v[198:201], v[28:31]
	v_mfma_f32_16x16x32_bf16 v[28:31], v[132:135], v[194:197], v[28:31]
	s_setprio 0
	s_setprio 1
	v_mfma_f32_16x16x32_bf16 v[36:39], v[148:151], v[164:167], v[36:39]
	v_mfma_f32_16x16x32_bf16 v[36:39], v[152:155], v[168:171], v[36:39]
	v_mfma_f32_16x16x32_bf16 v[40:43], v[160:163], v[168:171], v[40:43]
	v_mfma_f32_16x16x32_bf16 v[40:43], v[156:159], v[164:167], v[40:43]
	v_mfma_f32_16x16x32_bf16 v[48:51], v[156:159], v[172:175], v[48:51]
	v_mfma_f32_16x16x32_bf16 v[48:51], v[160:163], v[176:179], v[48:51]
	v_mfma_f32_16x16x32_bf16 v[44:47], v[152:155], v[176:179], v[44:47]
	v_mfma_f32_16x16x32_bf16 v[44:47], v[148:151], v[172:175], v[44:47]
	s_setprio 0
	s_setprio 1
	v_mfma_f32_16x16x32_bf16 v[52:55], v[148:151], v[180:183], v[52:55]
	v_mfma_f32_16x16x32_bf16 v[52:55], v[152:155], v[184:187], v[52:55]
	v_mfma_f32_16x16x32_bf16 v[56:59], v[160:163], v[184:187], v[56:59]
	v_mfma_f32_16x16x32_bf16 v[56:59], v[156:159], v[180:183], v[56:59]
	v_mfma_f32_16x16x32_bf16 v[64:67], v[156:159], v[194:197], v[64:67]
	v_mfma_f32_16x16x32_bf16 v[64:67], v[160:163], v[198:201], v[64:67]
	s_setprio 2
	s_barrier
	v_mfma_f32_16x16x32_bf16 v[60:63], v[152:155], v[198:201], v[60:63]
	v_mfma_f32_16x16x32_bf16 v[60:63], v[148:151], v[194:197], v[60:63]
	s_setprio 0
	s_add_i32 s29, s29, s38
	s_mov_b32 m0, s29
	ds_read_b128 v[164:167], v210 offset:16384
	ds_read_b128 v[168:171], v210 offset:17408
	ds_read_b128 v[172:175], v210 offset:18432
	ds_read_b128 v[176:179], v210 offset:19456
	ds_read_b128 v[180:183], v210 offset:20480
	ds_read_b128 v[184:187], v210 offset:21504
	ds_read_b128 v[194:197], v210 offset:22528
	ds_read_b128 v[198:201], v210 offset:23552
	global_load_lds_dwordx4 v192, s[12:13]
	s_add_i32 m0, s29, 0x2000
	s_add_u32 s40, s12, 0x100000
	s_addc_u32 s41, s13, 0
	s_add_i32 s29, s51, s38
	global_load_lds_dwordx4 v190, s[12:13]
	s_mov_b32 m0, s29
	v_mov_b32_e32 v193, v3
	global_load_lds_dwordx4 v192, s[40:41]
	s_add_i32 m0, s29, 0x2000
	v_mov_b32_e32 v191, v3
	global_load_lds_dwordx4 v190, s[40:41]
	s_mov_b32 m0, s56
	v_lshl_add_u64 v[202:203], s[12:13], 0, v[192:193]
	global_load_lds_dwordx4 v2, s[16:17]
	s_mov_b32 m0, s57
	v_lshl_add_u64 v[204:205], s[12:13], 0, v[190:191]
	global_load_lds_dwordx4 v188, s[16:17]
	s_waitcnt vmcnt(8)
	s_waitcnt lgkmcnt(0)
	v_lshl_add_u64 v[206:207], s[16:17], 0, v[2:3]
	v_lshl_add_u64 v[208:209], s[16:17], 0, v[188:189]
	s_barrier
	s_setprio 1
	s_waitcnt lgkmcnt(0)
	v_mfma_f32_16x16x32_bf16 v[68:71], v[132:135], v[164:167], v[68:71]
	v_mfma_f32_16x16x32_bf16 v[68:71], v[136:139], v[168:171], v[68:71]
	v_mfma_f32_16x16x32_bf16 v[72:75], v[144:147], v[168:171], v[72:75]
	v_mfma_f32_16x16x32_bf16 v[72:75], v[140:143], v[164:167], v[72:75]
	v_mfma_f32_16x16x32_bf16 v[80:83], v[140:143], v[172:175], v[80:83]
	v_mfma_f32_16x16x32_bf16 v[80:83], v[144:147], v[176:179], v[80:83]
	v_mfma_f32_16x16x32_bf16 v[76:79], v[136:139], v[176:179], v[76:79]
	v_mfma_f32_16x16x32_bf16 v[76:79], v[132:135], v[172:175], v[76:79]
	s_setprio 0
	s_setprio 1
	v_mfma_f32_16x16x32_bf16 v[84:87], v[132:135], v[180:183], v[84:87]
	v_mfma_f32_16x16x32_bf16 v[84:87], v[136:139], v[184:187], v[84:87]
	v_mfma_f32_16x16x32_bf16 v[88:91], v[144:147], v[184:187], v[88:91]
	v_mfma_f32_16x16x32_bf16 v[88:91], v[140:143], v[180:183], v[88:91]
	v_mfma_f32_16x16x32_bf16 v[96:99], v[140:143], v[194:197], v[96:99]
	v_mfma_f32_16x16x32_bf16 v[96:99], v[144:147], v[198:201], v[96:99]
	v_mfma_f32_16x16x32_bf16 v[92:95], v[136:139], v[198:201], v[92:95]
	v_mfma_f32_16x16x32_bf16 v[92:95], v[132:135], v[194:197], v[92:95]
	s_setprio 0
	s_setprio 1
	v_mfma_f32_16x16x32_bf16 v[100:103], v[148:151], v[164:167], v[100:103]
	v_mfma_f32_16x16x32_bf16 v[100:103], v[152:155], v[168:171], v[100:103]
	v_mfma_f32_16x16x32_bf16 v[104:107], v[160:163], v[168:171], v[104:107]
	v_mfma_f32_16x16x32_bf16 v[104:107], v[156:159], v[164:167], v[104:107]
	v_mfma_f32_16x16x32_bf16 v[112:115], v[156:159], v[172:175], v[112:115]
	v_mfma_f32_16x16x32_bf16 v[112:115], v[160:163], v[176:179], v[112:115]
	v_mfma_f32_16x16x32_bf16 v[108:111], v[152:155], v[176:179], v[108:111]
	v_mfma_f32_16x16x32_bf16 v[108:111], v[148:151], v[172:175], v[108:111]
	s_setprio 0
	s_setprio 1
	v_mfma_f32_16x16x32_bf16 v[116:119], v[148:151], v[180:183], v[116:119]
	v_mfma_f32_16x16x32_bf16 v[116:119], v[152:155], v[184:187], v[116:119]
	v_mfma_f32_16x16x32_bf16 v[120:123], v[160:163], v[184:187], v[120:123]
	v_mfma_f32_16x16x32_bf16 v[120:123], v[156:159], v[180:183], v[120:123]
	v_mfma_f32_16x16x32_bf16 v[128:131], v[156:159], v[194:197], v[128:131]
	v_mfma_f32_16x16x32_bf16 v[128:131], v[160:163], v[198:201], v[128:131]
	s_setprio 2
	s_barrier
	v_mfma_f32_16x16x32_bf16 v[124:127], v[152:155], v[198:201], v[124:127]
	v_mfma_f32_16x16x32_bf16 v[124:127], v[148:151], v[194:197], v[124:127]
	s_setprio 0
	s_add_i32 s29, 0, 0x18000
	s_add_i32 s40, 0, 0x1c000
	v_add_u32_e32 v144, s29, v232
	v_add_u32_e32 v160, s40, v232
	ds_read_b128 v[132:135], v144
	ds_read_b128 v[136:139], v144 offset:1024
	ds_read_b128 v[140:143], v144 offset:2048
	ds_read_b128 v[144:147], v144 offset:3072
	ds_read_b128 v[148:151], v160
	ds_read_b128 v[152:155], v160 offset:1024
	ds_read_b128 v[156:159], v160 offset:2048
	ds_read_b128 v[160:163], v160 offset:3072
	s_add_u32 s16, s16, 0x40000
	s_addc_u32 s17, s17, 0
	s_mov_b32 m0, s58
	ds_read_b128 v[164:167], v210 offset:32768
	ds_read_b128 v[168:171], v210 offset:33792
	ds_read_b128 v[172:175], v210 offset:34816
	ds_read_b128 v[176:179], v210 offset:35840
	ds_read_b128 v[180:183], v210 offset:36864
	ds_read_b128 v[184:187], v210 offset:37888
	ds_read_b128 v[194:197], v210 offset:38912
	ds_read_b128 v[198:201], v210 offset:39936
	global_load_lds_dwordx4 v2, s[16:17]
	s_mov_b32 m0, s59
	s_nop 0
	global_load_lds_dwordx4 v188, s[16:17]
	s_waitcnt vmcnt(8)
	s_waitcnt lgkmcnt(0)
	s_barrier
	s_setprio 1
	s_waitcnt lgkmcnt(0)
	v_mfma_f32_16x16x32_bf16 v[4:7], v[132:135], v[164:167], v[4:7]
	v_mfma_f32_16x16x32_bf16 v[4:7], v[136:139], v[168:171], v[4:7]
	v_mfma_f32_16x16x32_bf16 v[8:11], v[144:147], v[168:171], v[8:11]
	v_mfma_f32_16x16x32_bf16 v[8:11], v[140:143], v[164:167], v[8:11]
	v_mfma_f32_16x16x32_bf16 v[16:19], v[140:143], v[172:175], v[16:19]
	v_mfma_f32_16x16x32_bf16 v[16:19], v[144:147], v[176:179], v[16:19]
	v_mfma_f32_16x16x32_bf16 v[12:15], v[136:139], v[176:179], v[12:15]
	v_mfma_f32_16x16x32_bf16 v[12:15], v[132:135], v[172:175], v[12:15]
	s_setprio 0
	s_setprio 1
	v_mfma_f32_16x16x32_bf16 v[20:23], v[132:135], v[180:183], v[20:23]
	v_mfma_f32_16x16x32_bf16 v[20:23], v[136:139], v[184:187], v[20:23]
	v_mfma_f32_16x16x32_bf16 v[24:27], v[144:147], v[184:187], v[24:27]
	v_mfma_f32_16x16x32_bf16 v[24:27], v[140:143], v[180:183], v[24:27]
	v_mfma_f32_16x16x32_bf16 v[32:35], v[140:143], v[194:197], v[32:35]
	v_mfma_f32_16x16x32_bf16 v[32:35], v[144:147], v[198:201], v[32:35]
	v_mfma_f32_16x16x32_bf16 v[28:31], v[136:139], v[198:201], v[28:31]
	v_mfma_f32_16x16x32_bf16 v[28:31], v[132:135], v[194:197], v[28:31]
	s_setprio 0
	s_setprio 1
	v_mfma_f32_16x16x32_bf16 v[36:39], v[148:151], v[164:167], v[36:39]
	v_mfma_f32_16x16x32_bf16 v[36:39], v[152:155], v[168:171], v[36:39]
	v_mfma_f32_16x16x32_bf16 v[40:43], v[160:163], v[168:171], v[40:43]
	v_mfma_f32_16x16x32_bf16 v[40:43], v[156:159], v[164:167], v[40:43]
	v_mfma_f32_16x16x32_bf16 v[48:51], v[156:159], v[172:175], v[48:51]
	v_mfma_f32_16x16x32_bf16 v[48:51], v[160:163], v[176:179], v[48:51]
	v_mfma_f32_16x16x32_bf16 v[44:47], v[152:155], v[176:179], v[44:47]
	v_mfma_f32_16x16x32_bf16 v[44:47], v[148:151], v[172:175], v[44:47]
	s_setprio 0
	s_setprio 1
	v_mfma_f32_16x16x32_bf16 v[52:55], v[148:151], v[180:183], v[52:55]
	v_mfma_f32_16x16x32_bf16 v[52:55], v[152:155], v[184:187], v[52:55]
	v_mfma_f32_16x16x32_bf16 v[56:59], v[160:163], v[184:187], v[56:59]
	v_mfma_f32_16x16x32_bf16 v[56:59], v[156:159], v[180:183], v[56:59]
	v_mfma_f32_16x16x32_bf16 v[64:67], v[156:159], v[194:197], v[64:67]
	v_mfma_f32_16x16x32_bf16 v[64:67], v[160:163], v[198:201], v[64:67]
	s_setprio 2
	s_barrier
	v_mfma_f32_16x16x32_bf16 v[60:63], v[152:155], v[198:201], v[60:63]
	v_mfma_f32_16x16x32_bf16 v[60:63], v[148:151], v[194:197], v[60:63]
	s_setprio 0
	s_add_i32 s16, s29, s38
	v_lshl_add_u64 v[202:203], v[202:203], 0, s[86:87]
	s_mov_b32 m0, s16
	ds_read_b128 v[164:167], v210 offset:49152
	ds_read_b128 v[168:171], v210 offset:50176
	ds_read_b128 v[172:175], v210 offset:51200
	ds_read_b128 v[176:179], v210 offset:52224
	ds_read_b128 v[180:183], v210 offset:53248
	ds_read_b128 v[184:187], v210 offset:54272
	ds_read_b128 v[194:197], v210 offset:55296
	ds_read_b128 v[198:201], v210 offset:56320
	global_load_lds_dwordx4 v[202:203], off
	s_add_i32 m0, s16, 0x2000
	s_add_u32 s12, s12, 0x100080
	v_lshl_add_u64 v[202:203], v[204:205], 0, s[86:87]
	s_addc_u32 s13, s13, 0
	s_add_i32 s16, s40, s38
	global_load_lds_dwordx4 v[202:203], off
	s_mov_b32 m0, s16
	v_lshl_add_u64 v[202:203], v[206:207], 0, s[86:87]
	global_load_lds_dwordx4 v192, s[12:13]
	s_add_i32 m0, s16, 0x2000
	s_nop 0
	global_load_lds_dwordx4 v190, s[12:13]
	s_mov_b32 m0, s63
	s_nop 0
	global_load_lds_dwordx4 v[202:203], off
	v_lshl_add_u64 v[202:203], v[208:209], 0, s[86:87]
	s_mov_b32 m0, s64
	s_nop 0
	global_load_lds_dwordx4 v[202:203], off
	s_waitcnt vmcnt(8)
	s_waitcnt lgkmcnt(0)
	s_barrier
	s_setprio 1
	s_waitcnt lgkmcnt(0)
	v_mfma_f32_16x16x32_bf16 v[68:71], v[132:135], v[164:167], v[68:71]
	v_mfma_f32_16x16x32_bf16 v[68:71], v[136:139], v[168:171], v[68:71]
	v_mfma_f32_16x16x32_bf16 v[72:75], v[144:147], v[168:171], v[72:75]
	v_mfma_f32_16x16x32_bf16 v[72:75], v[140:143], v[164:167], v[72:75]
	v_mfma_f32_16x16x32_bf16 v[80:83], v[140:143], v[172:175], v[80:83]
	v_mfma_f32_16x16x32_bf16 v[80:83], v[144:147], v[176:179], v[80:83]
	v_mfma_f32_16x16x32_bf16 v[76:79], v[136:139], v[176:179], v[76:79]
	v_mfma_f32_16x16x32_bf16 v[76:79], v[132:135], v[172:175], v[76:79]
	s_setprio 0
	s_setprio 1
	v_mfma_f32_16x16x32_bf16 v[84:87], v[132:135], v[180:183], v[84:87]
	v_mfma_f32_16x16x32_bf16 v[84:87], v[136:139], v[184:187], v[84:87]
	v_mfma_f32_16x16x32_bf16 v[88:91], v[144:147], v[184:187], v[88:91]
	v_mfma_f32_16x16x32_bf16 v[88:91], v[140:143], v[180:183], v[88:91]
	v_mfma_f32_16x16x32_bf16 v[96:99], v[140:143], v[194:197], v[96:99]
	v_mfma_f32_16x16x32_bf16 v[96:99], v[144:147], v[198:201], v[96:99]
	v_mfma_f32_16x16x32_bf16 v[92:95], v[136:139], v[198:201], v[92:95]
	v_mfma_f32_16x16x32_bf16 v[92:95], v[132:135], v[194:197], v[92:95]
	s_setprio 0
	s_setprio 1
	v_mfma_f32_16x16x32_bf16 v[100:103], v[148:151], v[164:167], v[100:103]
	v_mfma_f32_16x16x32_bf16 v[100:103], v[152:155], v[168:171], v[100:103]
	v_mfma_f32_16x16x32_bf16 v[104:107], v[160:163], v[168:171], v[104:107]
	v_mfma_f32_16x16x32_bf16 v[104:107], v[156:159], v[164:167], v[104:107]
	v_mfma_f32_16x16x32_bf16 v[112:115], v[156:159], v[172:175], v[112:115]
	v_mfma_f32_16x16x32_bf16 v[112:115], v[160:163], v[176:179], v[112:115]
	v_mfma_f32_16x16x32_bf16 v[108:111], v[152:155], v[176:179], v[108:111]
	v_mfma_f32_16x16x32_bf16 v[108:111], v[148:151], v[172:175], v[108:111]
	s_setprio 0
	s_setprio 1
	v_mfma_f32_16x16x32_bf16 v[116:119], v[148:151], v[180:183], v[116:119]
	v_mfma_f32_16x16x32_bf16 v[116:119], v[152:155], v[184:187], v[116:119]
	v_mfma_f32_16x16x32_bf16 v[120:123], v[160:163], v[184:187], v[120:123]
	v_mfma_f32_16x16x32_bf16 v[120:123], v[156:159], v[180:183], v[120:123]
	v_mfma_f32_16x16x32_bf16 v[128:131], v[156:159], v[194:197], v[128:131]
	v_mfma_f32_16x16x32_bf16 v[128:131], v[160:163], v[198:201], v[128:131]
	s_setprio 2
	s_barrier
	v_mfma_f32_16x16x32_bf16 v[124:127], v[152:155], v[198:201], v[124:127]
	v_mfma_f32_16x16x32_bf16 v[124:127], v[148:151], v[194:197], v[124:127]
	s_setprio 0
	s_add_i32 s28, s28, 2
	s_add_u32 s14, s14, 0x100
	s_addc_u32 s15, s15, 0
	s_add_u32 s26, s26, 0x100
	s_addc_u32 s27, s27, 0
	s_cmp_gt_u32 s28, 13
	s_cbranch_scc0 .LBB0_2273
	s_and_b64 vcc, exec, s[48:49]
	s_cbranch_vccz .LBB0_2276
	s_barrier
